# redundant vmcnt(0) drains in front of the first DMA issue of every GEMM tile / attention unit removed (counted waits already cover older ops)
# baseline (speedup 1.0000x reference)
;     ...
;   const int tid = opaque_tid(), lane = tid & 63, h = lane >> 5, r = lane & 31;
;   const int nk = K >> 6;
;   const int cch = (tid & 7) ^ ((tid >> 4) & 7);
;   const u16* ga = A + (size_t)(tid >> 3) * lda + cch * 8;
;   const u16* gb = Bt + (size_t)(tid >> 3) * ldb + cch * 8;
;   char* lds_t = smem + tid * 16;
;   auto issue_piece = [&](int kt, int pc) {
;     char* st = lds_t + (kt % NSTG) * STAGE;
;     if (pc < 4)
;       __builtin_amdgcn_global_load_lds((const unsigned*)(ga + (size_t)(64 * pc) * lda + (size_t)kt * ksa), (unsigned __attribute__((address_space(3)))*)(st + pc * 8192), 16, 0, 0);
;     else
;       __builtin_amdgcn_global_load_lds((const unsigned*)(gb + (size_t)(64 * (pc - 4)) * ldb + (size_t)kt * ksb), (unsigned __attribute__((address_space(3)))*)(st + ABYTES + (pc - 4) * 8192), 16, 0, 0);
;   };
;   const int x = (r >> 1) & 7;
;   int xo[4];
; #pragma unroll
;   for (int s = 0; s < 4; ++s) xo[s] = (((2 * s + h) ^ x) << 4);
;   asm volatile("s_waitcnt vmcnt(0)" ::: "memory");
; #pragma unroll
;   for (int d = 0; d < DIST; ++d)
; #pragma unroll
;     for (int pc = 0; pc < NLD; ++pc) issue_piece(d, pc);
;   pre();
; DEV void phase_outproj(const Params& p, int l, int hf, char* smem) {
;     ...
;   for (int t = blockIdx.x; t < nslots; t += gridDim.x) {
;     int mq, nt;
;     if (!tile_decode(t, 64, 8, 4, mq, nt)) continue;
;     const int mt = (mq >> 5) * 33 + 1 + (mq & 31);
;     f32x16 acc[2][2];
; #pragma unroll
;     for (int i = 0; i < 2; ++i)
; #pragma unroll
;       for (int j = 0; j < 2; ++j)
; #pragma unroll
;         for (int e = 0; e < 16; ++e) acc[i][j][e] = 0.f;
;     float4 xpre[2][2][4];
;     auto load_x = [&]() {
; #pragma unroll
;       for (int j = 0; j < 2; ++j) {
;         const int m = mt * 256 + wm * 64 + 32 * j + r;
;         const int bl = m / TP, tp = m - bl * TP;
;         const int b = hf * 2 + bl;
;         const float* src = (tp < CTXL) ? p.ctx + ((size_t)b * CTXL + tp) * DM : xs + ((size_t)b * SEQ + (tp - CTXL)) * DM;
; #pragma unroll
;         for (int i = 0; i < 2; ++i)
; #pragma unroll
;           for (int g4 = 0; g4 < 4; ++g4) xpre[i][j][g4] = *(const float4*)(src + nt * 128 + wn * 64 + 32 * i + 8 * g4 + 4 * h);
;       }
;     };
;     gemm_main<2, 2, 128, 3>(acc, Y + (size_t)mt * 256 * 1024, 1024, W + (size_t)nt * 128 * 1024, 1024, 1024, smem, wm * 64, wn * 64,
;                             64, 64, load_x);
.LBB0_19:
	s_lshl_b32 s3, s20, 6
	s_ashr_i32 s2, s20, 3
	s_and_b32 s3, s3, 0x1c0
	s_add_i32 s2, s3, s2
	s_ashr_i32 s3, s2, 31
	s_lshr_b32 s3, s3, 27
	s_add_i32 s3, s2, s3
	s_ashr_i32 s12, s3, 5
	s_andn2_b32 s3, s3, 31
	s_sub_i32 s3, s2, s3
	s_ashr_i32 s2, s3, 31
	s_lshr_b32 s2, s2, 30
	s_lshl_b32 s12, s12, 2
	s_add_i32 s13, s3, s2
	s_add_i32 s3, s3, s12
	s_and_b32 s12, s13, -4
	s_sub_i32 s3, s3, s12
	s_ashr_i32 s12, s3, 5
	s_and_b32 s3, s3, 31
	s_mul_i32 s12, s12, 33
	s_add_i32 s3, s3, s12
	s_add_i32 s12, s3, 1
	s_ashr_i32 s2, s13, 2
	s_ashr_i32 s13, s12, 31
	s_lshl_b64 s[22:23], s[12:13], 19
	s_add_u32 s22, s14, s22
	v_mov_b32_e32 v6, v147
	s_addc_u32 s23, s15, s23
	s_ashr_i32 s3, s2, 31
	s_lshl_b64 s[24:25], s[2:3], 18
	v_lshrrev_b32_e32 v0, 4, v6
	v_xor_b32_e32 v4, v0, v6
	v_ashrrev_i32_e32 v0, 3, v6
	s_add_u32 s24, s16, s24
	v_ashrrev_i32_e32 v1, 31, v0
	s_addc_u32 s25, s17, s25
	v_lshlrev_b64 v[0:1], 11, v[0:1]
	v_lshlrev_b32_e32 v4, 4, v4
	v_lshl_add_u32 v205, v6, 4, 0
	v_lshl_add_u64 v[2:3], s[24:25], 0, v[0:1]
	v_lshl_add_u64 v[0:1], s[22:23], 0, v[0:1]
	v_and_b32_e32 v144, 0x70, v4
	v_readfirstlane_b32 s41, v205
	v_add_u32_e32 v204, 0x2000, v205
	v_lshl_add_u64 v[140:141], v[0:1], 0, v[144:145]
	s_mov_b32 m0, s41
	v_readfirstlane_b32 s37, v204
	v_add_u32_e32 v203, 0x4000, v205
	global_load_lds_dwordx4 v[140:141], off
	v_lshl_add_u64 v[0:1], v[140:141], 0, s[56:57]
	s_mov_b32 m0, s37
	v_readfirstlane_b32 s31, v203
	v_add_u32_e32 v200, 0x6000, v205
	v_add_u32_e32 v195, 0x8000, v205
	global_load_lds_dwordx4 v[0:1], off
	v_lshl_add_u64 v[0:1], v[140:141], 0, s[82:83]
	s_mov_b32 m0, s31
	v_readfirstlane_b32 s28, v200
	global_load_lds_dwordx4 v[0:1], off
	v_lshl_add_u64 v[0:1], v[140:141], 0, s[92:93]
	s_mov_b32 m0, s28
	v_readfirstlane_b32 s27, v195
	v_add_u32_e32 v197, 0xa000, v205
	v_lshl_add_u64 v[138:139], v[2:3], 0, v[144:145]
	global_load_lds_dwordx4 v[0:1], off
	s_mov_b32 m0, s27
	v_readfirstlane_b32 s26, v197
	v_add_u32_e32 v193, 0xc000, v205
	global_load_lds_dwordx4 v[138:139], off
	v_lshl_add_u64 v[0:1], v[138:139], 0, s[56:57]
	s_mov_b32 m0, s26
	v_readfirstlane_b32 s25, v193
	v_add_u32_e32 v192, 0xe000, v205
	global_load_lds_dwordx4 v[0:1], off
	v_lshl_add_u64 v[2:3], v[140:141], 0, s[62:63]
	s_mov_b32 m0, s25
	v_readfirstlane_b32 s24, v192
	v_add_u32_e32 v191, 0x10000, v205
	global_load_lds_dwordx4 v[2:3], off
	v_lshl_add_u64 v[2:3], v[140:141], 0, s[64:65]
	s_mov_b32 m0, s24
	v_readfirstlane_b32 s23, v191
	v_add_u32_e32 v190, 0x12000, v205
	global_load_lds_dwordx4 v[2:3], off
	v_lshl_add_u64 v[2:3], v[140:141], 0, s[66:67]
	s_mov_b32 m0, s23
	v_readfirstlane_b32 s22, v190
	v_add_u32_e32 v4, 0x14000, v205
	global_load_lds_dwordx4 v[2:3], off
	v_lshl_add_u64 v[2:3], v[140:141], 0, s[76:77]
	s_mov_b32 m0, s22
	v_readfirstlane_b32 s21, v4
	global_load_lds_dwordx4 v[2:3], off
	v_add_u32_e32 v2, 0x16000, v205
	v_lshl_add_u64 v[0:1], v[138:139], 0, s[62:63]
	s_mov_b32 m0, s21
	v_readfirstlane_b32 s13, v2
	s_lshl_b32 s12, s12, 8
	global_load_lds_dwordx4 v[0:1], off
	v_lshl_add_u64 v[0:1], v[138:139], 0, s[64:65]
	s_mov_b32 m0, s13
	v_add_u32_e32 v154, s12, v149
	global_load_lds_dwordx4 v[0:1], off
	v_mul_hi_i32 v0, v154, s72
	v_lshrrev_b32_e32 v1, 31, v0
	v_ashrrev_i32_e32 v0, 11, v0
	v_add_u32_e32 v0, v0, v1
	v_mad_i32_i24 v136, v0, s73, v154
	s_movk_i32 s29, 0x100
	v_add_u32_e32 v134, s19, v0
	v_cmp_gt_i32_e32 vcc, s29, v136
	v_ashrrev_i32_e32 v135, 31, v134
	v_add_u32_e32 v144, 0xffffff00, v136
	v_ashrrev_i32_e32 v137, 31, v136
	v_cndmask_b32_e64 v4, 25, 20, vcc
	v_cndmask_b32_e32 v1, v152, v167, vcc
	v_cndmask_b32_e32 v0, v153, v168, vcc
	v_cndmask_b32_e32 v3, 0, v137, vcc
	v_cndmask_b32_e32 v2, v144, v136, vcc
	v_lshlrev_b64 v[4:5], v4, v[134:135]
	s_lshl_b32 s2, s2, 7
	v_lshl_add_u64 v[0:1], v[0:1], 0, v[4:5]
	v_lshlrev_b64 v[2:3], 12, v[2:3]
	s_ashr_i32 s3, s2, 31
	v_lshl_add_u64 v[0:1], v[0:1], 0, v[2:3]
	s_lshl_b64 s[42:43], s[2:3], 2
	v_lshl_add_u64 v[0:1], v[0:1], 0, s[42:43]
	v_lshl_add_u64 v[0:1], v[0:1], 0, v[130:131]
	v_lshl_add_u64 v[0:1], v[0:1], 0, v[132:133]
	global_load_dwordx4 v[124:127], v[0:1], off
	global_load_dwordx4 v[120:123], v[0:1], off offset:32
	global_load_dwordx4 v[116:119], v[0:1], off offset:64
	global_load_dwordx4 v[112:115], v[0:1], off offset:96
	global_load_dwordx4 v[108:111], v[0:1], off offset:128
	global_load_dwordx4 v[104:107], v[0:1], off offset:160
	global_load_dwordx4 v[100:103], v[0:1], off offset:192
	global_load_dwordx4 v[96:99], v[0:1], off offset:224
	v_add_u32_e32 v0, s12, v150
	v_mul_hi_i32 v1, v0, s72
	v_lshrrev_b32_e32 v2, 31, v1
	v_ashrrev_i32_e32 v1, 11, v1
	v_add_u32_e32 v1, v1, v2
	v_mad_i32_i24 v4, v1, s73, v0
	v_add_u32_e32 v0, s19, v1
	v_add_u32_e32 v7, 0xffffff00, v4
	v_cmp_gt_i32_e32 vcc, s29, v4
	v_ashrrev_i32_e32 v1, 31, v0
	v_ashrrev_i32_e32 v5, 31, v4
	v_cndmask_b32_e32 v4, v7, v4, vcc
	v_cndmask_b32_e64 v7, 25, 20, vcc
	v_cndmask_b32_e32 v3, v152, v167, vcc
	v_cndmask_b32_e32 v2, v153, v168, vcc
	v_cndmask_b32_e32 v5, 0, v5, vcc
	v_lshlrev_b64 v[0:1], v7, v[0:1]
	v_lshl_add_u64 v[0:1], v[2:3], 0, v[0:1]
	v_lshlrev_b64 v[2:3], 12, v[4:5]
	v_lshl_add_u64 v[0:1], v[0:1], 0, v[2:3]
	v_lshl_add_u64 v[0:1], v[0:1], 0, s[42:43]
	v_lshl_add_u64 v[0:1], v[0:1], 0, v[130:131]
	v_lshl_add_u64 v[0:1], v[0:1], 0, v[132:133]
	global_load_dwordx4 v[92:95], v[0:1], off
	global_load_dwordx4 v[88:91], v[0:1], off offset:32
	global_load_dwordx4 v[84:87], v[0:1], off offset:64
	global_load_dwordx4 v[80:83], v[0:1], off offset:96
	global_load_dwordx4 v[76:79], v[0:1], off offset:128
	global_load_dwordx4 v[72:75], v[0:1], off offset:160
	global_load_dwordx4 v[68:71], v[0:1], off offset:192
	global_load_dwordx4 v[64:67], v[0:1], off offset:224
	v_lshrrev_b32_e32 v0, 5, v6
	v_bfe_u32 v2, v6, 1, 3
	v_bfe_u32 v1, v6, 5, 1
	v_bitop3_b32 v0, v0, v2, 1 bitop3:0x6c
	v_lshlrev_b32_e32 v220, 4, v0
	v_bitop3_b32 v0, v1, v2, 2 bitop3:0x36
	v_lshlrev_b32_e32 v221, 4, v0
	v_bitop3_b32 v0, v1, v2, 4 bitop3:0x36
	v_lshlrev_b32_e32 v224, 4, v0
	v_bitop3_b32 v0, v1, v2, 6 bitop3:0x36
	v_lshlrev_b32_e32 v225, 4, v0
	v_and_b32_e32 v0, 31, v6
	v_or_b32_e32 v1, v0, v148
	v_or_b32_e32 v0, v0, v128
	v_lshlrev_b32_e32 v181, 7, v0
	v_add_u32_e32 v159, 0, v181
	v_add_u32_e32 v155, v159, v220
	v_lshlrev_b32_e32 v222, 7, v1
	s_waitcnt vmcnt(6)
	s_barrier
; #define MFMA(a, b, c) __builtin_amdgcn_mfma_f32_32x32x16_bf16((a), (b), (c), 0, 0, 0)
;     ...
;   for (int kt = 0; kt < nk; ++kt) {
;     if (DIST == 2 && kt + 1 < nk) {
;       if (NLD == 6) asm volatile("s_waitcnt vmcnt(6)" ::: "memory");
;       else if (NLD == 5) asm volatile("s_waitcnt vmcnt(5)" ::: "memory");
;       else asm volatile("s_waitcnt vmcnt(8)" ::: "memory");
;     } else {
;       asm volatile("s_waitcnt vmcnt(0)" ::: "memory");
;     }
;     __builtin_amdgcn_s_barrier();
;     const bool pre = (kt + DIST < nk);
;     const char* base = smem + (kt % NSTG) * STAGE;
;     const char* pa = base + (wrow_act + r) * 128;
;     const char* pw = base + ABYTES + (wrow_w + r) * 128;
;     constexpr int NM = NI * MJ;
;     constexpr int PPS = (NLD + 1) / 2;
; #pragma unroll
;     for (int s = 0; s < 4; ++s) {
;       bf16x8 af[MJ], wf[NI];
; #pragma unroll
;       for (int j = 0; j < MJ; ++j) af[j] = *(const bf16x8*)(pa + j * 32 * 128 + xo[s]);
; #pragma unroll
;       for (int i = 0; i < NI; ++i) wf[i] = *(const bf16x8*)(pw + i * 32 * 128 + xo[s]);
; #pragma unroll
;       for (int m = 0; m < NM; ++m) {
;         const int i = m / MJ, j = m % MJ;
;         acc[i][j] = MFMA(wf[i], af[j], acc[i][j]);
;         if (s < 2 && NM >= PPS) {
;           constexpr int EVERY = (NM / PPS) > 0 ? (NM / PPS) : 1;
;           if ((m + 1) % EVERY == 0) {
;             const int pc = s * PPS + (m + 1) / EVERY - 1;
;             if ((m + 1) / EVERY <= PPS && pc < NLD) {
;               __builtin_amdgcn_sched_barrier(0);
;               if (pre) issue_piece(kt + DIST, pc);
;               __builtin_amdgcn_sched_barrier(0);
;             }
;           }
;         }
;         if (s < 2 && NM < PPS) {
;           const int slot = s * NM + m;
;           __builtin_amdgcn_sched_barrier(0);
; #pragma unroll
;           for (int pc = 0; pc < NLD; ++pc)
;             if ((pc * 2 * NM) / NLD == slot && pre) issue_piece(kt + DIST, pc);
;           __builtin_amdgcn_sched_barrier(0);
;         }
;       }
;     }
	ds_read_b128 v[0:3], v155 offset:32768
	v_add_u32_e32 v214, 0, v222
	v_add_u32_e32 v156, v214, v220
	ds_read_b128 v[4:7], v156
	s_waitcnt lgkmcnt(0)
	v_mfma_f32_32x32x16_bf16 v[48:63], v[0:3], v[4:7], 0
	ds_read_b128 v[8:11], v156 offset:4096
	ds_read_b128 v[12:15], v155 offset:36864
	v_cmp_lt_i32_e32 vcc, s70, v136
	v_add_u32_e32 v196, 0x18000, v205
	v_lshl_add_u64 v[164:165], v[138:139], 0, s[78:79]
	v_add_u32_e32 v194, 0x20000, v205
	v_readfirstlane_b32 s3, v196
	v_lshl_add_u64 v[16:17], v[140:141], 0, s[78:79]
	s_mov_b32 m0, s3
	s_nop 0
	global_load_lds_dwordx4 v[16:17], off
	s_waitcnt lgkmcnt(0)
	v_mfma_f32_32x32x16_bf16 v[16:31], v[0:3], v[8:11], 0
	v_add_u32_e32 v198, 0x1a000, v205
	s_mov_b64 s[42:43], 0x20100
	v_readfirstlane_b32 s12, v198
	v_lshl_add_u64 v[0:1], v[140:141], 0, s[42:43]
	s_mov_b32 m0, s12
	s_nop 0
	global_load_lds_dwordx4 v[0:1], off
	v_mfma_f32_32x32x16_bf16 v[32:47], v[12:15], v[4:7], 0
	v_add_u32_e32 v199, 0x1c000, v205
	s_mov_b64 s[44:45], 0x40100
	v_readfirstlane_b32 s29, v199
	v_lshl_add_u64 v[0:1], v[140:141], 0, s[44:45]
	s_mov_b32 m0, s29
	s_nop 0
	global_load_lds_dwordx4 v[0:1], off
	v_add_u32_e32 v157, v159, v221
	ds_read_b128 v[160:163], v157 offset:32768
	v_add_u32_e32 v158, v214, v221
	ds_read_b128 v[182:185], v158
	ds_read_b128 v[186:189], v158 offset:4096
	ds_read_b128 v[206:209], v157 offset:36864
	v_mfma_f32_32x32x16_bf16 v[0:15], v[12:15], v[8:11], 0
	s_waitcnt lgkmcnt(0)
	v_mfma_f32_32x32x16_bf16 v[48:63], v[160:163], v[182:185], v[48:63]
	v_add_u32_e32 v201, 0x1e000, v205
	s_mov_b64 s[44:45], 0x60100
	v_readfirstlane_b32 s30, v201
	v_lshl_add_u64 v[210:211], v[140:141], 0, s[44:45]
	s_mov_b32 m0, s30
	s_nop 0
	global_load_lds_dwordx4 v[210:211], off
	v_mfma_f32_32x32x16_bf16 v[16:31], v[160:163], v[186:189], v[16:31]
	v_readfirstlane_b32 s36, v194
	s_mov_b32 m0, s36
	s_nop 0
	global_load_lds_dwordx4 v[164:165], off
	v_mfma_f32_32x32x16_bf16 v[32:47], v[206:209], v[182:185], v[32:47]
	v_add_u32_e32 v202, 0x22000, v205
	v_lshl_add_u64 v[160:161], v[138:139], 0, s[42:43]
	v_readfirstlane_b32 s40, v202
	s_mov_b32 m0, s40
	s_nop 0
	global_load_lds_dwordx4 v[160:161], off
	v_add_u32_e32 v160, v159, v224
	ds_read_b128 v[182:185], v160 offset:32768
	v_add_u32_e32 v162, v214, v224
	v_mfma_f32_32x32x16_bf16 v[0:15], v[206:209], v[186:189], v[0:15]
	ds_read_b128 v[186:189], v162
	ds_read_b128 v[206:209], v162 offset:4096
	ds_read_b128 v[210:213], v160 offset:36864
	v_add_u32_e32 v159, v159, v225
	v_add_u32_e32 v161, v214, v225
	s_add_i32 s42, 0, 0x14000
	v_add_u32_e32 v163, s42, v181
	v_add_u32_e32 v165, v163, v220
	s_mov_b64 s[42:43], 0x180
	s_waitcnt lgkmcnt(0)
	v_mfma_f32_32x32x16_bf16 v[48:63], v[182:185], v[186:189], v[48:63]
	v_lshl_add_u64 v[218:219], v[138:139], 0, s[42:43]
	v_mfma_f32_32x32x16_bf16 v[16:31], v[182:185], v[206:209], v[16:31]
	ds_read_b128 v[182:185], v159 offset:32768
	v_mfma_f32_32x32x16_bf16 v[32:47], v[210:213], v[186:189], v[32:47]
	v_mfma_f32_32x32x16_bf16 v[0:15], v[210:213], v[206:209], v[0:15]
	ds_read_b128 v[186:189], v161
	ds_read_b128 v[206:209], v161 offset:4096
	ds_read_b128 v[210:213], v159 offset:36864
	s_waitcnt vmcnt(6)
	s_barrier
	s_waitcnt lgkmcnt(0)
	v_mfma_f32_32x32x16_bf16 v[48:63], v[182:185], v[186:189], v[48:63]
	v_mfma_f32_32x32x16_bf16 v[16:31], v[182:185], v[206:209], v[16:31]
	v_mfma_f32_32x32x16_bf16 v[32:47], v[210:213], v[186:189], v[32:47]
	ds_read_b128 v[182:185], v165
	ds_read_b128 v[186:189], v156 offset:49152
	v_mfma_f32_32x32x16_bf16 v[0:15], v[210:213], v[206:209], v[0:15]
	ds_read_b128 v[206:209], v156 offset:53248
	ds_read_b128 v[210:213], v165 offset:4096
	s_waitcnt lgkmcnt(0)
	v_mfma_f32_32x32x16_bf16 v[48:63], v[182:185], v[186:189], v[48:63]
	v_lshl_add_u64 v[214:215], v[140:141], 0, s[42:43]
	s_mov_b32 m0, s41
	s_nop 0
	global_load_lds_dwordx4 v[214:215], off
	v_mfma_f32_32x32x16_bf16 v[16:31], v[182:185], v[206:209], v[16:31]
	s_mov_b64 s[42:43], 0x20180
	v_lshl_add_u64 v[182:183], v[140:141], 0, s[42:43]
	s_mov_b32 m0, s37
	s_nop 0
	global_load_lds_dwordx4 v[182:183], off
	v_mfma_f32_32x32x16_bf16 v[32:47], v[210:213], v[186:189], v[32:47]
	s_mov_b64 s[44:45], 0x40180
	v_lshl_add_u64 v[182:183], v[140:141], 0, s[44:45]
	s_mov_b32 m0, s31
	s_nop 0
	global_load_lds_dwordx4 v[182:183], off
	v_add_u32_e32 v182, v163, v221
	v_mfma_f32_32x32x16_bf16 v[0:15], v[210:213], v[206:209], v[0:15]
	ds_read_b128 v[184:187], v182
	ds_read_b128 v[206:209], v158 offset:49152
	ds_read_b128 v[210:213], v158 offset:53248
	ds_read_b128 v[214:217], v182 offset:4096
	s_waitcnt lgkmcnt(0)
	v_mfma_f32_32x32x16_bf16 v[48:63], v[184:187], v[206:209], v[48:63]
	s_mov_b64 s[44:45], 0x60180
	v_lshl_add_u64 v[188:189], v[140:141], 0, s[44:45]
	s_mov_b32 m0, s28
	s_nop 0
	global_load_lds_dwordx4 v[188:189], off
	v_mfma_f32_32x32x16_bf16 v[16:31], v[184:187], v[210:213], v[16:31]
	s_mov_b32 m0, s27
	s_nop 0
	global_load_lds_dwordx4 v[218:219], off
	v_mfma_f32_32x32x16_bf16 v[32:47], v[214:217], v[206:209], v[32:47]
	v_lshl_add_u64 v[184:185], v[138:139], 0, s[42:43]
	s_mov_b32 m0, s26
	s_nop 0
	global_load_lds_dwordx4 v[184:185], off
	v_add_u32_e32 v164, v163, v224
	v_mfma_f32_32x32x16_bf16 v[0:15], v[214:217], v[210:213], v[0:15]
	ds_read_b128 v[184:187], v164
	ds_read_b128 v[206:209], v162 offset:49152
	ds_read_b128 v[210:213], v162 offset:53248
	ds_read_b128 v[214:217], v164 offset:4096
	v_add_u32_e32 v163, v163, v225
	s_add_i32 s42, 0, 0x20000
	v_add_u32_e32 v226, s42, v181
	v_add_u32_e32 v181, v226, v220
	s_add_i32 s42, 0, 0x18000
	v_add_u32_e32 v227, s42, v222
	s_waitcnt lgkmcnt(0)
	v_mfma_f32_32x32x16_bf16 v[48:63], v[184:187], v[206:209], v[48:63]
	v_add_u32_e32 v183, v227, v220
	s_mov_b64 s[42:43], 0x200
	v_lshl_add_u64 v[188:189], v[138:139], 0, s[42:43]
	v_mfma_f32_32x32x16_bf16 v[16:31], v[184:187], v[210:213], v[16:31]
	v_mfma_f32_32x32x16_bf16 v[32:47], v[214:217], v[206:209], v[32:47]
	v_mfma_f32_32x32x16_bf16 v[0:15], v[214:217], v[210:213], v[0:15]
	ds_read_b128 v[184:187], v163
	ds_read_b128 v[206:209], v161 offset:49152
	ds_read_b128 v[210:213], v161 offset:53248
	ds_read_b128 v[214:217], v163 offset:4096
	s_waitcnt vmcnt(6)
	s_barrier
; #define MFMA(a, b, c) __builtin_amdgcn_mfma_f32_32x32x16_bf16((a), (b), (c), 0, 0, 0)
;     ...
;   for (int kt = 0; kt < nk; ++kt) {
;     if (DIST == 2 && kt + 1 < nk) {
;       if (NLD == 6) asm volatile("s_waitcnt vmcnt(6)" ::: "memory");
;       else if (NLD == 5) asm volatile("s_waitcnt vmcnt(5)" ::: "memory");
;       else asm volatile("s_waitcnt vmcnt(8)" ::: "memory");
;     } else {
;       asm volatile("s_waitcnt vmcnt(0)" ::: "memory");
;     }
;     __builtin_amdgcn_s_barrier();
;     const bool pre = (kt + DIST < nk);
;     const char* base = smem + (kt % NSTG) * STAGE;
;     const char* pa = base + (wrow_act + r) * 128;
;     const char* pw = base + ABYTES + (wrow_w + r) * 128;
;     constexpr int NM = NI * MJ;
;     constexpr int PPS = (NLD + 1) / 2;
; #pragma unroll
;     for (int s = 0; s < 4; ++s) {
;       bf16x8 af[MJ], wf[NI];
; #pragma unroll
;       for (int j = 0; j < MJ; ++j) af[j] = *(const bf16x8*)(pa + j * 32 * 128 + xo[s]);
; #pragma unroll
;       for (int i = 0; i < NI; ++i) wf[i] = *(const bf16x8*)(pw + i * 32 * 128 + xo[s]);
; #pragma unroll
;       for (int m = 0; m < NM; ++m) {
;         const int i = m / MJ, j = m % MJ;
;         acc[i][j] = MFMA(wf[i], af[j], acc[i][j]);
;         if (s < 2 && NM >= PPS) {
;           constexpr int EVERY = (NM / PPS) > 0 ? (NM / PPS) : 1;
;           if ((m + 1) % EVERY == 0) {
;             const int pc = s * PPS + (m + 1) / EVERY - 1;
;             if ((m + 1) / EVERY <= PPS && pc < NLD) {
;               __builtin_amdgcn_sched_barrier(0);
;               if (pre) issue_piece(kt + DIST, pc);
;               __builtin_amdgcn_sched_barrier(0);
;             }
;           }
;         }
;         if (s < 2 && NM < PPS) {
;           const int slot = s * NM + m;
;           __builtin_amdgcn_sched_barrier(0);
; #pragma unroll
;           for (int pc = 0; pc < NLD; ++pc)
;             if ((pc * 2 * NM) / NLD == slot && pre) issue_piece(kt + DIST, pc);
;           __builtin_amdgcn_sched_barrier(0);
;         }
;       }
;     }
	s_waitcnt lgkmcnt(0)
	v_mfma_f32_32x32x16_bf16 v[48:63], v[184:187], v[206:209], v[48:63]
	v_mfma_f32_32x32x16_bf16 v[16:31], v[184:187], v[210:213], v[16:31]
	ds_read_b128 v[184:187], v181
	v_mfma_f32_32x32x16_bf16 v[32:47], v[214:217], v[206:209], v[32:47]
	ds_read_b128 v[206:209], v183
	v_mfma_f32_32x32x16_bf16 v[0:15], v[214:217], v[210:213], v[0:15]
	ds_read_b128 v[210:213], v183 offset:4096
	ds_read_b128 v[214:217], v181 offset:4096
	s_waitcnt lgkmcnt(0)
	v_mfma_f32_32x32x16_bf16 v[48:63], v[184:187], v[206:209], v[48:63]
	v_lshl_add_u64 v[218:219], v[140:141], 0, s[42:43]
	s_mov_b32 m0, s25
	s_nop 0
	global_load_lds_dwordx4 v[218:219], off
	v_mfma_f32_32x32x16_bf16 v[16:31], v[184:187], v[210:213], v[16:31]
	s_mov_b64 s[42:43], 0x20200
	v_lshl_add_u64 v[184:185], v[140:141], 0, s[42:43]
	s_mov_b32 m0, s24
	s_nop 0
	global_load_lds_dwordx4 v[184:185], off
	v_mfma_f32_32x32x16_bf16 v[32:47], v[214:217], v[206:209], v[32:47]
	s_mov_b64 s[44:45], 0x40200
	v_lshl_add_u64 v[184:185], v[140:141], 0, s[44:45]
	s_mov_b32 m0, s23
	s_nop 0
	global_load_lds_dwordx4 v[184:185], off
	v_add_u32_e32 v184, v226, v221
	ds_read_b128 v[206:209], v184
	v_add_u32_e32 v186, v227, v221
	v_mfma_f32_32x32x16_bf16 v[0:15], v[214:217], v[210:213], v[0:15]
	ds_read_b128 v[210:213], v186
	ds_read_b128 v[214:217], v186 offset:4096
	ds_read_b128 v[218:221], v184 offset:4096
	s_waitcnt lgkmcnt(0)
	v_mfma_f32_32x32x16_bf16 v[48:63], v[206:209], v[210:213], v[48:63]
	s_mov_b64 s[44:45], 0x60200
	v_lshl_add_u64 v[222:223], v[140:141], 0, s[44:45]
	s_mov_b32 m0, s22
	s_nop 0
	global_load_lds_dwordx4 v[222:223], off
	v_mfma_f32_32x32x16_bf16 v[16:31], v[206:209], v[214:217], v[16:31]
	s_mov_b32 m0, s21
	s_nop 0
	global_load_lds_dwordx4 v[188:189], off
	v_mfma_f32_32x32x16_bf16 v[32:47], v[218:221], v[210:213], v[32:47]
	v_lshl_add_u64 v[188:189], v[138:139], 0, s[42:43]
	s_mov_b32 m0, s13
	s_nop 0
	global_load_lds_dwordx4 v[188:189], off
	v_add_u32_e32 v187, v226, v224
	ds_read_b128 v[206:209], v187
	v_add_u32_e32 v189, v227, v224
	v_mfma_f32_32x32x16_bf16 v[0:15], v[218:221], v[214:217], v[0:15]
	ds_read_b128 v[210:213], v189
	ds_read_b128 v[214:217], v189 offset:4096
	ds_read_b128 v[218:221], v187 offset:4096
	v_add_u32_e32 v185, v226, v225
	v_add_u32_e32 v188, v227, v225
	s_mov_b64 s[42:43], 0x280
	v_lshl_add_u64 v[222:223], v[138:139], 0, s[42:43]
	s_waitcnt lgkmcnt(0)
	v_mfma_f32_32x32x16_bf16 v[48:63], v[206:209], v[210:213], v[48:63]
	v_mfma_f32_32x32x16_bf16 v[16:31], v[206:209], v[214:217], v[16:31]
	ds_read_b128 v[206:209], v185
	v_mfma_f32_32x32x16_bf16 v[32:47], v[218:221], v[210:213], v[32:47]
	v_mfma_f32_32x32x16_bf16 v[0:15], v[218:221], v[214:217], v[0:15]
	ds_read_b128 v[210:213], v188
	ds_read_b128 v[214:217], v188 offset:4096
	ds_read_b128 v[218:221], v185 offset:4096
	s_waitcnt vmcnt(6)
	s_barrier
	s_waitcnt lgkmcnt(0)
	v_mfma_f32_32x32x16_bf16 v[48:63], v[206:209], v[210:213], v[48:63]
	v_mfma_f32_32x32x16_bf16 v[16:31], v[206:209], v[214:217], v[16:31]
	v_mfma_f32_32x32x16_bf16 v[32:47], v[218:221], v[210:213], v[32:47]
	ds_read_b128 v[206:209], v155 offset:32768
	ds_read_b128 v[210:213], v156
	v_mfma_f32_32x32x16_bf16 v[0:15], v[218:221], v[214:217], v[0:15]
	ds_read_b128 v[214:217], v156 offset:4096
	ds_read_b128 v[218:221], v155 offset:36864
	s_waitcnt lgkmcnt(0)
	v_mfma_f32_32x32x16_bf16 v[48:63], v[206:209], v[210:213], v[48:63]
	v_lshl_add_u64 v[224:225], v[140:141], 0, s[42:43]
	s_mov_b32 m0, s3
	s_nop 0
	global_load_lds_dwordx4 v[224:225], off
	v_mfma_f32_32x32x16_bf16 v[16:31], v[206:209], v[214:217], v[16:31]
	s_mov_b64 s[42:43], 0x20280
	v_lshl_add_u64 v[206:207], v[140:141], 0, s[42:43]
	s_mov_b32 m0, s12
	s_nop 0
	global_load_lds_dwordx4 v[206:207], off
	v_mfma_f32_32x32x16_bf16 v[32:47], v[218:221], v[210:213], v[32:47]
	s_mov_b64 s[44:45], 0x40280
	v_lshl_add_u64 v[206:207], v[140:141], 0, s[44:45]
	s_mov_b32 m0, s29
	s_nop 0
	global_load_lds_dwordx4 v[206:207], off
	v_mfma_f32_32x32x16_bf16 v[0:15], v[218:221], v[214:217], v[0:15]
	ds_read_b128 v[206:209], v157 offset:32768
	ds_read_b128 v[210:213], v158
	ds_read_b128 v[214:217], v158 offset:4096
	ds_read_b128 v[218:221], v157 offset:36864
	s_waitcnt lgkmcnt(0)
	v_mfma_f32_32x32x16_bf16 v[48:63], v[206:209], v[210:213], v[48:63]
	s_mov_b64 s[44:45], 0x60280
	v_lshl_add_u64 v[224:225], v[140:141], 0, s[44:45]
	s_mov_b32 m0, s30
	s_nop 0
	global_load_lds_dwordx4 v[224:225], off
	v_mfma_f32_32x32x16_bf16 v[16:31], v[206:209], v[214:217], v[16:31]
	s_mov_b32 m0, s36
	s_nop 0
	global_load_lds_dwordx4 v[222:223], off
	v_mfma_f32_32x32x16_bf16 v[32:47], v[218:221], v[210:213], v[32:47]
	v_lshl_add_u64 v[206:207], v[138:139], 0, s[42:43]
	s_mov_b32 m0, s40
	s_nop 0
	global_load_lds_dwordx4 v[206:207], off
	v_mfma_f32_32x32x16_bf16 v[0:15], v[218:221], v[214:217], v[0:15]
	ds_read_b128 v[206:209], v160 offset:32768
	ds_read_b128 v[210:213], v162
	ds_read_b128 v[214:217], v162 offset:4096
	ds_read_b128 v[218:221], v160 offset:36864
	s_mov_b64 s[42:43], 0x300
	v_lshl_add_u64 v[222:223], v[138:139], 0, s[42:43]
	s_waitcnt lgkmcnt(0)
	v_mfma_f32_32x32x16_bf16 v[48:63], v[206:209], v[210:213], v[48:63]
	v_mfma_f32_32x32x16_bf16 v[16:31], v[206:209], v[214:217], v[16:31]
	v_mfma_f32_32x32x16_bf16 v[32:47], v[218:221], v[210:213], v[32:47]
	v_mfma_f32_32x32x16_bf16 v[0:15], v[218:221], v[214:217], v[0:15]
	ds_read_b128 v[206:209], v159 offset:32768
	ds_read_b128 v[210:213], v161
	ds_read_b128 v[214:217], v161 offset:4096
	ds_read_b128 v[218:221], v159 offset:36864
	s_waitcnt vmcnt(6)
	s_barrier
; #define MFMA(a, b, c) __builtin_amdgcn_mfma_f32_32x32x16_bf16((a), (b), (c), 0, 0, 0)
;     ...
;   for (int kt = 0; kt < nk; ++kt) {
;     if (DIST == 2 && kt + 1 < nk) {
;       if (NLD == 6) asm volatile("s_waitcnt vmcnt(6)" ::: "memory");
;       else if (NLD == 5) asm volatile("s_waitcnt vmcnt(5)" ::: "memory");
;       else asm volatile("s_waitcnt vmcnt(8)" ::: "memory");
;     } else {
;       asm volatile("s_waitcnt vmcnt(0)" ::: "memory");
;     }
;     __builtin_amdgcn_s_barrier();
;     const bool pre = (kt + DIST < nk);
;     const char* base = smem + (kt % NSTG) * STAGE;
;     const char* pa = base + (wrow_act + r) * 128;
;     const char* pw = base + ABYTES + (wrow_w + r) * 128;
;     constexpr int NM = NI * MJ;
;     constexpr int PPS = (NLD + 1) / 2;
; #pragma unroll
;     for (int s = 0; s < 4; ++s) {
;       bf16x8 af[MJ], wf[NI];
; #pragma unroll
;       for (int j = 0; j < MJ; ++j) af[j] = *(const bf16x8*)(pa + j * 32 * 128 + xo[s]);
; #pragma unroll
;       for (int i = 0; i < NI; ++i) wf[i] = *(const bf16x8*)(pw + i * 32 * 128 + xo[s]);
; #pragma unroll
;       for (int m = 0; m < NM; ++m) {
;         const int i = m / MJ, j = m % MJ;
;         acc[i][j] = MFMA(wf[i], af[j], acc[i][j]);
;         if (s < 2 && NM >= PPS) {
;           constexpr int EVERY = (NM / PPS) > 0 ? (NM / PPS) : 1;
;           if ((m + 1) % EVERY == 0) {
;             const int pc = s * PPS + (m + 1) / EVERY - 1;
;             if ((m + 1) / EVERY <= PPS && pc < NLD) {
;               __builtin_amdgcn_sched_barrier(0);
;               if (pre) issue_piece(kt + DIST, pc);
;               __builtin_amdgcn_sched_barrier(0);
;             }
;           }
;         }
;         if (s < 2 && NM < PPS) {
;           const int slot = s * NM + m;
;           __builtin_amdgcn_sched_barrier(0);
; #pragma unroll
;           for (int pc = 0; pc < NLD; ++pc)
;             if ((pc * 2 * NM) / NLD == slot && pre) issue_piece(kt + DIST, pc);
;           __builtin_amdgcn_sched_barrier(0);
;         }
;       }
;     }
	s_waitcnt lgkmcnt(0)
	v_mfma_f32_32x32x16_bf16 v[48:63], v[206:209], v[210:213], v[48:63]
	v_mfma_f32_32x32x16_bf16 v[16:31], v[206:209], v[214:217], v[16:31]
	v_mfma_f32_32x32x16_bf16 v[32:47], v[218:221], v[210:213], v[32:47]
	ds_read_b128 v[206:209], v165
	ds_read_b128 v[210:213], v156 offset:49152
	v_mfma_f32_32x32x16_bf16 v[0:15], v[218:221], v[214:217], v[0:15]
	ds_read_b128 v[214:217], v156 offset:53248
	ds_read_b128 v[218:221], v165 offset:4096
	s_waitcnt lgkmcnt(0)
	v_mfma_f32_32x32x16_bf16 v[48:63], v[206:209], v[210:213], v[48:63]
	v_lshl_add_u64 v[224:225], v[140:141], 0, s[42:43]
	s_mov_b32 m0, s41
	s_nop 0
	global_load_lds_dwordx4 v[224:225], off
	v_mfma_f32_32x32x16_bf16 v[16:31], v[206:209], v[214:217], v[16:31]
	s_mov_b64 s[38:39], 0x20300
	v_lshl_add_u64 v[206:207], v[140:141], 0, s[38:39]
	s_mov_b32 m0, s37
	s_nop 0
	global_load_lds_dwordx4 v[206:207], off
	v_mfma_f32_32x32x16_bf16 v[32:47], v[218:221], v[210:213], v[32:47]
	v_lshl_add_u64 v[206:207], v[140:141], 0, s[86:87]
	s_mov_b32 m0, s31
	s_nop 0
	global_load_lds_dwordx4 v[206:207], off
	v_mfma_f32_32x32x16_bf16 v[0:15], v[218:221], v[214:217], v[0:15]
	ds_read_b128 v[206:209], v182
	ds_read_b128 v[210:213], v158 offset:49152
	ds_read_b128 v[214:217], v158 offset:53248
	ds_read_b128 v[218:221], v182 offset:4096
	s_waitcnt lgkmcnt(0)
	v_mfma_f32_32x32x16_bf16 v[48:63], v[206:209], v[210:213], v[48:63]
	v_lshl_add_u64 v[224:225], v[140:141], 0, s[88:89]
	s_mov_b32 m0, s28
	s_nop 0
	global_load_lds_dwordx4 v[224:225], off
	v_mfma_f32_32x32x16_bf16 v[16:31], v[206:209], v[214:217], v[16:31]
	s_mov_b32 m0, s27
	s_nop 0
	global_load_lds_dwordx4 v[222:223], off
	v_mfma_f32_32x32x16_bf16 v[32:47], v[218:221], v[210:213], v[32:47]
	v_lshl_add_u64 v[206:207], v[138:139], 0, s[38:39]
	s_mov_b32 m0, s26
	s_nop 0
	global_load_lds_dwordx4 v[206:207], off
	v_mfma_f32_32x32x16_bf16 v[0:15], v[218:221], v[214:217], v[0:15]
	ds_read_b128 v[206:209], v164
	ds_read_b128 v[210:213], v162 offset:49152
	ds_read_b128 v[214:217], v162 offset:53248
	ds_read_b128 v[218:221], v164 offset:4096
	s_mov_b64 s[26:27], 0x380
	v_lshl_add_u64 v[222:223], v[138:139], 0, s[26:27]
	s_waitcnt lgkmcnt(0)
	v_mfma_f32_32x32x16_bf16 v[48:63], v[206:209], v[210:213], v[48:63]
	v_mfma_f32_32x32x16_bf16 v[16:31], v[206:209], v[214:217], v[16:31]
	v_mfma_f32_32x32x16_bf16 v[32:47], v[218:221], v[210:213], v[32:47]
	v_mfma_f32_32x32x16_bf16 v[0:15], v[218:221], v[214:217], v[0:15]
	ds_read_b128 v[206:209], v163
	ds_read_b128 v[210:213], v161 offset:49152
	ds_read_b128 v[214:217], v161 offset:53248
	ds_read_b128 v[218:221], v163 offset:4096
	s_waitcnt vmcnt(6)
	s_barrier
	s_waitcnt lgkmcnt(0)
	v_mfma_f32_32x32x16_bf16 v[48:63], v[206:209], v[210:213], v[48:63]
	v_mfma_f32_32x32x16_bf16 v[16:31], v[206:209], v[214:217], v[16:31]
	v_mfma_f32_32x32x16_bf16 v[32:47], v[218:221], v[210:213], v[32:47]
	ds_read_b128 v[206:209], v181
	ds_read_b128 v[210:213], v183
	v_mfma_f32_32x32x16_bf16 v[0:15], v[218:221], v[214:217], v[0:15]
	ds_read_b128 v[214:217], v183 offset:4096
	ds_read_b128 v[218:221], v181 offset:4096
	s_waitcnt lgkmcnt(0)
	v_mfma_f32_32x32x16_bf16 v[48:63], v[206:209], v[210:213], v[48:63]
	v_lshl_add_u64 v[224:225], v[140:141], 0, s[26:27]
	s_mov_b32 m0, s25
	s_nop 0
	global_load_lds_dwordx4 v[224:225], off
	v_mfma_f32_32x32x16_bf16 v[16:31], v[206:209], v[214:217], v[16:31]
	s_mov_b64 s[26:27], 0x20380
	v_lshl_add_u64 v[206:207], v[140:141], 0, s[26:27]
	s_mov_b32 m0, s24
	s_nop 0
	global_load_lds_dwordx4 v[206:207], off
	v_mfma_f32_32x32x16_bf16 v[32:47], v[218:221], v[210:213], v[32:47]
	s_mov_b64 s[24:25], 0x40380
	v_lshl_add_u64 v[206:207], v[140:141], 0, s[24:25]
	s_mov_b32 m0, s23
	s_nop 0
	global_load_lds_dwordx4 v[206:207], off
	v_mfma_f32_32x32x16_bf16 v[0:15], v[218:221], v[214:217], v[0:15]
	ds_read_b128 v[206:209], v184
	ds_read_b128 v[210:213], v186
	ds_read_b128 v[214:217], v186 offset:4096
	ds_read_b128 v[218:221], v184 offset:4096
	s_waitcnt lgkmcnt(0)
	v_mfma_f32_32x32x16_bf16 v[48:63], v[206:209], v[210:213], v[48:63]
	s_mov_b64 s[24:25], 0x60380
	v_lshl_add_u64 v[224:225], v[140:141], 0, s[24:25]
	s_mov_b32 m0, s22
	s_nop 0
	global_load_lds_dwordx4 v[224:225], off
	v_mfma_f32_32x32x16_bf16 v[16:31], v[206:209], v[214:217], v[16:31]
	s_mov_b32 m0, s21
	s_nop 0
	global_load_lds_dwordx4 v[222:223], off
	v_mfma_f32_32x32x16_bf16 v[32:47], v[218:221], v[210:213], v[32:47]
	v_lshl_add_u64 v[206:207], v[138:139], 0, s[26:27]
	s_mov_b32 m0, s13
	s_nop 0
	global_load_lds_dwordx4 v[206:207], off
	v_mfma_f32_32x32x16_bf16 v[0:15], v[218:221], v[214:217], v[0:15]
	ds_read_b128 v[206:209], v187
	ds_read_b128 v[210:213], v189
	ds_read_b128 v[214:217], v189 offset:4096
	ds_read_b128 v[218:221], v187 offset:4096
	s_mov_b64 s[22:23], 0x400
	v_lshl_add_u64 v[222:223], v[138:139], 0, s[22:23]
	s_waitcnt lgkmcnt(0)
	v_mfma_f32_32x32x16_bf16 v[48:63], v[206:209], v[210:213], v[48:63]
	v_mfma_f32_32x32x16_bf16 v[16:31], v[206:209], v[214:217], v[16:31]
	v_mfma_f32_32x32x16_bf16 v[32:47], v[218:221], v[210:213], v[32:47]
	v_mfma_f32_32x32x16_bf16 v[0:15], v[218:221], v[214:217], v[0:15]
	ds_read_b128 v[206:209], v185
	ds_read_b128 v[210:213], v188
	ds_read_b128 v[214:217], v188 offset:4096
	ds_read_b128 v[218:221], v185 offset:4096
	s_waitcnt vmcnt(6)
	s_barrier
; #define MFMA(a, b, c) __builtin_amdgcn_mfma_f32_32x32x16_bf16((a), (b), (c), 0, 0, 0)
;     ...
;   for (int kt = 0; kt < nk; ++kt) {
;     if (DIST == 2 && kt + 1 < nk) {
;       if (NLD == 6) asm volatile("s_waitcnt vmcnt(6)" ::: "memory");
;       else if (NLD == 5) asm volatile("s_waitcnt vmcnt(5)" ::: "memory");
;       else asm volatile("s_waitcnt vmcnt(8)" ::: "memory");
;     } else {
;       asm volatile("s_waitcnt vmcnt(0)" ::: "memory");
;     }
;     __builtin_amdgcn_s_barrier();
;     const bool pre = (kt + DIST < nk);
;     const char* base = smem + (kt % NSTG) * STAGE;
;     const char* pa = base + (wrow_act + r) * 128;
;     const char* pw = base + ABYTES + (wrow_w + r) * 128;
;     constexpr int NM = NI * MJ;
;     constexpr int PPS = (NLD + 1) / 2;
; #pragma unroll
;     for (int s = 0; s < 4; ++s) {
;       bf16x8 af[MJ], wf[NI];
; #pragma unroll
;       for (int j = 0; j < MJ; ++j) af[j] = *(const bf16x8*)(pa + j * 32 * 128 + xo[s]);
; #pragma unroll
;       for (int i = 0; i < NI; ++i) wf[i] = *(const bf16x8*)(pw + i * 32 * 128 + xo[s]);
; #pragma unroll
;       for (int m = 0; m < NM; ++m) {
;         const int i = m / MJ, j = m % MJ;
;         acc[i][j] = MFMA(wf[i], af[j], acc[i][j]);
;         if (s < 2 && NM >= PPS) {
;           constexpr int EVERY = (NM / PPS) > 0 ? (NM / PPS) : 1;
;           if ((m + 1) % EVERY == 0) {
;             const int pc = s * PPS + (m + 1) / EVERY - 1;
;             if ((m + 1) / EVERY <= PPS && pc < NLD) {
;               __builtin_amdgcn_sched_barrier(0);
;               if (pre) issue_piece(kt + DIST, pc);
;               __builtin_amdgcn_sched_barrier(0);
;             }
;           }
;         }
;         if (s < 2 && NM < PPS) {
;           const int slot = s * NM + m;
;           __builtin_amdgcn_sched_barrier(0);
; #pragma unroll
;           for (int pc = 0; pc < NLD; ++pc)
;             if ((pc * 2 * NM) / NLD == slot && pre) issue_piece(kt + DIST, pc);
;           __builtin_amdgcn_sched_barrier(0);
;         }
;       }
;     }
	s_waitcnt lgkmcnt(0)
	v_mfma_f32_32x32x16_bf16 v[48:63], v[206:209], v[210:213], v[48:63]
	v_mfma_f32_32x32x16_bf16 v[16:31], v[206:209], v[214:217], v[16:31]
	v_mfma_f32_32x32x16_bf16 v[32:47], v[218:221], v[210:213], v[32:47]
	ds_read_b128 v[206:209], v155 offset:32768
	ds_read_b128 v[210:213], v156
	v_mfma_f32_32x32x16_bf16 v[0:15], v[218:221], v[214:217], v[0:15]
	ds_read_b128 v[214:217], v156 offset:4096
	ds_read_b128 v[218:221], v155 offset:36864
	s_waitcnt lgkmcnt(0)
	v_mfma_f32_32x32x16_bf16 v[48:63], v[206:209], v[210:213], v[48:63]
	v_lshl_add_u64 v[224:225], v[140:141], 0, s[22:23]
	s_mov_b32 m0, s3
	s_nop 0
	global_load_lds_dwordx4 v[224:225], off
	v_mfma_f32_32x32x16_bf16 v[16:31], v[206:209], v[214:217], v[16:31]
	s_mov_b64 s[22:23], 0x20400
	v_lshl_add_u64 v[206:207], v[140:141], 0, s[22:23]
	s_mov_b32 m0, s12
	s_nop 0
	global_load_lds_dwordx4 v[206:207], off
	v_mfma_f32_32x32x16_bf16 v[32:47], v[218:221], v[210:213], v[32:47]
	s_mov_b64 s[24:25], 0x40400
	v_lshl_add_u64 v[206:207], v[140:141], 0, s[24:25]
	s_mov_b32 m0, s29
	s_nop 0
	global_load_lds_dwordx4 v[206:207], off
	v_mfma_f32_32x32x16_bf16 v[0:15], v[218:221], v[214:217], v[0:15]
	ds_read_b128 v[206:209], v157 offset:32768
	ds_read_b128 v[210:213], v158
	ds_read_b128 v[214:217], v158 offset:4096
	ds_read_b128 v[218:221], v157 offset:36864
	s_waitcnt lgkmcnt(0)
	v_mfma_f32_32x32x16_bf16 v[48:63], v[206:209], v[210:213], v[48:63]
	s_mov_b64 s[24:25], 0x60400
	v_lshl_add_u64 v[224:225], v[140:141], 0, s[24:25]
	s_mov_b32 m0, s30
	s_nop 0
	global_load_lds_dwordx4 v[224:225], off
	v_mfma_f32_32x32x16_bf16 v[16:31], v[206:209], v[214:217], v[16:31]
	s_mov_b32 m0, s36
	s_nop 0
	global_load_lds_dwordx4 v[222:223], off
	v_mfma_f32_32x32x16_bf16 v[32:47], v[218:221], v[210:213], v[32:47]
	v_lshl_add_u64 v[206:207], v[138:139], 0, s[22:23]
	s_mov_b32 m0, s40
	s_nop 0
	global_load_lds_dwordx4 v[206:207], off
	v_mfma_f32_32x32x16_bf16 v[0:15], v[218:221], v[214:217], v[0:15]
	ds_read_b128 v[206:209], v160 offset:32768
	ds_read_b128 v[210:213], v162
	ds_read_b128 v[214:217], v162 offset:4096
	ds_read_b128 v[218:221], v160 offset:36864
	s_mov_b64 s[22:23], 0x480
	v_lshl_add_u64 v[222:223], v[138:139], 0, s[22:23]
	s_waitcnt lgkmcnt(0)
	v_mfma_f32_32x32x16_bf16 v[48:63], v[206:209], v[210:213], v[48:63]
	v_mfma_f32_32x32x16_bf16 v[16:31], v[206:209], v[214:217], v[16:31]
	v_mfma_f32_32x32x16_bf16 v[32:47], v[218:221], v[210:213], v[32:47]
	v_mfma_f32_32x32x16_bf16 v[0:15], v[218:221], v[214:217], v[0:15]
	ds_read_b128 v[206:209], v159 offset:32768
	ds_read_b128 v[210:213], v161
	ds_read_b128 v[214:217], v161 offset:4096
	ds_read_b128 v[218:221], v159 offset:36864
	s_waitcnt vmcnt(6)
	s_barrier
	s_waitcnt lgkmcnt(0)
	v_mfma_f32_32x32x16_bf16 v[48:63], v[206:209], v[210:213], v[48:63]
	v_mfma_f32_32x32x16_bf16 v[16:31], v[206:209], v[214:217], v[16:31]
	v_mfma_f32_32x32x16_bf16 v[32:47], v[218:221], v[210:213], v[32:47]
	ds_read_b128 v[206:209], v165
	ds_read_b128 v[210:213], v156 offset:49152
	v_mfma_f32_32x32x16_bf16 v[0:15], v[218:221], v[214:217], v[0:15]
	ds_read_b128 v[214:217], v156 offset:53248
	ds_read_b128 v[218:221], v165 offset:4096
	s_waitcnt lgkmcnt(0)
	v_mfma_f32_32x32x16_bf16 v[48:63], v[206:209], v[210:213], v[48:63]
	v_readfirstlane_b32 s3, v205
	v_lshl_add_u64 v[224:225], v[140:141], 0, s[22:23]
	s_mov_b32 m0, s3
	s_nop 0
	global_load_lds_dwordx4 v[224:225], off
	v_mfma_f32_32x32x16_bf16 v[16:31], v[206:209], v[214:217], v[16:31]
	s_mov_b64 s[26:27], 0x20480
	v_readfirstlane_b32 s12, v204
	v_lshl_add_u64 v[206:207], v[140:141], 0, s[26:27]
	s_mov_b32 m0, s12
	s_nop 0
	global_load_lds_dwordx4 v[206:207], off
	v_mfma_f32_32x32x16_bf16 v[32:47], v[218:221], v[210:213], v[32:47]
	s_mov_b64 s[22:23], 0x40480
	v_lshl_add_u64 v[204:205], v[140:141], 0, s[22:23]
	v_readfirstlane_b32 s22, v203
	s_mov_b32 m0, s22
	s_nop 0
	global_load_lds_dwordx4 v[204:205], off
	v_mfma_f32_32x32x16_bf16 v[0:15], v[218:221], v[214:217], v[0:15]
	ds_read_b128 v[204:207], v182
	ds_read_b128 v[208:211], v158 offset:49152
	ds_read_b128 v[212:215], v158 offset:53248
	ds_read_b128 v[216:219], v182 offset:4096
	s_waitcnt lgkmcnt(0)
	v_mfma_f32_32x32x16_bf16 v[48:63], v[204:207], v[208:211], v[48:63]
	s_mov_b64 s[24:25], 0x60480
	v_readfirstlane_b32 s23, v200
	v_lshl_add_u64 v[220:221], v[140:141], 0, s[24:25]
	s_mov_b32 m0, s23
	s_nop 0
	global_load_lds_dwordx4 v[220:221], off
	v_mfma_f32_32x32x16_bf16 v[16:31], v[204:207], v[212:215], v[16:31]
	v_readfirstlane_b32 s24, v195
	s_mov_b32 m0, s24
	s_nop 0
	global_load_lds_dwordx4 v[222:223], off
	v_mfma_f32_32x32x16_bf16 v[32:47], v[216:219], v[208:211], v[32:47]
	v_readfirstlane_b32 s25, v197
	v_lshl_add_u64 v[204:205], v[138:139], 0, s[26:27]
	s_mov_b32 m0, s25
	s_nop 0
	global_load_lds_dwordx4 v[204:205], off
	v_mfma_f32_32x32x16_bf16 v[0:15], v[216:219], v[212:215], v[0:15]
	ds_read_b128 v[204:207], v164
	ds_read_b128 v[208:211], v162 offset:49152
	ds_read_b128 v[212:215], v162 offset:53248
	ds_read_b128 v[216:219], v164 offset:4096
	s_mov_b64 s[26:27], 0x500
	v_lshl_add_u64 v[220:221], v[138:139], 0, s[26:27]
	s_waitcnt lgkmcnt(0)
	v_mfma_f32_32x32x16_bf16 v[48:63], v[204:207], v[208:211], v[48:63]
	v_mfma_f32_32x32x16_bf16 v[16:31], v[204:207], v[212:215], v[16:31]
	v_mfma_f32_32x32x16_bf16 v[32:47], v[216:219], v[208:211], v[32:47]
	v_mfma_f32_32x32x16_bf16 v[0:15], v[216:219], v[212:215], v[0:15]
	ds_read_b128 v[204:207], v163
	ds_read_b128 v[208:211], v161 offset:49152
	ds_read_b128 v[212:215], v161 offset:53248
	ds_read_b128 v[216:219], v163 offset:4096
	s_waitcnt vmcnt(6)
	s_barrier
; #define MFMA(a, b, c) __builtin_amdgcn_mfma_f32_32x32x16_bf16((a), (b), (c), 0, 0, 0)
;     ...
;   for (int kt = 0; kt < nk; ++kt) {
;     if (DIST == 2 && kt + 1 < nk) {
;       if (NLD == 6) asm volatile("s_waitcnt vmcnt(6)" ::: "memory");
;       else if (NLD == 5) asm volatile("s_waitcnt vmcnt(5)" ::: "memory");
;       else asm volatile("s_waitcnt vmcnt(8)" ::: "memory");
;     } else {
;       asm volatile("s_waitcnt vmcnt(0)" ::: "memory");
;     }
;     __builtin_amdgcn_s_barrier();
;     const bool pre = (kt + DIST < nk);
;     const char* base = smem + (kt % NSTG) * STAGE;
;     const char* pa = base + (wrow_act + r) * 128;
;     const char* pw = base + ABYTES + (wrow_w + r) * 128;
;     constexpr int NM = NI * MJ;
;     constexpr int PPS = (NLD + 1) / 2;
; #pragma unroll
;     for (int s = 0; s < 4; ++s) {
;       bf16x8 af[MJ], wf[NI];
; #pragma unroll
;       for (int j = 0; j < MJ; ++j) af[j] = *(const bf16x8*)(pa + j * 32 * 128 + xo[s]);
; #pragma unroll
;       for (int i = 0; i < NI; ++i) wf[i] = *(const bf16x8*)(pw + i * 32 * 128 + xo[s]);
; #pragma unroll
;       for (int m = 0; m < NM; ++m) {
;         const int i = m / MJ, j = m % MJ;
;         acc[i][j] = MFMA(wf[i], af[j], acc[i][j]);
;         if (s < 2 && NM >= PPS) {
;           constexpr int EVERY = (NM / PPS) > 0 ? (NM / PPS) : 1;
;           if ((m + 1) % EVERY == 0) {
;             const int pc = s * PPS + (m + 1) / EVERY - 1;
;             if ((m + 1) / EVERY <= PPS && pc < NLD) {
;               __builtin_amdgcn_sched_barrier(0);
;               if (pre) issue_piece(kt + DIST, pc);
;               __builtin_amdgcn_sched_barrier(0);
;             }
;           }
;         }
;         if (s < 2 && NM < PPS) {
;           const int slot = s * NM + m;
;           __builtin_amdgcn_sched_barrier(0);
; #pragma unroll
;           for (int pc = 0; pc < NLD; ++pc)
;             if ((pc * 2 * NM) / NLD == slot && pre) issue_piece(kt + DIST, pc);
;           __builtin_amdgcn_sched_barrier(0);
;         }
;       }
;     }
	s_waitcnt lgkmcnt(0)
	v_mfma_f32_32x32x16_bf16 v[48:63], v[204:207], v[208:211], v[48:63]
	v_mfma_f32_32x32x16_bf16 v[16:31], v[204:207], v[212:215], v[16:31]
	v_mfma_f32_32x32x16_bf16 v[32:47], v[216:219], v[208:211], v[32:47]
	ds_read_b128 v[204:207], v181
	ds_read_b128 v[208:211], v183
	v_mfma_f32_32x32x16_bf16 v[0:15], v[216:219], v[212:215], v[0:15]
	ds_read_b128 v[212:215], v183 offset:4096
	ds_read_b128 v[216:219], v181 offset:4096
	s_waitcnt lgkmcnt(0)
	v_mfma_f32_32x32x16_bf16 v[48:63], v[204:207], v[208:211], v[48:63]
	v_lshl_add_u64 v[222:223], v[140:141], 0, s[26:27]
	v_readfirstlane_b32 s26, v193
	s_mov_b32 m0, s26
	s_nop 0
	global_load_lds_dwordx4 v[222:223], off
	v_mfma_f32_32x32x16_bf16 v[16:31], v[204:207], v[212:215], v[16:31]
	s_mov_b64 s[30:31], 0x20500
	v_readfirstlane_b32 s27, v192
	v_lshl_add_u64 v[204:205], v[140:141], 0, s[30:31]
	s_mov_b32 m0, s27
	s_nop 0
	global_load_lds_dwordx4 v[204:205], off
	v_mfma_f32_32x32x16_bf16 v[32:47], v[216:219], v[208:211], v[32:47]
	s_mov_b64 s[28:29], 0x40500
	v_lshl_add_u64 v[192:193], v[140:141], 0, s[28:29]
	v_readfirstlane_b32 s28, v191
	s_mov_b32 m0, s28
	s_nop 0
	global_load_lds_dwordx4 v[192:193], off
	v_mfma_f32_32x32x16_bf16 v[0:15], v[216:219], v[212:215], v[0:15]
	ds_read_b128 v[204:207], v184
	ds_read_b128 v[208:211], v186
	ds_read_b128 v[212:215], v186 offset:4096
	ds_read_b128 v[216:219], v184 offset:4096
	s_waitcnt lgkmcnt(0)
	v_mfma_f32_32x32x16_bf16 v[48:63], v[204:207], v[208:211], v[48:63]
	s_mov_b64 s[36:37], 0x60500
	v_readfirstlane_b32 s29, v190
	v_lshl_add_u64 v[192:193], v[140:141], 0, s[36:37]
	s_mov_b32 m0, s29
	s_nop 0
	global_load_lds_dwordx4 v[192:193], off
	v_mfma_f32_32x32x16_bf16 v[16:31], v[204:207], v[212:215], v[16:31]
	s_mov_b32 m0, s21
	s_nop 0
	global_load_lds_dwordx4 v[220:221], off
	v_mfma_f32_32x32x16_bf16 v[32:47], v[216:219], v[208:211], v[32:47]
	v_lshl_add_u64 v[190:191], v[138:139], 0, s[30:31]
	s_mov_b32 m0, s13
	s_nop 0
	global_load_lds_dwordx4 v[190:191], off
	v_mfma_f32_32x32x16_bf16 v[0:15], v[216:219], v[212:215], v[0:15]
	ds_read_b128 v[190:193], v187
	ds_read_b128 v[204:207], v189
	ds_read_b128 v[208:211], v189 offset:4096
	ds_read_b128 v[212:215], v187 offset:4096
	s_mov_b64 s[30:31], 0x580
	v_lshl_add_u64 v[216:217], v[138:139], 0, s[30:31]
	s_waitcnt lgkmcnt(0)
	v_mfma_f32_32x32x16_bf16 v[48:63], v[190:193], v[204:207], v[48:63]
	v_mfma_f32_32x32x16_bf16 v[16:31], v[190:193], v[208:211], v[16:31]
	v_mfma_f32_32x32x16_bf16 v[32:47], v[212:215], v[204:207], v[32:47]
	v_mfma_f32_32x32x16_bf16 v[0:15], v[212:215], v[208:211], v[0:15]
	ds_read_b128 v[190:193], v185
	ds_read_b128 v[204:207], v188
	ds_read_b128 v[208:211], v188 offset:4096
	ds_read_b128 v[212:215], v185 offset:4096
	s_waitcnt vmcnt(6)
	s_barrier
	s_waitcnt lgkmcnt(0)
	v_mfma_f32_32x32x16_bf16 v[48:63], v[190:193], v[204:207], v[48:63]
	v_mfma_f32_32x32x16_bf16 v[16:31], v[190:193], v[208:211], v[16:31]
	v_mfma_f32_32x32x16_bf16 v[32:47], v[212:215], v[204:207], v[32:47]
	ds_read_b128 v[190:193], v155 offset:32768
	ds_read_b128 v[204:207], v156
	v_mfma_f32_32x32x16_bf16 v[0:15], v[212:215], v[208:211], v[0:15]
	ds_read_b128 v[208:211], v156 offset:4096
	ds_read_b128 v[212:215], v155 offset:36864
	s_waitcnt lgkmcnt(0)
	v_mfma_f32_32x32x16_bf16 v[48:63], v[190:193], v[204:207], v[48:63]
	v_lshl_add_u64 v[218:219], v[140:141], 0, s[30:31]
	v_readfirstlane_b32 s30, v196
	s_mov_b32 m0, s30
	s_nop 0
	global_load_lds_dwordx4 v[218:219], off
	v_mfma_f32_32x32x16_bf16 v[16:31], v[190:193], v[208:211], v[16:31]
	s_mov_b64 s[38:39], 0x20580
	v_readfirstlane_b32 s31, v198
	v_lshl_add_u64 v[190:191], v[140:141], 0, s[38:39]
	s_mov_b32 m0, s31
	s_nop 0
	global_load_lds_dwordx4 v[190:191], off
	v_mfma_f32_32x32x16_bf16 v[32:47], v[212:215], v[204:207], v[32:47]
	v_readfirstlane_b32 s36, v199
	v_lshl_add_u64 v[190:191], v[140:141], 0, s[90:91]
	s_mov_b32 m0, s36
	s_nop 0
	global_load_lds_dwordx4 v[190:191], off
	v_mfma_f32_32x32x16_bf16 v[0:15], v[212:215], v[208:211], v[0:15]
	ds_read_b128 v[190:193], v157 offset:32768
	ds_read_b128 v[196:199], v158
	ds_read_b128 v[204:207], v158 offset:4096
	ds_read_b128 v[208:211], v157 offset:36864
	s_waitcnt lgkmcnt(0)
	v_mfma_f32_32x32x16_bf16 v[48:63], v[190:193], v[196:199], v[48:63]
	v_readfirstlane_b32 s37, v201
	v_lshl_add_u64 v[212:213], v[140:141], 0, s[96:97]
	s_mov_b32 m0, s37
	s_nop 0
	global_load_lds_dwordx4 v[212:213], off
	v_mfma_f32_32x32x16_bf16 v[16:31], v[190:193], v[204:207], v[16:31]
	v_readfirstlane_b32 s40, v194
	s_mov_b32 m0, s40
	s_nop 0
	global_load_lds_dwordx4 v[216:217], off
	v_mfma_f32_32x32x16_bf16 v[32:47], v[208:211], v[196:199], v[32:47]
	v_readfirstlane_b32 s41, v202
	v_lshl_add_u64 v[190:191], v[138:139], 0, s[38:39]
	s_mov_b32 m0, s41
	s_nop 0
	global_load_lds_dwordx4 v[190:191], off
	v_mfma_f32_32x32x16_bf16 v[0:15], v[208:211], v[204:207], v[0:15]
	ds_read_b128 v[190:193], v160 offset:32768
	ds_read_b128 v[194:197], v162
	ds_read_b128 v[198:201], v162 offset:4096
	ds_read_b128 v[202:205], v160 offset:36864
	s_mov_b64 s[38:39], 0x600
	v_lshl_add_u64 v[206:207], v[138:139], 0, s[38:39]
	s_waitcnt lgkmcnt(0)
	v_mfma_f32_32x32x16_bf16 v[48:63], v[190:193], v[194:197], v[48:63]
	v_mfma_f32_32x32x16_bf16 v[16:31], v[190:193], v[198:201], v[16:31]
	v_mfma_f32_32x32x16_bf16 v[32:47], v[202:205], v[194:197], v[32:47]
	v_mfma_f32_32x32x16_bf16 v[0:15], v[202:205], v[198:201], v[0:15]
	ds_read_b128 v[190:193], v159 offset:32768
	ds_read_b128 v[194:197], v161
	ds_read_b128 v[198:201], v161 offset:4096
	ds_read_b128 v[202:205], v159 offset:36864
	s_waitcnt vmcnt(6)
	s_barrier
; #define MFMA(a, b, c) __builtin_amdgcn_mfma_f32_32x32x16_bf16((a), (b), (c), 0, 0, 0)
;     ...
;   for (int kt = 0; kt < nk; ++kt) {
;     if (DIST == 2 && kt + 1 < nk) {
;       if (NLD == 6) asm volatile("s_waitcnt vmcnt(6)" ::: "memory");
;       else if (NLD == 5) asm volatile("s_waitcnt vmcnt(5)" ::: "memory");
;       else asm volatile("s_waitcnt vmcnt(8)" ::: "memory");
;     } else {
;       asm volatile("s_waitcnt vmcnt(0)" ::: "memory");
;     }
;     __builtin_amdgcn_s_barrier();
;     const bool pre = (kt + DIST < nk);
;     const char* base = smem + (kt % NSTG) * STAGE;
;     const char* pa = base + (wrow_act + r) * 128;
;     const char* pw = base + ABYTES + (wrow_w + r) * 128;
;     constexpr int NM = NI * MJ;
;     constexpr int PPS = (NLD + 1) / 2;
; #pragma unroll
;     for (int s = 0; s < 4; ++s) {
;       bf16x8 af[MJ], wf[NI];
; #pragma unroll
;       for (int j = 0; j < MJ; ++j) af[j] = *(const bf16x8*)(pa + j * 32 * 128 + xo[s]);
; #pragma unroll
;       for (int i = 0; i < NI; ++i) wf[i] = *(const bf16x8*)(pw + i * 32 * 128 + xo[s]);
; #pragma unroll
;       for (int m = 0; m < NM; ++m) {
;         const int i = m / MJ, j = m % MJ;
;         acc[i][j] = MFMA(wf[i], af[j], acc[i][j]);
;         if (s < 2 && NM >= PPS) {
;           constexpr int EVERY = (NM / PPS) > 0 ? (NM / PPS) : 1;
;           if ((m + 1) % EVERY == 0) {
;             const int pc = s * PPS + (m + 1) / EVERY - 1;
;             if ((m + 1) / EVERY <= PPS && pc < NLD) {
;               __builtin_amdgcn_sched_barrier(0);
;               if (pre) issue_piece(kt + DIST, pc);
;               __builtin_amdgcn_sched_barrier(0);
;             }
;           }
;         }
;         if (s < 2 && NM < PPS) {
;           const int slot = s * NM + m;
;           __builtin_amdgcn_sched_barrier(0);
; #pragma unroll
;           for (int pc = 0; pc < NLD; ++pc)
;             if ((pc * 2 * NM) / NLD == slot && pre) issue_piece(kt + DIST, pc);
;           __builtin_amdgcn_sched_barrier(0);
;         }
;       }
;     }
	s_waitcnt lgkmcnt(0)
	v_mfma_f32_32x32x16_bf16 v[48:63], v[190:193], v[194:197], v[48:63]
	v_mfma_f32_32x32x16_bf16 v[16:31], v[190:193], v[198:201], v[16:31]
	v_mfma_f32_32x32x16_bf16 v[32:47], v[202:205], v[194:197], v[32:47]
	ds_read_b128 v[190:193], v165
	ds_read_b128 v[194:197], v156 offset:49152
	v_mfma_f32_32x32x16_bf16 v[0:15], v[202:205], v[198:201], v[0:15]
	ds_read_b128 v[198:201], v156 offset:53248
	ds_read_b128 v[202:205], v165 offset:4096
	s_waitcnt lgkmcnt(0)
	v_mfma_f32_32x32x16_bf16 v[48:63], v[190:193], v[194:197], v[48:63]
	v_lshl_add_u64 v[208:209], v[140:141], 0, s[38:39]
	s_mov_b32 m0, s3
	s_nop 0
	global_load_lds_dwordx4 v[208:209], off
	v_mfma_f32_32x32x16_bf16 v[16:31], v[190:193], v[198:201], v[16:31]
	s_mov_b64 s[38:39], 0x20600
	v_lshl_add_u64 v[190:191], v[140:141], 0, s[38:39]
	s_mov_b32 m0, s12
	s_nop 0
	global_load_lds_dwordx4 v[190:191], off
	v_mfma_f32_32x32x16_bf16 v[32:47], v[202:205], v[194:197], v[32:47]
	v_lshl_add_u64 v[190:191], v[140:141], 0, s[6:7]
	s_mov_b32 m0, s22
	s_nop 0
	global_load_lds_dwordx4 v[190:191], off
	v_mfma_f32_32x32x16_bf16 v[0:15], v[202:205], v[198:201], v[0:15]
	ds_read_b128 v[190:193], v182
	ds_read_b128 v[194:197], v158 offset:49152
	ds_read_b128 v[198:201], v158 offset:53248
	ds_read_b128 v[202:205], v182 offset:4096
	s_waitcnt lgkmcnt(0)
	v_mfma_f32_32x32x16_bf16 v[48:63], v[190:193], v[194:197], v[48:63]
	v_lshl_add_u64 v[208:209], v[140:141], 0, s[68:69]
	s_mov_b32 m0, s23
	s_nop 0
	global_load_lds_dwordx4 v[208:209], off
	v_mfma_f32_32x32x16_bf16 v[16:31], v[190:193], v[198:201], v[16:31]
	s_mov_b32 m0, s24
	s_nop 0
	global_load_lds_dwordx4 v[206:207], off
	v_mfma_f32_32x32x16_bf16 v[32:47], v[202:205], v[194:197], v[32:47]
	v_lshl_add_u64 v[190:191], v[138:139], 0, s[38:39]
	s_mov_b32 m0, s25
	s_nop 0
	global_load_lds_dwordx4 v[190:191], off
	v_mfma_f32_32x32x16_bf16 v[0:15], v[202:205], v[198:201], v[0:15]
	ds_read_b128 v[190:193], v164
	ds_read_b128 v[194:197], v162 offset:49152
	ds_read_b128 v[198:201], v162 offset:53248
	ds_read_b128 v[202:205], v164 offset:4096
	s_mov_b64 s[38:39], 0x680
	v_lshl_add_u64 v[206:207], v[138:139], 0, s[38:39]
	s_waitcnt lgkmcnt(0)
	v_mfma_f32_32x32x16_bf16 v[48:63], v[190:193], v[194:197], v[48:63]
	v_mfma_f32_32x32x16_bf16 v[16:31], v[190:193], v[198:201], v[16:31]
	v_mfma_f32_32x32x16_bf16 v[32:47], v[202:205], v[194:197], v[32:47]
	v_mfma_f32_32x32x16_bf16 v[0:15], v[202:205], v[198:201], v[0:15]
	ds_read_b128 v[190:193], v163
	ds_read_b128 v[194:197], v161 offset:49152
	ds_read_b128 v[198:201], v161 offset:53248
	ds_read_b128 v[202:205], v163 offset:4096
	s_waitcnt vmcnt(6)
	s_barrier
	s_waitcnt lgkmcnt(0)
	v_mfma_f32_32x32x16_bf16 v[48:63], v[190:193], v[194:197], v[48:63]
	v_mfma_f32_32x32x16_bf16 v[16:31], v[190:193], v[198:201], v[16:31]
	v_mfma_f32_32x32x16_bf16 v[32:47], v[202:205], v[194:197], v[32:47]
	ds_read_b128 v[190:193], v181
	ds_read_b128 v[194:197], v183
	v_mfma_f32_32x32x16_bf16 v[0:15], v[202:205], v[198:201], v[0:15]
	ds_read_b128 v[198:201], v183 offset:4096
	ds_read_b128 v[202:205], v181 offset:4096
	s_waitcnt lgkmcnt(0)
	v_mfma_f32_32x32x16_bf16 v[48:63], v[190:193], v[194:197], v[48:63]
	v_lshl_add_u64 v[208:209], v[140:141], 0, s[38:39]
	s_mov_b32 m0, s26
	s_nop 0
	global_load_lds_dwordx4 v[208:209], off
	v_mfma_f32_32x32x16_bf16 v[16:31], v[190:193], v[198:201], v[16:31]
	s_mov_b64 s[38:39], 0x20680
	v_lshl_add_u64 v[190:191], v[140:141], 0, s[38:39]
	s_mov_b32 m0, s27
	s_nop 0
	global_load_lds_dwordx4 v[190:191], off
	v_mfma_f32_32x32x16_bf16 v[32:47], v[202:205], v[194:197], v[32:47]
	v_lshl_add_u64 v[190:191], v[140:141], 0, s[58:59]
	s_mov_b32 m0, s28
	s_nop 0
	global_load_lds_dwordx4 v[190:191], off
	v_mfma_f32_32x32x16_bf16 v[0:15], v[202:205], v[198:201], v[0:15]
	ds_read_b128 v[190:193], v184
	ds_read_b128 v[194:197], v186
	ds_read_b128 v[198:201], v186 offset:4096
	ds_read_b128 v[202:205], v184 offset:4096
	s_waitcnt lgkmcnt(0)
	v_mfma_f32_32x32x16_bf16 v[48:63], v[190:193], v[194:197], v[48:63]
	v_lshl_add_u64 v[208:209], v[140:141], 0, s[60:61]
	s_mov_b32 m0, s29
	s_nop 0
	global_load_lds_dwordx4 v[208:209], off
	v_mfma_f32_32x32x16_bf16 v[16:31], v[190:193], v[198:201], v[16:31]
	s_mov_b32 m0, s21
	s_nop 0
	global_load_lds_dwordx4 v[206:207], off
	v_mfma_f32_32x32x16_bf16 v[32:47], v[202:205], v[194:197], v[32:47]
	v_lshl_add_u64 v[190:191], v[138:139], 0, s[38:39]
	s_mov_b32 m0, s13
	s_nop 0
	global_load_lds_dwordx4 v[190:191], off
	v_mfma_f32_32x32x16_bf16 v[0:15], v[202:205], v[198:201], v[0:15]
	ds_read_b128 v[190:193], v187
	ds_read_b128 v[194:197], v189
	ds_read_b128 v[198:201], v189 offset:4096
	ds_read_b128 v[202:205], v187 offset:4096
	s_mov_b64 s[26:27], 0x700
	v_lshl_add_u64 v[206:207], v[138:139], 0, s[26:27]
	s_waitcnt lgkmcnt(0)
	v_mfma_f32_32x32x16_bf16 v[48:63], v[190:193], v[194:197], v[48:63]
	v_mfma_f32_32x32x16_bf16 v[16:31], v[190:193], v[198:201], v[16:31]
	v_mfma_f32_32x32x16_bf16 v[32:47], v[202:205], v[194:197], v[32:47]
	v_mfma_f32_32x32x16_bf16 v[0:15], v[202:205], v[198:201], v[0:15]
	ds_read_b128 v[190:193], v185
	ds_read_b128 v[194:197], v188
	ds_read_b128 v[198:201], v188 offset:4096
	ds_read_b128 v[202:205], v185 offset:4096
	s_waitcnt vmcnt(6)
	s_barrier
; #define MFMA(a, b, c) __builtin_amdgcn_mfma_f32_32x32x16_bf16((a), (b), (c), 0, 0, 0)
;     ...
;   for (int kt = 0; kt < nk; ++kt) {
;     if (DIST == 2 && kt + 1 < nk) {
;       if (NLD == 6) asm volatile("s_waitcnt vmcnt(6)" ::: "memory");
;       else if (NLD == 5) asm volatile("s_waitcnt vmcnt(5)" ::: "memory");
;       else asm volatile("s_waitcnt vmcnt(8)" ::: "memory");
;     } else {
;       asm volatile("s_waitcnt vmcnt(0)" ::: "memory");
;     }
;     __builtin_amdgcn_s_barrier();
;     const bool pre = (kt + DIST < nk);
;     const char* base = smem + (kt % NSTG) * STAGE;
;     const char* pa = base + (wrow_act + r) * 128;
;     const char* pw = base + ABYTES + (wrow_w + r) * 128;
;     constexpr int NM = NI * MJ;
;     constexpr int PPS = (NLD + 1) / 2;
; #pragma unroll
;     for (int s = 0; s < 4; ++s) {
;       bf16x8 af[MJ], wf[NI];
; #pragma unroll
;       for (int j = 0; j < MJ; ++j) af[j] = *(const bf16x8*)(pa + j * 32 * 128 + xo[s]);
; #pragma unroll
;       for (int i = 0; i < NI; ++i) wf[i] = *(const bf16x8*)(pw + i * 32 * 128 + xo[s]);
; #pragma unroll
;       for (int m = 0; m < NM; ++m) {
;         const int i = m / MJ, j = m % MJ;
;         acc[i][j] = MFMA(wf[i], af[j], acc[i][j]);
;         if (s < 2 && NM >= PPS) {
;           constexpr int EVERY = (NM / PPS) > 0 ? (NM / PPS) : 1;
;           if ((m + 1) % EVERY == 0) {
;             const int pc = s * PPS + (m + 1) / EVERY - 1;
;             if ((m + 1) / EVERY <= PPS && pc < NLD) {
;               __builtin_amdgcn_sched_barrier(0);
;               if (pre) issue_piece(kt + DIST, pc);
;               __builtin_amdgcn_sched_barrier(0);
;             }
;           }
;         }
;         if (s < 2 && NM < PPS) {
;           const int slot = s * NM + m;
;           __builtin_amdgcn_sched_barrier(0);
; #pragma unroll
;           for (int pc = 0; pc < NLD; ++pc)
;             if ((pc * 2 * NM) / NLD == slot && pre) issue_piece(kt + DIST, pc);
;           __builtin_amdgcn_sched_barrier(0);
;         }
;       }
;     }
	s_waitcnt lgkmcnt(0)
	v_mfma_f32_32x32x16_bf16 v[48:63], v[190:193], v[194:197], v[48:63]
	v_mfma_f32_32x32x16_bf16 v[16:31], v[190:193], v[198:201], v[16:31]
	v_mfma_f32_32x32x16_bf16 v[32:47], v[202:205], v[194:197], v[32:47]
	ds_read_b128 v[190:193], v155 offset:32768
	ds_read_b128 v[194:197], v156
	v_mfma_f32_32x32x16_bf16 v[0:15], v[202:205], v[198:201], v[0:15]
	ds_read_b128 v[198:201], v156 offset:4096
	ds_read_b128 v[202:205], v155 offset:36864
	s_waitcnt lgkmcnt(0)
	v_mfma_f32_32x32x16_bf16 v[48:63], v[190:193], v[194:197], v[48:63]
	v_lshl_add_u64 v[208:209], v[140:141], 0, s[26:27]
	s_mov_b32 m0, s30
	s_nop 0
	global_load_lds_dwordx4 v[208:209], off
	v_mfma_f32_32x32x16_bf16 v[16:31], v[190:193], v[198:201], v[16:31]
	s_mov_b64 s[26:27], 0x20700
	v_lshl_add_u64 v[190:191], v[140:141], 0, s[26:27]
	s_mov_b32 m0, s31
	s_nop 0
	global_load_lds_dwordx4 v[190:191], off
	v_mfma_f32_32x32x16_bf16 v[32:47], v[202:205], v[194:197], v[32:47]
	s_mov_b64 s[28:29], 0x40700
	v_lshl_add_u64 v[190:191], v[140:141], 0, s[28:29]
	s_mov_b32 m0, s36
	s_nop 0
	global_load_lds_dwordx4 v[190:191], off
	v_mfma_f32_32x32x16_bf16 v[0:15], v[202:205], v[198:201], v[0:15]
	ds_read_b128 v[190:193], v157 offset:32768
	ds_read_b128 v[194:197], v158
	ds_read_b128 v[198:201], v158 offset:4096
	ds_read_b128 v[202:205], v157 offset:36864
	s_waitcnt lgkmcnt(0)
	v_mfma_f32_32x32x16_bf16 v[48:63], v[190:193], v[194:197], v[48:63]
	s_mov_b64 s[28:29], 0x60700
	v_lshl_add_u64 v[208:209], v[140:141], 0, s[28:29]
	s_mov_b32 m0, s37
	s_nop 0
	global_load_lds_dwordx4 v[208:209], off
	v_mfma_f32_32x32x16_bf16 v[16:31], v[190:193], v[198:201], v[16:31]
	s_mov_b32 m0, s40
	s_nop 0
	global_load_lds_dwordx4 v[206:207], off
	v_mfma_f32_32x32x16_bf16 v[32:47], v[202:205], v[194:197], v[32:47]
	v_lshl_add_u64 v[190:191], v[138:139], 0, s[26:27]
	s_mov_b32 m0, s41
	s_nop 0
	global_load_lds_dwordx4 v[190:191], off
	v_mfma_f32_32x32x16_bf16 v[0:15], v[202:205], v[198:201], v[0:15]
	ds_read_b128 v[190:193], v160 offset:32768
	ds_read_b128 v[194:197], v162
	ds_read_b128 v[198:201], v162 offset:4096
	ds_read_b128 v[202:205], v160 offset:36864
	s_mov_b64 s[26:27], 0x780
	v_lshl_add_u64 v[206:207], v[138:139], 0, s[26:27]
	s_waitcnt lgkmcnt(0)
	v_mfma_f32_32x32x16_bf16 v[48:63], v[190:193], v[194:197], v[48:63]
	v_mfma_f32_32x32x16_bf16 v[16:31], v[190:193], v[198:201], v[16:31]
	v_mfma_f32_32x32x16_bf16 v[32:47], v[202:205], v[194:197], v[32:47]
	v_mfma_f32_32x32x16_bf16 v[0:15], v[202:205], v[198:201], v[0:15]
	ds_read_b128 v[190:193], v159 offset:32768
	ds_read_b128 v[194:197], v161
	ds_read_b128 v[198:201], v161 offset:4096
	ds_read_b128 v[202:205], v159 offset:36864
	s_waitcnt vmcnt(6)
	s_barrier
	s_waitcnt lgkmcnt(0)
	v_mfma_f32_32x32x16_bf16 v[48:63], v[190:193], v[194:197], v[48:63]
	v_mfma_f32_32x32x16_bf16 v[16:31], v[190:193], v[198:201], v[16:31]
	v_mfma_f32_32x32x16_bf16 v[32:47], v[202:205], v[194:197], v[32:47]
	ds_read_b128 v[190:193], v165
	ds_read_b128 v[194:197], v156 offset:49152
	v_mfma_f32_32x32x16_bf16 v[0:15], v[202:205], v[198:201], v[0:15]
	ds_read_b128 v[198:201], v156 offset:53248
	ds_read_b128 v[202:205], v165 offset:4096
	s_waitcnt lgkmcnt(0)
	v_mfma_f32_32x32x16_bf16 v[48:63], v[190:193], v[194:197], v[48:63]
	v_lshl_add_u64 v[208:209], v[140:141], 0, s[26:27]
	s_mov_b32 m0, s3
	s_nop 0
	global_load_lds_dwordx4 v[208:209], off
	v_mfma_f32_32x32x16_bf16 v[16:31], v[190:193], v[198:201], v[16:31]
	s_mov_b64 s[26:27], 0x20780
	v_lshl_add_u64 v[190:191], v[140:141], 0, s[26:27]
	s_mov_b32 m0, s12
	s_nop 0
	global_load_lds_dwordx4 v[190:191], off
	v_mfma_f32_32x32x16_bf16 v[32:47], v[202:205], v[194:197], v[32:47]
	s_mov_b64 s[12:13], 0x40780
	v_lshl_add_u64 v[190:191], v[140:141], 0, s[12:13]
	s_mov_b32 m0, s22
	s_nop 0
	global_load_lds_dwordx4 v[190:191], off
	v_mfma_f32_32x32x16_bf16 v[0:15], v[202:205], v[198:201], v[0:15]
	ds_read_b128 v[190:193], v182
	ds_read_b128 v[194:197], v158 offset:49152
	ds_read_b128 v[198:201], v158 offset:53248
	ds_read_b128 v[202:205], v182 offset:4096
	s_waitcnt lgkmcnt(0)
	v_mfma_f32_32x32x16_bf16 v[48:63], v[190:193], v[194:197], v[48:63]
	s_mov_b64 s[12:13], 0x60780
	v_lshl_add_u64 v[140:141], v[140:141], 0, s[12:13]
	s_mov_b32 m0, s23
	s_nop 0
	global_load_lds_dwordx4 v[140:141], off
	v_mfma_f32_32x32x16_bf16 v[16:31], v[190:193], v[198:201], v[16:31]
	s_mov_b32 m0, s24
	s_nop 0
	global_load_lds_dwordx4 v[206:207], off
	v_mfma_f32_32x32x16_bf16 v[32:47], v[202:205], v[194:197], v[32:47]
	v_lshl_add_u64 v[138:139], v[138:139], 0, s[26:27]
	s_mov_b32 m0, s25
	s_nop 0
	global_load_lds_dwordx4 v[138:139], off
	ds_read_b128 v[138:141], v164
	ds_read_b128 v[190:193], v162 offset:49152
	ds_read_b128 v[194:197], v162 offset:53248
	v_mfma_f32_32x32x16_bf16 v[0:15], v[202:205], v[198:201], v[0:15]
	s_waitcnt lgkmcnt(0)
	v_mfma_f32_32x32x16_bf16 v[48:63], v[138:141], v[190:193], v[48:63]
	v_mfma_f32_32x32x16_bf16 v[16:31], v[138:141], v[194:197], v[16:31]
	ds_read_b128 v[138:141], v164 offset:4096
	s_waitcnt lgkmcnt(0)
	v_mfma_f32_32x32x16_bf16 v[32:47], v[138:141], v[190:193], v[32:47]
	v_mfma_f32_32x32x16_bf16 v[0:15], v[138:141], v[194:197], v[0:15]
	ds_read_b128 v[138:141], v163
	ds_read_b128 v[190:193], v161 offset:49152
	ds_read_b128 v[194:197], v161 offset:53248
	s_waitcnt lgkmcnt(0)
	v_mfma_f32_32x32x16_bf16 v[48:63], v[138:141], v[190:193], v[48:63]
	v_mfma_f32_32x32x16_bf16 v[16:31], v[138:141], v[194:197], v[16:31]
	ds_read_b128 v[138:141], v163 offset:4096
	s_waitcnt vmcnt(6)
	s_barrier
;     ...
;   for (int kt = 0; kt < nk; ++kt) {
;     if (DIST == 2 && kt + 1 < nk) {
;       if (NLD == 6) asm volatile("s_waitcnt vmcnt(6)" ::: "memory");
;       else if (NLD == 5) asm volatile("s_waitcnt vmcnt(5)" ::: "memory");
;       else asm volatile("s_waitcnt vmcnt(8)" ::: "memory");
;     } else {
;       asm volatile("s_waitcnt vmcnt(0)" ::: "memory");
;     }
;     __builtin_amdgcn_s_barrier();
;     const bool pre = (kt + DIST < nk);
;     const char* base = smem + (kt % NSTG) * STAGE;
;     const char* pa = base + (wrow_act + r) * 128;
;     const char* pw = base + ABYTES + (wrow_w + r) * 128;
;     constexpr int NM = NI * MJ;
;     constexpr int PPS = (NLD + 1) / 2;
; #pragma unroll
;     for (int s = 0; s < 4; ++s) {
;       bf16x8 af[MJ], wf[NI];
; #pragma unroll
;       for (int j = 0; j < MJ; ++j) af[j] = *(const bf16x8*)(pa + j * 32 * 128 + xo[s]);
; #pragma unroll
;       for (int i = 0; i < NI; ++i) wf[i] = *(const bf16x8*)(pw + i * 32 * 128 + xo[s]);
; #pragma unroll
;       for (int m = 0; m < NM; ++m) {
;         const int i = m / MJ, j = m % MJ;
;         acc[i][j] = MFMA(wf[i], af[j], acc[i][j]);
;         if (s < 2 && NM >= PPS) {
;           constexpr int EVERY = (NM / PPS) > 0 ? (NM / PPS) : 1;
;           if ((m + 1) % EVERY == 0) {
;             const int pc = s * PPS + (m + 1) / EVERY - 1;
;             if ((m + 1) / EVERY <= PPS && pc < NLD) {
;               __builtin_amdgcn_sched_barrier(0);
;               if (pre) issue_piece(kt + DIST, pc);
;               __builtin_amdgcn_sched_barrier(0);
;             }
;           }
;         }
;         if (s < 2 && NM < PPS) {
;           const int slot = s * NM + m;
;           __builtin_amdgcn_sched_barrier(0);
; #pragma unroll
;           for (int pc = 0; pc < NLD; ++pc)
;             if ((pc * 2 * NM) / NLD == slot && pre) issue_piece(kt + DIST, pc);
;           __builtin_amdgcn_sched_barrier(0);
;         }
;       }
;     }
;   }
;   __builtin_amdgcn_s_barrier();
; DEV void phase_outproj(const Params& p, int l, int hf, char* smem) {
;     ...
; #pragma unroll
;     for (int j = 0; j < 2; ++j) {
;       const int m = mt * 256 + wm * 64 + 32 * j + r;
;       const int bl = m / TP, tp = m - bl * TP;
;       const int b = hf * 2 + bl;
;       const int n0 = nt * 128 + wn * 64;
;       const float* src;
;       float* dst;
;       const float* gate;
;       if (tp < CTXL) {
	s_waitcnt lgkmcnt(0)
	v_mfma_f32_32x32x16_bf16 v[32:47], v[138:141], v[190:193], v[32:47]
	v_mfma_f32_32x32x16_bf16 v[0:15], v[138:141], v[194:197], v[0:15]
	ds_read_b128 v[138:141], v181
	ds_read_b128 v[190:193], v183
	ds_read_b128 v[194:197], v183 offset:4096
	ds_read_b128 v[198:201], v181 offset:4096
	s_waitcnt lgkmcnt(0)
	v_mfma_f32_32x32x16_bf16 v[48:63], v[138:141], v[190:193], v[48:63]
	v_mfma_f32_32x32x16_bf16 v[16:31], v[138:141], v[194:197], v[16:31]
	v_mfma_f32_32x32x16_bf16 v[32:47], v[198:201], v[190:193], v[32:47]
	v_mfma_f32_32x32x16_bf16 v[0:15], v[198:201], v[194:197], v[0:15]
	ds_read_b128 v[138:141], v184
	ds_read_b128 v[190:193], v186
	ds_read_b128 v[194:197], v186 offset:4096
	ds_read_b128 v[198:201], v184 offset:4096
	s_waitcnt lgkmcnt(0)
	v_mfma_f32_32x32x16_bf16 v[48:63], v[138:141], v[190:193], v[48:63]
	v_mfma_f32_32x32x16_bf16 v[16:31], v[138:141], v[194:197], v[16:31]
	v_mfma_f32_32x32x16_bf16 v[32:47], v[198:201], v[190:193], v[32:47]
	v_mfma_f32_32x32x16_bf16 v[0:15], v[198:201], v[194:197], v[0:15]
	ds_read_b128 v[138:141], v187
	ds_read_b128 v[190:193], v189
	ds_read_b128 v[194:197], v189 offset:4096
	s_waitcnt lgkmcnt(0)
	v_mfma_f32_32x32x16_bf16 v[48:63], v[138:141], v[190:193], v[48:63]
	v_mfma_f32_32x32x16_bf16 v[16:31], v[138:141], v[194:197], v[16:31]
	ds_read_b128 v[138:141], v187 offset:4096
	s_waitcnt lgkmcnt(0)
	v_mfma_f32_32x32x16_bf16 v[32:47], v[138:141], v[190:193], v[32:47]
	v_mfma_f32_32x32x16_bf16 v[0:15], v[138:141], v[194:197], v[0:15]
	ds_read_b128 v[138:141], v185
	ds_read_b128 v[190:193], v188
	ds_read_b128 v[186:189], v188 offset:4096
	s_waitcnt lgkmcnt(0)
	v_mfma_f32_32x32x16_bf16 v[48:63], v[138:141], v[190:193], v[48:63]
	v_mfma_f32_32x32x16_bf16 v[16:31], v[138:141], v[186:189], v[16:31]
	ds_read_b128 v[138:141], v185 offset:4096
	s_waitcnt vmcnt(0)
	s_barrier
	s_waitcnt lgkmcnt(0)
	v_mfma_f32_32x32x16_bf16 v[32:47], v[138:141], v[190:193], v[32:47]
	v_mfma_f32_32x32x16_bf16 v[0:15], v[138:141], v[186:189], v[0:15]
	ds_read_b128 v[138:141], v155 offset:32768
	ds_read_b128 v[182:185], v156
	ds_read_b128 v[186:189], v156 offset:4096
	ds_read_b128 v[190:193], v155 offset:36864
	s_waitcnt lgkmcnt(0)
	v_mfma_f32_32x32x16_bf16 v[48:63], v[138:141], v[182:185], v[48:63]
	v_mfma_f32_32x32x16_bf16 v[16:31], v[138:141], v[186:189], v[16:31]
	v_mfma_f32_32x32x16_bf16 v[32:47], v[190:193], v[182:185], v[32:47]
	v_mfma_f32_32x32x16_bf16 v[0:15], v[190:193], v[186:189], v[0:15]
	ds_read_b128 v[138:141], v157 offset:32768
	ds_read_b128 v[182:185], v158
	ds_read_b128 v[186:189], v158 offset:4096
	ds_read_b128 v[190:193], v157 offset:36864
	s_waitcnt lgkmcnt(0)
	v_mfma_f32_32x32x16_bf16 v[48:63], v[138:141], v[182:185], v[48:63]
	v_mfma_f32_32x32x16_bf16 v[16:31], v[138:141], v[186:189], v[16:31]
	v_mfma_f32_32x32x16_bf16 v[32:47], v[190:193], v[182:185], v[32:47]
	ds_read_b128 v[138:141], v160 offset:32768
	ds_read_b128 v[182:185], v162
	ds_read_b128 v[162:165], v162 offset:4096
	v_mfma_f32_32x32x16_bf16 v[0:15], v[190:193], v[186:189], v[0:15]
	s_waitcnt lgkmcnt(0)
	v_mfma_f32_32x32x16_bf16 v[48:63], v[138:141], v[182:185], v[48:63]
	v_mfma_f32_32x32x16_bf16 v[16:31], v[138:141], v[162:165], v[16:31]
	ds_read_b128 v[138:141], v160 offset:36864
	s_waitcnt lgkmcnt(0)
	v_mfma_f32_32x32x16_bf16 v[32:47], v[138:141], v[182:185], v[32:47]
	v_mfma_f32_32x32x16_bf16 v[0:15], v[138:141], v[162:165], v[0:15]
	ds_read_b128 v[138:141], v159 offset:32768
	ds_read_b128 v[162:165], v161
	ds_read_b128 v[182:185], v161 offset:4096
	ds_read_b128 v[156:159], v159 offset:36864
	s_barrier
	s_waitcnt lgkmcnt(0)
	v_mfma_f32_32x32x16_bf16 v[48:63], v[138:141], v[162:165], v[48:63]
	v_mfma_f32_32x32x16_bf16 v[16:31], v[138:141], v[182:185], v[16:31]
	v_mfma_f32_32x32x16_bf16 v[32:47], v[156:159], v[162:165], v[32:47]
	v_mfma_f32_32x32x16_bf16 v[0:15], v[156:159], v[182:185], v[0:15]
	s_and_saveexec_b64 s[12:13], vcc
	s_xor_b64 s[12:13], exec, s[12:13]
	s_cbranch_execz .LBB0_21
	v_lshlrev_b64 v[136:137], 25, v[134:135]
	v_readlane_b32 s24, v242, 1
	v_mul_i32_i24_e32 v134, 0xc00, v134
	v_readlane_b32 s28, v242, 5
	v_readlane_b32 s29, v242, 6
	v_ashrrev_i32_e32 v135, 31, v134
	v_lshlrev_b64 v[138:139], 12, v[144:145]
	v_lshl_add_u64 v[136:137], s[28:29], 0, v[136:137]
	v_lshl_add_u64 v[134:135], v[134:135], 2, s[0:1]
	s_mov_b64 s[22:23], 0x2000
	v_readlane_b32 s25, v242, 2
	v_readlane_b32 s26, v242, 3
	v_readlane_b32 s27, v242, 4
	v_readlane_b32 s30, v242, 7
	v_readlane_b32 s31, v242, 8
	v_lshl_add_u64 v[138:139], v[136:137], 0, v[138:139]
	v_lshl_add_u64 v[140:141], v[134:135], 0, s[22:23]

; DEV int opaque_tid() { int t = threadIdx.x; asm volatile("" : "+v"(t)); return t; }
;     ...
;   const int tid = opaque_tid(), lane = tid & 63, h = lane >> 5, r = lane & 31;
;   const int nk = K >> 6;
;   const int cch = (tid & 7) ^ ((tid >> 4) & 7);
;   const u16* ga = A + (size_t)(tid >> 3) * lda + cch * 8;
;   const u16* gb = Bt + (size_t)(tid >> 3) * ldb + cch * 8;
;   char* lds_t = smem + tid * 16;
;   auto issue_piece = [&](int kt, int pc) {
;     char* st = lds_t + (kt % NSTG) * STAGE;
;     if (pc < 4)
;       __builtin_amdgcn_global_load_lds((const unsigned*)(ga + (size_t)(64 * pc) * lda + (size_t)kt * ksa), (unsigned __attribute__((address_space(3)))*)(st + pc * 8192), 16, 0, 0);
;     else
;       __builtin_amdgcn_global_load_lds((const unsigned*)(gb + (size_t)(64 * (pc - 4)) * ldb + (size_t)kt * ksb), (unsigned __attribute__((address_space(3)))*)(st + ABYTES + (pc - 4) * 8192), 16, 0, 0);
;   };
;   const int x = (r >> 1) & 7;
;   int xo[4];
; #pragma unroll
;   for (int s = 0; s < 4; ++s) xo[s] = (((2 * s + h) ^ x) << 4);
;   asm volatile("s_waitcnt vmcnt(0)" ::: "memory");
; #pragma unroll
;   for (int d = 0; d < DIST; ++d)
; #pragma unroll
;     for (int pc = 0; pc < NLD; ++pc) issue_piece(d, pc);
; DEV void phase_outproj(const Params& p, int l, int hf, char* smem) {
;     ...
;     for (int u = (int)gridDim.x - 1 - (int)blockIdx.x; u < 32; u += gridDim.x) {
;       const int mt = (u >> 4) * 33, nt64 = u & 15;
;       f32x16 acc[1][2];
; #pragma unroll
;       for (int j = 0; j < 2; ++j)
; #pragma unroll
;         for (int e = 0; e < 16; ++e) acc[0][j][e] = 0.f;
;       gemm_main<1, 2, 64, 3>(acc, Y + (size_t)mt * 256 * 1024, 1024, W + (size_t)nt64 * 64 * 1024, 1024, 1024, smem, wm * 64, wn * 32);
.LBB0_31:
	s_ashr_i32 s6, s3, 4
	s_mul_i32 s8, s6, 33
	s_ashr_i32 s9, s8, 31
	s_and_b32 s5, s3, 15
	s_lshl_b64 s[8:9], s[8:9], 19
	v_mov_b32_e32 v4, v147
	s_add_u32 s8, s14, s8
	s_addc_u32 s9, s15, s9
	v_lshrrev_b32_e32 v0, 4, v4
	s_lshl_b32 s7, s5, 17
	v_xor_b32_e32 v5, v0, v4
	v_ashrrev_i32_e32 v0, 3, v4
	s_add_u32 s10, s16, s7
	v_ashrrev_i32_e32 v1, 31, v0
	s_addc_u32 s11, s17, 0
	v_lshlrev_b64 v[0:1], 11, v[0:1]
	v_lshlrev_b32_e32 v5, 4, v5
	v_lshl_add_u32 v70, v4, 4, 0
	v_lshl_add_u64 v[2:3], s[10:11], 0, v[0:1]
	v_lshl_add_u64 v[0:1], s[8:9], 0, v[0:1]
	v_and_b32_e32 v144, 0x70, v5
	v_readfirstlane_b32 s25, v70
	v_add_u32_e32 v71, 0x2000, v70
	v_lshl_add_u64 v[32:33], v[0:1], 0, v[144:145]
	s_mov_b32 m0, s25
	v_readfirstlane_b32 s24, v71
	v_add_u32_e32 v69, 0x4000, v70
	global_load_lds_dwordx4 v[32:33], off
	v_lshl_add_u64 v[0:1], v[32:33], 0, s[56:57]
	s_mov_b32 m0, s24
	v_readfirstlane_b32 s23, v69
	v_add_u32_e32 v68, 0x6000, v70
	global_load_lds_dwordx4 v[0:1], off
	v_lshl_add_u64 v[0:1], v[32:33], 0, s[82:83]
	s_mov_b32 m0, s23
	v_readfirstlane_b32 s22, v68
	v_add_u32_e32 v65, 0x8000, v70
	global_load_lds_dwordx4 v[0:1], off
	v_lshl_add_u64 v[0:1], v[32:33], 0, s[92:93]
	s_mov_b32 m0, s22
	v_readfirstlane_b32 s21, v65
	v_add_u32_e32 v56, 0xc000, v70
	v_lshl_add_u64 v[34:35], v[2:3], 0, v[144:145]
	global_load_lds_dwordx4 v[0:1], off
	s_mov_b32 m0, s21
	v_readfirstlane_b32 s20, v56
	v_add_u32_e32 v59, 0xe000, v70
	global_load_lds_dwordx4 v[34:35], off
	v_lshl_add_u64 v[0:1], v[32:33], 0, s[62:63]
	s_mov_b32 m0, s20
	v_readfirstlane_b32 s19, v59
	v_add_u32_e32 v57, 0x10000, v70
	global_load_lds_dwordx4 v[0:1], off
	v_lshl_add_u64 v[0:1], v[32:33], 0, s[64:65]
	s_mov_b32 m0, s19
	v_readfirstlane_b32 s18, v57
	v_add_u32_e32 v50, 0x12000, v70
	global_load_lds_dwordx4 v[0:1], off
	v_lshl_add_u64 v[0:1], v[32:33], 0, s[66:67]
	s_mov_b32 m0, s18
	v_readfirstlane_b32 s13, v50
	v_add_u32_e32 v49, 0x14000, v70
	global_load_lds_dwordx4 v[0:1], off
	v_lshl_add_u64 v[0:1], v[32:33], 0, s[76:77]
	s_mov_b32 m0, s13
	v_readfirstlane_b32 s12, v49
	v_lshl_add_u64 v[2:3], v[34:35], 0, s[62:63]
	global_load_lds_dwordx4 v[0:1], off
	s_mov_b32 m0, s12
	v_lshrrev_b32_e32 v0, 5, v4
	global_load_lds_dwordx4 v[2:3], off
	v_bfe_u32 v2, v4, 1, 3
	v_bfe_u32 v1, v4, 5, 1
	v_bitop3_b32 v0, v0, v2, 1 bitop3:0x6c
	v_lshlrev_b32_e32 v64, 4, v0
	v_bitop3_b32 v0, v1, v2, 2 bitop3:0x36
	v_lshlrev_b32_e32 v86, 4, v0
	v_bitop3_b32 v0, v1, v2, 4 bitop3:0x36
	v_lshlrev_b32_e32 v87, 4, v0
	v_and_b32_e32 v0, 31, v4
	v_or_b32_e32 v4, v0, v52
	v_or_b32_e32 v0, v0, v53
	v_lshlrev_b32_e32 v84, 7, v0
	v_add_u32_e32 v51, 0, v84
	v_add_u32_e32 v36, v51, v64
	v_bitop3_b32 v8, v1, v2, 6 bitop3:0x36
	s_waitcnt vmcnt(5)
	s_barrier
	ds_read_b128 v[0:3], v36 offset:32768
	v_lshlrev_b32_e32 v85, 7, v4
	v_add_u32_e32 v58, 0, v85
	v_add_u32_e32 v37, v58, v64
	ds_read_b128 v[4:7], v37
	v_lshlrev_b32_e32 v88, 4, v8
	ds_read_b128 v[8:11], v37 offset:4096
	v_lshl_add_u64 v[66:67], v[34:35], 0, s[78:79]
	v_add_u32_e32 v44, 0x18000, v70
	s_waitcnt lgkmcnt(0)
	v_mfma_f32_32x32x16_bf16 v[16:31], v[0:3], v[4:7], 0
	v_add_u32_e32 v45, 0x1a000, v70
	v_readfirstlane_b32 s9, v44
	v_lshl_add_u64 v[4:5], v[32:33], 0, s[78:79]
	s_mov_b32 m0, s9
	v_readfirstlane_b32 s7, v45
	v_lshl_add_u64 v[6:7], v[32:33], 0, s[94:95]
	global_load_lds_dwordx4 v[4:5], off
	s_mov_b32 m0, s7
	s_nop 0
	global_load_lds_dwordx4 v[6:7], off
	v_mfma_f32_32x32x16_bf16 v[0:15], v[0:3], v[8:11], 0
	v_add_u32_e32 v46, 0x1c000, v70
	s_mov_b64 s[10:11], 0x40100
	v_readfirstlane_b32 s8, v46
	v_lshl_add_u64 v[38:39], v[32:33], 0, s[10:11]
	s_mov_b32 m0, s8
	s_nop 0
	global_load_lds_dwordx4 v[38:39], off
	v_add_u32_e32 v39, v51, v86
	ds_read_b128 v[40:43], v39 offset:32768
	v_add_u32_e32 v38, v58, v86
	ds_read_b128 v[60:63], v38
	ds_read_b128 v[72:75], v38 offset:4096
	s_waitcnt lgkmcnt(0)
	v_mfma_f32_32x32x16_bf16 v[16:31], v[40:43], v[60:63], v[16:31]
	v_add_u32_e32 v47, 0x1e000, v70
	s_mov_b64 s[10:11], 0x60100
	v_lshl_add_u64 v[60:61], v[32:33], 0, s[10:11]
	v_readfirstlane_b32 s10, v47
	s_mov_b32 m0, s10
	s_nop 0
	global_load_lds_dwordx4 v[60:61], off
	v_mfma_f32_32x32x16_bf16 v[0:15], v[40:43], v[72:75], v[0:15]
	v_add_u32_e32 v48, 0x20000, v70
	s_nop 0
	v_readfirstlane_b32 s11, v48
	s_mov_b32 m0, s11
	s_nop 0
	global_load_lds_dwordx4 v[66:67], off
	v_add_u32_e32 v40, v58, v87
	v_add_u32_e32 v41, v51, v87
	ds_read_b128 v[60:63], v40
	ds_read_b128 v[72:75], v40 offset:4096
	ds_read_b128 v[76:79], v41 offset:32768
	v_add_u32_e32 v42, v51, v88
	v_add_u32_e32 v43, v58, v88
	s_add_i32 s26, 0, 0x14000
	v_add_u32_e32 v89, s26, v84
	v_add_u32_e32 v51, v89, v64
	v_lshl_add_u64 v[66:67], v[34:35], 0, s[42:43]
	s_waitcnt lgkmcnt(0)
	v_mfma_f32_32x32x16_bf16 v[16:31], v[76:79], v[60:63], v[16:31]
	ds_read_b128 v[60:63], v42 offset:32768
	v_mfma_f32_32x32x16_bf16 v[0:15], v[76:79], v[72:75], v[0:15]
	ds_read_b128 v[72:75], v43 offset:4096
	ds_read_b128 v[76:79], v43
	s_waitcnt vmcnt(5)
	s_barrier
; #define MFMA(a, b, c) __builtin_amdgcn_mfma_f32_32x32x16_bf16((a), (b), (c), 0, 0, 0)
;     ...
;   for (int kt = 0; kt < nk; ++kt) {
;     if (DIST == 2 && kt + 1 < nk) {
;       if (NLD == 6) asm volatile("s_waitcnt vmcnt(6)" ::: "memory");
;       else if (NLD == 5) asm volatile("s_waitcnt vmcnt(5)" ::: "memory");
;       else asm volatile("s_waitcnt vmcnt(8)" ::: "memory");
;     } else {
;       asm volatile("s_waitcnt vmcnt(0)" ::: "memory");
;     }
;     __builtin_amdgcn_s_barrier();
;     const bool pre = (kt + DIST < nk);
;     const char* base = smem + (kt % NSTG) * STAGE;
;     const char* pa = base + (wrow_act + r) * 128;
;     const char* pw = base + ABYTES + (wrow_w + r) * 128;
;     constexpr int NM = NI * MJ;
;     constexpr int PPS = (NLD + 1) / 2;
; #pragma unroll
;     for (int s = 0; s < 4; ++s) {
;       bf16x8 af[MJ], wf[NI];
; #pragma unroll
;       for (int j = 0; j < MJ; ++j) af[j] = *(const bf16x8*)(pa + j * 32 * 128 + xo[s]);
; #pragma unroll
;       for (int i = 0; i < NI; ++i) wf[i] = *(const bf16x8*)(pw + i * 32 * 128 + xo[s]);
; #pragma unroll
;       for (int m = 0; m < NM; ++m) {
;         const int i = m / MJ, j = m % MJ;
;         acc[i][j] = MFMA(wf[i], af[j], acc[i][j]);
;         if (s < 2 && NM >= PPS) {
;           constexpr int EVERY = (NM / PPS) > 0 ? (NM / PPS) : 1;
;           if ((m + 1) % EVERY == 0) {
;             const int pc = s * PPS + (m + 1) / EVERY - 1;
;             if ((m + 1) / EVERY <= PPS && pc < NLD) {
;               __builtin_amdgcn_sched_barrier(0);
;               if (pre) issue_piece(kt + DIST, pc);
;               __builtin_amdgcn_sched_barrier(0);
;             }
;           }
;         }
;         if (s < 2 && NM < PPS) {
;           const int slot = s * NM + m;
;           __builtin_amdgcn_sched_barrier(0);
; #pragma unroll
;           for (int pc = 0; pc < NLD; ++pc)
;             if ((pc * 2 * NM) / NLD == slot && pre) issue_piece(kt + DIST, pc);
;           __builtin_amdgcn_sched_barrier(0);
;         }
;       }
;     }
	s_waitcnt lgkmcnt(0)
	v_mfma_f32_32x32x16_bf16 v[16:31], v[60:63], v[76:79], v[16:31]
	v_mfma_f32_32x32x16_bf16 v[0:15], v[60:63], v[72:75], v[0:15]
	ds_read_b128 v[60:63], v37 offset:49152
	ds_read_b128 v[72:75], v37 offset:53248
	ds_read_b128 v[76:79], v51
	s_waitcnt lgkmcnt(0)
	v_mfma_f32_32x32x16_bf16 v[16:31], v[76:79], v[60:63], v[16:31]
	s_mov_b32 m0, s25
	v_lshl_add_u64 v[60:61], v[32:33], 0, s[42:43]
	s_mov_b64 s[26:27], 0x20180
	v_lshl_add_u64 v[62:63], v[32:33], 0, s[26:27]
	global_load_lds_dwordx4 v[60:61], off
	s_mov_b32 m0, s24
	s_nop 0
	global_load_lds_dwordx4 v[62:63], off
	v_mfma_f32_32x32x16_bf16 v[0:15], v[76:79], v[72:75], v[0:15]
	s_mov_b64 s[26:27], 0x40180
	v_lshl_add_u64 v[60:61], v[32:33], 0, s[26:27]
	s_mov_b32 m0, s23
	s_nop 0
	global_load_lds_dwordx4 v[60:61], off
	v_add_u32_e32 v58, v89, v86
	ds_read_b128 v[60:63], v58
	ds_read_b128 v[72:75], v38 offset:49152
	ds_read_b128 v[76:79], v38 offset:53248
	s_waitcnt lgkmcnt(0)
	v_mfma_f32_32x32x16_bf16 v[16:31], v[60:63], v[72:75], v[16:31]
	s_mov_b64 s[26:27], 0x60180
	v_lshl_add_u64 v[72:73], v[32:33], 0, s[26:27]
	s_mov_b32 m0, s22
	s_nop 0
	global_load_lds_dwordx4 v[72:73], off
	v_mfma_f32_32x32x16_bf16 v[0:15], v[60:63], v[76:79], v[0:15]
	s_mov_b32 m0, s21
	s_nop 0
	global_load_lds_dwordx4 v[66:67], off
	v_add_u32_e32 v60, v89, v87
	ds_read_b128 v[72:75], v40 offset:49152
	ds_read_b128 v[76:79], v40 offset:53248
	ds_read_b128 v[80:83], v60
	v_add_u32_e32 v61, v89, v88
	s_add_i32 s26, 0, 0x18000
	v_add_u32_e32 v89, s26, v85
	s_add_i32 s26, 0, 0x20000
	v_add_u32_e32 v90, s26, v84
	v_add_u32_e32 v62, v89, v64
	v_add_u32_e32 v63, v90, v64
	s_waitcnt lgkmcnt(0)
	v_mfma_f32_32x32x16_bf16 v[16:31], v[80:83], v[72:75], v[16:31]
	v_lshl_add_u64 v[84:85], v[34:35], 0, s[52:53]
	v_mfma_f32_32x32x16_bf16 v[0:15], v[80:83], v[76:79], v[0:15]
	ds_read_b128 v[72:75], v61
	ds_read_b128 v[76:79], v43 offset:53248
	ds_read_b128 v[80:83], v43 offset:49152
	s_waitcnt vmcnt(5)
	s_barrier
	s_waitcnt lgkmcnt(0)
	v_mfma_f32_32x32x16_bf16 v[16:31], v[72:75], v[80:83], v[16:31]
	v_mfma_f32_32x32x16_bf16 v[0:15], v[72:75], v[76:79], v[0:15]
	ds_read_b128 v[72:75], v62
	ds_read_b128 v[76:79], v62 offset:4096
	ds_read_b128 v[80:83], v63
	s_waitcnt lgkmcnt(0)
	v_mfma_f32_32x32x16_bf16 v[16:31], v[80:83], v[72:75], v[16:31]
	s_mov_b32 m0, s20
	v_lshl_add_u64 v[66:67], v[32:33], 0, s[52:53]
	s_mov_b64 s[26:27], 0x20200
	v_lshl_add_u64 v[72:73], v[32:33], 0, s[26:27]
	global_load_lds_dwordx4 v[66:67], off
	s_mov_b32 m0, s19
	s_nop 0
	global_load_lds_dwordx4 v[72:73], off
	v_mfma_f32_32x32x16_bf16 v[0:15], v[80:83], v[76:79], v[0:15]
	s_mov_b64 s[26:27], 0x40200
	v_lshl_add_u64 v[66:67], v[32:33], 0, s[26:27]
	s_mov_b32 m0, s18
	s_nop 0
	global_load_lds_dwordx4 v[66:67], off
	v_add_u32_e32 v67, v90, v86
	ds_read_b128 v[72:75], v67
	v_add_u32_e32 v66, v89, v86
	ds_read_b128 v[76:79], v66
	ds_read_b128 v[80:83], v66 offset:4096
	s_waitcnt lgkmcnt(0)
	v_mfma_f32_32x32x16_bf16 v[16:31], v[72:75], v[76:79], v[16:31]
	s_mov_b64 s[26:27], 0x60200
	v_lshl_add_u64 v[76:77], v[32:33], 0, s[26:27]
	s_mov_b32 m0, s13
	s_nop 0
	global_load_lds_dwordx4 v[76:77], off
	v_mfma_f32_32x32x16_bf16 v[0:15], v[72:75], v[80:83], v[0:15]
	s_mov_b32 m0, s12
	s_nop 0
	global_load_lds_dwordx4 v[84:85], off
	v_add_u32_e32 v64, v89, v87
	v_add_u32_e32 v72, v90, v87
	ds_read_b128 v[74:77], v64
	ds_read_b128 v[78:81], v64 offset:4096
	ds_read_b128 v[82:85], v72
	v_add_u32_e32 v73, v89, v88
	s_waitcnt lgkmcnt(0)
	v_mfma_f32_32x32x16_bf16 v[16:31], v[82:85], v[74:77], v[16:31]
	v_add_u32_e32 v74, v90, v88
	v_lshl_add_u64 v[88:89], v[34:35], 0, s[88:89]
	v_mfma_f32_32x32x16_bf16 v[0:15], v[82:85], v[78:81], v[0:15]
	ds_read_b128 v[76:79], v74
	ds_read_b128 v[80:83], v73 offset:4096
	ds_read_b128 v[84:87], v73
	s_waitcnt vmcnt(5)
	s_barrier
	s_waitcnt lgkmcnt(0)
	v_mfma_f32_32x32x16_bf16 v[16:31], v[76:79], v[84:87], v[16:31]
	v_mfma_f32_32x32x16_bf16 v[0:15], v[76:79], v[80:83], v[0:15]
	ds_read_b128 v[76:79], v37
	ds_read_b128 v[80:83], v37 offset:4096
	ds_read_b128 v[84:87], v36 offset:32768
	s_waitcnt lgkmcnt(0)
	v_mfma_f32_32x32x16_bf16 v[16:31], v[84:87], v[76:79], v[16:31]
	s_mov_b32 m0, s9
	v_lshl_add_u64 v[76:77], v[32:33], 0, s[88:89]
	s_mov_b64 s[26:27], 0x20280
	v_lshl_add_u64 v[78:79], v[32:33], 0, s[26:27]
	global_load_lds_dwordx4 v[76:77], off
	s_mov_b32 m0, s7
	s_nop 0
	global_load_lds_dwordx4 v[78:79], off
	v_mfma_f32_32x32x16_bf16 v[0:15], v[84:87], v[80:83], v[0:15]
	s_mov_b64 s[26:27], 0x40280
	v_lshl_add_u64 v[76:77], v[32:33], 0, s[26:27]
	s_mov_b32 m0, s8
	s_nop 0
	global_load_lds_dwordx4 v[76:77], off
	ds_read_b128 v[76:79], v39 offset:32768
	ds_read_b128 v[80:83], v38
	ds_read_b128 v[84:87], v38 offset:4096
	s_waitcnt lgkmcnt(0)
	v_mfma_f32_32x32x16_bf16 v[16:31], v[76:79], v[80:83], v[16:31]
	s_mov_b64 s[26:27], 0x60280
	v_lshl_add_u64 v[80:81], v[32:33], 0, s[26:27]
	s_mov_b32 m0, s10
	s_nop 0
	global_load_lds_dwordx4 v[80:81], off
	v_mfma_f32_32x32x16_bf16 v[0:15], v[76:79], v[84:87], v[0:15]
	s_mov_b32 m0, s11
	s_nop 0
	global_load_lds_dwordx4 v[88:89], off
	ds_read_b128 v[76:79], v40
	ds_read_b128 v[80:83], v40 offset:4096
	ds_read_b128 v[84:87], v41 offset:32768
	v_lshl_add_u64 v[88:89], v[34:35], 0, s[70:71]
	s_waitcnt lgkmcnt(0)
	v_mfma_f32_32x32x16_bf16 v[16:31], v[84:87], v[76:79], v[16:31]
	v_mfma_f32_32x32x16_bf16 v[0:15], v[84:87], v[80:83], v[0:15]
	ds_read_b128 v[76:79], v42 offset:32768
	ds_read_b128 v[80:83], v43 offset:4096
	ds_read_b128 v[84:87], v43
	s_waitcnt vmcnt(5)
	s_barrier
; #define MFMA(a, b, c) __builtin_amdgcn_mfma_f32_32x32x16_bf16((a), (b), (c), 0, 0, 0)
;     ...
;   for (int kt = 0; kt < nk; ++kt) {
;     if (DIST == 2 && kt + 1 < nk) {
;       if (NLD == 6) asm volatile("s_waitcnt vmcnt(6)" ::: "memory");
;       else if (NLD == 5) asm volatile("s_waitcnt vmcnt(5)" ::: "memory");
;       else asm volatile("s_waitcnt vmcnt(8)" ::: "memory");
;     } else {
;       asm volatile("s_waitcnt vmcnt(0)" ::: "memory");
;     }
;     __builtin_amdgcn_s_barrier();
;     const bool pre = (kt + DIST < nk);
;     const char* base = smem + (kt % NSTG) * STAGE;
;     const char* pa = base + (wrow_act + r) * 128;
;     const char* pw = base + ABYTES + (wrow_w + r) * 128;
;     constexpr int NM = NI * MJ;
;     constexpr int PPS = (NLD + 1) / 2;
; #pragma unroll
;     for (int s = 0; s < 4; ++s) {
;       bf16x8 af[MJ], wf[NI];
; #pragma unroll
;       for (int j = 0; j < MJ; ++j) af[j] = *(const bf16x8*)(pa + j * 32 * 128 + xo[s]);
; #pragma unroll
;       for (int i = 0; i < NI; ++i) wf[i] = *(const bf16x8*)(pw + i * 32 * 128 + xo[s]);
; #pragma unroll
;       for (int m = 0; m < NM; ++m) {
;         const int i = m / MJ, j = m % MJ;
;         acc[i][j] = MFMA(wf[i], af[j], acc[i][j]);
;         if (s < 2 && NM >= PPS) {
;           constexpr int EVERY = (NM / PPS) > 0 ? (NM / PPS) : 1;
;           if ((m + 1) % EVERY == 0) {
;             const int pc = s * PPS + (m + 1) / EVERY - 1;
;             if ((m + 1) / EVERY <= PPS && pc < NLD) {
;               __builtin_amdgcn_sched_barrier(0);
;               if (pre) issue_piece(kt + DIST, pc);
;               __builtin_amdgcn_sched_barrier(0);
;             }
;           }
;         }
;         if (s < 2 && NM < PPS) {
;           const int slot = s * NM + m;
;           __builtin_amdgcn_sched_barrier(0);
; #pragma unroll
;           for (int pc = 0; pc < NLD; ++pc)
;             if ((pc * 2 * NM) / NLD == slot && pre) issue_piece(kt + DIST, pc);
;           __builtin_amdgcn_sched_barrier(0);
;         }
;       }
;     }
	s_waitcnt lgkmcnt(0)
	v_mfma_f32_32x32x16_bf16 v[16:31], v[76:79], v[84:87], v[16:31]
	v_mfma_f32_32x32x16_bf16 v[0:15], v[76:79], v[80:83], v[0:15]
	ds_read_b128 v[76:79], v37 offset:49152
	ds_read_b128 v[80:83], v37 offset:53248
	ds_read_b128 v[84:87], v51
	s_waitcnt lgkmcnt(0)
	v_mfma_f32_32x32x16_bf16 v[16:31], v[84:87], v[76:79], v[16:31]
	s_mov_b32 m0, s25
	v_lshl_add_u64 v[76:77], v[32:33], 0, s[70:71]
	s_mov_b64 s[26:27], 0x20300
	v_lshl_add_u64 v[78:79], v[32:33], 0, s[26:27]
	global_load_lds_dwordx4 v[76:77], off
	s_mov_b32 m0, s24
	s_nop 0
	global_load_lds_dwordx4 v[78:79], off
	v_mfma_f32_32x32x16_bf16 v[0:15], v[84:87], v[80:83], v[0:15]
	s_mov_b64 s[26:27], 0x40300
	v_lshl_add_u64 v[76:77], v[32:33], 0, s[26:27]
	s_mov_b32 m0, s23
	s_nop 0
	global_load_lds_dwordx4 v[76:77], off
	ds_read_b128 v[76:79], v58
	ds_read_b128 v[80:83], v38 offset:49152
	ds_read_b128 v[84:87], v38 offset:53248
	s_waitcnt lgkmcnt(0)
	v_mfma_f32_32x32x16_bf16 v[16:31], v[76:79], v[80:83], v[16:31]
	s_mov_b64 s[26:27], 0x60300
	v_lshl_add_u64 v[80:81], v[32:33], 0, s[26:27]
	s_mov_b32 m0, s22
	s_nop 0
	global_load_lds_dwordx4 v[80:81], off
	v_mfma_f32_32x32x16_bf16 v[0:15], v[76:79], v[84:87], v[0:15]
	s_mov_b32 m0, s21
	s_nop 0
	global_load_lds_dwordx4 v[88:89], off
	ds_read_b128 v[76:79], v40 offset:49152
	ds_read_b128 v[80:83], v40 offset:53248
	ds_read_b128 v[84:87], v60
	v_lshl_add_u64 v[88:89], v[34:35], 0, s[36:37]
	s_waitcnt lgkmcnt(0)
	v_mfma_f32_32x32x16_bf16 v[16:31], v[84:87], v[76:79], v[16:31]
	v_mfma_f32_32x32x16_bf16 v[0:15], v[84:87], v[80:83], v[0:15]
	ds_read_b128 v[76:79], v61
	ds_read_b128 v[80:83], v43 offset:53248
	ds_read_b128 v[84:87], v43 offset:49152
	s_waitcnt vmcnt(5)
	s_barrier
	s_waitcnt lgkmcnt(0)
	v_mfma_f32_32x32x16_bf16 v[16:31], v[76:79], v[84:87], v[16:31]
	v_mfma_f32_32x32x16_bf16 v[0:15], v[76:79], v[80:83], v[0:15]
	ds_read_b128 v[76:79], v62
	ds_read_b128 v[80:83], v62 offset:4096
	ds_read_b128 v[84:87], v63
	s_waitcnt lgkmcnt(0)
	v_mfma_f32_32x32x16_bf16 v[16:31], v[84:87], v[76:79], v[16:31]
	s_mov_b32 m0, s20
	v_lshl_add_u64 v[76:77], v[32:33], 0, s[36:37]
	s_mov_b64 s[26:27], 0x20380
	v_lshl_add_u64 v[78:79], v[32:33], 0, s[26:27]
	global_load_lds_dwordx4 v[76:77], off
	s_mov_b32 m0, s19
	s_nop 0
	global_load_lds_dwordx4 v[78:79], off
	v_mfma_f32_32x32x16_bf16 v[0:15], v[84:87], v[80:83], v[0:15]
	s_mov_b64 s[26:27], 0x40380
	v_lshl_add_u64 v[76:77], v[32:33], 0, s[26:27]
	s_mov_b32 m0, s18
	s_nop 0
	global_load_lds_dwordx4 v[76:77], off
	ds_read_b128 v[76:79], v67
	ds_read_b128 v[80:83], v66
	ds_read_b128 v[84:87], v66 offset:4096
	s_waitcnt lgkmcnt(0)
	v_mfma_f32_32x32x16_bf16 v[16:31], v[76:79], v[80:83], v[16:31]
	s_mov_b64 s[26:27], 0x60380
	v_lshl_add_u64 v[80:81], v[32:33], 0, s[26:27]
	s_mov_b32 m0, s13
	s_nop 0
	global_load_lds_dwordx4 v[80:81], off
	v_mfma_f32_32x32x16_bf16 v[0:15], v[76:79], v[84:87], v[0:15]
	s_mov_b32 m0, s12
	s_nop 0
	global_load_lds_dwordx4 v[88:89], off
	ds_read_b128 v[76:79], v64
	ds_read_b128 v[80:83], v64 offset:4096
	ds_read_b128 v[84:87], v72
	v_lshl_add_u64 v[88:89], v[34:35], 0, s[54:55]
	s_waitcnt lgkmcnt(0)
	v_mfma_f32_32x32x16_bf16 v[16:31], v[84:87], v[76:79], v[16:31]
	v_mfma_f32_32x32x16_bf16 v[0:15], v[84:87], v[80:83], v[0:15]
	ds_read_b128 v[76:79], v74
	ds_read_b128 v[80:83], v73 offset:4096
	ds_read_b128 v[84:87], v73
	s_waitcnt vmcnt(5)
	s_barrier
	s_waitcnt lgkmcnt(0)
	v_mfma_f32_32x32x16_bf16 v[16:31], v[76:79], v[84:87], v[16:31]
	v_mfma_f32_32x32x16_bf16 v[0:15], v[76:79], v[80:83], v[0:15]
	ds_read_b128 v[76:79], v37
	ds_read_b128 v[80:83], v37 offset:4096
	ds_read_b128 v[84:87], v36 offset:32768
	s_waitcnt lgkmcnt(0)
	v_mfma_f32_32x32x16_bf16 v[16:31], v[84:87], v[76:79], v[16:31]
	s_mov_b32 m0, s9
	v_lshl_add_u64 v[76:77], v[32:33], 0, s[54:55]
	s_mov_b64 s[26:27], 0x20400
	v_lshl_add_u64 v[78:79], v[32:33], 0, s[26:27]
	global_load_lds_dwordx4 v[76:77], off
	s_mov_b32 m0, s7
	s_nop 0
	global_load_lds_dwordx4 v[78:79], off
	v_mfma_f32_32x32x16_bf16 v[0:15], v[84:87], v[80:83], v[0:15]
	s_mov_b64 s[26:27], 0x40400
	v_lshl_add_u64 v[76:77], v[32:33], 0, s[26:27]
	s_mov_b32 m0, s8
	s_nop 0
	global_load_lds_dwordx4 v[76:77], off
	ds_read_b128 v[76:79], v39 offset:32768
	ds_read_b128 v[80:83], v38
	ds_read_b128 v[84:87], v38 offset:4096
	s_waitcnt lgkmcnt(0)
	v_mfma_f32_32x32x16_bf16 v[16:31], v[76:79], v[80:83], v[16:31]
	s_mov_b64 s[26:27], 0x60400
	v_lshl_add_u64 v[80:81], v[32:33], 0, s[26:27]
	s_mov_b32 m0, s10
	s_nop 0
	global_load_lds_dwordx4 v[80:81], off
	v_mfma_f32_32x32x16_bf16 v[0:15], v[76:79], v[84:87], v[0:15]
	s_mov_b32 m0, s11
	s_nop 0
	global_load_lds_dwordx4 v[88:89], off
	ds_read_b128 v[76:79], v40
	ds_read_b128 v[80:83], v40 offset:4096
	ds_read_b128 v[84:87], v41 offset:32768
	v_lshl_add_u64 v[88:89], v[34:35], 0, s[96:97]
	s_waitcnt lgkmcnt(0)
	v_mfma_f32_32x32x16_bf16 v[16:31], v[84:87], v[76:79], v[16:31]
	v_mfma_f32_32x32x16_bf16 v[0:15], v[84:87], v[80:83], v[0:15]
	ds_read_b128 v[76:79], v42 offset:32768
	ds_read_b128 v[80:83], v43 offset:4096
	ds_read_b128 v[84:87], v43
	s_waitcnt vmcnt(5)
	s_barrier
; #define MFMA(a, b, c) __builtin_amdgcn_mfma_f32_32x32x16_bf16((a), (b), (c), 0, 0, 0)
;     ...
;   for (int kt = 0; kt < nk; ++kt) {
;     if (DIST == 2 && kt + 1 < nk) {
;       if (NLD == 6) asm volatile("s_waitcnt vmcnt(6)" ::: "memory");
;       else if (NLD == 5) asm volatile("s_waitcnt vmcnt(5)" ::: "memory");
;       else asm volatile("s_waitcnt vmcnt(8)" ::: "memory");
;     } else {
;       asm volatile("s_waitcnt vmcnt(0)" ::: "memory");
;     }
;     __builtin_amdgcn_s_barrier();
;     const bool pre = (kt + DIST < nk);
;     const char* base = smem + (kt % NSTG) * STAGE;
;     const char* pa = base + (wrow_act + r) * 128;
;     const char* pw = base + ABYTES + (wrow_w + r) * 128;
;     constexpr int NM = NI * MJ;
;     constexpr int PPS = (NLD + 1) / 2;
; #pragma unroll
;     for (int s = 0; s < 4; ++s) {
;       bf16x8 af[MJ], wf[NI];
; #pragma unroll
;       for (int j = 0; j < MJ; ++j) af[j] = *(const bf16x8*)(pa + j * 32 * 128 + xo[s]);
; #pragma unroll
;       for (int i = 0; i < NI; ++i) wf[i] = *(const bf16x8*)(pw + i * 32 * 128 + xo[s]);
; #pragma unroll
;       for (int m = 0; m < NM; ++m) {
;         const int i = m / MJ, j = m % MJ;
;         acc[i][j] = MFMA(wf[i], af[j], acc[i][j]);
;         if (s < 2 && NM >= PPS) {
;           constexpr int EVERY = (NM / PPS) > 0 ? (NM / PPS) : 1;
;           if ((m + 1) % EVERY == 0) {
;             const int pc = s * PPS + (m + 1) / EVERY - 1;
;             if ((m + 1) / EVERY <= PPS && pc < NLD) {
;               __builtin_amdgcn_sched_barrier(0);
;               if (pre) issue_piece(kt + DIST, pc);
;               __builtin_amdgcn_sched_barrier(0);
;             }
;           }
;         }
;         if (s < 2 && NM < PPS) {
;           const int slot = s * NM + m;
;           __builtin_amdgcn_sched_barrier(0);
; #pragma unroll
;           for (int pc = 0; pc < NLD; ++pc)
;             if ((pc * 2 * NM) / NLD == slot && pre) issue_piece(kt + DIST, pc);
;           __builtin_amdgcn_sched_barrier(0);
;         }
;       }
;     }
	s_waitcnt lgkmcnt(0)
	v_mfma_f32_32x32x16_bf16 v[16:31], v[76:79], v[84:87], v[16:31]
	v_mfma_f32_32x32x16_bf16 v[0:15], v[76:79], v[80:83], v[0:15]
	ds_read_b128 v[76:79], v37 offset:49152
	ds_read_b128 v[80:83], v37 offset:53248
	ds_read_b128 v[84:87], v51
	s_waitcnt lgkmcnt(0)
	v_mfma_f32_32x32x16_bf16 v[16:31], v[84:87], v[76:79], v[16:31]
	s_mov_b32 m0, s25
	v_lshl_add_u64 v[76:77], v[32:33], 0, s[96:97]
	s_mov_b64 s[26:27], 0x20480
	v_lshl_add_u64 v[78:79], v[32:33], 0, s[26:27]
	global_load_lds_dwordx4 v[76:77], off
	s_mov_b32 m0, s24
	s_nop 0
	global_load_lds_dwordx4 v[78:79], off
	v_mfma_f32_32x32x16_bf16 v[0:15], v[84:87], v[80:83], v[0:15]
	s_mov_b64 s[24:25], 0x40480
	v_lshl_add_u64 v[76:77], v[32:33], 0, s[24:25]
	s_mov_b32 m0, s23
	s_nop 0
	global_load_lds_dwordx4 v[76:77], off
	ds_read_b128 v[76:79], v58
	ds_read_b128 v[80:83], v38 offset:49152
	ds_read_b128 v[84:87], v38 offset:53248
	s_waitcnt lgkmcnt(0)
	v_mfma_f32_32x32x16_bf16 v[16:31], v[76:79], v[80:83], v[16:31]
	s_mov_b64 s[24:25], 0x60480
	v_lshl_add_u64 v[80:81], v[32:33], 0, s[24:25]
	s_mov_b32 m0, s22
	s_nop 0
	global_load_lds_dwordx4 v[80:81], off
	v_mfma_f32_32x32x16_bf16 v[0:15], v[76:79], v[84:87], v[0:15]
	s_mov_b32 m0, s21
	s_nop 0
	global_load_lds_dwordx4 v[88:89], off
	ds_read_b128 v[76:79], v40 offset:49152
	ds_read_b128 v[80:83], v40 offset:53248
	ds_read_b128 v[84:87], v60
	v_lshl_add_u64 v[88:89], v[34:35], 0, s[30:31]
	s_waitcnt lgkmcnt(0)
	v_mfma_f32_32x32x16_bf16 v[16:31], v[84:87], v[76:79], v[16:31]
	v_mfma_f32_32x32x16_bf16 v[0:15], v[84:87], v[80:83], v[0:15]
	ds_read_b128 v[76:79], v61
	ds_read_b128 v[80:83], v43 offset:53248
	ds_read_b128 v[84:87], v43 offset:49152
	s_waitcnt vmcnt(5)
	s_barrier
	s_waitcnt lgkmcnt(0)
	v_mfma_f32_32x32x16_bf16 v[16:31], v[76:79], v[84:87], v[16:31]
	v_mfma_f32_32x32x16_bf16 v[0:15], v[76:79], v[80:83], v[0:15]
	ds_read_b128 v[76:79], v62
	ds_read_b128 v[80:83], v62 offset:4096
	ds_read_b128 v[84:87], v63
	s_waitcnt lgkmcnt(0)
	v_mfma_f32_32x32x16_bf16 v[16:31], v[84:87], v[76:79], v[16:31]
	s_mov_b32 m0, s20
	v_lshl_add_u64 v[76:77], v[32:33], 0, s[30:31]
	s_mov_b64 s[20:21], 0x20500
	v_lshl_add_u64 v[78:79], v[32:33], 0, s[20:21]
	global_load_lds_dwordx4 v[76:77], off
	s_mov_b32 m0, s19
	s_nop 0
	global_load_lds_dwordx4 v[78:79], off
	v_mfma_f32_32x32x16_bf16 v[0:15], v[84:87], v[80:83], v[0:15]
	s_mov_b64 s[20:21], 0x40500
	v_lshl_add_u64 v[76:77], v[32:33], 0, s[20:21]
	s_mov_b32 m0, s18
	s_nop 0
	global_load_lds_dwordx4 v[76:77], off
	ds_read_b128 v[76:79], v67
	ds_read_b128 v[80:83], v66
	ds_read_b128 v[84:87], v66 offset:4096
	s_waitcnt lgkmcnt(0)
	v_mfma_f32_32x32x16_bf16 v[16:31], v[76:79], v[80:83], v[16:31]
	s_mov_b64 s[18:19], 0x60500
	v_lshl_add_u64 v[80:81], v[32:33], 0, s[18:19]
	s_mov_b32 m0, s13
	s_nop 0
	global_load_lds_dwordx4 v[80:81], off
	v_mfma_f32_32x32x16_bf16 v[0:15], v[76:79], v[84:87], v[0:15]
	s_mov_b32 m0, s12
	s_nop 0
	global_load_lds_dwordx4 v[88:89], off
	ds_read_b128 v[76:79], v64
	ds_read_b128 v[80:83], v64 offset:4096
	ds_read_b128 v[84:87], v72
	v_lshl_add_u64 v[88:89], v[34:35], 0, s[84:85]
	s_waitcnt lgkmcnt(0)
	v_mfma_f32_32x32x16_bf16 v[16:31], v[84:87], v[76:79], v[16:31]
	v_mfma_f32_32x32x16_bf16 v[0:15], v[84:87], v[80:83], v[0:15]
	ds_read_b128 v[76:79], v74
	ds_read_b128 v[80:83], v73 offset:4096
	ds_read_b128 v[84:87], v73
	s_waitcnt vmcnt(5)
	s_barrier
	s_waitcnt lgkmcnt(0)
	v_mfma_f32_32x32x16_bf16 v[16:31], v[76:79], v[84:87], v[16:31]
	v_mfma_f32_32x32x16_bf16 v[0:15], v[76:79], v[80:83], v[0:15]
	ds_read_b128 v[76:79], v37
	ds_read_b128 v[80:83], v37 offset:4096
	ds_read_b128 v[84:87], v36 offset:32768
	s_waitcnt lgkmcnt(0)
	v_mfma_f32_32x32x16_bf16 v[16:31], v[84:87], v[76:79], v[16:31]
	s_mov_b32 m0, s9
	v_lshl_add_u64 v[76:77], v[32:33], 0, s[84:85]
	s_mov_b64 s[12:13], 0x20580
	v_lshl_add_u64 v[78:79], v[32:33], 0, s[12:13]
	global_load_lds_dwordx4 v[76:77], off
	s_mov_b32 m0, s7
	s_nop 0
	global_load_lds_dwordx4 v[78:79], off
	v_mfma_f32_32x32x16_bf16 v[0:15], v[84:87], v[80:83], v[0:15]
	s_mov_b64 s[12:13], 0x40580
	v_lshl_add_u64 v[76:77], v[32:33], 0, s[12:13]
	s_mov_b32 m0, s8
	s_nop 0
	global_load_lds_dwordx4 v[76:77], off
	ds_read_b128 v[76:79], v39 offset:32768
	ds_read_b128 v[80:83], v38
	ds_read_b128 v[84:87], v38 offset:4096
	s_waitcnt lgkmcnt(0)
	v_mfma_f32_32x32x16_bf16 v[16:31], v[76:79], v[80:83], v[16:31]
	s_mov_b64 s[8:9], 0x60580
	v_lshl_add_u64 v[80:81], v[32:33], 0, s[8:9]
	s_mov_b32 m0, s10
	s_nop 0
	global_load_lds_dwordx4 v[80:81], off
	v_mfma_f32_32x32x16_bf16 v[0:15], v[76:79], v[84:87], v[0:15]
	s_mov_b32 m0, s11
	s_nop 0
	global_load_lds_dwordx4 v[88:89], off
	ds_read_b128 v[76:79], v40
	ds_read_b128 v[80:83], v40 offset:4096
	ds_read_b128 v[84:87], v41 offset:32768
	v_lshl_add_u64 v[88:89], v[34:35], 0, s[38:39]
	s_waitcnt lgkmcnt(0)
	v_mfma_f32_32x32x16_bf16 v[16:31], v[84:87], v[76:79], v[16:31]
	v_mfma_f32_32x32x16_bf16 v[0:15], v[84:87], v[80:83], v[0:15]
	ds_read_b128 v[76:79], v42 offset:32768
	ds_read_b128 v[80:83], v43 offset:4096
	ds_read_b128 v[84:87], v43
	s_waitcnt vmcnt(5)
	s_barrier
; #define MFMA(a, b, c) __builtin_amdgcn_mfma_f32_32x32x16_bf16((a), (b), (c), 0, 0, 0)
;     ...
;   for (int kt = 0; kt < nk; ++kt) {
;     if (DIST == 2 && kt + 1 < nk) {
;       if (NLD == 6) asm volatile("s_waitcnt vmcnt(6)" ::: "memory");
;       else if (NLD == 5) asm volatile("s_waitcnt vmcnt(5)" ::: "memory");
;       else asm volatile("s_waitcnt vmcnt(8)" ::: "memory");
;     } else {
;       asm volatile("s_waitcnt vmcnt(0)" ::: "memory");
;     }
;     __builtin_amdgcn_s_barrier();
;     const bool pre = (kt + DIST < nk);
;     const char* base = smem + (kt % NSTG) * STAGE;
;     const char* pa = base + (wrow_act + r) * 128;
;     const char* pw = base + ABYTES + (wrow_w + r) * 128;
;     constexpr int NM = NI * MJ;
;     constexpr int PPS = (NLD + 1) / 2;
; #pragma unroll
;     for (int s = 0; s < 4; ++s) {
;       bf16x8 af[MJ], wf[NI];
; #pragma unroll
;       for (int j = 0; j < MJ; ++j) af[j] = *(const bf16x8*)(pa + j * 32 * 128 + xo[s]);
; #pragma unroll
;       for (int i = 0; i < NI; ++i) wf[i] = *(const bf16x8*)(pw + i * 32 * 128 + xo[s]);
; #pragma unroll
;       for (int m = 0; m < NM; ++m) {
;         const int i = m / MJ, j = m % MJ;
;         acc[i][j] = MFMA(wf[i], af[j], acc[i][j]);
;         if (s < 2 && NM >= PPS) {
;           constexpr int EVERY = (NM / PPS) > 0 ? (NM / PPS) : 1;
;           if ((m + 1) % EVERY == 0) {
;             const int pc = s * PPS + (m + 1) / EVERY - 1;
;             if ((m + 1) / EVERY <= PPS && pc < NLD) {
;               __builtin_amdgcn_sched_barrier(0);
;               if (pre) issue_piece(kt + DIST, pc);
;               __builtin_amdgcn_sched_barrier(0);
;             }
;           }
;         }
;         if (s < 2 && NM < PPS) {
;           const int slot = s * NM + m;
;           __builtin_amdgcn_sched_barrier(0);
; #pragma unroll
;           for (int pc = 0; pc < NLD; ++pc)
;             if ((pc * 2 * NM) / NLD == slot && pre) issue_piece(kt + DIST, pc);
;           __builtin_amdgcn_sched_barrier(0);
;         }
;       }
;     }
	s_waitcnt lgkmcnt(0)
	v_mfma_f32_32x32x16_bf16 v[16:31], v[76:79], v[84:87], v[16:31]
	v_mfma_f32_32x32x16_bf16 v[0:15], v[76:79], v[80:83], v[0:15]
	ds_read_b128 v[76:79], v37 offset:49152
	ds_read_b128 v[80:83], v37 offset:53248
	ds_read_b128 v[84:87], v51
	s_waitcnt lgkmcnt(0)
	v_mfma_f32_32x32x16_bf16 v[16:31], v[84:87], v[76:79], v[16:31]
	v_readfirstlane_b32 s10, v70
	v_lshl_add_u64 v[76:77], v[32:33], 0, s[38:39]
	s_mov_b64 s[8:9], 0x20600
	s_mov_b32 m0, s10
	v_readfirstlane_b32 s7, v71
	v_lshl_add_u64 v[78:79], v[32:33], 0, s[8:9]
	global_load_lds_dwordx4 v[76:77], off
	s_mov_b32 m0, s7
	s_nop 0
	global_load_lds_dwordx4 v[78:79], off
	v_mfma_f32_32x32x16_bf16 v[0:15], v[84:87], v[80:83], v[0:15]
	s_mov_b64 s[8:9], 0x40600
	v_lshl_add_u64 v[70:71], v[32:33], 0, s[8:9]
	v_readfirstlane_b32 s8, v69
	s_mov_b32 m0, s8
	s_nop 0
	global_load_lds_dwordx4 v[70:71], off
	ds_read_b128 v[76:79], v58
	ds_read_b128 v[80:83], v38 offset:49152
	ds_read_b128 v[84:87], v38 offset:53248
	s_waitcnt lgkmcnt(0)
	v_mfma_f32_32x32x16_bf16 v[16:31], v[76:79], v[80:83], v[16:31]
	s_mov_b64 s[12:13], 0x60600
	v_readfirstlane_b32 s9, v68
	v_lshl_add_u64 v[70:71], v[32:33], 0, s[12:13]
	s_mov_b32 m0, s9
	s_nop 0
	global_load_lds_dwordx4 v[70:71], off
	v_mfma_f32_32x32x16_bf16 v[0:15], v[76:79], v[84:87], v[0:15]
	v_readfirstlane_b32 s11, v65
	s_mov_b32 m0, s11
	s_nop 0
	global_load_lds_dwordx4 v[88:89], off
	ds_read_b128 v[68:71], v40 offset:49152
	ds_read_b128 v[76:79], v40 offset:53248
	ds_read_b128 v[80:83], v60
	v_lshl_add_u64 v[84:85], v[34:35], 0, s[68:69]
	s_waitcnt lgkmcnt(0)
	v_mfma_f32_32x32x16_bf16 v[16:31], v[80:83], v[68:71], v[16:31]
	v_mfma_f32_32x32x16_bf16 v[0:15], v[80:83], v[76:79], v[0:15]
	ds_read_b128 v[68:71], v61
	ds_read_b128 v[76:79], v43 offset:53248
	ds_read_b128 v[80:83], v43 offset:49152
	s_waitcnt vmcnt(5)
	s_barrier
	s_waitcnt lgkmcnt(0)
	v_mfma_f32_32x32x16_bf16 v[16:31], v[68:71], v[80:83], v[16:31]
	v_mfma_f32_32x32x16_bf16 v[0:15], v[68:71], v[76:79], v[0:15]
	ds_read_b128 v[68:71], v62
	ds_read_b128 v[76:79], v62 offset:4096
	ds_read_b128 v[80:83], v63
	s_waitcnt lgkmcnt(0)
	v_mfma_f32_32x32x16_bf16 v[16:31], v[80:83], v[68:71], v[16:31]
	s_mov_b64 s[12:13], 0x20680
	v_lshl_add_u64 v[70:71], v[32:33], 0, s[12:13]
	v_readfirstlane_b32 s12, v56
	v_lshl_add_u64 v[68:69], v[32:33], 0, s[68:69]
	s_mov_b32 m0, s12
	v_readfirstlane_b32 s12, v59
	global_load_lds_dwordx4 v[68:69], off
	s_mov_b32 m0, s12
	s_nop 0
	global_load_lds_dwordx4 v[70:71], off
	v_mfma_f32_32x32x16_bf16 v[0:15], v[80:83], v[76:79], v[0:15]
	s_mov_b64 s[12:13], 0x40680
	v_lshl_add_u64 v[68:69], v[32:33], 0, s[12:13]
	v_readfirstlane_b32 s12, v57
	s_mov_b32 m0, s12
	s_nop 0
	global_load_lds_dwordx4 v[68:69], off
	ds_read_b128 v[68:71], v67
	ds_read_b128 v[76:79], v66
	ds_read_b128 v[80:83], v66 offset:4096
	s_waitcnt lgkmcnt(0)
	v_mfma_f32_32x32x16_bf16 v[16:31], v[68:71], v[76:79], v[16:31]
	v_readfirstlane_b32 s12, v50
	v_lshl_add_u64 v[56:57], v[32:33], 0, s[58:59]
	s_mov_b32 m0, s12
	s_nop 0
	global_load_lds_dwordx4 v[56:57], off
	v_mfma_f32_32x32x16_bf16 v[0:15], v[68:71], v[80:83], v[0:15]
	v_readfirstlane_b32 s12, v49
	s_mov_b32 m0, s12
	s_nop 0
	global_load_lds_dwordx4 v[84:85], off
	ds_read_b128 v[68:71], v64
	ds_read_b128 v[76:79], v64 offset:4096
	ds_read_b128 v[80:83], v72
	v_lshl_add_u64 v[56:57], v[34:35], 0, s[60:61]
	s_waitcnt lgkmcnt(0)
	v_mfma_f32_32x32x16_bf16 v[16:31], v[80:83], v[68:71], v[16:31]
	v_mfma_f32_32x32x16_bf16 v[0:15], v[80:83], v[76:79], v[0:15]
	ds_read_b128 v[68:71], v74
	ds_read_b128 v[76:79], v73 offset:4096
	ds_read_b128 v[80:83], v73
	s_waitcnt vmcnt(5)
	s_barrier
	s_waitcnt lgkmcnt(0)
	v_mfma_f32_32x32x16_bf16 v[16:31], v[68:71], v[80:83], v[16:31]
	v_mfma_f32_32x32x16_bf16 v[0:15], v[68:71], v[76:79], v[0:15]
	ds_read_b128 v[68:71], v37
	ds_read_b128 v[76:79], v37 offset:4096
	ds_read_b128 v[80:83], v36 offset:32768
	s_waitcnt lgkmcnt(0)
	v_mfma_f32_32x32x16_bf16 v[16:31], v[80:83], v[68:71], v[16:31]
	v_readfirstlane_b32 s12, v44
	v_lshl_add_u64 v[68:69], v[32:33], 0, s[60:61]
	s_mov_b32 m0, s12
	v_readfirstlane_b32 s12, v45
	v_lshl_add_u64 v[70:71], v[32:33], 0, s[90:91]
	global_load_lds_dwordx4 v[68:69], off
	s_mov_b32 m0, s12
	s_nop 0
	global_load_lds_dwordx4 v[70:71], off
	v_mfma_f32_32x32x16_bf16 v[0:15], v[80:83], v[76:79], v[0:15]
	v_readfirstlane_b32 s12, v46
	v_lshl_add_u64 v[44:45], v[32:33], 0, vcc
	s_mov_b32 m0, s12
	s_nop 0
	global_load_lds_dwordx4 v[44:45], off
	ds_read_b128 v[68:71], v39 offset:32768
	ds_read_b128 v[76:79], v38
	ds_read_b128 v[80:83], v38 offset:4096
	s_waitcnt lgkmcnt(0)
	v_mfma_f32_32x32x16_bf16 v[16:31], v[68:71], v[76:79], v[16:31]
	v_readfirstlane_b32 s12, v47
	v_lshl_add_u64 v[44:45], v[32:33], 0, s[28:29]
	s_mov_b32 m0, s12
	s_nop 0
	global_load_lds_dwordx4 v[44:45], off
	v_mfma_f32_32x32x16_bf16 v[0:15], v[68:71], v[80:83], v[0:15]
	v_readfirstlane_b32 s12, v48
	s_mov_b32 m0, s12
	s_nop 0
	global_load_lds_dwordx4 v[56:57], off
	ds_read_b128 v[44:47], v41 offset:32768
	ds_read_b128 v[68:71], v40
	v_lshl_add_u64 v[34:35], v[34:35], 0, s[46:47]
	s_waitcnt lgkmcnt(0)
	v_mfma_f32_32x32x16_bf16 v[16:31], v[44:47], v[68:71], v[16:31]
	ds_read_b128 v[68:71], v40 offset:4096
	s_waitcnt lgkmcnt(0)
	v_mfma_f32_32x32x16_bf16 v[0:15], v[44:47], v[68:71], v[0:15]
	ds_read_b128 v[44:47], v42 offset:32768
	ds_read_b128 v[68:71], v43
	s_waitcnt lgkmcnt(0)
	v_mfma_f32_32x32x16_bf16 v[16:31], v[44:47], v[68:71], v[16:31]
	ds_read_b128 v[68:71], v43 offset:4096
	s_waitcnt vmcnt(5)
	s_barrier
; #define MFMA(a, b, c) __builtin_amdgcn_mfma_f32_32x32x16_bf16((a), (b), (c), 0, 0, 0)
;     ...
;   for (int kt = 0; kt < nk; ++kt) {
;     if (DIST == 2 && kt + 1 < nk) {
;       if (NLD == 6) asm volatile("s_waitcnt vmcnt(6)" ::: "memory");
;       else if (NLD == 5) asm volatile("s_waitcnt vmcnt(5)" ::: "memory");
;       else asm volatile("s_waitcnt vmcnt(8)" ::: "memory");
;     } else {
;       asm volatile("s_waitcnt vmcnt(0)" ::: "memory");
;     }
;     __builtin_amdgcn_s_barrier();
;     const bool pre = (kt + DIST < nk);
;     const char* base = smem + (kt % NSTG) * STAGE;
;     const char* pa = base + (wrow_act + r) * 128;
;     const char* pw = base + ABYTES + (wrow_w + r) * 128;
;     constexpr int NM = NI * MJ;
;     constexpr int PPS = (NLD + 1) / 2;
; #pragma unroll
;     for (int s = 0; s < 4; ++s) {
;       bf16x8 af[MJ], wf[NI];
; #pragma unroll
;       for (int j = 0; j < MJ; ++j) af[j] = *(const bf16x8*)(pa + j * 32 * 128 + xo[s]);
; #pragma unroll
;       for (int i = 0; i < NI; ++i) wf[i] = *(const bf16x8*)(pw + i * 32 * 128 + xo[s]);
; #pragma unroll
;       for (int m = 0; m < NM; ++m) {
;         const int i = m / MJ, j = m % MJ;
;         acc[i][j] = MFMA(wf[i], af[j], acc[i][j]);
;         if (s < 2 && NM >= PPS) {
;           constexpr int EVERY = (NM / PPS) > 0 ? (NM / PPS) : 1;
;           if ((m + 1) % EVERY == 0) {
;             const int pc = s * PPS + (m + 1) / EVERY - 1;
;             if ((m + 1) / EVERY <= PPS && pc < NLD) {
;               __builtin_amdgcn_sched_barrier(0);
;               if (pre) issue_piece(kt + DIST, pc);
;               __builtin_amdgcn_sched_barrier(0);
;             }
;           }
;         }
;         if (s < 2 && NM < PPS) {
;           const int slot = s * NM + m;
;           __builtin_amdgcn_sched_barrier(0);
; #pragma unroll
;           for (int pc = 0; pc < NLD; ++pc)
;             if ((pc * 2 * NM) / NLD == slot && pre) issue_piece(kt + DIST, pc);
;           __builtin_amdgcn_sched_barrier(0);
;         }
;       }
;     }
;   }
;   __builtin_amdgcn_s_barrier();
	s_waitcnt lgkmcnt(0)
	v_mfma_f32_32x32x16_bf16 v[0:15], v[44:47], v[68:71], v[0:15]
	ds_read_b128 v[44:47], v51
	ds_read_b128 v[48:51], v37 offset:49152
	ds_read_b128 v[68:71], v37 offset:53248
	s_waitcnt lgkmcnt(0)
	v_mfma_f32_32x32x16_bf16 v[16:31], v[44:47], v[48:51], v[16:31]
	s_mov_b32 m0, s10
	v_lshl_add_u64 v[48:49], v[32:33], 0, s[46:47]
	v_lshl_add_u64 v[50:51], v[32:33], 0, s[48:49]
	global_load_lds_dwordx4 v[48:49], off
	s_mov_b32 m0, s7
	s_nop 0
	global_load_lds_dwordx4 v[50:51], off
	v_mfma_f32_32x32x16_bf16 v[0:15], v[44:47], v[68:71], v[0:15]
	v_lshl_add_u64 v[44:45], v[32:33], 0, s[50:51]
	s_mov_b32 m0, s8
	s_nop 0
	global_load_lds_dwordx4 v[44:45], off
	ds_read_b128 v[44:47], v58
	ds_read_b128 v[48:51], v38 offset:49152
	ds_read_b128 v[56:59], v38 offset:53248
	s_waitcnt lgkmcnt(0)
	v_mfma_f32_32x32x16_bf16 v[16:31], v[44:47], v[48:51], v[16:31]
	v_lshl_add_u64 v[32:33], v[32:33], 0, s[86:87]
	s_mov_b32 m0, s9
	s_nop 0
	global_load_lds_dwordx4 v[32:33], off
	v_mfma_f32_32x32x16_bf16 v[0:15], v[44:47], v[56:59], v[0:15]
	s_mov_b32 m0, s11
	s_nop 0
	global_load_lds_dwordx4 v[34:35], off
	ds_read_b128 v[32:35], v60
	ds_read_b128 v[44:47], v40 offset:49152
	s_waitcnt lgkmcnt(0)
	v_mfma_f32_32x32x16_bf16 v[16:31], v[32:35], v[44:47], v[16:31]
	ds_read_b128 v[44:47], v40 offset:53248
	s_waitcnt lgkmcnt(0)
	v_mfma_f32_32x32x16_bf16 v[0:15], v[32:35], v[44:47], v[0:15]
	ds_read_b128 v[32:35], v61
	ds_read_b128 v[44:47], v43 offset:49152
	s_waitcnt lgkmcnt(0)
	v_mfma_f32_32x32x16_bf16 v[16:31], v[32:35], v[44:47], v[16:31]
	ds_read_b128 v[44:47], v43 offset:53248
	s_waitcnt vmcnt(5)
	s_barrier
	s_waitcnt lgkmcnt(0)
	v_mfma_f32_32x32x16_bf16 v[0:15], v[32:35], v[44:47], v[0:15]
	ds_read_b128 v[32:35], v63
	ds_read_b128 v[44:47], v62
	ds_read_b128 v[48:51], v62 offset:4096
	s_waitcnt lgkmcnt(0)
	v_mfma_f32_32x32x16_bf16 v[16:31], v[32:35], v[44:47], v[16:31]
	v_mfma_f32_32x32x16_bf16 v[0:15], v[32:35], v[48:51], v[0:15]
	ds_read_b128 v[32:35], v67
	ds_read_b128 v[44:47], v66
	ds_read_b128 v[48:51], v66 offset:4096
	s_waitcnt lgkmcnt(0)
	v_mfma_f32_32x32x16_bf16 v[16:31], v[32:35], v[44:47], v[16:31]
	v_mfma_f32_32x32x16_bf16 v[0:15], v[32:35], v[48:51], v[0:15]
	ds_read_b128 v[32:35], v72
	ds_read_b128 v[44:47], v64
	s_waitcnt lgkmcnt(0)
	v_mfma_f32_32x32x16_bf16 v[16:31], v[32:35], v[44:47], v[16:31]
	ds_read_b128 v[44:47], v64 offset:4096
	s_waitcnt lgkmcnt(0)
	v_mfma_f32_32x32x16_bf16 v[0:15], v[32:35], v[44:47], v[0:15]
	ds_read_b128 v[32:35], v74
	ds_read_b128 v[44:47], v73
	s_waitcnt lgkmcnt(0)
	v_mfma_f32_32x32x16_bf16 v[16:31], v[32:35], v[44:47], v[16:31]
	ds_read_b128 v[44:47], v73 offset:4096
	s_waitcnt vmcnt(0)
	s_barrier
	s_waitcnt lgkmcnt(0)
	v_mfma_f32_32x32x16_bf16 v[0:15], v[32:35], v[44:47], v[0:15]
	ds_read_b128 v[32:35], v36 offset:32768
	ds_read_b128 v[44:47], v37
	ds_read_b128 v[48:51], v37 offset:4096
	s_waitcnt lgkmcnt(0)
	v_mfma_f32_32x32x16_bf16 v[16:31], v[32:35], v[44:47], v[16:31]
	v_mfma_f32_32x32x16_bf16 v[0:15], v[32:35], v[48:51], v[0:15]
	ds_read_b128 v[32:35], v39 offset:32768
	ds_read_b128 v[44:47], v38
	ds_read_b128 v[36:39], v38 offset:4096
	s_waitcnt lgkmcnt(0)
	v_mfma_f32_32x32x16_bf16 v[16:31], v[32:35], v[44:47], v[16:31]
	v_mfma_f32_32x32x16_bf16 v[0:15], v[32:35], v[36:39], v[0:15]
	ds_read_b128 v[32:35], v40
	ds_read_b128 v[36:39], v40 offset:4096
	ds_read_b128 v[44:47], v41 offset:32768
	s_mulk_i32 s6, 0x2100
	v_lshl_or_b32 v144, s5, 8, v55
	v_lshl_add_u64 v[56:57], s[0:1], 0, v[144:145]
	s_add_i32 s3, s3, s2
	s_waitcnt lgkmcnt(0)
	v_mfma_f32_32x32x16_bf16 v[0:15], v[44:47], v[36:39], v[0:15]
	s_cmp_lt_i32 s3, 32
	v_mfma_f32_32x32x16_bf16 v[16:31], v[44:47], v[32:35], v[16:31]
	ds_read_b128 v[32:35], v42 offset:32768
	ds_read_b128 v[36:39], v43 offset:4096
	ds_read_b128 v[40:43], v43
	s_barrier
; DEV void phase_outproj(const Params& p, int l, int hf, char* smem) {
;     ...
;       const float* gate = mod + 4 * 3072 + 2048;
; #pragma unroll
;       for (int j = 0; j < 2; ++j) {
;         const int m = mt * 256 + wm * 64 + 32 * j + r;
;         const int bl = m / TP, tp = m - bl * TP;
;         float* dst = (float*)(ws + OFF_CTX1) + ((size_t)(hf * 2 + bl) * CTXL + tp) * DM;
; #pragma unroll
;         for (int g4 = 0; g4 < 4; ++g4) {
;           const int n = nt64 * 64 + wn * 32 + 8 * g4 + 4 * h;
;           const float4 xv = *(const float4*)(p.ctx + ((size_t)(hf * 2 + bl) * CTXL + tp) * DM + n);
;           const float4 gv = *(const float4*)(gate + n);
;           float4 o;
;           o.x = xv.x + gv.x * acc[0][j][4 * g4];
;           o.y = xv.y + gv.y * acc[0][j][4 * g4 + 1];
;           o.z = xv.z + gv.z * acc[0][j][4 * g4 + 2];
;           o.w = xv.w + gv.w * acc[0][j][4 * g4 + 3];
;           *(float4*)(dst + n) = o;
;         }
;       }
;     }
	s_waitcnt lgkmcnt(0)
	v_mfma_f32_32x32x16_bf16 v[0:15], v[32:35], v[36:39], v[0:15]
	v_add_u32_e32 v38, s6, v54
	v_mfma_f32_32x32x16_bf16 v[16:31], v[32:35], v[40:43], v[16:31]
	v_mul_hi_i32 v32, v38, s72
	v_lshrrev_b32_e32 v33, 31, v32
	v_ashrrev_i32_e32 v32, 11, v32
	v_add_u32_e32 v33, v32, v33
	v_add_u32_e32 v34, s4, v33
	v_mad_i32_i24 v32, v33, s73, v38
	v_ashrrev_i32_e32 v35, 31, v34
	v_ashrrev_i32_e32 v33, 31, v32
	v_lshlrev_b64 v[34:35], 20, v[34:35]
	v_lshl_add_u64 v[36:37], s[40:41], 0, v[34:35]
	v_lshlrev_b64 v[32:33], 12, v[32:33]
	v_lshl_add_u64 v[34:35], s[44:45], 0, v[34:35]
	v_lshl_add_u64 v[36:37], v[36:37], 0, v[32:33]
	v_lshl_add_u64 v[32:33], v[34:35], 0, v[32:33]
	v_or_b32_e32 v34, 32, v38
	v_mul_hi_i32 v35, v34, s72
	v_lshrrev_b32_e32 v38, 31, v35
	v_ashrrev_i32_e32 v35, 11, v35
	v_add_u32_e32 v35, v35, v38
	v_add_u32_e32 v38, s4, v35
	v_lshl_add_u64 v[50:51], v[32:33], 0, v[144:145]
	v_or_b32_e32 v32, 32, v144
	v_mov_b32_e32 v33, v145
	v_mad_i32_i24 v34, v35, s73, v34
	v_ashrrev_i32_e32 v39, 31, v38
	v_lshl_add_u64 v[40:41], s[0:1], 0, v[32:33]
	v_or_b32_e32 v32, 64, v144
	v_ashrrev_i32_e32 v35, 31, v34
	v_lshlrev_b64 v[38:39], 20, v[38:39]
	v_lshl_add_u64 v[48:49], v[36:37], 0, v[144:145]
	v_lshl_add_u64 v[36:37], s[0:1], 0, v[32:33]
	v_or_b32_e32 v32, 0x60, v144
	v_lshl_add_u64 v[42:43], s[40:41], 0, v[38:39]
	v_lshlrev_b64 v[34:35], 12, v[34:35]
	v_lshl_add_u64 v[38:39], s[44:45], 0, v[38:39]
	v_lshl_add_u64 v[32:33], s[0:1], 0, v[32:33]
	v_lshl_add_u64 v[42:43], v[42:43], 0, v[34:35]
	v_lshl_add_u64 v[34:35], v[38:39], 0, v[34:35]
	v_lshl_add_u64 v[46:47], v[34:35], 0, v[144:145]
	v_lshl_add_u64 v[44:45], v[42:43], 0, v[144:145]
	s_waitcnt vmcnt(0)
	flat_load_dwordx4 v[32:35], v[32:33]
	s_nop 0
	flat_load_dwordx4 v[36:39], v[36:37]
	s_nop 0
	flat_load_dwordx4 v[40:43], v[40:41]
	s_nop 0
	flat_load_dwordx4 v[56:59], v[56:57]
	s_nop 0
	global_load_dwordx4 v[60:63], v[50:51], off
	s_waitcnt vmcnt(0) lgkmcnt(0)
	v_pk_fma_f32 v[16:17], v[16:17], v[56:57], v[60:61]
	v_pk_fma_f32 v[18:19], v[18:19], v[58:59], v[62:63]
	flat_store_dwordx4 v[48:49], v[16:19]
	global_load_dwordx4 v[16:19], v[50:51], off offset:32
	s_waitcnt vmcnt(0)
	v_pk_fma_f32 v[16:17], v[20:21], v[40:41], v[16:17]
	v_pk_fma_f32 v[18:19], v[22:23], v[42:43], v[18:19]
	flat_store_dwordx4 v[48:49], v[16:19] offset:32
	global_load_dwordx4 v[16:19], v[50:51], off offset:64
	s_waitcnt vmcnt(0)
	v_pk_fma_f32 v[16:17], v[24:25], v[36:37], v[16:17]
	v_pk_fma_f32 v[18:19], v[26:27], v[38:39], v[18:19]
	flat_store_dwordx4 v[48:49], v[16:19] offset:64
	global_load_dwordx4 v[16:19], v[50:51], off offset:96
	s_waitcnt vmcnt(0)
	v_pk_fma_f32 v[16:17], v[28:29], v[32:33], v[16:17]
	v_pk_fma_f32 v[18:19], v[30:31], v[34:35], v[18:19]
	flat_store_dwordx4 v[48:49], v[16:19] offset:96
	global_load_dwordx4 v[16:19], v[46:47], off
	s_waitcnt vmcnt(0)
	v_pk_fma_f32 v[0:1], v[0:1], v[56:57], v[16:17]
	v_pk_fma_f32 v[2:3], v[2:3], v[58:59], v[18:19]
	flat_store_dwordx4 v[44:45], v[0:3]
	global_load_dwordx4 v[0:3], v[46:47], off offset:32
	s_waitcnt vmcnt(0)
	v_pk_fma_f32 v[0:1], v[4:5], v[40:41], v[0:1]
	v_pk_fma_f32 v[2:3], v[6:7], v[42:43], v[2:3]
	flat_store_dwordx4 v[44:45], v[0:3] offset:32
	global_load_dwordx4 v[0:3], v[46:47], off offset:64
	s_waitcnt vmcnt(0)
	v_pk_fma_f32 v[0:1], v[8:9], v[36:37], v[0:1]
	v_pk_fma_f32 v[2:3], v[10:11], v[38:39], v[2:3]
	flat_store_dwordx4 v[44:45], v[0:3] offset:64
	global_load_dwordx4 v[0:3], v[46:47], off offset:96
	s_waitcnt vmcnt(0)
	v_pk_fma_f32 v[0:1], v[12:13], v[32:33], v[0:1]
	v_pk_fma_f32 v[2:3], v[14:15], v[34:35], v[2:3]
	flat_store_dwordx4 v[44:45], v[0:3] offset:96
	s_cbranch_scc1 .LBB0_31

; DEV int opaque_tid() { int t = threadIdx.x; asm volatile("" : "+v"(t)); return t; }
;     ...
;   const int tid = opaque_tid(), lane = tid & 63, h = lane >> 5, r = lane & 31;
;   const int nk = K >> 6;
;   const int cch = (tid & 7) ^ ((tid >> 4) & 7);
;   const u16* ga = A + (size_t)(tid >> 3) * lda + cch * 8;
;   const u16* gb = Bt + (size_t)(tid >> 3) * ldb + cch * 8;
;   char* lds_t = smem + tid * 16;
;   auto issue_piece = [&](int kt, int pc) {
;     char* st = lds_t + (kt % NSTG) * STAGE;
;     if (pc < 4)
;       __builtin_amdgcn_global_load_lds((const unsigned*)(ga + (size_t)(64 * pc) * lda + (size_t)kt * ksa), (unsigned __attribute__((address_space(3)))*)(st + pc * 8192), 16, 0, 0);
;     else
;       __builtin_amdgcn_global_load_lds((const unsigned*)(gb + (size_t)(64 * (pc - 4)) * ldb + (size_t)kt * ksb), (unsigned __attribute__((address_space(3)))*)(st + ABYTES + (pc - 4) * 8192), 16, 0, 0);
;   };
;   const int x = (r >> 1) & 7;
;   int xo[4];
; #pragma unroll
;   for (int s = 0; s < 4; ++s) xo[s] = (((2 * s + h) ^ x) << 4);
;   asm volatile("s_waitcnt vmcnt(0)" ::: "memory");
; #pragma unroll
;   for (int d = 0; d < DIST; ++d)
; #pragma unroll
;     for (int pc = 0; pc < NLD; ++pc) issue_piece(d, pc);
;   pre();
; DEV void phase_merge(const Params& p, int l, int hf, char* smem) {
;     ...
;     for (int br = 0; br < 3; ++br) {
;       f32x16 acc[2][2];
; #pragma unroll
;       for (int i = 0; i < 2; ++i)
; #pragma unroll
;         for (int j = 0; j < 2; ++j)
; #pragma unroll
;           for (int e = 0; e < 16; ++e) acc[i][j][e] = 0.f;
;       uint2 gpre[2][2][4];
;       auto load_gates = [&]() {
; #pragma unroll
;         for (int j = 0; j < 2; ++j) {
;           const size_t m = (size_t)mt * 256 + wm * 64 + 32 * j + r;
;           const u16* grow = G + m * 3072 + br * 1024 + nt * 128 + wn * 64;
; #pragma unroll
;           for (int i = 0; i < 2; ++i)
; #pragma unroll
;             for (int g4 = 0; g4 < 4; ++g4) gpre[i][j][g4] = *(const uint2*)(grow + 32 * i + 8 * g4 + 4 * h);
;         }
;       };
;       gemm_main<2, 2, 128, 3>(acc, A + (size_t)mt * 256 * 1536 + br * 512, 1536,
;                               (const u16*)(ws + OFF_WBR) + ((size_t)(l * 3 + br) * 1024 + nt * 128) * 512, 512, 512, smem, wm * 64,
;                               wn * 64, 64, 64, load_gates);
.LBB0_37:
	v_mov_b32_e32 v4, v147
	s_mov_b64 s[30:31], 0x2390080
	v_lshrrev_b32_e32 v5, 4, v4
	v_ashrrev_i32_e32 v0, 3, v4
	v_mad_i64_i32 v[2:3], s[18:19], v0, s92, 0
	v_bitop3_b32 v5, v5, 7, v4 bitop3:0x48
	v_lshlrev_b32_e32 v5, 4, v5
	s_add_u32 s18, s0, s15
	v_or_b32_e32 v2, v2, v5
	s_addc_u32 s19, s1, s14
	v_lshl_add_u32 v200, v4, 4, 0
	v_lshl_add_u64 v[110:111], s[18:19], 0, v[2:3]
	v_readfirstlane_b32 s29, v200
	v_add_u32_e32 v6, 0x2000, v200
	v_lshl_add_u64 v[2:3], v[110:111], 0, s[74:75]
	s_mov_b32 m0, s29
	v_readfirstlane_b32 s28, v6
	global_load_lds_dwordx4 v[2:3], off
	v_lshl_add_u64 v[2:3], v[110:111], 0, s[24:25]
	s_mov_b32 m0, s28
	v_add_u32_e32 v6, 0x4000, v200
	v_ashrrev_i32_e32 v1, 31, v0
	global_load_lds_dwordx4 v[2:3], off
	v_lshl_add_u64 v[2:3], v[110:111], 0, s[26:27]
	v_readfirstlane_b32 s27, v6
	v_add_u32_e32 v6, 0x6000, v200
	v_lshlrev_b64 v[0:1], 10, v[0:1]
	s_add_u32 s18, s0, s16
	s_mov_b32 m0, s27
	v_readfirstlane_b32 s26, v6
	v_or_b32_e32 v0, v0, v5
	s_addc_u32 s19, s1, s17
	v_add_u32_e32 v5, 0x8000, v200
	global_load_lds_dwordx4 v[2:3], off
	v_lshl_add_u64 v[2:3], v[110:111], 0, s[66:67]
	s_mov_b32 m0, s26
	v_lshl_add_u64 v[108:109], s[18:19], 0, v[0:1]
	global_load_lds_dwordx4 v[2:3], off
	v_readfirstlane_b32 s25, v5
	v_add_u32_e32 v2, 0xa000, v200
	v_lshl_add_u64 v[0:1], v[108:109], 0, s[22:23]
	s_mov_b32 m0, s25
	s_mov_b64 s[18:19], 0x2390000
	v_readfirstlane_b32 s24, v2
	v_add_u32_e32 v5, 0xc000, v200
	global_load_lds_dwordx4 v[0:1], off
	v_lshl_add_u64 v[0:1], v[108:109], 0, s[18:19]
	s_mov_b32 m0, s24
	v_readfirstlane_b32 s23, v5
	v_add_u32_e32 v5, 0xe000, v200
	global_load_lds_dwordx4 v[0:1], off
	v_lshl_add_u64 v[2:3], v[110:111], 0, s[70:71]
	s_mov_b32 m0, s23
	v_readfirstlane_b32 s22, v5
	v_add_u32_e32 v5, 0x10000, v200
	global_load_lds_dwordx4 v[2:3], off
	v_lshl_add_u64 v[2:3], v[110:111], 0, s[68:69]
	s_mov_b32 m0, s22
	v_readfirstlane_b32 s21, v5
	v_add_u32_e32 v5, 0x12000, v200
	global_load_lds_dwordx4 v[2:3], off
	v_lshl_add_u64 v[2:3], v[110:111], 0, s[76:77]
	s_mov_b32 m0, s21
	v_readfirstlane_b32 s20, v5
	v_add_u32_e32 v6, 0x14000, v200
	global_load_lds_dwordx4 v[2:3], off
	v_lshl_add_u64 v[2:3], v[110:111], 0, s[72:73]
	s_mov_b32 m0, s20
	v_readfirstlane_b32 s19, v6
	global_load_lds_dwordx4 v[2:3], off
	v_add_u32_e32 v2, 0x16000, v200
	v_lshl_add_u64 v[0:1], v[108:109], 0, s[64:65]
	s_mov_b32 m0, s19
	v_readfirstlane_b32 s18, v2
	global_load_lds_dwordx4 v[0:1], off
	v_lshl_add_u64 v[0:1], v[108:109], 0, s[30:31]
	s_mov_b32 m0, s18
	v_bfe_u32 v2, v4, 1, 3
	global_load_lds_dwordx4 v[0:1], off
	v_lshl_add_u64 v[0:1], s[0:1], 0, v[74:75]
	v_add_co_u32_e32 v0, vcc, s33, v0
	v_add_u32_e32 v18, 0x18000, v200
	s_nop 0
	v_addc_co_u32_e32 v1, vcc, 0, v1, vcc
	flat_load_dwordx2 v[106:107], v[0:1] offset:256
	flat_load_dwordx2 v[104:105], v[0:1] offset:272
	flat_load_dwordx2 v[102:103], v[0:1] offset:288
	flat_load_dwordx2 v[100:101], v[0:1] offset:304
	flat_load_dwordx2 v[98:99], v[0:1] offset:320
	flat_load_dwordx2 v[96:97], v[0:1] offset:336
	flat_load_dwordx2 v[94:95], v[0:1] offset:352
	flat_load_dwordx2 v[92:93], v[0:1] offset:368
	v_lshl_add_u64 v[0:1], s[10:11], 0, v[72:73]
	v_add_co_u32_e32 v0, vcc, s93, v0
	v_lshl_add_u64 v[222:223], v[108:109], 0, s[84:85]
	s_nop 0
	v_addc_co_u32_e32 v1, vcc, 0, v1, vcc
	flat_load_dwordx2 v[90:91], v[0:1] offset:256
	flat_load_dwordx2 v[88:89], v[0:1] offset:272
	flat_load_dwordx2 v[86:87], v[0:1] offset:288
	flat_load_dwordx2 v[84:85], v[0:1] offset:304
	flat_load_dwordx2 v[82:83], v[0:1] offset:320
	flat_load_dwordx2 v[80:81], v[0:1] offset:336
	flat_load_dwordx2 v[78:79], v[0:1] offset:352
	flat_load_dwordx2 v[76:77], v[0:1] offset:368
	v_lshrrev_b32_e32 v0, 5, v4
	v_bfe_u32 v1, v4, 5, 1
	v_bitop3_b32 v0, v0, v2, 1 bitop3:0x6c
	v_lshlrev_b32_e32 v232, 4, v0
	v_bitop3_b32 v0, v1, v2, 2 bitop3:0x36
	v_lshlrev_b32_e32 v233, 4, v0
	v_bitop3_b32 v0, v1, v2, 4 bitop3:0x36
	v_lshlrev_b32_e32 v234, 4, v0
	v_bitop3_b32 v0, v1, v2, 6 bitop3:0x36
	v_lshlrev_b32_e32 v235, 4, v0
	v_and_b32_e32 v0, 31, v4
	v_or_b32_e32 v1, v0, v116
	v_or_b32_e32 v0, v0, v117
	v_lshlrev_b32_e32 v237, 7, v0
	v_add_u32_e32 v205, 0, v237
	v_add_u32_e32 v203, v205, v232
	v_lshlrev_b32_e32 v236, 7, v1
	s_waitcnt vmcnt(6)
	s_barrier
; #define MFMA(a, b, c) __builtin_amdgcn_mfma_f32_32x32x16_bf16((a), (b), (c), 0, 0, 0)
;     ...
;   for (int kt = 0; kt < nk; ++kt) {
;     if (DIST == 2 && kt + 1 < nk) {
;       if (NLD == 6) asm volatile("s_waitcnt vmcnt(6)" ::: "memory");
;       else if (NLD == 5) asm volatile("s_waitcnt vmcnt(5)" ::: "memory");
;       else asm volatile("s_waitcnt vmcnt(8)" ::: "memory");
;     } else {
;       asm volatile("s_waitcnt vmcnt(0)" ::: "memory");
;     }
;     __builtin_amdgcn_s_barrier();
;     const bool pre = (kt + DIST < nk);
;     const char* base = smem + (kt % NSTG) * STAGE;
;     const char* pa = base + (wrow_act + r) * 128;
;     const char* pw = base + ABYTES + (wrow_w + r) * 128;
;     constexpr int NM = NI * MJ;
;     constexpr int PPS = (NLD + 1) / 2;
; #pragma unroll
;     for (int s = 0; s < 4; ++s) {
;       bf16x8 af[MJ], wf[NI];
; #pragma unroll
;       for (int j = 0; j < MJ; ++j) af[j] = *(const bf16x8*)(pa + j * 32 * 128 + xo[s]);
; #pragma unroll
;       for (int i = 0; i < NI; ++i) wf[i] = *(const bf16x8*)(pw + i * 32 * 128 + xo[s]);
; #pragma unroll
;       for (int m = 0; m < NM; ++m) {
;         const int i = m / MJ, j = m % MJ;
;         acc[i][j] = MFMA(wf[i], af[j], acc[i][j]);
;         if (s < 2 && NM >= PPS) {
;           constexpr int EVERY = (NM / PPS) > 0 ? (NM / PPS) : 1;
;           if ((m + 1) % EVERY == 0) {
;             const int pc = s * PPS + (m + 1) / EVERY - 1;
;             if ((m + 1) / EVERY <= PPS && pc < NLD) {
;               __builtin_amdgcn_sched_barrier(0);
;               if (pre) issue_piece(kt + DIST, pc);
;               __builtin_amdgcn_sched_barrier(0);
;             }
;           }
;         }
;         if (s < 2 && NM < PPS) {
;           const int slot = s * NM + m;
;           __builtin_amdgcn_sched_barrier(0);
; #pragma unroll
;           for (int pc = 0; pc < NLD; ++pc)
;             if ((pc * 2 * NM) / NLD == slot && pre) issue_piece(kt + DIST, pc);
;           __builtin_amdgcn_sched_barrier(0);
;         }
;       }
;     }
	ds_read_b128 v[0:3], v203 offset:32768
	v_add_u32_e32 v226, 0, v236
	v_add_u32_e32 v199, v226, v232
	ds_read_b128 v[4:7], v199
	ds_read_b128 v[8:11], v199 offset:4096
	ds_read_b128 v[12:15], v203 offset:36864
	v_add_u32_e32 v202, 0x20000, v200
	s_waitcnt lgkmcnt(0)
	v_mfma_f32_32x32x16_bf16 v[48:63], v[0:3], v[4:7], 0
	v_readfirstlane_b32 s30, v18
	v_lshl_add_u64 v[16:17], v[110:111], 0, s[78:79]
	s_mov_b32 m0, s30
	s_nop 0
	global_load_lds_dwordx4 v[16:17], off
	v_mfma_f32_32x32x16_bf16 v[16:31], v[0:3], v[8:11], 0
	v_add_u32_e32 v2, 0x1a000, v200
	v_lshl_add_u64 v[0:1], v[110:111], 0, s[88:89]
	v_readfirstlane_b32 s31, v2
	s_mov_b32 m0, s31
	s_nop 0
	global_load_lds_dwordx4 v[0:1], off
	v_mfma_f32_32x32x16_bf16 v[32:47], v[12:15], v[4:7], 0
	v_add_u32_e32 v2, 0x1c000, v200
	v_lshl_add_u64 v[0:1], v[110:111], 0, s[86:87]
	v_readfirstlane_b32 s36, v2
	s_mov_b32 m0, s36
	s_nop 0
	global_load_lds_dwordx4 v[0:1], off
	v_add_u32_e32 v204, v205, v233
	ds_read_b128 v[206:209], v204 offset:32768
	v_add_u32_e32 v201, v226, v233
	ds_read_b128 v[210:213], v201
	ds_read_b128 v[214:217], v201 offset:4096
	ds_read_b128 v[218:221], v204 offset:36864
	v_mfma_f32_32x32x16_bf16 v[0:15], v[12:15], v[8:11], 0
	s_waitcnt lgkmcnt(0)
	v_mfma_f32_32x32x16_bf16 v[48:63], v[206:209], v[210:213], v[48:63]
	v_add_u32_e32 v227, 0x1e000, v200
	v_lshl_add_u64 v[224:225], v[110:111], 0, s[96:97]
	v_readfirstlane_b32 s37, v227
	s_mov_b32 m0, s37
	s_nop 0
	global_load_lds_dwordx4 v[224:225], off
	v_mfma_f32_32x32x16_bf16 v[16:31], v[206:209], v[214:217], v[16:31]
	v_readfirstlane_b32 s38, v202
	s_mov_b32 m0, s38
	s_nop 0
	global_load_lds_dwordx4 v[222:223], off
	v_mfma_f32_32x32x16_bf16 v[32:47], v[218:221], v[210:213], v[32:47]
	v_add_u32_e32 v200, 0x22000, v200
	s_mov_b64 s[40:41], 0x2390100
	v_readfirstlane_b32 s39, v200
	v_lshl_add_u64 v[206:207], v[108:109], 0, s[40:41]
	s_mov_b32 m0, s39
	s_nop 0
	global_load_lds_dwordx4 v[206:207], off
	v_add_u32_e32 v206, v205, v234
	ds_read_b128 v[208:211], v206 offset:32768
	v_add_u32_e32 v202, v226, v234
	v_mfma_f32_32x32x16_bf16 v[0:15], v[218:221], v[214:217], v[0:15]
	ds_read_b128 v[212:215], v202
	ds_read_b128 v[216:219], v202 offset:4096
	ds_read_b128 v[220:223], v206 offset:36864
	v_add_u32_e32 v205, v205, v235
	v_add_u32_e32 v200, v226, v235
	s_add_i32 s40, 0, 0x14000
	v_add_u32_e32 v207, s40, v237
	v_lshl_add_u64 v[228:229], v[108:109], 0, s[90:91]
	s_waitcnt lgkmcnt(0)
	v_mfma_f32_32x32x16_bf16 v[48:63], v[208:211], v[212:215], v[48:63]
	v_mfma_f32_32x32x16_bf16 v[16:31], v[208:211], v[216:219], v[16:31]
	ds_read_b128 v[208:211], v205 offset:32768
	v_mfma_f32_32x32x16_bf16 v[32:47], v[220:223], v[212:215], v[32:47]
	v_mfma_f32_32x32x16_bf16 v[0:15], v[220:223], v[216:219], v[0:15]
	ds_read_b128 v[212:215], v200
	ds_read_b128 v[216:219], v200 offset:4096
	ds_read_b128 v[220:223], v205 offset:36864
	s_waitcnt vmcnt(6)
	s_barrier
	s_waitcnt lgkmcnt(0)
	v_mfma_f32_32x32x16_bf16 v[48:63], v[208:211], v[212:215], v[48:63]
	v_mfma_f32_32x32x16_bf16 v[16:31], v[208:211], v[216:219], v[16:31]
	v_add_u32_e32 v208, v207, v232
	v_mfma_f32_32x32x16_bf16 v[32:47], v[220:223], v[212:215], v[32:47]
	v_mfma_f32_32x32x16_bf16 v[0:15], v[220:223], v[216:219], v[0:15]
	ds_read_b128 v[210:213], v208
	ds_read_b128 v[214:217], v199 offset:49152
	ds_read_b128 v[218:221], v199 offset:53248
	ds_read_b128 v[222:225], v208 offset:4096
	s_waitcnt lgkmcnt(0)
	v_mfma_f32_32x32x16_bf16 v[48:63], v[210:213], v[214:217], v[48:63]
	v_lshl_add_u64 v[226:227], v[110:111], 0, s[2:3]
	s_mov_b32 m0, s29
	s_nop 0
	global_load_lds_dwordx4 v[226:227], off
	v_mfma_f32_32x32x16_bf16 v[16:31], v[210:213], v[218:221], v[16:31]
	s_mov_b64 s[40:41], 0x1c506280
	v_lshl_add_u64 v[210:211], v[110:111], 0, s[40:41]
	s_mov_b32 m0, s28
	s_nop 0
	global_load_lds_dwordx4 v[210:211], off
	v_mfma_f32_32x32x16_bf16 v[32:47], v[222:225], v[214:217], v[32:47]
	v_lshl_add_u64 v[210:211], v[110:111], 0, s[8:9]
	s_mov_b32 m0, s27
	s_nop 0
	global_load_lds_dwordx4 v[210:211], off
	v_add_u32_e32 v210, v207, v233
	v_mfma_f32_32x32x16_bf16 v[0:15], v[222:225], v[218:221], v[0:15]
	ds_read_b128 v[212:215], v210
	ds_read_b128 v[216:219], v201 offset:49152
	ds_read_b128 v[220:223], v201 offset:53248
	ds_read_b128 v[224:227], v210 offset:4096
	s_waitcnt lgkmcnt(0)
	v_mfma_f32_32x32x16_bf16 v[48:63], v[212:215], v[216:219], v[48:63]
	s_mov_b64 s[40:41], 0x1c566280
	v_lshl_add_u64 v[230:231], v[110:111], 0, s[40:41]
	s_mov_b32 m0, s26
	s_nop 0
	global_load_lds_dwordx4 v[230:231], off
	v_mfma_f32_32x32x16_bf16 v[16:31], v[212:215], v[220:223], v[16:31]
	s_mov_b32 m0, s25
	s_nop 0
	global_load_lds_dwordx4 v[228:229], off
	v_mfma_f32_32x32x16_bf16 v[32:47], v[224:227], v[216:219], v[32:47]
	s_mov_b64 s[40:41], 0x2390180
	v_lshl_add_u64 v[212:213], v[108:109], 0, s[40:41]
	s_mov_b32 m0, s24
	s_nop 0
	global_load_lds_dwordx4 v[212:213], off
	v_add_u32_e32 v209, v207, v234
	v_mfma_f32_32x32x16_bf16 v[0:15], v[224:227], v[220:223], v[0:15]
	ds_read_b128 v[212:215], v209
	ds_read_b128 v[216:219], v202 offset:49152
	ds_read_b128 v[220:223], v202 offset:53248
	ds_read_b128 v[224:227], v209 offset:4096
	v_add_u32_e32 v207, v207, v235
	s_add_i32 s40, 0, 0x20000
	v_add_u32_e32 v211, s40, v237
	v_add_u32_e32 v237, v211, v232
	s_add_i32 s40, 0, 0x18000
	v_add_u32_e32 v236, s40, v236
	s_waitcnt lgkmcnt(0)
	v_mfma_f32_32x32x16_bf16 v[48:63], v[212:215], v[216:219], v[48:63]
	v_add_u32_e32 v232, v236, v232
	v_lshl_add_u64 v[228:229], v[108:109], 0, s[42:43]
	v_mfma_f32_32x32x16_bf16 v[16:31], v[212:215], v[220:223], v[16:31]
	v_mfma_f32_32x32x16_bf16 v[32:47], v[224:227], v[216:219], v[32:47]
	v_mfma_f32_32x32x16_bf16 v[0:15], v[224:227], v[220:223], v[0:15]
	ds_read_b128 v[212:215], v207
	ds_read_b128 v[216:219], v200 offset:49152
	ds_read_b128 v[220:223], v200 offset:53248
	ds_read_b128 v[224:227], v207 offset:4096
	s_waitcnt vmcnt(6)
	s_barrier
; #define MFMA(a, b, c) __builtin_amdgcn_mfma_f32_32x32x16_bf16((a), (b), (c), 0, 0, 0)
;     ...
;   for (int kt = 0; kt < nk; ++kt) {
;     if (DIST == 2 && kt + 1 < nk) {
;       if (NLD == 6) asm volatile("s_waitcnt vmcnt(6)" ::: "memory");
;       else if (NLD == 5) asm volatile("s_waitcnt vmcnt(5)" ::: "memory");
;       else asm volatile("s_waitcnt vmcnt(8)" ::: "memory");
;     } else {
;       asm volatile("s_waitcnt vmcnt(0)" ::: "memory");
;     }
;     __builtin_amdgcn_s_barrier();
;     const bool pre = (kt + DIST < nk);
;     const char* base = smem + (kt % NSTG) * STAGE;
;     const char* pa = base + (wrow_act + r) * 128;
;     const char* pw = base + ABYTES + (wrow_w + r) * 128;
;     constexpr int NM = NI * MJ;
;     constexpr int PPS = (NLD + 1) / 2;
; #pragma unroll
;     for (int s = 0; s < 4; ++s) {
;       bf16x8 af[MJ], wf[NI];
; #pragma unroll
;       for (int j = 0; j < MJ; ++j) af[j] = *(const bf16x8*)(pa + j * 32 * 128 + xo[s]);
; #pragma unroll
;       for (int i = 0; i < NI; ++i) wf[i] = *(const bf16x8*)(pw + i * 32 * 128 + xo[s]);
; #pragma unroll
;       for (int m = 0; m < NM; ++m) {
;         const int i = m / MJ, j = m % MJ;
;         acc[i][j] = MFMA(wf[i], af[j], acc[i][j]);
;         if (s < 2 && NM >= PPS) {
;           constexpr int EVERY = (NM / PPS) > 0 ? (NM / PPS) : 1;
;           if ((m + 1) % EVERY == 0) {
;             const int pc = s * PPS + (m + 1) / EVERY - 1;
;             if ((m + 1) / EVERY <= PPS && pc < NLD) {
;               __builtin_amdgcn_sched_barrier(0);
;               if (pre) issue_piece(kt + DIST, pc);
;               __builtin_amdgcn_sched_barrier(0);
;             }
;           }
;         }
;         if (s < 2 && NM < PPS) {
;           const int slot = s * NM + m;
;           __builtin_amdgcn_sched_barrier(0);
; #pragma unroll
;           for (int pc = 0; pc < NLD; ++pc)
;             if ((pc * 2 * NM) / NLD == slot && pre) issue_piece(kt + DIST, pc);
;           __builtin_amdgcn_sched_barrier(0);
;         }
;       }
;     }
	s_waitcnt lgkmcnt(0)
	v_mfma_f32_32x32x16_bf16 v[48:63], v[212:215], v[216:219], v[48:63]
	v_mfma_f32_32x32x16_bf16 v[16:31], v[212:215], v[220:223], v[16:31]
	ds_read_b128 v[212:215], v237
	v_mfma_f32_32x32x16_bf16 v[32:47], v[224:227], v[216:219], v[32:47]
	ds_read_b128 v[216:219], v232
	v_mfma_f32_32x32x16_bf16 v[0:15], v[224:227], v[220:223], v[0:15]
	ds_read_b128 v[220:223], v232 offset:4096
	ds_read_b128 v[224:227], v237 offset:4096
	s_waitcnt lgkmcnt(0)
	v_mfma_f32_32x32x16_bf16 v[48:63], v[212:215], v[216:219], v[48:63]
	s_mov_b64 s[40:41], 0x1c4d6300
	v_lshl_add_u64 v[230:231], v[110:111], 0, s[40:41]
	s_mov_b32 m0, s23
	s_nop 0
	global_load_lds_dwordx4 v[230:231], off
	v_mfma_f32_32x32x16_bf16 v[16:31], v[212:215], v[220:223], v[16:31]
	s_mov_b64 s[40:41], 0x1c506300
	v_lshl_add_u64 v[212:213], v[110:111], 0, s[40:41]
	s_mov_b32 m0, s22
	s_nop 0
	global_load_lds_dwordx4 v[212:213], off
	v_mfma_f32_32x32x16_bf16 v[32:47], v[224:227], v[216:219], v[32:47]
	s_mov_b64 s[40:41], 0x1c536300
	v_lshl_add_u64 v[212:213], v[110:111], 0, s[40:41]
	s_mov_b32 m0, s21
	s_nop 0
	global_load_lds_dwordx4 v[212:213], off
	v_add_u32_e32 v238, v211, v233
	ds_read_b128 v[212:215], v238
	v_add_u32_e32 v233, v236, v233
	v_mfma_f32_32x32x16_bf16 v[0:15], v[224:227], v[220:223], v[0:15]
	ds_read_b128 v[216:219], v233
	ds_read_b128 v[220:223], v233 offset:4096
	ds_read_b128 v[224:227], v238 offset:4096
	s_waitcnt lgkmcnt(0)
	v_mfma_f32_32x32x16_bf16 v[48:63], v[212:215], v[216:219], v[48:63]
	v_lshl_add_u64 v[230:231], v[110:111], 0, s[80:81]
	s_mov_b32 m0, s20
	s_nop 0
	global_load_lds_dwordx4 v[230:231], off
	v_mfma_f32_32x32x16_bf16 v[16:31], v[212:215], v[220:223], v[16:31]
	s_mov_b32 m0, s19
	s_nop 0
	global_load_lds_dwordx4 v[228:229], off
	v_mfma_f32_32x32x16_bf16 v[32:47], v[224:227], v[216:219], v[32:47]
	s_mov_b64 s[40:41], 0x2390200
	v_lshl_add_u64 v[212:213], v[108:109], 0, s[40:41]
	s_mov_b32 m0, s18
	s_nop 0
	global_load_lds_dwordx4 v[212:213], off
	v_add_u32_e32 v239, v211, v234
	ds_read_b128 v[212:215], v239
	v_add_u32_e32 v234, v236, v234
	v_mfma_f32_32x32x16_bf16 v[0:15], v[224:227], v[220:223], v[0:15]
	ds_read_b128 v[216:219], v234
	ds_read_b128 v[220:223], v234 offset:4096
	ds_read_b128 v[224:227], v239 offset:4096
	v_add_u32_e32 v211, v211, v235
	v_add_u32_e32 v235, v236, v235
	v_lshl_add_u64 v[228:229], v[108:109], 0, s[34:35]
	s_waitcnt lgkmcnt(0)
	v_mfma_f32_32x32x16_bf16 v[48:63], v[212:215], v[216:219], v[48:63]
	v_mfma_f32_32x32x16_bf16 v[16:31], v[212:215], v[220:223], v[16:31]
	ds_read_b128 v[212:215], v211
	v_mfma_f32_32x32x16_bf16 v[32:47], v[224:227], v[216:219], v[32:47]
	v_mfma_f32_32x32x16_bf16 v[0:15], v[224:227], v[220:223], v[0:15]
	ds_read_b128 v[216:219], v235
	ds_read_b128 v[220:223], v235 offset:4096
	ds_read_b128 v[224:227], v211 offset:4096
	s_waitcnt vmcnt(6)
	s_barrier
	s_waitcnt lgkmcnt(0)
	v_mfma_f32_32x32x16_bf16 v[48:63], v[212:215], v[216:219], v[48:63]
	v_mfma_f32_32x32x16_bf16 v[16:31], v[212:215], v[220:223], v[16:31]
	v_mfma_f32_32x32x16_bf16 v[32:47], v[224:227], v[216:219], v[32:47]
	ds_read_b128 v[212:215], v203 offset:32768
	ds_read_b128 v[216:219], v199
	v_mfma_f32_32x32x16_bf16 v[0:15], v[224:227], v[220:223], v[0:15]
	ds_read_b128 v[220:223], v199 offset:4096
	ds_read_b128 v[224:227], v203 offset:36864
	s_waitcnt lgkmcnt(0)
	v_mfma_f32_32x32x16_bf16 v[48:63], v[212:215], v[216:219], v[48:63]
	v_lshl_add_u64 v[230:231], v[110:111], 0, s[4:5]
	s_mov_b32 m0, s30
	s_nop 0
	global_load_lds_dwordx4 v[230:231], off
	v_mfma_f32_32x32x16_bf16 v[16:31], v[212:215], v[220:223], v[16:31]
	v_lshl_add_u64 v[212:213], v[110:111], 0, s[94:95]
	s_mov_b32 m0, s31
	s_nop 0
	global_load_lds_dwordx4 v[212:213], off
	v_mfma_f32_32x32x16_bf16 v[32:47], v[224:227], v[216:219], v[32:47]
	v_lshl_add_u64 v[212:213], v[110:111], 0, s[82:83]
	s_mov_b32 m0, s36
	s_nop 0
	global_load_lds_dwordx4 v[212:213], off
	v_mfma_f32_32x32x16_bf16 v[0:15], v[224:227], v[220:223], v[0:15]
	ds_read_b128 v[212:215], v204 offset:32768
	ds_read_b128 v[216:219], v201
	ds_read_b128 v[220:223], v201 offset:4096
	ds_read_b128 v[224:227], v204 offset:36864
	s_waitcnt lgkmcnt(0)
	v_mfma_f32_32x32x16_bf16 v[48:63], v[212:215], v[216:219], v[48:63]
	v_lshl_add_u64 v[230:231], v[110:111], 0, s[6:7]
	s_mov_b32 m0, s37
	s_nop 0
	global_load_lds_dwordx4 v[230:231], off
	v_mfma_f32_32x32x16_bf16 v[16:31], v[212:215], v[220:223], v[16:31]
	s_mov_b32 m0, s38
	s_nop 0
	global_load_lds_dwordx4 v[228:229], off
	v_mfma_f32_32x32x16_bf16 v[32:47], v[224:227], v[216:219], v[32:47]
	s_mov_b64 s[30:31], 0x2390280
	v_lshl_add_u64 v[212:213], v[108:109], 0, s[30:31]
	s_mov_b32 m0, s39
	s_nop 0
	global_load_lds_dwordx4 v[212:213], off
	v_mfma_f32_32x32x16_bf16 v[0:15], v[224:227], v[220:223], v[0:15]
	ds_read_b128 v[212:215], v206 offset:32768
	ds_read_b128 v[216:219], v202
	ds_read_b128 v[220:223], v202 offset:4096
	ds_read_b128 v[224:227], v206 offset:36864
	s_mov_b64 s[30:31], 0x2380300
	v_lshl_add_u64 v[228:229], v[108:109], 0, s[30:31]
	s_waitcnt lgkmcnt(0)
	v_mfma_f32_32x32x16_bf16 v[48:63], v[212:215], v[216:219], v[48:63]
	v_mfma_f32_32x32x16_bf16 v[16:31], v[212:215], v[220:223], v[16:31]
	v_mfma_f32_32x32x16_bf16 v[32:47], v[224:227], v[216:219], v[32:47]
	v_mfma_f32_32x32x16_bf16 v[0:15], v[224:227], v[220:223], v[0:15]
	ds_read_b128 v[212:215], v205 offset:32768
	ds_read_b128 v[216:219], v200
	ds_read_b128 v[220:223], v200 offset:4096
	ds_read_b128 v[224:227], v205 offset:36864
	s_waitcnt vmcnt(6)
	s_barrier
; #define MFMA(a, b, c) __builtin_amdgcn_mfma_f32_32x32x16_bf16((a), (b), (c), 0, 0, 0)
;     ...
;   for (int kt = 0; kt < nk; ++kt) {
;     if (DIST == 2 && kt + 1 < nk) {
;       if (NLD == 6) asm volatile("s_waitcnt vmcnt(6)" ::: "memory");
;       else if (NLD == 5) asm volatile("s_waitcnt vmcnt(5)" ::: "memory");
;       else asm volatile("s_waitcnt vmcnt(8)" ::: "memory");
;     } else {
;       asm volatile("s_waitcnt vmcnt(0)" ::: "memory");
;     }
;     __builtin_amdgcn_s_barrier();
;     const bool pre = (kt + DIST < nk);
;     const char* base = smem + (kt % NSTG) * STAGE;
;     const char* pa = base + (wrow_act + r) * 128;
;     const char* pw = base + ABYTES + (wrow_w + r) * 128;
;     constexpr int NM = NI * MJ;
;     constexpr int PPS = (NLD + 1) / 2;
; #pragma unroll
;     for (int s = 0; s < 4; ++s) {
;       bf16x8 af[MJ], wf[NI];
; #pragma unroll
;       for (int j = 0; j < MJ; ++j) af[j] = *(const bf16x8*)(pa + j * 32 * 128 + xo[s]);
; #pragma unroll
;       for (int i = 0; i < NI; ++i) wf[i] = *(const bf16x8*)(pw + i * 32 * 128 + xo[s]);
; #pragma unroll
;       for (int m = 0; m < NM; ++m) {
;         const int i = m / MJ, j = m % MJ;
;         acc[i][j] = MFMA(wf[i], af[j], acc[i][j]);
;         if (s < 2 && NM >= PPS) {
;           constexpr int EVERY = (NM / PPS) > 0 ? (NM / PPS) : 1;
;           if ((m + 1) % EVERY == 0) {
;             const int pc = s * PPS + (m + 1) / EVERY - 1;
;             if ((m + 1) / EVERY <= PPS && pc < NLD) {
;               __builtin_amdgcn_sched_barrier(0);
;               if (pre) issue_piece(kt + DIST, pc);
;               __builtin_amdgcn_sched_barrier(0);
;             }
;           }
;         }
;         if (s < 2 && NM < PPS) {
;           const int slot = s * NM + m;
;           __builtin_amdgcn_sched_barrier(0);
; #pragma unroll
;           for (int pc = 0; pc < NLD; ++pc)
;             if ((pc * 2 * NM) / NLD == slot && pre) issue_piece(kt + DIST, pc);
;           __builtin_amdgcn_sched_barrier(0);
;         }
;       }
;     }
	s_waitcnt lgkmcnt(0)
	v_mfma_f32_32x32x16_bf16 v[48:63], v[212:215], v[216:219], v[48:63]
	v_mfma_f32_32x32x16_bf16 v[16:31], v[212:215], v[220:223], v[16:31]
	v_mfma_f32_32x32x16_bf16 v[32:47], v[224:227], v[216:219], v[32:47]
	ds_read_b128 v[212:215], v208
	ds_read_b128 v[216:219], v199 offset:49152
	v_mfma_f32_32x32x16_bf16 v[0:15], v[224:227], v[220:223], v[0:15]
	ds_read_b128 v[220:223], v199 offset:53248
	ds_read_b128 v[224:227], v208 offset:4096
	s_waitcnt lgkmcnt(0)
	v_mfma_f32_32x32x16_bf16 v[48:63], v[212:215], v[216:219], v[48:63]
	v_lshl_add_u64 v[230:231], v[110:111], 0, s[44:45]
	s_mov_b32 m0, s29
	s_nop 0
	global_load_lds_dwordx4 v[230:231], off
	v_mfma_f32_32x32x16_bf16 v[16:31], v[212:215], v[220:223], v[16:31]
	v_lshl_add_u64 v[212:213], v[110:111], 0, s[46:47]
	s_mov_b32 m0, s28
	s_nop 0
	global_load_lds_dwordx4 v[212:213], off
	v_mfma_f32_32x32x16_bf16 v[32:47], v[224:227], v[216:219], v[32:47]
	v_lshl_add_u64 v[212:213], v[110:111], 0, s[50:51]
	s_mov_b32 m0, s27
	s_nop 0
	global_load_lds_dwordx4 v[212:213], off
	v_mfma_f32_32x32x16_bf16 v[0:15], v[224:227], v[220:223], v[0:15]
	ds_read_b128 v[212:215], v210
	ds_read_b128 v[216:219], v201 offset:49152
	ds_read_b128 v[220:223], v201 offset:53248
	ds_read_b128 v[224:227], v210 offset:4096
	s_waitcnt lgkmcnt(0)
	v_mfma_f32_32x32x16_bf16 v[48:63], v[212:215], v[216:219], v[48:63]
	v_lshl_add_u64 v[230:231], v[110:111], 0, s[48:49]
	s_mov_b32 m0, s26
	s_nop 0
	global_load_lds_dwordx4 v[230:231], off
	v_mfma_f32_32x32x16_bf16 v[16:31], v[212:215], v[220:223], v[16:31]
	s_mov_b32 m0, s25
	s_nop 0
	global_load_lds_dwordx4 v[228:229], off
	v_mfma_f32_32x32x16_bf16 v[32:47], v[224:227], v[216:219], v[32:47]
	s_mov_b64 s[26:27], 0x2390300
	v_lshl_add_u64 v[212:213], v[108:109], 0, s[26:27]
	s_mov_b32 m0, s24
	s_mov_b64 s[26:27], 0x1c536100
	global_load_lds_dwordx4 v[212:213], off
	s_mov_b64 s[24:25], 0x1c506100
	v_mfma_f32_32x32x16_bf16 v[0:15], v[224:227], v[220:223], v[0:15]
	ds_read_b128 v[212:215], v209
	ds_read_b128 v[216:219], v202 offset:49152
	ds_read_b128 v[220:223], v202 offset:53248
	ds_read_b128 v[224:227], v209 offset:4096
	v_lshl_add_u64 v[228:229], v[108:109], 0, s[54:55]
	s_waitcnt lgkmcnt(0)
	v_mfma_f32_32x32x16_bf16 v[48:63], v[212:215], v[216:219], v[48:63]
	v_mfma_f32_32x32x16_bf16 v[16:31], v[212:215], v[220:223], v[16:31]
	v_mfma_f32_32x32x16_bf16 v[32:47], v[224:227], v[216:219], v[32:47]
	v_mfma_f32_32x32x16_bf16 v[0:15], v[224:227], v[220:223], v[0:15]
	ds_read_b128 v[212:215], v207
	ds_read_b128 v[216:219], v200 offset:49152
	ds_read_b128 v[220:223], v200 offset:53248
	ds_read_b128 v[224:227], v207 offset:4096
	s_waitcnt vmcnt(6)
	s_barrier
	s_waitcnt lgkmcnt(0)
	v_mfma_f32_32x32x16_bf16 v[48:63], v[212:215], v[216:219], v[48:63]
	v_mfma_f32_32x32x16_bf16 v[16:31], v[212:215], v[220:223], v[16:31]
	v_mfma_f32_32x32x16_bf16 v[32:47], v[224:227], v[216:219], v[32:47]
	ds_read_b128 v[212:215], v237
	ds_read_b128 v[216:219], v232
	v_mfma_f32_32x32x16_bf16 v[0:15], v[224:227], v[220:223], v[0:15]
	ds_read_b128 v[220:223], v232 offset:4096
	ds_read_b128 v[224:227], v237 offset:4096
	s_waitcnt lgkmcnt(0)
	v_mfma_f32_32x32x16_bf16 v[48:63], v[212:215], v[216:219], v[48:63]
	v_lshl_add_u64 v[230:231], v[110:111], 0, s[52:53]
	s_mov_b32 m0, s23
	s_nop 0
	global_load_lds_dwordx4 v[230:231], off
	v_mfma_f32_32x32x16_bf16 v[16:31], v[212:215], v[220:223], v[16:31]
	v_lshl_add_u64 v[212:213], v[110:111], 0, s[58:59]
	s_mov_b32 m0, s22
	s_mov_b64 s[22:23], 0x2380000
	global_load_lds_dwordx4 v[212:213], off
	v_mfma_f32_32x32x16_bf16 v[32:47], v[224:227], v[216:219], v[32:47]
	v_lshl_add_u64 v[212:213], v[110:111], 0, s[56:57]
	s_mov_b32 m0, s21
	s_nop 0
	global_load_lds_dwordx4 v[212:213], off
	v_mfma_f32_32x32x16_bf16 v[0:15], v[224:227], v[220:223], v[0:15]
	ds_read_b128 v[212:215], v238
	ds_read_b128 v[216:219], v233
	ds_read_b128 v[220:223], v233 offset:4096
	ds_read_b128 v[224:227], v238 offset:4096
	s_waitcnt lgkmcnt(0)
	v_mfma_f32_32x32x16_bf16 v[48:63], v[212:215], v[216:219], v[48:63]
	v_lshl_add_u64 v[110:111], v[110:111], 0, s[62:63]
	s_mov_b32 m0, s20
	s_nop 0
	global_load_lds_dwordx4 v[110:111], off
	v_mfma_f32_32x32x16_bf16 v[16:31], v[212:215], v[220:223], v[16:31]
	s_mov_b32 m0, s19
	s_nop 0
	global_load_lds_dwordx4 v[228:229], off
	v_mfma_f32_32x32x16_bf16 v[32:47], v[224:227], v[216:219], v[32:47]
	s_mov_b64 s[20:21], 0x2390380
	v_lshl_add_u64 v[108:109], v[108:109], 0, s[20:21]
	s_mov_b32 m0, s18
	s_nop 0
	global_load_lds_dwordx4 v[108:109], off
	ds_read_b128 v[108:111], v239
	ds_read_b128 v[212:215], v234
	ds_read_b128 v[216:219], v234 offset:4096
	v_mfma_f32_32x32x16_bf16 v[0:15], v[224:227], v[220:223], v[0:15]
	s_waitcnt lgkmcnt(0)
	v_mfma_f32_32x32x16_bf16 v[48:63], v[108:111], v[212:215], v[48:63]
	v_mfma_f32_32x32x16_bf16 v[16:31], v[108:111], v[216:219], v[16:31]
	ds_read_b128 v[108:111], v239 offset:4096
	s_waitcnt lgkmcnt(0)
	v_mfma_f32_32x32x16_bf16 v[32:47], v[108:111], v[212:215], v[32:47]
	v_mfma_f32_32x32x16_bf16 v[0:15], v[108:111], v[216:219], v[0:15]
	ds_read_b128 v[108:111], v211
	ds_read_b128 v[212:215], v235
	ds_read_b128 v[216:219], v235 offset:4096
	s_waitcnt lgkmcnt(0)
	v_mfma_f32_32x32x16_bf16 v[48:63], v[108:111], v[212:215], v[48:63]
	v_mfma_f32_32x32x16_bf16 v[16:31], v[108:111], v[216:219], v[16:31]
	ds_read_b128 v[108:111], v211 offset:4096
	s_waitcnt vmcnt(6)
	s_barrier
; #define MFMA(a, b, c) __builtin_amdgcn_mfma_f32_32x32x16_bf16((a), (b), (c), 0, 0, 0)
;     ...
;   for (int kt = 0; kt < nk; ++kt) {
;     if (DIST == 2 && kt + 1 < nk) {
;       if (NLD == 6) asm volatile("s_waitcnt vmcnt(6)" ::: "memory");
;       else if (NLD == 5) asm volatile("s_waitcnt vmcnt(5)" ::: "memory");
;       else asm volatile("s_waitcnt vmcnt(8)" ::: "memory");
;     } else {
;       asm volatile("s_waitcnt vmcnt(0)" ::: "memory");
;     }
;     __builtin_amdgcn_s_barrier();
;     const bool pre = (kt + DIST < nk);
;     const char* base = smem + (kt % NSTG) * STAGE;
;     const char* pa = base + (wrow_act + r) * 128;
;     const char* pw = base + ABYTES + (wrow_w + r) * 128;
;     constexpr int NM = NI * MJ;
;     constexpr int PPS = (NLD + 1) / 2;
; #pragma unroll
;     for (int s = 0; s < 4; ++s) {
;       bf16x8 af[MJ], wf[NI];
; #pragma unroll
;       for (int j = 0; j < MJ; ++j) af[j] = *(const bf16x8*)(pa + j * 32 * 128 + xo[s]);
; #pragma unroll
;       for (int i = 0; i < NI; ++i) wf[i] = *(const bf16x8*)(pw + i * 32 * 128 + xo[s]);
; #pragma unroll
;       for (int m = 0; m < NM; ++m) {
;         const int i = m / MJ, j = m % MJ;
;         acc[i][j] = MFMA(wf[i], af[j], acc[i][j]);
;         if (s < 2 && NM >= PPS) {
;           constexpr int EVERY = (NM / PPS) > 0 ? (NM / PPS) : 1;
;           if ((m + 1) % EVERY == 0) {
;             const int pc = s * PPS + (m + 1) / EVERY - 1;
;             if ((m + 1) / EVERY <= PPS && pc < NLD) {
;               __builtin_amdgcn_sched_barrier(0);
;               if (pre) issue_piece(kt + DIST, pc);
;               __builtin_amdgcn_sched_barrier(0);
;             }
;           }
;         }
;         if (s < 2 && NM < PPS) {
;           const int slot = s * NM + m;
;           __builtin_amdgcn_sched_barrier(0);
; #pragma unroll
;           for (int pc = 0; pc < NLD; ++pc)
;             if ((pc * 2 * NM) / NLD == slot && pre) issue_piece(kt + DIST, pc);
;           __builtin_amdgcn_sched_barrier(0);
;         }
;       }
;     }
;   }
;   __builtin_amdgcn_s_barrier();
; DEV void phase_merge(const Params& p, int l, int hf, char* smem) {
;     ...
;     for (int br = 0; br < 3; ++br) {
	s_waitcnt lgkmcnt(0)
	v_mfma_f32_32x32x16_bf16 v[32:47], v[108:111], v[212:215], v[32:47]
	v_mfma_f32_32x32x16_bf16 v[0:15], v[108:111], v[216:219], v[0:15]
	ds_read_b128 v[108:111], v203 offset:32768
	ds_read_b128 v[212:215], v199
	ds_read_b128 v[216:219], v199 offset:4096
	ds_read_b128 v[220:223], v203 offset:36864
	s_waitcnt lgkmcnt(0)
	v_mfma_f32_32x32x16_bf16 v[48:63], v[108:111], v[212:215], v[48:63]
	v_mfma_f32_32x32x16_bf16 v[16:31], v[108:111], v[216:219], v[16:31]
	v_mfma_f32_32x32x16_bf16 v[32:47], v[220:223], v[212:215], v[32:47]
	v_mfma_f32_32x32x16_bf16 v[0:15], v[220:223], v[216:219], v[0:15]
	ds_read_b128 v[108:111], v204 offset:32768
	ds_read_b128 v[212:215], v201
	ds_read_b128 v[216:219], v201 offset:4096
	ds_read_b128 v[220:223], v204 offset:36864
	s_waitcnt lgkmcnt(0)
	v_mfma_f32_32x32x16_bf16 v[48:63], v[108:111], v[212:215], v[48:63]
	v_mfma_f32_32x32x16_bf16 v[16:31], v[108:111], v[216:219], v[16:31]
	v_mfma_f32_32x32x16_bf16 v[32:47], v[220:223], v[212:215], v[32:47]
	v_mfma_f32_32x32x16_bf16 v[0:15], v[220:223], v[216:219], v[0:15]
	ds_read_b128 v[108:111], v206 offset:32768
	ds_read_b128 v[212:215], v202
	ds_read_b128 v[216:219], v202 offset:4096
	s_waitcnt lgkmcnt(0)
	v_mfma_f32_32x32x16_bf16 v[48:63], v[108:111], v[212:215], v[48:63]
	v_mfma_f32_32x32x16_bf16 v[16:31], v[108:111], v[216:219], v[16:31]
	ds_read_b128 v[108:111], v206 offset:36864
	s_waitcnt lgkmcnt(0)
	v_mfma_f32_32x32x16_bf16 v[32:47], v[108:111], v[212:215], v[32:47]
	v_mfma_f32_32x32x16_bf16 v[0:15], v[108:111], v[216:219], v[0:15]
	ds_read_b128 v[108:111], v205 offset:32768
	ds_read_b128 v[212:215], v200
	ds_read_b128 v[216:219], v200 offset:4096
	s_waitcnt lgkmcnt(0)
	v_mfma_f32_32x32x16_bf16 v[48:63], v[108:111], v[212:215], v[48:63]
	v_mfma_f32_32x32x16_bf16 v[16:31], v[108:111], v[216:219], v[16:31]
	ds_read_b128 v[108:111], v205 offset:36864
	s_waitcnt vmcnt(0)
	s_barrier
	s_waitcnt lgkmcnt(0)
	v_mfma_f32_32x32x16_bf16 v[32:47], v[108:111], v[212:215], v[32:47]
	v_mfma_f32_32x32x16_bf16 v[0:15], v[108:111], v[216:219], v[0:15]
	ds_read_b128 v[108:111], v208
	ds_read_b128 v[212:215], v199 offset:49152
	ds_read_b128 v[216:219], v199 offset:53248
	ds_read_b128 v[220:223], v208 offset:4096
	s_waitcnt lgkmcnt(0)
	v_mfma_f32_32x32x16_bf16 v[48:63], v[108:111], v[212:215], v[48:63]
	v_mfma_f32_32x32x16_bf16 v[16:31], v[108:111], v[216:219], v[16:31]
	v_mfma_f32_32x32x16_bf16 v[32:47], v[220:223], v[212:215], v[32:47]
	v_mfma_f32_32x32x16_bf16 v[0:15], v[220:223], v[216:219], v[0:15]
	ds_read_b128 v[108:111], v210
	ds_read_b128 v[212:215], v201 offset:49152
	ds_read_b128 v[216:219], v201 offset:53248
	ds_read_b128 v[220:223], v210 offset:4096
	s_waitcnt lgkmcnt(0)
	v_mfma_f32_32x32x16_bf16 v[48:63], v[108:111], v[212:215], v[48:63]
	v_mfma_f32_32x32x16_bf16 v[16:31], v[108:111], v[216:219], v[16:31]
	v_mfma_f32_32x32x16_bf16 v[32:47], v[220:223], v[212:215], v[32:47]
	v_mfma_f32_32x32x16_bf16 v[0:15], v[220:223], v[216:219], v[0:15]
	ds_read_b128 v[108:111], v202 offset:49152
	ds_read_b128 v[202:205], v202 offset:53248
	ds_read_b128 v[210:213], v209
	ds_read_b128 v[214:217], v209 offset:4096
	s_add_i32 s13, s13, -1
	s_add_u32 s15, s15, 0x400
	s_addc_u32 s14, s14, 0
	s_add_u32 s16, s16, 0x100000
	s_addc_u32 s17, s17, 0
	v_lshl_add_u64 v[72:73], v[72:73], 0, s[60:61]
	s_waitcnt lgkmcnt(0)
	v_mfma_f32_32x32x16_bf16 v[48:63], v[210:213], v[108:111], v[48:63]
	v_lshl_add_u64 v[74:75], v[74:75], 0, s[60:61]
	s_cmp_eq_u32 s13, 0
	v_mfma_f32_32x32x16_bf16 v[16:31], v[210:213], v[202:205], v[16:31]
	v_mfma_f32_32x32x16_bf16 v[32:47], v[214:217], v[108:111], v[32:47]
	v_mfma_f32_32x32x16_bf16 v[0:15], v[214:217], v[202:205], v[0:15]
	ds_read_b128 v[108:111], v200 offset:49152
	ds_read_b128 v[200:203], v200 offset:53248
	ds_read_b128 v[208:211], v207
	ds_read_b128 v[204:207], v207 offset:4096
	s_barrier
	s_waitcnt lgkmcnt(0)
	v_mfma_f32_32x32x16_bf16 v[48:63], v[208:211], v[108:111], v[48:63]
	v_mfma_f32_32x32x16_bf16 v[32:47], v[204:207], v[108:111], v[32:47]
	s_waitcnt vmcnt(0)
; DEV void phase_merge(const Params& p, int l, int hf, char* smem) {
;     ...
; #pragma unroll
;       for (int j = 0; j < 2; ++j) {
; #pragma unroll
;         for (int i = 0; i < 2; ++i)
; #pragma unroll
;           for (int g4 = 0; g4 < 4; ++g4) {
;             const uint2 gg = gpre[i][j][g4];
;             yacc[i][j][4 * g4] += acc[i][j][4 * g4] * __uint_as_float(gg.x << 16);
;             yacc[i][j][4 * g4 + 1] += acc[i][j][4 * g4 + 1] * __uint_as_float(gg.x & 0xffff0000u);
;             yacc[i][j][4 * g4 + 2] += acc[i][j][4 * g4 + 2] * __uint_as_float(gg.y << 16);
;             yacc[i][j][4 * g4 + 3] += acc[i][j][4 * g4 + 3] * __uint_as_float(gg.y & 0xffff0000u);
;           }
;       }
;     }
; #pragma unroll
;     for (int j = 0; j < 2; ++j) {
;       const size_t m = (size_t)mt * 256 + wm * 64 + 32 * j + r;
;       u16* yrow = Y + m * 1024 + nt * 128 + wn * 64;
; #pragma unroll
;       for (int i = 0; i < 2; ++i) {
;         float v[16];
; #pragma unroll
;         for (int e = 0; e < 16; ++e) v[e] = yacc[i][j][e];
;         store_row32(yrow + 32 * i, v, h);
;       }
;     }
;   }
	v_lshlrev_b32_e32 v108, 16, v106
	s_nop 8
	v_fmac_f32_e32 v152, v48, v108
	v_and_b32_e32 v48, 0xffff0000, v106
	v_fmac_f32_e32 v153, v49, v48
	v_lshlrev_b32_e32 v48, 16, v107
	v_fmac_f32_e32 v154, v50, v48
	v_and_b32_e32 v48, 0xffff0000, v107
	v_fmac_f32_e32 v155, v51, v48
	v_lshlrev_b32_e32 v48, 16, v104
	v_fmac_f32_e32 v156, v52, v48
	v_and_b32_e32 v48, 0xffff0000, v104
	v_fmac_f32_e32 v158, v53, v48
	v_lshlrev_b32_e32 v48, 16, v105
	v_fmac_f32_e32 v159, v54, v48
	v_and_b32_e32 v48, 0xffff0000, v105
	v_fmac_f32_e32 v162, v55, v48
	v_lshlrev_b32_e32 v48, 16, v102
	v_fmac_f32_e32 v163, v56, v48
	v_and_b32_e32 v48, 0xffff0000, v102
	v_fmac_f32_e32 v181, v57, v48
	v_lshlrev_b32_e32 v48, 16, v103
	v_fmac_f32_e32 v182, v58, v48
	v_and_b32_e32 v48, 0xffff0000, v103
	v_fmac_f32_e32 v185, v59, v48
	v_lshlrev_b32_e32 v48, 16, v100
	v_fmac_f32_e32 v186, v60, v48
	v_and_b32_e32 v48, 0xffff0000, v100
	v_fmac_f32_e32 v189, v61, v48
	v_lshlrev_b32_e32 v48, 16, v101
	v_fmac_f32_e32 v190, v62, v48
	v_and_b32_e32 v48, 0xffff0000, v101
	v_fmac_f32_e32 v193, v63, v48
	v_lshlrev_b32_e32 v48, 16, v98
	v_fmac_f32_e32 v157, v32, v48
	v_and_b32_e32 v32, 0xffff0000, v98
	v_fmac_f32_e32 v160, v33, v32
	v_lshlrev_b32_e32 v32, 16, v99
	v_fmac_f32_e32 v161, v34, v32
	v_and_b32_e32 v32, 0xffff0000, v99
	v_fmac_f32_e32 v164, v35, v32
	v_lshlrev_b32_e32 v32, 16, v96
	v_fmac_f32_e32 v165, v36, v32
	v_and_b32_e32 v32, 0xffff0000, v96
	v_fmac_f32_e32 v183, v37, v32
	v_lshlrev_b32_e32 v32, 16, v97
	v_fmac_f32_e32 v184, v38, v32
	v_and_b32_e32 v32, 0xffff0000, v97
	v_fmac_f32_e32 v187, v39, v32
	v_lshlrev_b32_e32 v32, 16, v94
	v_mfma_f32_32x32x16_bf16 v[16:31], v[208:211], v[200:203], v[16:31]
	v_fmac_f32_e32 v188, v40, v32
	v_and_b32_e32 v32, 0xffff0000, v94
	v_fmac_f32_e32 v191, v41, v32
	v_lshlrev_b32_e32 v32, 16, v95
	v_fmac_f32_e32 v192, v42, v32
	v_and_b32_e32 v32, 0xffff0000, v95
	v_fmac_f32_e32 v194, v43, v32
	v_lshlrev_b32_e32 v32, 16, v92
	v_fmac_f32_e32 v195, v44, v32
	v_and_b32_e32 v32, 0xffff0000, v92
	v_fmac_f32_e32 v196, v45, v32
	v_lshlrev_b32_e32 v32, 16, v93
	v_fmac_f32_e32 v197, v46, v32
	v_and_b32_e32 v32, 0xffff0000, v93
	v_fmac_f32_e32 v198, v47, v32
	v_lshlrev_b32_e32 v32, 16, v90
	v_fmac_f32_e32 v123, v16, v32
	v_and_b32_e32 v16, 0xffff0000, v90
	v_fmac_f32_e32 v126, v17, v16
	v_lshlrev_b32_e32 v16, 16, v91
	v_fmac_f32_e32 v127, v18, v16
	v_and_b32_e32 v16, 0xffff0000, v91
	v_fmac_f32_e32 v130, v19, v16
	v_lshlrev_b32_e32 v16, 16, v88
	v_fmac_f32_e32 v131, v20, v16
	v_and_b32_e32 v16, 0xffff0000, v88
	v_fmac_f32_e32 v134, v21, v16
	v_lshlrev_b32_e32 v16, 16, v89
	v_fmac_f32_e32 v135, v22, v16
	v_and_b32_e32 v16, 0xffff0000, v89
	v_fmac_f32_e32 v138, v23, v16
	v_lshlrev_b32_e32 v16, 16, v86
	v_mfma_f32_32x32x16_bf16 v[0:15], v[204:207], v[200:203], v[0:15]
	v_fmac_f32_e32 v139, v24, v16
	v_and_b32_e32 v16, 0xffff0000, v86
	v_fmac_f32_e32 v142, v25, v16
	v_lshlrev_b32_e32 v16, 16, v87
	v_fmac_f32_e32 v143, v26, v16
	v_and_b32_e32 v16, 0xffff0000, v87
	v_fmac_f32_e32 v146, v27, v16
	v_lshlrev_b32_e32 v16, 16, v84
	v_fmac_f32_e32 v148, v28, v16
	v_and_b32_e32 v16, 0xffff0000, v84
	v_fmac_f32_e32 v149, v29, v16
	v_lshlrev_b32_e32 v16, 16, v85
	v_fmac_f32_e32 v150, v30, v16
	v_and_b32_e32 v16, 0xffff0000, v85
	v_fmac_f32_e32 v151, v31, v16
	v_lshlrev_b32_e32 v16, 16, v82
	v_fmac_f32_e32 v118, v0, v16
	v_and_b32_e32 v0, 0xffff0000, v82
	v_fmac_f32_e32 v119, v1, v0
	v_lshlrev_b32_e32 v0, 16, v83
	v_fmac_f32_e32 v120, v2, v0
	v_and_b32_e32 v0, 0xffff0000, v83
	v_fmac_f32_e32 v121, v3, v0
	v_lshlrev_b32_e32 v0, 16, v80
	v_fmac_f32_e32 v122, v4, v0
	v_and_b32_e32 v0, 0xffff0000, v80
	v_fmac_f32_e32 v124, v5, v0
	v_lshlrev_b32_e32 v0, 16, v81
	v_fmac_f32_e32 v125, v6, v0
	v_and_b32_e32 v0, 0xffff0000, v81
	v_fmac_f32_e32 v128, v7, v0
	v_lshlrev_b32_e32 v0, 16, v78
	v_fmac_f32_e32 v129, v8, v0
	v_and_b32_e32 v0, 0xffff0000, v78
	v_fmac_f32_e32 v132, v9, v0
	v_lshlrev_b32_e32 v0, 16, v79
	v_fmac_f32_e32 v133, v10, v0
	v_and_b32_e32 v0, 0xffff0000, v79
	v_fmac_f32_e32 v136, v11, v0
	v_lshlrev_b32_e32 v0, 16, v76
	v_fmac_f32_e32 v137, v12, v0
	v_and_b32_e32 v0, 0xffff0000, v76
	v_fmac_f32_e32 v140, v13, v0
	v_lshlrev_b32_e32 v0, 16, v77
	v_fmac_f32_e32 v141, v14, v0
	v_and_b32_e32 v0, 0xffff0000, v77
	v_fmac_f32_e32 v144, v15, v0
	s_cbranch_scc0 .LBB0_37
	v_readlane_b32 s2, v240, 42
	v_readlane_b32 s3, v240, 43
	s_lshl_b64 s[8:9], s[2:3], 8
	v_readlane_b32 s2, v240, 40
	v_lshl_add_u64 v[0:1], s[8:9], 0, v[64:65]
	v_readlane_b32 s3, v240, 41
	v_lshlrev_b64 v[0:1], 11, v[0:1]
	v_cvt_pk_bf16_f32 v4, v163, v181
	v_lshl_add_u64 v[2:3], s[2:3], 1, v[66:67]
	v_lshl_add_u64 v[8:9], v[2:3], 0, v[0:1]
	v_cvt_pk_bf16_f32 v0, v152, v153
	v_cvt_pk_bf16_f32 v1, v154, v155
	v_cvt_pk_bf16_f32 v2, v156, v158
	v_cvt_pk_bf16_f32 v3, v159, v162
	v_cvt_pk_bf16_f32 v5, v182, v185
	v_cvt_pk_bf16_f32 v6, v186, v189
	v_cvt_pk_bf16_f32 v7, v190, v193
	v_permlane32_swap_b32_e32 v0, v2
	v_permlane32_swap_b32_e32 v1, v3
	v_permlane32_swap_b32_e32 v4, v6
	v_permlane32_swap_b32_e32 v5, v7
	flat_store_dwordx4 v[8:9], v[0:3]
	flat_store_dwordx4 v[8:9], v[4:7] offset:32
	s_mov_b32 s2, 0x10000
	v_cvt_pk_bf16_f32 v0, v157, v160
	v_cvt_pk_bf16_f32 v1, v161, v164
	v_cvt_pk_bf16_f32 v2, v165, v183
	v_cvt_pk_bf16_f32 v3, v184, v187
	v_cvt_pk_bf16_f32 v4, v188, v191
	v_cvt_pk_bf16_f32 v5, v192, v194
	v_cvt_pk_bf16_f32 v6, v195, v196
	v_cvt_pk_bf16_f32 v7, v197, v198
	v_permlane32_swap_b32_e32 v0, v2
	v_permlane32_swap_b32_e32 v1, v3
	v_permlane32_swap_b32_e32 v4, v6
	v_permlane32_swap_b32_e32 v5, v7
	flat_store_dwordx4 v[8:9], v[0:3] offset:64
	flat_store_dwordx4 v[8:9], v[4:7] offset:96
	v_add_co_u32_e32 v8, vcc, s2, v8
	v_cvt_pk_bf16_f32 v0, v123, v126
	v_cvt_pk_bf16_f32 v1, v127, v130
	v_cvt_pk_bf16_f32 v2, v131, v134
	v_cvt_pk_bf16_f32 v3, v135, v138
	v_cvt_pk_bf16_f32 v4, v139, v142
	v_cvt_pk_bf16_f32 v5, v143, v146
	v_cvt_pk_bf16_f32 v6, v148, v149
	v_cvt_pk_bf16_f32 v7, v150, v151
	v_permlane32_swap_b32_e32 v0, v2
	v_permlane32_swap_b32_e32 v1, v3
	v_addc_co_u32_e32 v9, vcc, 0, v9, vcc
	v_permlane32_swap_b32_e32 v4, v6
	v_permlane32_swap_b32_e32 v5, v7
	flat_store_dwordx4 v[8:9], v[0:3]
	flat_store_dwordx4 v[8:9], v[4:7] offset:32
	v_readlane_b32 s2, v240, 29
	v_cvt_pk_bf16_f32 v0, v118, v119
	v_cvt_pk_bf16_f32 v1, v120, v121
	v_cvt_pk_bf16_f32 v2, v122, v124
	v_cvt_pk_bf16_f32 v3, v125, v128
	v_cvt_pk_bf16_f32 v4, v129, v132
	v_cvt_pk_bf16_f32 v5, v133, v136
	v_cvt_pk_bf16_f32 v6, v137, v140
	v_cvt_pk_bf16_f32 v7, v141, v144
	v_permlane32_swap_b32_e32 v0, v2
	v_permlane32_swap_b32_e32 v1, v3
	v_permlane32_swap_b32_e32 v4, v6
	v_permlane32_swap_b32_e32 v5, v7
	flat_store_dwordx4 v[8:9], v[0:3] offset:64
	flat_store_dwordx4 v[8:9], v[4:7] offset:96
	v_readlane_b32 s3, v240, 30
	s_load_dword s6, s[2:3], 0x0
	s_movk_i32 s80, 0xc00
	s_waitcnt lgkmcnt(0)
	s_add_i32 s12, s6, s12
	s_cmpk_gt_i32 s12, 0x1ff
	s_cbranch_scc0 .LBB0_36

; DEV int opaque_tid() { int t = threadIdx.x; asm volatile("" : "+v"(t)); return t; }
;     ...
;   const int tid = opaque_tid(), lane = tid & 63, h = lane >> 5, r = lane & 31;
;   const int nk = K >> 6;
;   const int cch = (tid & 7) ^ ((tid >> 4) & 7);
;   const u16* ga = A + (size_t)(tid >> 3) * lda + cch * 8;
;   const u16* gb = Bt + (size_t)(tid >> 3) * ldb + cch * 8;
;   char* lds_t = smem + tid * 16;
;   auto issue_piece = [&](int kt, int pc) {
;     char* st = lds_t + (kt % NSTG) * STAGE;
;     if (pc < 4)
;       __builtin_amdgcn_global_load_lds((const unsigned*)(ga + (size_t)(64 * pc) * lda + (size_t)kt * ksa), (unsigned __attribute__((address_space(3)))*)(st + pc * 8192), 16, 0, 0);
;     else
;       __builtin_amdgcn_global_load_lds((const unsigned*)(gb + (size_t)(64 * (pc - 4)) * ldb + (size_t)kt * ksb), (unsigned __attribute__((address_space(3)))*)(st + ABYTES + (pc - 4) * 8192), 16, 0, 0);
;   };
;   const int x = (r >> 1) & 7;
;   int xo[4];
; #pragma unroll
;   for (int s = 0; s < 4; ++s) xo[s] = (((2 * s + h) ^ x) << 4);
;   asm volatile("s_waitcnt vmcnt(0)" ::: "memory");
; #pragma unroll
;   for (int d = 0; d < DIST; ++d)
; #pragma unroll
;     for (int pc = 0; pc < NLD; ++pc) issue_piece(d, pc);
;   pre();
; DEV void phase_merge(const Params& p, int l, int hf, char* smem) {
;     ...
;       for (int br = 0; br < 3; ++br) {
;         f32x16 acc[1][2];
; #pragma unroll
;         for (int j = 0; j < 2; ++j)
; #pragma unroll
;           for (int e = 0; e < 16; ++e) acc[0][j][e] = 0.f;
;         uint2 gpre[2][4];
;         auto load_gates = [&]() {
; #pragma unroll
;           for (int j = 0; j < 2; ++j) {
;             const size_t m = (size_t)mt * 256 + wm * 64 + 32 * j + r;
;             const u16* grow = G + m * 3072 + br * 1024 + nt64 * 64 + wn * 32;
; #pragma unroll
;             for (int g4 = 0; g4 < 4; ++g4) gpre[j][g4] = *(const uint2*)(grow + 8 * g4 + 4 * h);
;           }
;         };
;         gemm_main<1, 2, 64, 3>(acc, A + (size_t)mt * 256 * 1536 + br * 512, 1536,
;                                (const u16*)(ws + OFF_WBR) + ((size_t)(l * 3 + br) * 1024 + nt64 * 64) * 512, 512, 512, smem, wm * 64,
;                                wn * 32, 64, 64, load_gates);
.LBB0_43:
	v_mov_b32_e32 v4, v147
	s_nop 0
	v_lshrrev_b32_e32 v5, 4, v4
	v_ashrrev_i32_e32 v0, 3, v4
	v_mad_i64_i32 v[2:3], s[14:15], v0, s29, 0
	v_bitop3_b32 v5, v5, 7, v4 bitop3:0x48
	v_lshlrev_b32_e32 v5, 4, v5
	s_add_u32 s14, s0, s10
	v_ashrrev_i32_e32 v1, 31, v0
	v_or_b32_e32 v2, v2, v5
	s_addc_u32 s15, s1, s11
	v_lshlrev_b64 v[0:1], 10, v[0:1]
	v_lshl_add_u64 v[60:61], s[14:15], 0, v[2:3]
	s_add_u32 s14, s0, s4
	v_or_b32_e32 v0, v0, v5
	s_addc_u32 s15, s1, s5
	v_lshl_add_u64 v[62:63], s[14:15], 0, v[0:1]
	v_lshl_add_u32 v100, v4, 4, 0
	v_lshl_add_u64 v[0:1], v[62:63], 0, s[22:23]
	v_readfirstlane_b32 s22, v100
	v_add_u32_e32 v5, 0x2000, v100
	v_lshl_add_u64 v[2:3], v[60:61], 0, s[74:75]
	s_mov_b32 m0, s22
	v_readfirstlane_b32 s21, v5
	v_add_u32_e32 v5, 0x4000, v100
	global_load_lds_dwordx4 v[2:3], off
	v_lshl_add_u64 v[2:3], v[60:61], 0, s[24:25]
	s_mov_b32 m0, s21
	v_readfirstlane_b32 s20, v5
	v_add_u32_e32 v5, 0x6000, v100
	global_load_lds_dwordx4 v[2:3], off
	v_lshl_add_u64 v[2:3], v[60:61], 0, s[26:27]
	s_mov_b32 m0, s20
	v_readfirstlane_b32 s19, v5
	global_load_lds_dwordx4 v[2:3], off
	v_lshl_add_u64 v[2:3], v[60:61], 0, s[66:67]
	s_mov_b32 m0, s19
	v_add_u32_e32 v5, 0xc000, v100
	global_load_lds_dwordx4 v[2:3], off
	v_add_u32_e32 v2, 0x8000, v100
	v_readfirstlane_b32 s17, v5
	v_readfirstlane_b32 s18, v2
	s_mov_b32 m0, s18
	v_add_u32_e32 v5, 0xe000, v100
	global_load_lds_dwordx4 v[0:1], off
	v_lshl_add_u64 v[0:1], v[60:61], 0, s[70:71]
	s_mov_b32 m0, s17
	v_readfirstlane_b32 s16, v5
	v_add_u32_e32 v5, 0x10000, v100
	global_load_lds_dwordx4 v[0:1], off
	v_lshl_add_u64 v[0:1], v[60:61], 0, s[68:69]
	s_mov_b32 m0, s16
	v_readfirstlane_b32 s15, v5
	v_add_u32_e32 v5, 0x12000, v100
	global_load_lds_dwordx4 v[0:1], off
	v_lshl_add_u64 v[0:1], v[60:61], 0, s[76:77]
	s_mov_b32 m0, s15
	v_readfirstlane_b32 s14, v5
	global_load_lds_dwordx4 v[0:1], off
	v_lshl_add_u64 v[0:1], v[60:61], 0, s[72:73]
	s_mov_b32 m0, s14
	v_lshl_add_u64 v[2:3], v[62:63], 0, s[64:65]
	global_load_lds_dwordx4 v[0:1], off
	v_add_u32_e32 v0, 0x14000, v100
	v_lshl_add_u64 v[116:117], v[62:63], 0, s[84:85]
	v_readfirstlane_b32 s13, v0
	v_lshl_add_u64 v[0:1], s[0:1], 0, v[42:43]
	s_mov_b32 m0, s13
	v_add_co_u32_e32 v0, vcc, s33, v0
	global_load_lds_dwordx4 v[2:3], off
	s_nop 0
	v_addc_co_u32_e32 v1, vcc, 0, v1, vcc
	flat_load_dwordx2 v[58:59], v[0:1] offset:256
	flat_load_dwordx2 v[56:57], v[0:1] offset:272
	flat_load_dwordx2 v[54:55], v[0:1] offset:288
	flat_load_dwordx2 v[52:53], v[0:1] offset:304
	v_lshl_add_u64 v[0:1], s[0:1], 0, v[40:41]
	v_add_co_u32_e32 v0, vcc, s93, v0
	v_bfe_u32 v2, v4, 1, 3
	s_nop 0
	v_addc_co_u32_e32 v1, vcc, 0, v1, vcc
	flat_load_dwordx2 v[50:51], v[0:1] offset:256
	flat_load_dwordx2 v[48:49], v[0:1] offset:272
	flat_load_dwordx2 v[46:47], v[0:1] offset:288
	flat_load_dwordx2 v[44:45], v[0:1] offset:304
	v_lshrrev_b32_e32 v0, 5, v4
	v_bfe_u32 v1, v4, 5, 1
	v_bitop3_b32 v0, v0, v2, 1 bitop3:0x6c
	v_lshlrev_b32_e32 v124, 4, v0
	v_bitop3_b32 v0, v1, v2, 2 bitop3:0x36
	v_lshlrev_b32_e32 v125, 4, v0
	v_bitop3_b32 v0, v1, v2, 4 bitop3:0x36
	v_lshlrev_b32_e32 v126, 4, v0
	v_and_b32_e32 v0, 31, v4
	v_or_b32_e32 v4, v0, v39
	v_or_b32_e32 v0, v0, v64
	v_lshlrev_b32_e32 v122, 7, v0
	v_add_u32_e32 v118, 0, v122
	v_add_u32_e32 v101, v118, v124
	v_bitop3_b32 v8, v1, v2, 6 bitop3:0x36
	s_waitcnt vmcnt(5)
	s_barrier
	ds_read_b128 v[0:3], v101 offset:32768
	v_lshlrev_b32_e32 v123, 7, v4
	v_add_u32_e32 v119, 0, v123
	v_add_u32_e32 v97, v119, v124
	ds_read_b128 v[4:7], v97
	v_lshlrev_b32_e32 v127, 4, v8
	ds_read_b128 v[8:11], v97 offset:4096
	v_add_u32_e32 v12, 0x18000, v100
	s_waitcnt lgkmcnt(0)
	v_mfma_f32_32x32x16_bf16 v[16:31], v[0:3], v[4:7], 0
	v_add_u32_e32 v13, 0x1a000, v100
	v_readfirstlane_b32 s25, v12
	v_lshl_add_u64 v[4:5], v[60:61], 0, s[78:79]
	s_mov_b32 m0, s25
	v_readfirstlane_b32 s23, v13
	v_lshl_add_u64 v[6:7], v[60:61], 0, s[88:89]
	global_load_lds_dwordx4 v[4:5], off
	s_mov_b32 m0, s23
	s_nop 0
	global_load_lds_dwordx4 v[6:7], off
	v_mfma_f32_32x32x16_bf16 v[0:15], v[0:3], v[8:11], 0
	v_add_u32_e32 v102, 0x1c000, v100
	v_lshl_add_u64 v[98:99], v[60:61], 0, s[86:87]
	v_readfirstlane_b32 s24, v102
	s_mov_b32 m0, s24
	s_nop 0
	global_load_lds_dwordx4 v[98:99], off
	v_add_u32_e32 v102, v118, v125
	ds_read_b128 v[104:107], v102 offset:32768
	v_add_u32_e32 v98, v119, v125
	ds_read_b128 v[108:111], v98
	ds_read_b128 v[112:115], v98 offset:4096
	s_waitcnt lgkmcnt(0)
	v_mfma_f32_32x32x16_bf16 v[16:31], v[104:107], v[108:111], v[16:31]
	v_add_u32_e32 v99, 0x1e000, v100
	v_lshl_add_u64 v[108:109], v[60:61], 0, s[96:97]
	v_readfirstlane_b32 s26, v99
	s_mov_b32 m0, s26
	s_nop 0
	global_load_lds_dwordx4 v[108:109], off
	v_mfma_f32_32x32x16_bf16 v[0:15], v[104:107], v[112:115], v[0:15]
	v_add_u32_e32 v99, 0x20000, v100
	s_nop 0
	v_readfirstlane_b32 s27, v99
	s_mov_b32 m0, s27
	s_nop 0
	global_load_lds_dwordx4 v[116:117], off
	v_add_u32_e32 v99, v119, v126
	v_add_u32_e32 v103, v118, v126
	ds_read_b128 v[104:107], v99
	ds_read_b128 v[108:111], v99 offset:4096
	ds_read_b128 v[112:115], v103 offset:32768
	v_add_u32_e32 v100, v119, v127
	s_add_i32 s28, 0, 0x14000
	v_add_u32_e32 v128, s28, v122
	v_lshl_add_u64 v[120:121], v[62:63], 0, s[90:91]
	s_waitcnt lgkmcnt(0)
	v_mfma_f32_32x32x16_bf16 v[16:31], v[112:115], v[104:107], v[16:31]
	v_add_u32_e32 v104, v118, v127
	v_add_u32_e32 v105, v128, v124
	v_mfma_f32_32x32x16_bf16 v[0:15], v[112:115], v[108:111], v[0:15]
	ds_read_b128 v[106:109], v104 offset:32768
	ds_read_b128 v[110:113], v100 offset:4096
	ds_read_b128 v[114:117], v100
	s_waitcnt vmcnt(5)
	s_barrier
; #define MFMA(a, b, c) __builtin_amdgcn_mfma_f32_32x32x16_bf16((a), (b), (c), 0, 0, 0)
;     ...
;   for (int kt = 0; kt < nk; ++kt) {
;     if (DIST == 2 && kt + 1 < nk) {
;       if (NLD == 6) asm volatile("s_waitcnt vmcnt(6)" ::: "memory");
;       else if (NLD == 5) asm volatile("s_waitcnt vmcnt(5)" ::: "memory");
;       else asm volatile("s_waitcnt vmcnt(8)" ::: "memory");
;     } else {
;       asm volatile("s_waitcnt vmcnt(0)" ::: "memory");
;     }
;     __builtin_amdgcn_s_barrier();
;     const bool pre = (kt + DIST < nk);
;     const char* base = smem + (kt % NSTG) * STAGE;
;     const char* pa = base + (wrow_act + r) * 128;
;     const char* pw = base + ABYTES + (wrow_w + r) * 128;
;     constexpr int NM = NI * MJ;
;     constexpr int PPS = (NLD + 1) / 2;
; #pragma unroll
;     for (int s = 0; s < 4; ++s) {
;       bf16x8 af[MJ], wf[NI];
; #pragma unroll
;       for (int j = 0; j < MJ; ++j) af[j] = *(const bf16x8*)(pa + j * 32 * 128 + xo[s]);
; #pragma unroll
;       for (int i = 0; i < NI; ++i) wf[i] = *(const bf16x8*)(pw + i * 32 * 128 + xo[s]);
; #pragma unroll
;       for (int m = 0; m < NM; ++m) {
;         const int i = m / MJ, j = m % MJ;
;         acc[i][j] = MFMA(wf[i], af[j], acc[i][j]);
;         if (s < 2 && NM >= PPS) {
;           constexpr int EVERY = (NM / PPS) > 0 ? (NM / PPS) : 1;
;           if ((m + 1) % EVERY == 0) {
;             const int pc = s * PPS + (m + 1) / EVERY - 1;
;             if ((m + 1) / EVERY <= PPS && pc < NLD) {
;               __builtin_amdgcn_sched_barrier(0);
;               if (pre) issue_piece(kt + DIST, pc);
;               __builtin_amdgcn_sched_barrier(0);
;             }
;           }
;         }
;         if (s < 2 && NM < PPS) {
;           const int slot = s * NM + m;
;           __builtin_amdgcn_sched_barrier(0);
; #pragma unroll
;           for (int pc = 0; pc < NLD; ++pc)
;             if ((pc * 2 * NM) / NLD == slot && pre) issue_piece(kt + DIST, pc);
;           __builtin_amdgcn_sched_barrier(0);
;         }
;       }
;     }
	s_waitcnt lgkmcnt(0)
	v_mfma_f32_32x32x16_bf16 v[16:31], v[106:109], v[114:117], v[16:31]
	v_mfma_f32_32x32x16_bf16 v[0:15], v[106:109], v[110:113], v[0:15]
	ds_read_b128 v[106:109], v97 offset:49152
	ds_read_b128 v[110:113], v97 offset:53248
	ds_read_b128 v[114:117], v105
	s_waitcnt lgkmcnt(0)
	v_mfma_f32_32x32x16_bf16 v[16:31], v[114:117], v[106:109], v[16:31]
	s_mov_b64 vcc, 0x1c4d6280
	s_mov_b32 m0, s22
	v_lshl_add_u64 v[106:107], v[60:61], 0, vcc
	v_lshl_add_u64 v[108:109], v[60:61], 0, s[8:9]
	global_load_lds_dwordx4 v[106:107], off
	s_mov_b32 m0, s21
	s_nop 0
	global_load_lds_dwordx4 v[108:109], off
	v_mfma_f32_32x32x16_bf16 v[0:15], v[114:117], v[110:113], v[0:15]
	v_lshl_add_u64 v[106:107], v[60:61], 0, s[6:7]
	s_mov_b32 m0, s20
	s_nop 0
	global_load_lds_dwordx4 v[106:107], off
	v_add_u32_e32 v106, v128, v125
	ds_read_b128 v[108:111], v106
	ds_read_b128 v[112:115], v98 offset:49152
	ds_read_b128 v[116:119], v98 offset:53248
	s_waitcnt lgkmcnt(0)
	v_mfma_f32_32x32x16_bf16 v[16:31], v[108:111], v[112:115], v[16:31]
	v_lshl_add_u64 v[112:113], v[60:61], 0, s[36:37]
	s_mov_b32 m0, s19
	s_nop 0
	global_load_lds_dwordx4 v[112:113], off
	v_mfma_f32_32x32x16_bf16 v[0:15], v[108:111], v[116:119], v[0:15]
	s_mov_b32 m0, s18
	s_nop 0
	global_load_lds_dwordx4 v[120:121], off
	v_add_u32_e32 v107, v128, v126
	ds_read_b128 v[108:111], v99 offset:49152
	ds_read_b128 v[112:115], v99 offset:53248
	ds_read_b128 v[116:119], v107
	s_add_i32 s28, 0, 0x18000
	s_waitcnt lgkmcnt(0)
	v_mfma_f32_32x32x16_bf16 v[16:31], v[116:119], v[108:111], v[16:31]
	v_add_u32_e32 v108, v128, v127
	v_add_u32_e32 v109, s28, v123
	s_add_i32 s28, 0, 0x20000
	v_add_u32_e32 v128, s28, v122
	v_add_u32_e32 v129, v109, v124
	v_add_u32_e32 v124, v128, v124
	v_lshl_add_u64 v[122:123], v[62:63], 0, s[40:41]
	v_mfma_f32_32x32x16_bf16 v[0:15], v[116:119], v[112:115], v[0:15]
	ds_read_b128 v[110:113], v108
	ds_read_b128 v[114:117], v100 offset:53248
	ds_read_b128 v[118:121], v100 offset:49152
	s_waitcnt vmcnt(5)
	s_barrier
	s_waitcnt lgkmcnt(0)
	v_mfma_f32_32x32x16_bf16 v[16:31], v[110:113], v[118:121], v[16:31]
	v_mfma_f32_32x32x16_bf16 v[0:15], v[110:113], v[114:117], v[0:15]
	ds_read_b128 v[110:113], v129
	ds_read_b128 v[114:117], v129 offset:4096
	ds_read_b128 v[118:121], v124
	s_waitcnt lgkmcnt(0)
	v_mfma_f32_32x32x16_bf16 v[16:31], v[118:121], v[110:113], v[16:31]
	s_mov_b32 m0, s17
	v_lshl_add_u64 v[110:111], v[60:61], 0, s[42:43]
	v_lshl_add_u64 v[112:113], v[60:61], 0, s[38:39]
	global_load_lds_dwordx4 v[110:111], off
	s_mov_b32 m0, s16
	s_nop 0
	global_load_lds_dwordx4 v[112:113], off
	v_mfma_f32_32x32x16_bf16 v[0:15], v[118:121], v[114:117], v[0:15]
	v_lshl_add_u64 v[110:111], v[60:61], 0, s[30:31]
	s_mov_b32 m0, s15
	s_nop 0
	global_load_lds_dwordx4 v[110:111], off
	v_add_u32_e32 v130, v128, v125
	ds_read_b128 v[110:113], v130
	v_add_u32_e32 v125, v109, v125
	ds_read_b128 v[114:117], v125
	ds_read_b128 v[118:121], v125 offset:4096
	s_waitcnt lgkmcnt(0)
	v_mfma_f32_32x32x16_bf16 v[16:31], v[110:113], v[114:117], v[16:31]
	v_lshl_add_u64 v[114:115], v[60:61], 0, s[80:81]
	s_mov_b32 m0, s14
	s_nop 0
	global_load_lds_dwordx4 v[114:115], off
	v_mfma_f32_32x32x16_bf16 v[0:15], v[110:113], v[118:121], v[0:15]
	s_mov_b32 m0, s13
	s_nop 0
	global_load_lds_dwordx4 v[122:123], off
	v_add_u32_e32 v131, v109, v126
	v_add_u32_e32 v126, v128, v126
	ds_read_b128 v[110:113], v131
	ds_read_b128 v[114:117], v131 offset:4096
	ds_read_b128 v[118:121], v126
	v_add_u32_e32 v128, v128, v127
	v_add_u32_e32 v109, v109, v127
	v_lshl_add_u64 v[122:123], v[62:63], 0, s[2:3]
	s_waitcnt lgkmcnt(0)
	v_mfma_f32_32x32x16_bf16 v[16:31], v[118:121], v[110:113], v[16:31]
	ds_read_b128 v[110:113], v128
	v_mfma_f32_32x32x16_bf16 v[0:15], v[118:121], v[114:117], v[0:15]
	ds_read_b128 v[114:117], v109 offset:4096
	ds_read_b128 v[118:121], v109
	s_waitcnt vmcnt(5)
	s_barrier
	s_waitcnt lgkmcnt(0)
	v_mfma_f32_32x32x16_bf16 v[16:31], v[110:113], v[118:121], v[16:31]
	v_mfma_f32_32x32x16_bf16 v[0:15], v[110:113], v[114:117], v[0:15]
	ds_read_b128 v[110:113], v97
	ds_read_b128 v[114:117], v97 offset:4096
	ds_read_b128 v[118:121], v101 offset:32768
	s_waitcnt lgkmcnt(0)
	v_mfma_f32_32x32x16_bf16 v[16:31], v[118:121], v[110:113], v[16:31]
	s_mov_b64 vcc, 0x1c4d6380
	s_mov_b32 m0, s25
	v_lshl_add_u64 v[110:111], v[60:61], 0, vcc
	s_mov_b64 vcc, 0x1c506380
	v_lshl_add_u64 v[112:113], v[60:61], 0, vcc
	global_load_lds_dwordx4 v[110:111], off
	s_mov_b32 m0, s23
	s_nop 0
	global_load_lds_dwordx4 v[112:113], off
	v_mfma_f32_32x32x16_bf16 v[0:15], v[118:121], v[114:117], v[0:15]
	v_lshl_add_u64 v[110:111], v[60:61], 0, s[82:83]
	s_mov_b32 m0, s24
	s_mov_b64 s[24:25], 0x1c506100
	global_load_lds_dwordx4 v[110:111], off
	ds_read_b128 v[110:113], v102 offset:32768
	ds_read_b128 v[114:117], v98
	ds_read_b128 v[118:121], v98 offset:4096
	s_waitcnt lgkmcnt(0)
	v_mfma_f32_32x32x16_bf16 v[16:31], v[110:113], v[114:117], v[16:31]
	v_lshl_add_u64 v[114:115], v[60:61], 0, s[94:95]
	s_mov_b32 m0, s26
	s_nop 0
	global_load_lds_dwordx4 v[114:115], off
	v_mfma_f32_32x32x16_bf16 v[0:15], v[110:113], v[118:121], v[0:15]
	s_mov_b32 m0, s27
	s_mov_b64 s[26:27], 0x1c536100
	global_load_lds_dwordx4 v[122:123], off
	ds_read_b128 v[110:113], v99
	ds_read_b128 v[114:117], v99 offset:4096
	ds_read_b128 v[118:121], v103 offset:32768
	v_lshl_add_u64 v[122:123], v[62:63], 0, s[34:35]
	s_waitcnt lgkmcnt(0)
	v_mfma_f32_32x32x16_bf16 v[16:31], v[118:121], v[110:113], v[16:31]
	v_mfma_f32_32x32x16_bf16 v[0:15], v[118:121], v[114:117], v[0:15]
	ds_read_b128 v[110:113], v104 offset:32768
	ds_read_b128 v[114:117], v100 offset:4096
	ds_read_b128 v[118:121], v100
	s_waitcnt vmcnt(5)
	s_barrier
; #define MFMA(a, b, c) __builtin_amdgcn_mfma_f32_32x32x16_bf16((a), (b), (c), 0, 0, 0)
;     ...
;   for (int kt = 0; kt < nk; ++kt) {
;     if (DIST == 2 && kt + 1 < nk) {
;       if (NLD == 6) asm volatile("s_waitcnt vmcnt(6)" ::: "memory");
;       else if (NLD == 5) asm volatile("s_waitcnt vmcnt(5)" ::: "memory");
;       else asm volatile("s_waitcnt vmcnt(8)" ::: "memory");
;     } else {
;       asm volatile("s_waitcnt vmcnt(0)" ::: "memory");
;     }
;     __builtin_amdgcn_s_barrier();
;     const bool pre = (kt + DIST < nk);
;     const char* base = smem + (kt % NSTG) * STAGE;
;     const char* pa = base + (wrow_act + r) * 128;
;     const char* pw = base + ABYTES + (wrow_w + r) * 128;
;     constexpr int NM = NI * MJ;
;     constexpr int PPS = (NLD + 1) / 2;
; #pragma unroll
;     for (int s = 0; s < 4; ++s) {
;       bf16x8 af[MJ], wf[NI];
; #pragma unroll
;       for (int j = 0; j < MJ; ++j) af[j] = *(const bf16x8*)(pa + j * 32 * 128 + xo[s]);
; #pragma unroll
;       for (int i = 0; i < NI; ++i) wf[i] = *(const bf16x8*)(pw + i * 32 * 128 + xo[s]);
; #pragma unroll
;       for (int m = 0; m < NM; ++m) {
;         const int i = m / MJ, j = m % MJ;
;         acc[i][j] = MFMA(wf[i], af[j], acc[i][j]);
;         if (s < 2 && NM >= PPS) {
;           constexpr int EVERY = (NM / PPS) > 0 ? (NM / PPS) : 1;
;           if ((m + 1) % EVERY == 0) {
;             const int pc = s * PPS + (m + 1) / EVERY - 1;
;             if ((m + 1) / EVERY <= PPS && pc < NLD) {
;               __builtin_amdgcn_sched_barrier(0);
;               if (pre) issue_piece(kt + DIST, pc);
;               __builtin_amdgcn_sched_barrier(0);
;             }
;           }
;         }
;         if (s < 2 && NM < PPS) {
;           const int slot = s * NM + m;
;           __builtin_amdgcn_sched_barrier(0);
; #pragma unroll
;           for (int pc = 0; pc < NLD; ++pc)
;             if ((pc * 2 * NM) / NLD == slot && pre) issue_piece(kt + DIST, pc);
;           __builtin_amdgcn_sched_barrier(0);
;         }
;       }
;     }
;   }
	s_waitcnt lgkmcnt(0)
	v_mfma_f32_32x32x16_bf16 v[16:31], v[110:113], v[118:121], v[16:31]
	v_mfma_f32_32x32x16_bf16 v[0:15], v[110:113], v[114:117], v[0:15]
	ds_read_b128 v[110:113], v97 offset:49152
	ds_read_b128 v[114:117], v97 offset:53248
	ds_read_b128 v[118:121], v105
	s_waitcnt lgkmcnt(0)
	v_mfma_f32_32x32x16_bf16 v[16:31], v[118:121], v[110:113], v[16:31]
	s_mov_b32 m0, s22
	v_lshl_add_u64 v[110:111], v[60:61], 0, s[44:45]
	v_lshl_add_u64 v[112:113], v[60:61], 0, s[46:47]
	global_load_lds_dwordx4 v[110:111], off
	s_mov_b32 m0, s21
	s_mov_b64 s[22:23], 0x2380000
	global_load_lds_dwordx4 v[112:113], off
	v_mfma_f32_32x32x16_bf16 v[0:15], v[118:121], v[114:117], v[0:15]
	v_lshl_add_u64 v[110:111], v[60:61], 0, s[50:51]
	s_mov_b32 m0, s20
	s_nop 0
	global_load_lds_dwordx4 v[110:111], off
	ds_read_b128 v[110:113], v106
	ds_read_b128 v[114:117], v98 offset:49152
	ds_read_b128 v[118:121], v98 offset:53248
	s_waitcnt lgkmcnt(0)
	v_mfma_f32_32x32x16_bf16 v[16:31], v[110:113], v[114:117], v[16:31]
	v_lshl_add_u64 v[114:115], v[60:61], 0, s[48:49]
	s_mov_b32 m0, s19
	s_nop 0
	global_load_lds_dwordx4 v[114:115], off
	v_mfma_f32_32x32x16_bf16 v[0:15], v[110:113], v[118:121], v[0:15]
	s_mov_b32 m0, s18
	s_nop 0
	global_load_lds_dwordx4 v[122:123], off
	ds_read_b128 v[110:113], v107
	ds_read_b128 v[114:117], v99 offset:49152
	v_lshl_add_u64 v[62:63], v[62:63], 0, s[54:55]
	s_waitcnt lgkmcnt(0)
	v_mfma_f32_32x32x16_bf16 v[16:31], v[110:113], v[114:117], v[16:31]
	ds_read_b128 v[114:117], v99 offset:53248
	s_waitcnt lgkmcnt(0)
	v_mfma_f32_32x32x16_bf16 v[0:15], v[110:113], v[114:117], v[0:15]
	ds_read_b128 v[110:113], v108
	ds_read_b128 v[114:117], v100 offset:49152
	s_waitcnt lgkmcnt(0)
	v_mfma_f32_32x32x16_bf16 v[16:31], v[110:113], v[114:117], v[16:31]
	ds_read_b128 v[114:117], v100 offset:53248
	s_waitcnt vmcnt(5)
	s_barrier
	s_waitcnt lgkmcnt(0)
	v_mfma_f32_32x32x16_bf16 v[0:15], v[110:113], v[114:117], v[0:15]
	ds_read_b128 v[110:113], v124
	ds_read_b128 v[114:117], v129
	ds_read_b128 v[118:121], v129 offset:4096
	s_waitcnt lgkmcnt(0)
	v_mfma_f32_32x32x16_bf16 v[16:31], v[110:113], v[114:117], v[16:31]
	s_mov_b32 m0, s17
	v_lshl_add_u64 v[114:115], v[60:61], 0, s[52:53]
	v_lshl_add_u64 v[116:117], v[60:61], 0, s[58:59]
	global_load_lds_dwordx4 v[114:115], off
	s_mov_b32 m0, s16
	s_nop 0
	global_load_lds_dwordx4 v[116:117], off
	v_mfma_f32_32x32x16_bf16 v[0:15], v[110:113], v[118:121], v[0:15]
	v_lshl_add_u64 v[110:111], v[60:61], 0, s[56:57]
	s_mov_b32 m0, s15
	s_nop 0
	global_load_lds_dwordx4 v[110:111], off
	ds_read_b128 v[110:113], v130
	ds_read_b128 v[114:117], v125
	ds_read_b128 v[118:121], v125 offset:4096
	s_waitcnt lgkmcnt(0)
	v_mfma_f32_32x32x16_bf16 v[16:31], v[110:113], v[114:117], v[16:31]
	v_lshl_add_u64 v[60:61], v[60:61], 0, s[62:63]
	s_mov_b32 m0, s14
	s_nop 0
	global_load_lds_dwordx4 v[60:61], off
	v_mfma_f32_32x32x16_bf16 v[0:15], v[110:113], v[118:121], v[0:15]
	s_mov_b32 m0, s13
	s_nop 0
	global_load_lds_dwordx4 v[62:63], off
	ds_read_b128 v[60:63], v126
	ds_read_b128 v[110:113], v131
	s_waitcnt lgkmcnt(0)
	v_mfma_f32_32x32x16_bf16 v[16:31], v[60:63], v[110:113], v[16:31]
	ds_read_b128 v[110:113], v131 offset:4096
	s_waitcnt lgkmcnt(0)
	v_mfma_f32_32x32x16_bf16 v[0:15], v[60:63], v[110:113], v[0:15]
	ds_read_b128 v[60:63], v128
	ds_read_b128 v[110:113], v109
	s_waitcnt lgkmcnt(0)
	v_mfma_f32_32x32x16_bf16 v[16:31], v[60:63], v[110:113], v[16:31]
	ds_read_b128 v[110:113], v109 offset:4096
	s_waitcnt vmcnt(5)
	s_barrier
	s_waitcnt lgkmcnt(0)
	v_mfma_f32_32x32x16_bf16 v[0:15], v[60:63], v[110:113], v[0:15]
	ds_read_b128 v[60:63], v101 offset:32768
	ds_read_b128 v[110:113], v97
	ds_read_b128 v[114:117], v97 offset:4096
	s_waitcnt lgkmcnt(0)
	v_mfma_f32_32x32x16_bf16 v[16:31], v[60:63], v[110:113], v[16:31]
	v_mfma_f32_32x32x16_bf16 v[0:15], v[60:63], v[114:117], v[0:15]
	ds_read_b128 v[60:63], v102 offset:32768
	ds_read_b128 v[110:113], v98
	ds_read_b128 v[114:117], v98 offset:4096
	s_waitcnt lgkmcnt(0)
	v_mfma_f32_32x32x16_bf16 v[16:31], v[60:63], v[110:113], v[16:31]
	v_mfma_f32_32x32x16_bf16 v[0:15], v[60:63], v[114:117], v[0:15]
	ds_read_b128 v[60:63], v103 offset:32768
	ds_read_b128 v[110:113], v99
	s_waitcnt lgkmcnt(0)
	v_mfma_f32_32x32x16_bf16 v[16:31], v[60:63], v[110:113], v[16:31]
	ds_read_b128 v[110:113], v99 offset:4096
	s_waitcnt lgkmcnt(0)
	v_mfma_f32_32x32x16_bf16 v[0:15], v[60:63], v[110:113], v[0:15]
	ds_read_b128 v[60:63], v104 offset:32768
	ds_read_b128 v[110:113], v100
	s_waitcnt lgkmcnt(0)
	v_mfma_f32_32x32x16_bf16 v[16:31], v[60:63], v[110:113], v[16:31]
	ds_read_b128 v[110:113], v100 offset:4096
	s_waitcnt vmcnt(0)
	s_barrier
; #define MFMA(a, b, c) __builtin_amdgcn_mfma_f32_32x32x16_bf16((a), (b), (c), 0, 0, 0)
;     ...
;     const char* base = smem + (kt % NSTG) * STAGE;
;     const char* pa = base + (wrow_act + r) * 128;
;     const char* pw = base + ABYTES + (wrow_w + r) * 128;
;     constexpr int NM = NI * MJ;
;     constexpr int PPS = (NLD + 1) / 2;
; #pragma unroll
;     for (int s = 0; s < 4; ++s) {
;       bf16x8 af[MJ], wf[NI];
; #pragma unroll
;       for (int j = 0; j < MJ; ++j) af[j] = *(const bf16x8*)(pa + j * 32 * 128 + xo[s]);
; #pragma unroll
;       for (int i = 0; i < NI; ++i) wf[i] = *(const bf16x8*)(pw + i * 32 * 128 + xo[s]);
; #pragma unroll
;       for (int m = 0; m < NM; ++m) {
;         const int i = m / MJ, j = m % MJ;
;         acc[i][j] = MFMA(wf[i], af[j], acc[i][j]);
; DEV void phase_merge(const Params& p, int l, int hf, char* smem) {
;     ...
; #pragma unroll
;         for (int j = 0; j < 2; ++j)
; #pragma unroll
;           for (int g4 = 0; g4 < 4; ++g4) {
;             const uint2 gg = gpre[j][g4];
;             yacc[0][j][4 * g4] += acc[0][j][4 * g4] * __uint_as_float(gg.x << 16);
;             yacc[0][j][4 * g4 + 1] += acc[0][j][4 * g4 + 1] * __uint_as_float(gg.x & 0xffff0000u);
;             yacc[0][j][4 * g4 + 2] += acc[0][j][4 * g4 + 2] * __uint_as_float(gg.y << 16);
;             yacc[0][j][4 * g4 + 3] += acc[0][j][4 * g4 + 3] * __uint_as_float(gg.y & 0xffff0000u);
;           }
;       }
; #pragma unroll
;       for (int j = 0; j < 2; ++j) {
;         const size_t m = (size_t)mt * 256 + wm * 64 + 32 * j + r;
;         float v[16];
; #pragma unroll
;         for (int e = 0; e < 16; ++e) v[e] = yacc[0][j][e];
;         store_row32(Y + m * 1024 + nt64 * 64 + wn * 32, v, h);
;       }
	s_waitcnt lgkmcnt(0)
	v_mfma_f32_32x32x16_bf16 v[0:15], v[60:63], v[110:113], v[0:15]
	ds_read_b128 v[60:63], v105
	ds_read_b128 v[102:105], v97 offset:49152
	ds_read_b128 v[110:113], v97 offset:53248
	s_waitcnt lgkmcnt(0)
	v_mfma_f32_32x32x16_bf16 v[16:31], v[60:63], v[102:105], v[16:31]
	v_mfma_f32_32x32x16_bf16 v[0:15], v[60:63], v[110:113], v[0:15]
	ds_read_b128 v[60:63], v106
	ds_read_b128 v[102:105], v98 offset:49152
	ds_read_b128 v[110:113], v98 offset:53248
	s_waitcnt lgkmcnt(0)
	v_mfma_f32_32x32x16_bf16 v[16:31], v[60:63], v[102:105], v[16:31]
	v_mfma_f32_32x32x16_bf16 v[0:15], v[60:63], v[110:113], v[0:15]
	ds_read_b128 v[60:63], v99 offset:49152
	ds_read_b128 v[102:105], v99 offset:53248
	ds_read_b128 v[110:113], v107
	s_add_i32 s12, s12, -1
	s_add_u32 s10, s10, 0x400
	s_addc_u32 s11, s11, 0
	s_add_u32 s4, s4, 0x100000
	s_waitcnt lgkmcnt(0)
	v_mfma_f32_32x32x16_bf16 v[16:31], v[110:113], v[60:63], v[16:31]
	s_addc_u32 s5, s5, 0
	v_lshl_add_u64 v[40:41], v[40:41], 0, s[60:61]
	v_lshl_add_u64 v[42:43], v[42:43], 0, s[60:61]
	s_cmp_eq_u32 s12, 0
	v_mfma_f32_32x32x16_bf16 v[0:15], v[110:113], v[102:105], v[0:15]
	ds_read_b128 v[60:63], v108
	ds_read_b128 v[102:105], v100 offset:53248
	ds_read_b128 v[98:101], v100 offset:49152
	s_barrier
	s_waitcnt lgkmcnt(0)
	v_mfma_f32_32x32x16_bf16 v[16:31], v[60:63], v[98:101], v[16:31]
	v_mfma_f32_32x32x16_bf16 v[0:15], v[60:63], v[102:105], v[0:15]
	s_waitcnt vmcnt(0)
	v_lshlrev_b32_e32 v60, 16, v58
	s_nop 8
	v_fmac_f32_e32 v81, v16, v60
	v_and_b32_e32 v16, 0xffff0000, v58
	v_fmac_f32_e32 v82, v17, v16
	v_lshlrev_b32_e32 v16, 16, v59
	v_fmac_f32_e32 v83, v18, v16
	v_and_b32_e32 v16, 0xffff0000, v59
	v_fmac_f32_e32 v84, v19, v16
	v_lshlrev_b32_e32 v16, 16, v56
	v_fmac_f32_e32 v85, v20, v16
	v_and_b32_e32 v16, 0xffff0000, v56
	v_fmac_f32_e32 v86, v21, v16
	v_lshlrev_b32_e32 v16, 16, v57
	v_fmac_f32_e32 v87, v22, v16
	v_and_b32_e32 v16, 0xffff0000, v57
	v_fmac_f32_e32 v88, v23, v16
	v_lshlrev_b32_e32 v16, 16, v54
	v_fmac_f32_e32 v89, v24, v16
	v_and_b32_e32 v16, 0xffff0000, v54
	v_fmac_f32_e32 v90, v25, v16
	v_lshlrev_b32_e32 v16, 16, v55
	v_fmac_f32_e32 v91, v26, v16
	v_and_b32_e32 v16, 0xffff0000, v55
	v_fmac_f32_e32 v92, v27, v16
	v_lshlrev_b32_e32 v16, 16, v52
	v_fmac_f32_e32 v93, v28, v16
	v_and_b32_e32 v16, 0xffff0000, v52
	v_fmac_f32_e32 v94, v29, v16
	v_lshlrev_b32_e32 v16, 16, v53
	v_fmac_f32_e32 v95, v30, v16
	v_and_b32_e32 v16, 0xffff0000, v53
	v_fmac_f32_e32 v96, v31, v16
	v_lshlrev_b32_e32 v16, 16, v50
	v_fmac_f32_e32 v65, v0, v16
	v_and_b32_e32 v0, 0xffff0000, v50
	v_fmac_f32_e32 v66, v1, v0
	v_lshlrev_b32_e32 v0, 16, v51
	v_fmac_f32_e32 v67, v2, v0
	v_and_b32_e32 v0, 0xffff0000, v51
	v_fmac_f32_e32 v68, v3, v0
	v_lshlrev_b32_e32 v0, 16, v48
	v_fmac_f32_e32 v69, v4, v0
	v_and_b32_e32 v0, 0xffff0000, v48
	v_fmac_f32_e32 v70, v5, v0
	v_lshlrev_b32_e32 v0, 16, v49
	v_fmac_f32_e32 v71, v6, v0
	v_and_b32_e32 v0, 0xffff0000, v49
	v_fmac_f32_e32 v72, v7, v0
	v_lshlrev_b32_e32 v0, 16, v46
	v_fmac_f32_e32 v73, v8, v0
	v_and_b32_e32 v0, 0xffff0000, v46
	v_fmac_f32_e32 v74, v9, v0
	v_lshlrev_b32_e32 v0, 16, v47
	v_fmac_f32_e32 v75, v10, v0
	v_and_b32_e32 v0, 0xffff0000, v47
	v_fmac_f32_e32 v76, v11, v0
	v_lshlrev_b32_e32 v0, 16, v44
	v_fmac_f32_e32 v77, v12, v0
	v_and_b32_e32 v0, 0xffff0000, v44
	v_fmac_f32_e32 v78, v13, v0
	v_lshlrev_b32_e32 v0, 16, v45
	v_fmac_f32_e32 v79, v14, v0
	v_and_b32_e32 v0, 0xffff0000, v45
	v_fmac_f32_e32 v80, v15, v0
	s_cbranch_scc0 .LBB0_43
	v_readlane_b32 s2, v240, 42
	v_readlane_b32 s3, v240, 43
	v_readlane_b32 s14, v240, 7
	v_readlane_b32 s15, v240, 8
	v_lshl_add_u64 v[0:1], s[2:3], 0, v[32:33]
	s_lshl_b32 s2, s92, 7
	s_and_b32 s14, s2, 0x780
	v_lshl_add_u64 v[8:9], v[34:35], 0, s[14:15]
	v_lshlrev_b64 v[10:11], 11, v[0:1]
	v_cvt_pk_bf16_f32 v0, v81, v82
	v_cvt_pk_bf16_f32 v1, v83, v84
	v_cvt_pk_bf16_f32 v2, v85, v86
	v_cvt_pk_bf16_f32 v3, v87, v88
	v_cvt_pk_bf16_f32 v4, v89, v90
	v_cvt_pk_bf16_f32 v5, v91, v92
	v_cvt_pk_bf16_f32 v6, v93, v94
	v_cvt_pk_bf16_f32 v7, v95, v96
	v_lshl_add_u64 v[8:9], v[8:9], 0, v[10:11]
	v_permlane32_swap_b32_e32 v0, v2
	v_permlane32_swap_b32_e32 v1, v3
	v_permlane32_swap_b32_e32 v4, v6
	v_permlane32_swap_b32_e32 v5, v7
	s_mov_b32 s2, 0x10000
	flat_store_dwordx4 v[8:9], v[0:3]
	flat_store_dwordx4 v[8:9], v[4:7] offset:32
	v_add_co_u32_e32 v8, vcc, s2, v8
	v_readlane_b32 s2, v240, 37
	s_add_i32 s92, s92, s2
	v_readlane_b32 s3, v240, 40
	v_readlane_b32 s2, v240, 35
	v_cvt_pk_bf16_f32 v0, v65, v66
	v_cvt_pk_bf16_f32 v1, v67, v68
	v_cvt_pk_bf16_f32 v2, v69, v70
	v_cvt_pk_bf16_f32 v3, v71, v72
	v_cvt_pk_bf16_f32 v4, v73, v74
	v_cvt_pk_bf16_f32 v5, v75, v76
	v_cvt_pk_bf16_f32 v6, v77, v78
	v_cvt_pk_bf16_f32 v7, v79, v80
	s_add_i32 s3, s3, s2
	s_movk_i32 s80, 0xc00
	v_permlane32_swap_b32_e32 v0, v2
	v_permlane32_swap_b32_e32 v1, v3
	v_addc_co_u32_e32 v9, vcc, 0, v9, vcc
	v_permlane32_swap_b32_e32 v4, v6
	v_permlane32_swap_b32_e32 v5, v7
	s_cmp_gt_i32 s92, 31
	flat_store_dwordx4 v[8:9], v[0:3]
	flat_store_dwordx4 v[8:9], v[4:7] offset:32
	s_cbranch_scc0 .LBB0_42

; template <int DQK, int DV, int NKH, int MODE>
; DEV void flash_unit(const FlashArgs& fa, char* smem, f32x16 (&oacc)[DV / 32], float& linv_out) {
;     ...
;   bf16x8 qf[NS];
;   {
;     const u16* qp = (kh ? fa.Q1 : fa.Q0) + (size_t)(fa.q_t0 + qsub * 32 + r) * DQK + 8 * h;
; #pragma unroll
;     for (int s = 0; s < NS; ++s) qf[s] = *(const bf16x8*)(qp + 16 * s);
;   }
;   int na_row = 0, na_rs = 0, na_qc = 0, na_cstart = 0;
;   if (MODE == 1) {
;     na_row = fa.r0 + (w >> 1);
;     na_rs = min(max(na_row - 4, 0), 120);
;     na_qc = (w & 1) * 32 + r;
;     na_cstart = min(max(na_qc - 8, 0), 48);
;     for (int i = tid; i < 15 * 31; i += 512) rpbs[i] = fa.rpb[i] * LOG2E;
;   }
; #pragma unroll
;   for (int v = 0; v < NV; ++v)
; #pragma unroll
;     for (int e = 0; e < 16; ++e) oacc[v][e] = 0.f;
;   float mrun = 0.f;
;   f32x16 negm;
; #pragma unroll
;   for (int e = 0; e < 16; ++e) negm[e] = 0.f;
;   float lrun = 0.f;
;   const int kx = (r >> 1) & 7;
;   int kxo[4];
; #pragma unroll
;   for (int s = 0; s < 4; ++s) kxo[s] = (((2 * s + h) ^ kx) << 4);
;   const int k32x = (r >> 2) & 3;
;   const int blk = (lane >> 4) & 1, i16 = lane & 15, q4 = i16 >> 2, p4 = i16 & 3;
;   int vlow0, vlow1, vhi[NV];
;   if (DV == 64) {
;     vlow0 = (4 * h + q4) * 128 + (blk * 2 + (p4 >> 1)) * 16 + (p4 & 1) * 8;
;     vlow1 = vlow0;
; #pragma unroll
;     for (int v = 0; v < NV; ++v) vhi[v] = ((v ^ ((q4 >> 1) & 1)) * 64);
;   } else {
;     vlow0 = (4 * h + q4) * 256 + (((blk * 2 + (p4 >> 1)) ^ (h)) * 16) + (p4 & 1) * 8;
;     vlow1 = (4 * h + q4) * 256 + (((blk * 2 + (p4 >> 1)) ^ (2 + h)) * 16) + (p4 & 1) * 8;
; #pragma unroll
;     for (int v = 0; v < NV; ++v) vhi[v] = ((v ^ q4) * 64);
;   }
;   constexpr int VROW = DV * 2;
;   asm volatile("s_waitcnt vmcnt(0)" ::: "memory");
;   issue(0);
;   issue(1);
;   issue(2);
;   for (int it = 0; it < fa.n_tiles; ++it) {
;     {
;       const int newer = min(2, fa.n_tiles - 1 - it) * nld;
;       if (newer >= 8) asm volatile("s_waitcnt vmcnt(8)" ::: "memory");
;       else if (newer == 6) asm volatile("s_waitcnt vmcnt(6)" ::: "memory");
;       else if (newer == 4) asm volatile("s_waitcnt vmcnt(4)" ::: "memory");
;       else if (newer == 3) asm volatile("s_waitcnt vmcnt(3)" ::: "memory");
;       else if (newer == 2) asm volatile("s_waitcnt vmcnt(2)" ::: "memory");
;       else asm volatile("s_waitcnt vmcnt(0)" ::: "memory");
;     }
.LBB0_71:
	s_or_b64 exec, exec, s[2:3]
	v_lshlrev_b32_e32 v16, 10, v4
	v_lshlrev_b32_e32 v4, 5, v4
	v_and_b32_e32 v15, 31, v2
	s_movk_i32 s2, 0x100
	v_and_b32_e32 v4, 0x60, v4
	s_add_u32 s0, s38, s0
	v_cmp_gt_u32_e32 vcc, s2, v2
	v_add3_u32 v12, v15, s9, v4
	s_addc_u32 s1, s39, s1
	v_cndmask_b32_e64 v10, v174, 0, vcc
	v_mov_b32_e32 v11, v145
	v_ashrrev_i32_e32 v13, 31, v12
	v_lshrrev_b32_e32 v14, 5, v3
	v_lshl_add_u64 v[10:11], s[0:1], 0, v[10:11]
	v_lshlrev_b64 v[12:13], 7, v[12:13]
	v_lshl_add_u64 v[10:11], v[10:11], 0, v[12:13]
	v_lshlrev_b32_e32 v12, 4, v14
	v_mov_b32_e32 v13, v145
	v_lshl_add_u64 v[10:11], v[10:11], 0, v[12:13]
	s_mov_b64 s[0:1], 0xbcd6100
	v_lshl_add_u64 v[12:13], v[10:11], 0, s[0:1]
	s_mov_b32 s0, 0xbcd6000
	v_add3_u32 v183, 0, v16, v5
	v_mov_b32_e32 v99, v145
	v_add_co_u32_e32 v10, vcc, s0, v10
	v_readfirstlane_b32 s0, v183
	v_add_u32_e32 v4, 0x2000, v183
	v_mov_b32_e32 v103, v145
	v_lshl_add_u64 v[8:9], v[96:97], 0, v[98:99]
	v_addc_co_u32_e32 v11, vcc, 0, v11, vcc
	flat_load_dwordx4 v[112:115], v[12:13] offset:32
	flat_load_dwordx4 v[116:119], v[12:13] offset:64
	flat_load_dwordx4 v[120:123], v[10:11] offset:256
	flat_load_dwordx4 v[124:127], v[12:13] offset:96
	s_mov_b32 m0, s0
	v_readfirstlane_b32 s0, v4
	v_add_u32_e32 v4, 0x4000, v183
	v_lshl_add_u64 v[6:7], v[100:101], 0, v[102:103]
	global_load_lds_dwordx4 v[8:9], off
	s_mov_b32 m0, s0
	v_readfirstlane_b32 s0, v4
	v_add_u32_e32 v4, 0x6000, v183
	v_lshl_add_u64 v[0:1], v[104:105], 0, v[144:145]
	v_mov_b32_e32 v109, v145
	global_load_lds_dwordx4 v[6:7], off
	s_mov_b32 m0, s0
	v_readfirstlane_b32 s0, v4
	v_add_u32_e32 v12, 0x8000, v183
	v_lshl_add_u64 v[10:11], v[106:107], 0, v[108:109]
	global_load_lds_dwordx4 v[0:1], off
	s_mov_b32 m0, s0
	v_lshl_add_u64 v[4:5], v[8:9], 0, v[148:149]
	v_readfirstlane_b32 s0, v12
	v_add_u32_e32 v8, 0xa000, v183
	global_load_lds_dwordx4 v[10:11], off
	s_mov_b32 m0, s0
	v_readfirstlane_b32 s0, v8
	v_add_u32_e32 v8, 0xc000, v183
	global_load_lds_dwordx4 v[4:5], off
	v_lshl_add_u64 v[6:7], v[6:7], 0, v[150:151]
	s_mov_b32 m0, s0
	v_readfirstlane_b32 s0, v8
	v_add_u32_e32 v12, 0xe000, v183
	global_load_lds_dwordx4 v[6:7], off
	v_lshl_add_u64 v[0:1], v[0:1], 0, v[152:153]
	s_mov_b32 m0, s0
	v_lshl_add_u64 v[8:9], v[10:11], 0, v[154:155]
	v_readfirstlane_b32 s0, v12
	v_add_u32_e32 v10, 0x10000, v183
	global_load_lds_dwordx4 v[0:1], off
	s_mov_b32 m0, s0
	v_lshl_add_u64 v[44:45], v[4:5], 0, v[148:149]
	v_readfirstlane_b32 s0, v10
	v_add_u32_e32 v4, 0x12000, v183
	global_load_lds_dwordx4 v[8:9], off
	s_mov_b32 m0, s0
	v_readfirstlane_b32 s0, v4
	v_add_u32_e32 v4, 0x14000, v183
	global_load_lds_dwordx4 v[44:45], off
	v_lshl_add_u64 v[46:47], v[6:7], 0, v[150:151]
	s_mov_b32 m0, s0
	v_lshl_add_u64 v[48:49], v[0:1], 0, v[152:153]
	v_readfirstlane_b32 s0, v4
	v_add_u32_e32 v0, 0x16000, v183
	global_load_lds_dwordx4 v[46:47], off
	s_mov_b32 m0, s0
	v_readfirstlane_b32 s0, v0
	global_load_lds_dwordx4 v[48:49], off
	v_lshl_add_u64 v[50:51], v[8:9], 0, v[154:155]
	s_mov_b32 m0, s0
	v_lshrrev_b32_e32 v0, 1, v2
	global_load_lds_dwordx4 v[50:51], off
	v_bitop3_b32 v0, v14, v0, 7 bitop3:0x78
	v_lshrrev_b32_e32 v5, 3, v2
	v_lshlrev_b32_e32 v184, 4, v0
	v_or_b32_e32 v0, 2, v14
	v_and_b32_e32 v5, 2, v5
	v_bfe_u32 v6, v2, 1, 1
	v_bfe_u32 v1, v2, 1, 3
	v_bitop3_b32 v7, v5, v14, v6 bitop3:0x36
	v_bitop3_b32 v5, v5, v0, v6 bitop3:0x36
	v_lshlrev_b32_e32 v0, 5, v2
	v_bitop3_b32 v4, v14, v1, 2 bitop3:0x36
	v_and_b32_e32 v192, 0xffffe000, v0
	v_lshlrev_b32_e32 v193, 7, v15
	v_lshlrev_b32_e32 v185, 4, v4
	v_bitop3_b32 v4, v14, v1, 4 bitop3:0x36
	v_bitop3_b32 v1, v14, v1, 6 bitop3:0x36
	v_add3_u32 v0, 0, v192, v193
	v_lshlrev_b32_e32 v186, 4, v4
	v_lshlrev_b32_e32 v187, 4, v1
	v_bfe_u32 v1, v2, 2, 2
	v_add_u32_e32 v6, v0, v184
	v_lshlrev_b32_e32 v4, 8, v1
	v_lshlrev_b32_e32 v8, 3, v3
	v_lshlrev_b32_e32 v188, 6, v1
	s_waitcnt vmcnt(8)
	s_barrier
	v_add_u32_e32 v9, v0, v185
	v_add_u32_e32 v10, v0, v186
	v_add_u32_e32 v11, v0, v187
	ds_read_b128 v[0:3], v6
	ds_read_b128 v[16:19], v6 offset:4096
	ds_read_b128 v[20:23], v9
	ds_read_b128 v[32:35], v9 offset:4096
	ds_read_b128 v[24:27], v10
	ds_read_b128 v[36:39], v10 offset:4096
	ds_read_b128 v[28:31], v11
	ds_read_b128 v[40:43], v11 offset:4096
	s_mov_b32 s17, 0
	s_mov_b32 s4, 4
	v_xor_b32_e32 v189, 64, v188
	v_xor_b32_e32 v190, 0x80, v188
	v_xor_b32_e32 v191, 0xc0, v188
	v_lshl_or_b32 v194, v14, 10, v4
	v_lshlrev_b32_e32 v195, 4, v7
	v_and_b32_e32 v196, 8, v8
	v_lshlrev_b32_e32 v197, 4, v5
	s_waitcnt lgkmcnt(0)
; template <int DQK, int DV, int NKH, int MODE>
; DEV void flash_unit(const FlashArgs& fa, char* smem, f32x16 (&oacc)[DV / 32], float& linv_out) {
;     ...
;       for (int k2 = 0; k2 < 2; ++k2) {
; #pragma unroll
;         for (int s = 0; s < NS; ++s) {
;           const bf16x8 kf = kfr[k2][s];
;           if (s == 0) st[k2] = MFMA(kf, qf[s], negm);
;           else st[k2] = MFMA(kf, qf[s], st[k2]);
;           constexpr int NQK = 2 * NS, EVERY = NQK / LPT;
;           const int m = k2 * NS + s;
;           if ((m + 1) % EVERY == 0 && (m + 1) / EVERY <= LPT) {
;             __builtin_amdgcn_sched_barrier(0);
;             if (pre) issue_piece(it + 3, (m + 1) / EVERY - 1);
;             __builtin_amdgcn_sched_barrier(0);
;           }
;         }
;       }
;     ...
;       float rel = st[0][0];
; #pragma unroll
;       for (int e = 1; e < 16; ++e) rel = fmaxf(rel, st[0][e]);
; #pragma unroll
;       for (int e = 0; e < 16; ++e) rel = fmaxf(rel, st[1][e]);
;       rel = half_max(rel);
;       const bool first = (it == 0);
;       if (first || __builtin_amdgcn_ballot_w64(rel > 8.f) != 0) {
;         const float d = first ? rel : fmaxf(rel, 0.f);
;         const float alpha = fast_exp2(-d);
;         mrun += d;
; #pragma unroll
;         for (int k2 = 0; k2 < 2; ++k2)
; #pragma unroll
;           for (int e = 0; e < 16; ++e) st[k2][e] -= d;
; #pragma unroll
;         for (int v = 0; v < NV; ++v)
; #pragma unroll
;           for (int e = 0; e < 16; ++e) oacc[v][e] *= alpha;
; #pragma unroll
;         for (int e = 0; e < 16; ++e) negm[e] = -mrun;
;         lrun *= alpha;
;       }
;       float psum = 0.f;
; #pragma unroll
;       for (int k2 = 0; k2 < 2; ++k2)
; #pragma unroll
;         for (int e = 0; e < 16; ++e) { st[k2][e] = fast_exp2(st[k2][e]); psum += st[k2][e]; }
;       lrun += psum;
;       bf16x8 pf[2][2];
; #pragma unroll
;       for (int k2 = 0; k2 < 2; ++k2)
; #pragma unroll
;         for (int s2 = 0; s2 < 2; ++s2) {
;           uint4 u = make_uint4(pk2(st[k2][8 * s2], st[k2][8 * s2 + 1]), pk2(st[k2][8 * s2 + 2], st[k2][8 * s2 + 3]),
;                                pk2(st[k2][8 * s2 + 4], st[k2][8 * s2 + 5]), pk2(st[k2][8 * s2 + 6], st[k2][8 * s2 + 7]));
;           pf[k2][s2] = __builtin_bit_cast(bf16x8, u);
;         }
; #pragma unroll
;       for (int v = 0; v < NV; ++v)
; #pragma unroll
;         for (int k2 = 0; k2 < 2; ++k2)
; #pragma unroll
	v_mfma_f32_32x32x16_bf16 v[0:15], v[0:3], v[120:123], 0
	v_add_u32_e32 v52, 0x1e000, v183
	v_add_u32_e32 v53, 0x1c000, v183
	v_add_u32_e32 v54, 0x1a000, v183
	v_mfma_f32_32x32x16_bf16 v[0:15], v[20:23], v[112:115], v[0:15]
	v_add_u32_e32 v22, 0x18000, v183
	v_lshl_add_u64 v[20:21], v[44:45], 0, v[148:149]
	v_readfirstlane_b32 s0, v22
	s_mov_b32 m0, s0
	s_nop 0
	global_load_lds_dwordx4 v[20:21], off
	v_mfma_f32_32x32x16_bf16 v[0:15], v[24:27], v[116:119], v[0:15]
	v_mfma_f32_32x32x16_bf16 v[0:15], v[28:31], v[124:127], v[0:15]
	v_readfirstlane_b32 s0, v54
	v_lshl_add_u64 v[20:21], v[46:47], 0, v[150:151]
	s_mov_b32 m0, s0
	s_nop 0
	global_load_lds_dwordx4 v[20:21], off
	v_mfma_f32_32x32x16_bf16 v[16:31], v[16:19], v[120:123], 0
	v_mfma_f32_32x32x16_bf16 v[16:31], v[32:35], v[112:115], v[16:31]
	v_readfirstlane_b32 s0, v53
	v_lshl_add_u64 v[32:33], v[48:49], 0, v[152:153]
	s_mov_b32 m0, s0
	s_nop 0
	global_load_lds_dwordx4 v[32:33], off
	v_mfma_f32_32x32x16_bf16 v[16:31], v[36:39], v[116:119], v[16:31]
	v_mfma_f32_32x32x16_bf16 v[16:31], v[40:43], v[124:127], v[16:31]
	v_readfirstlane_b32 s0, v52
	v_lshl_add_u64 v[32:33], v[50:51], 0, v[154:155]
	s_mov_b32 m0, s0
	s_nop 0
	global_load_lds_dwordx4 v[32:33], off
	v_max_f32_e32 v32, v1, v1
	v_max_f32_e32 v33, v0, v0
	v_max_f32_e32 v32, v33, v32
	v_max3_f32 v32, v32, v2, v3
	v_max3_f32 v32, v32, v4, v5
	v_max3_f32 v32, v32, v6, v7
	v_max3_f32 v32, v32, v8, v9
	v_max3_f32 v32, v32, v10, v11
	v_max3_f32 v32, v32, v12, v13
	v_max3_f32 v32, v32, v14, v15
	v_max3_f32 v32, v32, v16, v17
	v_max3_f32 v32, v32, v18, v19
	v_max3_f32 v32, v32, v20, v21
	v_max3_f32 v32, v32, v22, v23
	v_max3_f32 v32, v32, v24, v25
	v_max3_f32 v32, v32, v26, v27
	v_max3_f32 v32, v32, v28, v29
	v_max3_f32 v32, v32, v30, v31
	v_mov_b32_e32 v33, v32
	s_nop 1
	v_permlane32_swap_b32_e32 v32, v33
	v_max_f32_e32 v33, v33, v33
	v_max_f32_e32 v32, v32, v32
	v_max_f32_e32 v110, v32, v33
	v_sub_f32_e32 v0, v0, v110
	v_sub_f32_e32 v4, v4, v110
	v_exp_f32_e32 v111, v0
	v_add3_u32 v0, 0, v188, v194
	v_exp_f32_e64 v32, -v110
	v_sub_f32_e32 v1, v1, v110
	v_sub_f32_e32 v2, v2, v110
	v_sub_f32_e32 v3, v3, v110
	v_sub_f32_e32 v5, v5, v110
	v_sub_f32_e32 v6, v6, v110
	v_sub_f32_e32 v7, v7, v110
	v_exp_f32_e32 v131, v4
	v_add3_u32 v4, v0, v195, v196
	v_exp_f32_e32 v128, v1
	v_exp_f32_e32 v129, v2
	v_exp_f32_e32 v130, v3
	v_exp_f32_e32 v132, v5
	v_exp_f32_e32 v133, v6
	v_exp_f32_e32 v134, v7
	v_add3_u32 v5, v0, v197, v196
	ds_read_b64_tr_b16 v[0:1], v4 offset:16384
	ds_read_b64_tr_b16 v[2:3], v5 offset:18432
	v_mul_f32_e32 v64, 0, v32
	v_mov_b32_e32 v65, v64
	v_mov_b32_e32 v66, v64
	v_mov_b32_e32 v67, v64
	v_mov_b32_e32 v68, v64
	v_mov_b32_e32 v69, v64
	v_mov_b32_e32 v70, v64
	v_mov_b32_e32 v71, v64
	v_mov_b32_e32 v72, v64
	v_mov_b32_e32 v73, v64
	v_mov_b32_e32 v74, v64
	v_mov_b32_e32 v75, v64
	v_mov_b32_e32 v76, v64
	v_mov_b32_e32 v77, v64
	v_mov_b32_e32 v78, v64
	v_mov_b32_e32 v79, v64
	v_cvt_pk_bf16_f32 v92, v111, v128
	v_cvt_pk_bf16_f32 v93, v129, v130
	v_cvt_pk_bf16_f32 v94, v131, v132
	v_cvt_pk_bf16_f32 v95, v133, v134
	v_sub_f32_e32 v8, v8, v110
	v_sub_f32_e32 v9, v9, v110
	s_waitcnt lgkmcnt(0)
	v_mfma_f32_32x32x16_bf16 v[32:47], v[0:3], v[92:95], v[64:79]
	v_sub_f32_e32 v10, v10, v110
	v_sub_f32_e32 v11, v11, v110
	v_sub_f32_e32 v12, v12, v110
	v_sub_f32_e32 v13, v13, v110
	v_sub_f32_e32 v14, v14, v110
	v_sub_f32_e32 v15, v15, v110
	v_exp_f32_e32 v135, v8
	v_exp_f32_e32 v136, v9
	v_exp_f32_e32 v137, v10
	v_exp_f32_e32 v138, v11
	v_exp_f32_e32 v139, v12
	v_exp_f32_e32 v140, v13
	v_exp_f32_e32 v141, v14
	v_exp_f32_e32 v142, v15
	ds_read_b64_tr_b16 v[0:1], v4 offset:20480
	ds_read_b64_tr_b16 v[2:3], v5 offset:22528
	v_cvt_pk_bf16_f32 v88, v135, v136
	v_cvt_pk_bf16_f32 v89, v137, v138
	v_cvt_pk_bf16_f32 v90, v139, v140
	v_cvt_pk_bf16_f32 v91, v141, v142
	v_sub_f32_e32 v16, v16, v110
	v_sub_f32_e32 v17, v17, v110
	s_waitcnt lgkmcnt(0)
	v_mfma_f32_32x32x16_bf16 v[32:47], v[0:3], v[88:91], v[32:47]
	v_sub_f32_e32 v18, v18, v110
	v_sub_f32_e32 v19, v19, v110
	v_sub_f32_e32 v20, v20, v110
	v_sub_f32_e32 v21, v21, v110
	v_sub_f32_e32 v22, v22, v110
	v_sub_f32_e32 v23, v23, v110
	v_exp_f32_e32 v143, v16
	v_exp_f32_e32 v156, v17
	v_exp_f32_e32 v157, v18
	v_exp_f32_e32 v158, v19
	v_exp_f32_e32 v159, v20
	v_exp_f32_e32 v160, v21
	v_exp_f32_e32 v161, v22
	v_exp_f32_e32 v162, v23
	ds_read_b64_tr_b16 v[0:1], v4 offset:24576
	ds_read_b64_tr_b16 v[2:3], v5 offset:26624
	v_cvt_pk_bf16_f32 v84, v143, v156
	v_cvt_pk_bf16_f32 v85, v157, v158
	v_cvt_pk_bf16_f32 v86, v159, v160
	v_cvt_pk_bf16_f32 v87, v161, v162
	v_sub_f32_e32 v24, v24, v110
	v_sub_f32_e32 v25, v25, v110
	s_waitcnt lgkmcnt(0)
	v_mfma_f32_32x32x16_bf16 v[32:47], v[0:3], v[84:87], v[32:47]
	v_sub_f32_e32 v26, v26, v110
	v_sub_f32_e32 v27, v27, v110
	v_sub_f32_e32 v28, v28, v110
	v_sub_f32_e32 v29, v29, v110
	v_sub_f32_e32 v30, v30, v110
	v_sub_f32_e32 v31, v31, v110
	v_exp_f32_e32 v163, v24
	v_exp_f32_e32 v164, v25
	v_exp_f32_e32 v165, v26
	v_exp_f32_e32 v198, v27
	v_exp_f32_e32 v199, v28
	v_exp_f32_e32 v200, v29
	v_exp_f32_e32 v201, v30
	v_exp_f32_e32 v202, v31
	ds_read_b64_tr_b16 v[0:1], v4 offset:28672
	ds_read_b64_tr_b16 v[2:3], v5 offset:30720
	v_cvt_pk_bf16_f32 v80, v163, v164
	v_cvt_pk_bf16_f32 v81, v165, v198
	v_cvt_pk_bf16_f32 v82, v199, v200
	v_cvt_pk_bf16_f32 v83, v201, v202
	s_lshl_b32 s13, s11, 15
	s_add_i32 s5, s13, 0xffff8000
	s_waitcnt lgkmcnt(0)
; #define MFMA(a, b, c) __builtin_amdgcn_mfma_f32_32x32x16_bf16((a), (b), (c), 0, 0, 0)
; DEV float fast_exp2(float x) { return __builtin_amdgcn_exp2f(x); }
; template <int DQK, int DV, int NKH, int MODE>
; DEV void flash_unit(const FlashArgs& fa, char* smem, f32x16 (&oacc)[DV / 32], float& linv_out) {
;     ...
;         for (int e = 0; e < 16; ++e) negm[e] = -mrun;
;         lrun *= alpha;
;       }
;       float psum = 0.f;
; #pragma unroll
;       for (int k2 = 0; k2 < 2; ++k2)
; #pragma unroll
;         for (int e = 0; e < 16; ++e) { st[k2][e] = fast_exp2(st[k2][e]); psum += st[k2][e]; }
;       lrun += psum;
;       bf16x8 pf[2][2];
; #pragma unroll
;       for (int k2 = 0; k2 < 2; ++k2)
; #pragma unroll
;         for (int s2 = 0; s2 < 2; ++s2) {
;           uint4 u = make_uint4(pk2(st[k2][8 * s2], st[k2][8 * s2 + 1]), pk2(st[k2][8 * s2 + 2], st[k2][8 * s2 + 3]),
;                                pk2(st[k2][8 * s2 + 4], st[k2][8 * s2 + 5]), pk2(st[k2][8 * s2 + 6], st[k2][8 * s2 + 7]));
;           pf[k2][s2] = __builtin_bit_cast(bf16x8, u);
;         }
; #pragma unroll
;       for (int v = 0; v < NV; ++v)
; #pragma unroll
;         for (int k2 = 0; k2 < 2; ++k2)
; #pragma unroll
;           for (int s2 = 0; s2 < 2; ++s2) {
;             const char* a1 = vb + (k2 * 32 + s2 * 16) * VROW + vhi[v] + vlow0;
;             const char* a2 = vb + (k2 * 32 + s2 * 16 + 8) * VROW + vhi[v] + vlow1;
;             s16x4 lo = __builtin_amdgcn_ds_read_tr16_b64_v4i16((__attribute__((address_space(3))) s16x4*)(a1));
;             s16x4 hi = __builtin_amdgcn_ds_read_tr16_b64_v4i16((__attribute__((address_space(3))) s16x4*)(a2));
;             const bf16x8 vf = __builtin_shufflevector(lo, hi, 0, 1, 2, 3, 4, 5, 6, 7);
;             oacc[v] = MFMA(vf, pf[k2][s2], oacc[v]);
;           }
	v_mfma_f32_32x32x16_bf16 v[32:47], v[0:3], v[80:83], v[32:47]
	v_add3_u32 v0, 0, v189, v194
	v_add3_u32 v4, v0, v195, v196
	v_add3_u32 v5, v0, v197, v196
	ds_read_b64_tr_b16 v[0:1], v4 offset:16384
	ds_read_b64_tr_b16 v[2:3], v5 offset:18432
	s_add_i32 s13, s13, 0xfffe8000
	s_add_i32 s14, s11, -2
	s_waitcnt lgkmcnt(0)
	v_mfma_f32_32x32x16_bf16 v[48:63], v[0:3], v[92:95], v[64:79]
	ds_read_b64_tr_b16 v[0:1], v4 offset:20480
	ds_read_b64_tr_b16 v[2:3], v5 offset:22528
	s_waitcnt lgkmcnt(0)
	v_mfma_f32_32x32x16_bf16 v[48:63], v[0:3], v[88:91], v[48:63]
	ds_read_b64_tr_b16 v[0:1], v4 offset:24576
	ds_read_b64_tr_b16 v[2:3], v5 offset:26624
	s_waitcnt lgkmcnt(0)
	v_mfma_f32_32x32x16_bf16 v[48:63], v[0:3], v[84:87], v[48:63]
	ds_read_b64_tr_b16 v[0:1], v4 offset:28672
	ds_read_b64_tr_b16 v[2:3], v5 offset:30720
	s_waitcnt lgkmcnt(0)
	v_mfma_f32_32x32x16_bf16 v[48:63], v[0:3], v[80:83], v[48:63]
	v_add3_u32 v0, 0, v190, v194
	v_add3_u32 v4, v0, v195, v196
	v_add3_u32 v5, v0, v197, v196
	ds_read_b64_tr_b16 v[0:1], v4 offset:16384
	ds_read_b64_tr_b16 v[2:3], v5 offset:18432
	s_waitcnt lgkmcnt(0)
	v_mfma_f32_32x32x16_bf16 v[16:31], v[0:3], v[92:95], v[64:79]
	ds_read_b64_tr_b16 v[0:1], v4 offset:20480
	ds_read_b64_tr_b16 v[2:3], v5 offset:22528
	s_waitcnt lgkmcnt(0)
	v_mfma_f32_32x32x16_bf16 v[16:31], v[0:3], v[88:91], v[16:31]
	ds_read_b64_tr_b16 v[0:1], v4 offset:24576
	ds_read_b64_tr_b16 v[2:3], v5 offset:26624
	s_waitcnt lgkmcnt(0)
	v_mfma_f32_32x32x16_bf16 v[16:31], v[0:3], v[84:87], v[16:31]
	ds_read_b64_tr_b16 v[0:1], v4 offset:28672
	ds_read_b64_tr_b16 v[2:3], v5 offset:30720
	s_waitcnt lgkmcnt(0)
	v_mfma_f32_32x32x16_bf16 v[16:31], v[0:3], v[80:83], v[16:31]
	v_add3_u32 v0, 0, v191, v194
	v_add3_u32 v203, v0, v195, v196
	v_add3_u32 v208, v0, v197, v196
	v_mov_b64_e32 v[0:1], v[64:65]
	v_mov_b64_e32 v[2:3], v[66:67]
	v_mov_b64_e32 v[4:5], v[68:69]
	v_mov_b64_e32 v[6:7], v[70:71]
	v_mov_b64_e32 v[8:9], v[72:73]
	v_mov_b64_e32 v[10:11], v[74:75]
	v_mov_b64_e32 v[12:13], v[76:77]
	v_mov_b64_e32 v[14:15], v[78:79]
	v_add_f32_e32 v65, 0, v111
	v_add_f32_e32 v65, v128, v65
	ds_read_b64_tr_b16 v[204:205], v203 offset:16384
	ds_read_b64_tr_b16 v[206:207], v208 offset:18432
	v_add_f32_e32 v65, v129, v65
	v_add_f32_e32 v65, v130, v65
	v_add_f32_e32 v65, v131, v65
	v_add_f32_e32 v65, v132, v65
	v_add_f32_e32 v65, v133, v65
	s_waitcnt lgkmcnt(0)
	v_mfma_f32_32x32x16_bf16 v[0:15], v[204:207], v[92:95], v[0:15]
	v_add_f32_e32 v65, v134, v65
	v_add_f32_e32 v65, v135, v65
	v_add_f32_e32 v65, v136, v65
	ds_read_b64_tr_b16 v[66:67], v203 offset:20480
	ds_read_b64_tr_b16 v[68:69], v208 offset:22528
	v_add_f32_e32 v65, v137, v65
	v_add_f32_e32 v65, v138, v65
	v_add_f32_e32 v65, v139, v65
	v_add_f32_e32 v65, v140, v65
	v_add_f32_e32 v65, v141, v65
	s_waitcnt lgkmcnt(0)
	v_mfma_f32_32x32x16_bf16 v[0:15], v[66:69], v[88:91], v[0:15]
	v_add_f32_e32 v65, v142, v65
	v_add_f32_e32 v65, v143, v65
	v_add_f32_e32 v65, v156, v65
	ds_read_b64_tr_b16 v[66:67], v203 offset:24576
	ds_read_b64_tr_b16 v[68:69], v208 offset:26624
	v_add_f32_e32 v65, v157, v65
	v_add_f32_e32 v65, v158, v65
	v_add_f32_e32 v65, v159, v65
	v_add_f32_e32 v65, v160, v65
	v_add_f32_e32 v65, v161, v65
	s_waitcnt lgkmcnt(0)
	v_mfma_f32_32x32x16_bf16 v[0:15], v[66:69], v[84:87], v[0:15]
	v_add_f32_e32 v65, v162, v65
	v_add_f32_e32 v65, v163, v65
	v_add_f32_e32 v65, v164, v65
	ds_read_b64_tr_b16 v[66:67], v203 offset:28672
	ds_read_b64_tr_b16 v[68:69], v208 offset:30720
	v_add_f32_e32 v65, v165, v65
	v_add_f32_e32 v65, v198, v65
	v_add_f32_e32 v65, v199, v65
	v_add_f32_e32 v65, v200, v65
	v_add_f32_e32 v65, v201, v65
	s_waitcnt lgkmcnt(0)
	v_mfma_f32_32x32x16_bf16 v[0:15], v[66:69], v[80:83], v[0:15]
	v_add_f32_e32 v66, v202, v65
	v_mov_b32_e32 v65, v110
	v_mov_b32_e32 v67, v145
	v_add_f32_e64 v156, v64, v66
	v_add_f32_e64 v157, v65, v67
	v_lshlrev_b32_e32 v66, 2, v154
	v_lshl_add_u64 v[66:67], v[66:67], 0, v[108:109]
	v_lshl_add_u64 v[158:159], v[106:107], 0, v[66:67]
	v_lshlrev_b32_e32 v66, 2, v152
	v_mov_b32_e32 v67, v145
	v_lshl_add_u64 v[66:67], v[66:67], 0, v[144:145]
	v_lshlrev_b32_e32 v144, 2, v150
	v_lshl_add_u64 v[160:161], v[104:105], 0, v[66:67]
	v_lshl_add_u64 v[66:67], v[144:145], 0, v[102:103]
	v_lshlrev_b32_e32 v144, 2, v148
	v_xor_b32_e32 v64, 0x80000000, v157
	v_lshl_add_u64 v[162:163], v[100:101], 0, v[66:67]
	v_lshl_add_u64 v[66:67], v[144:145], 0, v[98:99]
	v_lshl_add_u64 v[164:165], v[96:97], 0, v[66:67]
	v_mov_b32_e32 v65, v64
	v_mov_b32_e32 v66, v64
	v_mov_b32_e32 v67, v64
	v_mov_b32_e32 v68, v64
	v_mov_b32_e32 v69, v64
	v_mov_b32_e32 v70, v64
	v_mov_b32_e32 v71, v64
	v_mov_b32_e32 v72, v64
	v_mov_b32_e32 v73, v64
	v_mov_b32_e32 v74, v64
	v_mov_b32_e32 v75, v64
	v_mov_b32_e32 v76, v64
	v_mov_b32_e32 v77, v64
	v_mov_b32_e32 v78, v64
	v_mov_b32_e32 v79, v64
	s_cmp_lt_i32 s14, 2
	s_mov_b64 s[0:1], -1
	s_cbranch_scc0 .LBB0_78
	s_branch .LBB0_73

; template <int DQK, int DV, int NKH, int MODE>
; DEV void flash_unit(const FlashArgs& fa, char* smem, f32x16 (&oacc)[DV / 32], float& linv_out) {
;     ...
;   bf16x8 qf[NS];
;   {
;     const u16* qp = (kh ? fa.Q1 : fa.Q0) + (size_t)(fa.q_t0 + qsub * 32 + r) * DQK + 8 * h;
; #pragma unroll
;     for (int s = 0; s < NS; ++s) qf[s] = *(const bf16x8*)(qp + 16 * s);
;   }
;   int na_row = 0, na_rs = 0, na_qc = 0, na_cstart = 0;
;   if (MODE == 1) {
;     na_row = fa.r0 + (w >> 1);
;     na_rs = min(max(na_row - 4, 0), 120);
;     na_qc = (w & 1) * 32 + r;
;     na_cstart = min(max(na_qc - 8, 0), 48);
;     for (int i = tid; i < 15 * 31; i += 512) rpbs[i] = fa.rpb[i] * LOG2E;
;   }
; #pragma unroll
;   for (int v = 0; v < NV; ++v)
; #pragma unroll
;     for (int e = 0; e < 16; ++e) oacc[v][e] = 0.f;
;   float mrun = 0.f;
;   f32x16 negm;
; #pragma unroll
;   for (int e = 0; e < 16; ++e) negm[e] = 0.f;
;   float lrun = 0.f;
;   const int kx = (r >> 1) & 7;
;   int kxo[4];
; #pragma unroll
;   for (int s = 0; s < 4; ++s) kxo[s] = (((2 * s + h) ^ kx) << 4);
;   const int k32x = (r >> 2) & 3;
;   const int blk = (lane >> 4) & 1, i16 = lane & 15, q4 = i16 >> 2, p4 = i16 & 3;
;   int vlow0, vlow1, vhi[NV];
;   if (DV == 64) {
;     vlow0 = (4 * h + q4) * 128 + (blk * 2 + (p4 >> 1)) * 16 + (p4 & 1) * 8;
;     vlow1 = vlow0;
; #pragma unroll
;     for (int v = 0; v < NV; ++v) vhi[v] = ((v ^ ((q4 >> 1) & 1)) * 64);
;   } else {
;     vlow0 = (4 * h + q4) * 256 + (((blk * 2 + (p4 >> 1)) ^ (h)) * 16) + (p4 & 1) * 8;
;     vlow1 = (4 * h + q4) * 256 + (((blk * 2 + (p4 >> 1)) ^ (2 + h)) * 16) + (p4 & 1) * 8;
; #pragma unroll
;     for (int v = 0; v < NV; ++v) vhi[v] = ((v ^ q4) * 64);
;   }
;   constexpr int VROW = DV * 2;
;   asm volatile("s_waitcnt vmcnt(0)" ::: "memory");
;   issue(0);
;   issue(1);
;   issue(2);
.LBB0_157:
	s_andn2_saveexec_b64 s[6:7], s[8:9]
	v_mov_b32_e32 v1, v145
	v_lshl_add_u64 v[70:71], s[4:5], 0, v[0:1]
	v_bitop3_b32 v72, v5, s36, v37 bitop3:0x48
	v_mov_b64_e32 v[132:133], 0x3000
	s_or_b64 exec, exec, s[6:7]
	s_add_u32 s2, s0, s2
	s_addc_u32 s3, s1, s3
	s_add_u32 s2, s2, 0x182d6100
	s_addc_u32 s3, s3, 0
	v_and_b32_e32 v8, 31, v37
	v_lshlrev_b32_e32 v6, 5, v4
	v_lshrrev_b32_e32 v38, 5, v36
	v_add3_u32 v10, v8, s17, v6
	v_mov_b64_e32 v[6:7], s[2:3]
	v_mad_i64_i32 v[6:7], s[2:3], v10, s45, v[6:7]
	v_lshlrev_b32_e32 v10, 4, v38
	v_mov_b32_e32 v11, v145
	v_lshl_add_u64 v[6:7], v[6:7], 0, v[10:11]
	v_lshlrev_b32_e32 v9, 10, v4
	flat_load_dwordx4 v[80:83], v[6:7]
	flat_load_dwordx4 v[84:87], v[6:7] offset:32
	flat_load_dwordx4 v[88:91], v[6:7] offset:64
	flat_load_dwordx4 v[92:95], v[6:7] offset:96
	flat_load_dwordx4 v[96:99], v[6:7] offset:128
	flat_load_dwordx4 v[100:103], v[6:7] offset:160
	v_add3_u32 v143, 0, v9, v5
	v_mov_b32_e32 v67, v145
	v_readfirstlane_b32 s2, v143
	v_add_u32_e32 v5, 0x2000, v143
	v_lshl_add_u64 v[2:3], v[64:65], 0, v[66:67]
	s_mov_b32 m0, s2
	v_readfirstlane_b32 s2, v5
	v_lshl_add_u64 v[0:1], v[68:69], 0, v[144:145]
	global_load_lds_dwordx4 v[2:3], off
	s_mov_b32 m0, s2
	v_mov_b32_e32 v73, v145
	global_load_lds_dwordx4 v[0:1], off
	v_cmp_lt_i32_e64 s[38:39], 3, v4
	v_cmp_gt_i32_e32 vcc, 4, v4
	v_lshl_add_u64 v[32:33], v[70:71], 0, v[72:73]
	v_add_u32_e32 v9, 0x7000, v143
	v_add_u32_e32 v10, 0x5000, v143
	v_lshl_add_u64 v[6:7], v[2:3], 0, v[128:129]
	v_lshl_add_u64 v[4:5], v[0:1], 0, v[130:131]
	s_and_saveexec_b64 s[2:3], vcc
	s_xor_b64 s[2:3], exec, s[2:3]
	s_cbranch_execz .LBB0_161
	v_add_u32_e32 v4, 0x4000, v143
	v_add_u32_e32 v9, 0x9000, v143
	v_readfirstlane_b32 s4, v4
	s_mov_b32 m0, s4
	v_readfirstlane_b32 s4, v10
	global_load_lds_dwordx4 v[32:33], off
	s_mov_b32 m0, s4
	v_lshl_add_u64 v[4:5], v[0:1], 0, v[130:131]
	global_load_lds_dwordx4 v[6:7], off
	v_add_u32_e32 v6, 0x7000, v143
	s_nop 0
	v_readfirstlane_b32 s4, v6
	s_mov_b32 m0, s4
	s_nop 0
	global_load_lds_dwordx4 v[4:5], off
	v_lshl_add_u64 v[4:5], v[32:33], 0, v[132:133]

; template <int DQK, int DV, int NKH, int MODE>
; DEV void flash_unit(const FlashArgs& fa, char* smem, f32x16 (&oacc)[DV / 32], float& linv_out) {
;     ...
;   asm volatile("s_waitcnt vmcnt(0)" ::: "memory");
;   issue(0);
;   issue(1);
;   issue(2);
;   for (int it = 0; it < fa.n_tiles; ++it) {
;     {
;       const int newer = min(2, fa.n_tiles - 1 - it) * nld;
;       if (newer >= 8) asm volatile("s_waitcnt vmcnt(8)" ::: "memory");
;       else if (newer == 6) asm volatile("s_waitcnt vmcnt(6)" ::: "memory");
;       else if (newer == 4) asm volatile("s_waitcnt vmcnt(4)" ::: "memory");
;       else if (newer == 3) asm volatile("s_waitcnt vmcnt(3)" ::: "memory");
;       else if (newer == 2) asm volatile("s_waitcnt vmcnt(2)" ::: "memory");
;       else asm volatile("s_waitcnt vmcnt(0)" ::: "memory");
;     }
.LBB0_228:
	s_or_b64 exec, exec, s[0:1]
	v_lshlrev_b32_e32 v3, 10, v3
	v_add3_u32 v133, 0, v3, v8
	v_mov_b32_e32 v3, v145
	v_lshl_add_u64 v[114:115], v[0:1], 0, v[2:3]
	v_readfirstlane_b32 s0, v133
	v_add_u32_e32 v0, 0x2000, v133
	s_mov_b32 m0, s0
	v_readfirstlane_b32 s0, v0
	v_add_u32_e32 v2, 0x4000, v133
	v_lshl_add_u64 v[112:113], v[4:5], 0, v[144:145]
	global_load_lds_dwordx4 v[114:115], off
	s_mov_b32 m0, s0
	s_mov_b64 s[2:3], 0x2000
	v_readfirstlane_b32 s0, v2
	v_add_u32_e32 v2, 0x6000, v133
	global_load_lds_dwordx4 v[112:113], off
	v_lshl_add_u64 v[0:1], v[114:115], 0, s[2:3]
	s_mov_b32 m0, s0
	v_readfirstlane_b32 s0, v2
	v_add_u32_e32 v2, 0x8000, v133
	global_load_lds_dwordx4 v[0:1], off
	v_lshl_add_u64 v[0:1], v[112:113], 0, s[2:3]
	s_mov_b32 m0, s0
	s_mov_b64 s[2:3], 0x4000
	v_readfirstlane_b32 s0, v2
	v_add_u32_e32 v2, 0xa000, v133
	global_load_lds_dwordx4 v[0:1], off
	v_lshl_add_u64 v[0:1], v[114:115], 0, s[2:3]
	s_mov_b32 m0, s0
	v_readfirstlane_b32 s0, v2
	global_load_lds_dwordx4 v[0:1], off
	v_lshl_add_u64 v[0:1], v[112:113], 0, s[2:3]
	s_mov_b32 m0, s0
	s_cmp_gt_i32 s37, 0
	global_load_lds_dwordx4 v[0:1], off
	s_cbranch_scc0 .LBB0_201
	s_min_u32 s2, s37, 3
	s_cmp_gt_i32 s2, 2
	s_mov_b64 s[0:1], -1
	s_cbranch_scc0 .LBB0_231
	s_waitcnt vmcnt(4)
	s_mov_b64 s[0:1], 0

;     ...
;   const int nk = K >> 6;
;   const int cch = (tid & 7) ^ ((tid >> 4) & 7);
;   const u16* ga = A + (size_t)(tid >> 3) * lda + cch * 8;
;   const u16* gb = Bt + (size_t)(tid >> 3) * ldb + cch * 8;
;   char* lds_t = smem + tid * 16;
;   auto issue_piece = [&](int kt, int pc) {
;     char* st = lds_t + (kt % NSTG) * STAGE;
;     if (pc < 4)
;       __builtin_amdgcn_global_load_lds((const unsigned*)(ga + (size_t)(64 * pc) * lda + (size_t)kt * ksa), (unsigned __attribute__((address_space(3)))*)(st + pc * 8192), 16, 0, 0);
;     else
;       __builtin_amdgcn_global_load_lds((const unsigned*)(gb + (size_t)(64 * (pc - 4)) * ldb + (size_t)kt * ksb), (unsigned __attribute__((address_space(3)))*)(st + ABYTES + (pc - 4) * 8192), 16, 0, 0);
;   };
;   const int x = (r >> 1) & 7;
;   int xo[4];
; #pragma unroll
;   for (int s = 0; s < 4; ++s) xo[s] = (((2 * s + h) ^ x) << 4);
;   asm volatile("s_waitcnt vmcnt(0)" ::: "memory");
; #pragma unroll
;   for (int d = 0; d < DIST; ++d)
; #pragma unroll
;     for (int pc = 0; pc < NLD; ++pc) issue_piece(d, pc);
;   pre();
;   for (int kt = 0; kt < nk; ++kt) {
;     if (DIST == 2 && kt + 1 < nk) {
;       if (NLD == 6) asm volatile("s_waitcnt vmcnt(6)" ::: "memory");
;       else if (NLD == 5) asm volatile("s_waitcnt vmcnt(5)" ::: "memory");
;       else asm volatile("s_waitcnt vmcnt(8)" ::: "memory");
;     } else {
;       asm volatile("s_waitcnt vmcnt(0)" ::: "memory");
;     }
;     __builtin_amdgcn_s_barrier();
; DEV void phase_upproj(const Params& p, int l, int hf, char* smem) {
;     ...
;       const int hd = nt - 8;
;       float sqv[4];
;       float kr[16];
;       auto load_pre = [&]() {
;         const float* sq = ssq + (size_t)m * 16 + 6;
; #pragma unroll
;         for (int i = 0; i < 4; ++i) sqv[i] = sq[i];
;         const float* krp = (const float*)(ws + OFF_KROPE) + (size_t)m * 32;
; #pragma unroll
;         for (int g4 = 0; g4 < 4; ++g4) {
;           const float4 v = *(const float4*)(krp + 8 * g4 + 4 * h);
;           kr[4 * g4] = v.x; kr[4 * g4 + 1] = v.y; kr[4 * g4 + 2] = v.z; kr[4 * g4 + 3] = v.w;
;         }
;       };
;       gemm_main<4, 1, 128, 3>(acc, (const u16*)(ws + OFF_CKV) + (size_t)mt * 256 * 256, 256,
;                       (const u16*)(ws + OFF_WUKV) + ((size_t)l * 1024 + hd * 128) * 256, 256, 256, smem, w * 32, 0, 64, 64, load_pre);
.LBB0_336:
	s_and_b32 s3, s12, 7
	s_ashr_i32 s2, s12, 3
	s_mulk_i32 s3, 0x84
	s_add_i32 s3, s3, s2
	s_mul_hi_i32 s2, s3, 0x2aaaaaab
	s_lshr_b32 s13, s2, 31
	s_ashr_i32 s2, s2, 3
	s_add_i32 s2, s2, s13
	s_mul_i32 s13, s2, 0xffffffd0
	s_add_i32 s14, s13, s3
	s_mul_hi_i32 s13, s14, 0x55555556
	s_lshr_b32 s3, s13, 31
	s_add_i32 s13, s13, s3
	s_sub_i32 s2, s2, s13
	s_mul_i32 s2, s2, 3
	s_add_i32 s44, s2, s14
	v_lshl_add_u32 v112, s44, 8, v135
	v_mul_hi_i32 v0, v112, s72
	v_lshrrev_b32_e32 v1, 31, v0
	v_ashrrev_i32_e32 v0, 11, v0
	v_add_u32_e32 v151, v0, v1
	v_mad_i32_i24 v110, v151, s73, v112
	v_add_u32_e32 v0, 0xffffff00, v110
	v_ashrrev_i32_e32 v0, 6, v0
	v_cvt_f32_i32_e32 v152, v0
	v_cmp_lt_i32_e64 s[38:39], s70, v110
	s_mov_b64 s[2:3], -1
	s_cmp_gt_i32 s14, 23
	v_ashrrev_i32_e32 v113, 31, v112
	s_cbranch_scc0 .LBB0_340
	s_ashr_i32 s45, s44, 31
	s_add_i32 s14, s13, -8
	s_lshl_b64 s[2:3], s[44:45], 17
	s_add_u32 s2, s4, s2
	v_readlane_b32 s16, v240, 7
	v_mov_b32_e32 v10, v147
	s_addc_u32 s3, s5, s3
	v_readlane_b32 s17, v240, 8
	s_lshl_b32 s16, s14, 7
	s_mov_b32 s15, s17
	v_lshrrev_b32_e32 v0, 4, v10
	s_lshl_b64 s[16:17], s[16:17], 9
	v_xor_b32_e32 v4, v0, v10
	v_ashrrev_i32_e32 v0, 3, v10
	s_add_u32 s16, s6, s16
	v_ashrrev_i32_e32 v1, 31, v0
	s_addc_u32 s17, s7, s17
	v_lshlrev_b64 v[0:1], 9, v[0:1]
	v_lshlrev_b32_e32 v4, 4, v4
	v_lshl_add_u64 v[2:3], s[16:17], 0, v[0:1]
	v_and_b32_e32 v144, 0x70, v4
	v_lshl_add_u32 v11, v10, 4, 0
	v_lshl_add_u64 v[0:1], s[2:3], 0, v[0:1]
	v_lshl_add_u64 v[6:7], v[2:3], 0, v[144:145]
	v_readfirstlane_b32 s18, v11
	v_add_u32_e32 v3, 0x2000, v11
	v_lshl_add_u64 v[4:5], v[0:1], 0, v[144:145]
	s_mov_b32 m0, s18
	v_readfirstlane_b32 s17, v3
	v_add_u32_e32 v3, 0x4000, v11
	v_writelane_b32 v240, s14, 7
	global_load_lds_dwordx4 v[4:5], off
	v_lshl_add_u64 v[0:1], v[4:5], 0, s[34:35]
	s_mov_b32 m0, s17
	v_readfirstlane_b32 s16, v3
	v_add_u32_e32 v3, 0x6000, v11
	v_writelane_b32 v240, s15, 8
	v_add_u32_e32 v2, 0x8000, v11
	global_load_lds_dwordx4 v[0:1], off
	v_lshl_add_u64 v[0:1], v[4:5], 0, s[56:57]
	s_mov_b32 m0, s16
	v_readfirstlane_b32 s15, v3
	global_load_lds_dwordx4 v[0:1], off
	v_lshl_add_u64 v[0:1], v[4:5], 0, s[58:59]
	s_mov_b32 m0, s15
	v_readfirstlane_b32 s3, v2
	v_add_u32_e32 v2, 0xa000, v11
	global_load_lds_dwordx4 v[0:1], off
	s_mov_b32 m0, s3
	v_readfirstlane_b32 s2, v2
	v_add_u32_e32 v8, 0xc000, v11
	global_load_lds_dwordx4 v[6:7], off
	v_lshl_add_u64 v[0:1], v[6:7], 0, s[34:35]
	s_mov_b32 m0, s2
	s_mov_b64 s[20:21], 0x80
	v_readfirstlane_b32 s19, v8
	v_add_u32_e32 v8, 0xe000, v11
	global_load_lds_dwordx4 v[0:1], off
	v_lshl_add_u64 v[2:3], v[4:5], 0, s[20:21]
	s_mov_b32 m0, s19
	v_readfirstlane_b32 s19, v8
	v_add_u32_e32 v8, 0x10000, v11
	v_lshl_add_u64 v[0:1], v[6:7], 0, s[20:21]
	global_load_lds_dwordx4 v[2:3], off
	v_lshl_add_u64 v[2:3], v[4:5], 0, s[46:47]
	s_mov_b32 m0, s19
	s_mov_b64 s[20:21], 0x10080
	v_readfirstlane_b32 s19, v8
	v_add_u32_e32 v8, 0x12000, v11
	global_load_lds_dwordx4 v[2:3], off
	v_lshl_add_u64 v[2:3], v[4:5], 0, s[20:21]
	s_mov_b32 m0, s19
	v_readfirstlane_b32 s19, v8
	v_add_u32_e32 v9, 0x14000, v11
	global_load_lds_dwordx4 v[2:3], off
	v_lshl_add_u64 v[2:3], v[4:5], 0, s[48:49]
	s_mov_b32 m0, s19
	v_readfirstlane_b32 s19, v9
	global_load_lds_dwordx4 v[2:3], off
	v_add_u32_e32 v2, 0x16000, v11
	s_mov_b32 m0, s19
	v_readfirstlane_b32 s19, v2
	global_load_lds_dwordx4 v[0:1], off
	v_lshl_add_u64 v[0:1], v[6:7], 0, s[46:47]
	s_mov_b32 m0, s19
	v_lshlrev_b64 v[8:9], 7, v[112:113]
	global_load_lds_dwordx4 v[0:1], off
	v_lshlrev_b64 v[0:1], 6, v[112:113]
	v_lshl_add_u64 v[0:1], s[40:41], 0, v[0:1]
	flat_load_dwordx4 v[0:3], v[0:1] offset:24
	v_lshl_add_u64 v[8:9], v[82:83], 0, v[8:9]
	flat_load_dwordx4 v[64:67], v[8:9] offset:32
	flat_load_dwordx4 v[72:75], v[8:9] offset:64
	flat_load_dwordx4 v[68:71], v[8:9] offset:96
	flat_load_dwordx4 v[76:79], v[8:9]
	v_bfe_u32 v13, v10, 5, 1
	v_bfe_u32 v14, v10, 1, 3
	v_and_b32_e32 v8, 31, v10
	v_lshrrev_b32_e32 v12, 5, v10
	v_bitop3_b32 v16, v13, v14, 4 bitop3:0x36
	v_or_b32_e32 v9, v8, v134
	s_mov_b64 s[20:21], 0x100
	v_bitop3_b32 v12, v12, v14, 1 bitop3:0x6c
	v_bitop3_b32 v15, v13, v14, 2 bitop3:0x36
	v_lshlrev_b32_e32 v20, 4, v16
	v_bitop3_b32 v13, v13, v14, 6 bitop3:0x36
	v_lshlrev_b32_e32 v9, 7, v9
	v_lshl_add_u64 v[124:125], v[6:7], 0, s[20:21]
	v_lshl_add_u64 v[16:17], v[4:5], 0, s[20:21]
	s_mov_b64 s[20:21], 0x10100
	v_lshlrev_b32_e32 v12, 4, v12
	v_lshlrev_b32_e32 v15, 4, v15
	v_lshlrev_b32_e32 v13, 4, v13
	v_lshlrev_b32_e32 v8, 7, v8
	v_add_u32_e32 v10, 0, v9
	v_lshl_add_u64 v[120:121], v[4:5], 0, s[20:21]
	s_add_i32 s19, 0, 0x14000
	s_mov_b64 s[20:21], 0x180
	v_add_u32_e32 v115, v10, v12
	v_add_u32_e32 v153, v10, v15
	v_add_u32_e32 v200, v10, v20
	v_add_u32_e32 v202, v10, v13
	v_add_u32_e32 v10, s19, v8
	v_lshl_add_u64 v[186:187], v[6:7], 0, s[20:21]
	v_lshl_add_u64 v[188:189], v[4:5], 0, s[20:21]
	s_mov_b64 s[22:23], 0x8180
	s_mov_b64 s[20:21], 0x10180
	s_add_i32 s19, 0, 0x18000
	v_lshl_add_u64 v[18:19], v[4:5], 0, s[50:51]
	v_lshl_add_u64 v[182:183], v[4:5], 0, s[52:53]
	v_lshl_add_u64 v[190:191], v[4:5], 0, s[22:23]
	v_lshl_add_u64 v[192:193], v[4:5], 0, s[20:21]
	v_lshl_add_u64 v[194:195], v[4:5], 0, s[54:55]
	v_add_u32_e32 v4, s19, v9
	s_add_i32 s19, 0, 0x20000
	v_add_u32_e32 v14, 0, v8
	v_add_u32_e32 v5, s19, v8
	v_add_u32_e32 v144, v14, v12
	v_lshl_add_u64 v[184:185], v[6:7], 0, s[50:51]
	v_lshl_add_u64 v[196:197], v[6:7], 0, s[22:23]
	v_add_u32_e32 v208, v4, v12
	v_add_u32_e32 v209, v5, v12
	v_add_u32_e32 v210, v4, v15
	v_add_u32_e32 v211, v5, v15
	v_add_u32_e32 v212, v4, v20
	v_add_u32_e32 v213, v5, v20
	v_add_u32_e32 v214, v4, v13
	v_add_u32_e32 v215, v5, v13
	s_waitcnt vmcnt(6)
	s_barrier
; #define MFMA(a, b, c) __builtin_amdgcn_mfma_f32_32x32x16_bf16((a), (b), (c), 0, 0, 0)
;     ...
;   for (int kt = 0; kt < nk; ++kt) {
;     if (DIST == 2 && kt + 1 < nk) {
;       if (NLD == 6) asm volatile("s_waitcnt vmcnt(6)" ::: "memory");
;       else if (NLD == 5) asm volatile("s_waitcnt vmcnt(5)" ::: "memory");
;       else asm volatile("s_waitcnt vmcnt(8)" ::: "memory");
;     } else {
;       asm volatile("s_waitcnt vmcnt(0)" ::: "memory");
;     }
;     __builtin_amdgcn_s_barrier();
;     const bool pre = (kt + DIST < nk);
;     const char* base = smem + (kt % NSTG) * STAGE;
;     const char* pa = base + (wrow_act + r) * 128;
;     const char* pw = base + ABYTES + (wrow_w + r) * 128;
;     constexpr int NM = NI * MJ;
;     constexpr int PPS = (NLD + 1) / 2;
; #pragma unroll
;     for (int s = 0; s < 4; ++s) {
;       bf16x8 af[MJ], wf[NI];
; #pragma unroll
;       for (int j = 0; j < MJ; ++j) af[j] = *(const bf16x8*)(pa + j * 32 * 128 + xo[s]);
; #pragma unroll
;       for (int i = 0; i < NI; ++i) wf[i] = *(const bf16x8*)(pw + i * 32 * 128 + xo[s]);
; #pragma unroll
;       for (int m = 0; m < NM; ++m) {
;         const int i = m / MJ, j = m % MJ;
;         acc[i][j] = MFMA(wf[i], af[j], acc[i][j]);
;         if (s < 2 && NM >= PPS) {
;           constexpr int EVERY = (NM / PPS) > 0 ? (NM / PPS) : 1;
;           if ((m + 1) % EVERY == 0) {
;             const int pc = s * PPS + (m + 1) / EVERY - 1;
;             if ((m + 1) / EVERY <= PPS && pc < NLD) {
;               __builtin_amdgcn_sched_barrier(0);
;               if (pre) issue_piece(kt + DIST, pc);
;               __builtin_amdgcn_sched_barrier(0);
;             }
;           }
;         }
;         if (s < 2 && NM < PPS) {
;           const int slot = s * NM + m;
;           __builtin_amdgcn_sched_barrier(0);
; #pragma unroll
;           for (int pc = 0; pc < NLD; ++pc)
;             if ((pc * 2 * NM) / NLD == slot && pre) issue_piece(kt + DIST, pc);
;           __builtin_amdgcn_sched_barrier(0);
;         }
;       }
;     }
;   }
	v_add_u32_e32 v21, 0x18000, v11
	v_add_u32_e32 v111, 0x20000, v11
	v_add_u32_e32 v22, 0x1a000, v11
	v_add_u32_e32 v122, 0x1c000, v11
	v_add_u32_e32 v181, v14, v15
	v_add_u32_e32 v198, 0x1e000, v11
	v_add_u32_e32 v199, 0x22000, v11
	v_add_u32_e32 v201, v14, v20
	v_add_u32_e32 v203, v14, v13
	v_add_u32_e32 v204, v10, v12
	v_add_u32_e32 v205, v10, v15
	v_add_u32_e32 v206, v10, v20
	v_add_u32_e32 v207, v10, v13
	s_waitcnt vmcnt(0) lgkmcnt(0)
	v_add_f32_e32 v0, v0, v1
	v_add_f32_e32 v0, v0, v2
	v_add_f32_e32 v0, v0, v3
	v_fmamk_f32 v0, v0, 0x3b800000, v169
	v_mul_f32_e32 v1, 0x4b800000, v0
	v_cmp_gt_f32_e32 vcc, s77, v0
	v_pk_mul_f32 v[128:129], v[74:75], v[74:75]
	v_pk_mul_f32 v[126:127], v[68:69], v[68:69]
	v_cndmask_b32_e32 v0, v0, v1, vcc
	v_rsq_f32_e32 v8, v0
	ds_read_b128 v[0:3], v115
	ds_read_b128 v[4:7], v144 offset:32768
	s_waitcnt lgkmcnt(0)
	v_mfma_f32_32x32x16_bf16 v[48:63], v[4:7], v[0:3], 0
	v_mul_f32_e32 v9, 0x45800000, v8
	v_cndmask_b32_e32 v114, v8, v9, vcc
	ds_read_b128 v[8:11], v144 offset:36864
	ds_read_b128 v[12:15], v144 offset:40960
	ds_read_b128 v[116:119], v144 offset:45056
	v_pk_mul_f32 v[132:133], v[66:67], v[66:67]
	v_pk_mul_f32 v[130:131], v[72:73], v[72:73]
	v_readfirstlane_b32 s19, v21
	s_mov_b32 m0, s19
	s_nop 0
	global_load_lds_dwordx4 v[16:17], off
	s_waitcnt lgkmcnt(0)
	v_mfma_f32_32x32x16_bf16 v[32:47], v[8:11], v[0:3], 0
	v_readfirstlane_b32 s19, v22
	s_mov_b32 m0, s19
	s_nop 0
	global_load_lds_dwordx4 v[18:19], off
	v_mfma_f32_32x32x16_bf16 v[16:31], v[12:15], v[0:3], 0
	v_readfirstlane_b32 s19, v122
	s_mov_b32 m0, s19
	s_nop 0
	global_load_lds_dwordx4 v[120:121], off
	v_mfma_f32_32x32x16_bf16 v[0:15], v[116:119], v[0:3], 0
	ds_read_b128 v[116:119], v181 offset:32768
	ds_read_b128 v[120:123], v153
	ds_read_b128 v[154:157], v181 offset:36864
	ds_read_b128 v[158:161], v181 offset:40960
	ds_read_b128 v[162:165], v181 offset:45056
	s_waitcnt lgkmcnt(0)
	v_mfma_f32_32x32x16_bf16 v[48:63], v[116:119], v[120:123], v[48:63]
	v_readfirstlane_b32 s19, v198
	s_mov_b32 m0, s19
	s_nop 0
	global_load_lds_dwordx4 v[182:183], off
	v_mfma_f32_32x32x16_bf16 v[32:47], v[154:157], v[120:123], v[32:47]
	v_readfirstlane_b32 s19, v111
	s_mov_b32 m0, s19
	s_nop 0
	global_load_lds_dwordx4 v[124:125], off
	v_mfma_f32_32x32x16_bf16 v[16:31], v[158:161], v[120:123], v[16:31]
	v_readfirstlane_b32 s19, v199
	s_mov_b32 m0, s19
	s_nop 0
	global_load_lds_dwordx4 v[184:185], off
	v_mfma_f32_32x32x16_bf16 v[0:15], v[162:165], v[120:123], v[0:15]
	ds_read_b128 v[116:119], v201 offset:32768
	ds_read_b128 v[120:123], v200
	s_waitcnt lgkmcnt(0)
	v_mfma_f32_32x32x16_bf16 v[48:63], v[116:119], v[120:123], v[48:63]
	ds_read_b128 v[116:119], v201 offset:36864
	ds_read_b128 v[154:157], v201 offset:40960
	s_waitcnt lgkmcnt(0)
	v_mfma_f32_32x32x16_bf16 v[32:47], v[116:119], v[120:123], v[32:47]
	v_mfma_f32_32x32x16_bf16 v[16:31], v[154:157], v[120:123], v[16:31]
	ds_read_b128 v[116:119], v201 offset:45056
	ds_read_b128 v[154:157], v202
	s_waitcnt lgkmcnt(0)
	v_mfma_f32_32x32x16_bf16 v[0:15], v[116:119], v[120:123], v[0:15]
	ds_read_b128 v[116:119], v203 offset:32768
	ds_read_b128 v[120:123], v203 offset:36864
	s_waitcnt lgkmcnt(0)
	v_mfma_f32_32x32x16_bf16 v[48:63], v[116:119], v[154:157], v[48:63]
	v_mfma_f32_32x32x16_bf16 v[32:47], v[120:123], v[154:157], v[32:47]
	ds_read_b128 v[116:119], v203 offset:40960
	ds_read_b128 v[120:123], v203 offset:45056
	s_waitcnt vmcnt(6)
	s_barrier
	s_waitcnt lgkmcnt(0)
	v_mfma_f32_32x32x16_bf16 v[16:31], v[116:119], v[154:157], v[16:31]
	v_mfma_f32_32x32x16_bf16 v[0:15], v[120:123], v[154:157], v[0:15]
	ds_read_b128 v[116:119], v204
	ds_read_b128 v[120:123], v115 offset:49152
	ds_read_b128 v[154:157], v204 offset:4096
	ds_read_b128 v[158:161], v204 offset:8192
	ds_read_b128 v[162:165], v204 offset:12288
	s_waitcnt lgkmcnt(0)
	v_mfma_f32_32x32x16_bf16 v[48:63], v[116:119], v[120:123], v[48:63]
	s_mov_b32 m0, s18
	s_nop 0
	global_load_lds_dwordx4 v[188:189], off
	v_mfma_f32_32x32x16_bf16 v[32:47], v[154:157], v[120:123], v[32:47]
	s_mov_b32 m0, s17
	s_nop 0
	global_load_lds_dwordx4 v[190:191], off
	v_mfma_f32_32x32x16_bf16 v[16:31], v[158:161], v[120:123], v[16:31]
	s_mov_b32 m0, s16
	s_nop 0
	global_load_lds_dwordx4 v[192:193], off
	v_mfma_f32_32x32x16_bf16 v[0:15], v[162:165], v[120:123], v[0:15]
	ds_read_b128 v[116:119], v205
	ds_read_b128 v[120:123], v153 offset:49152
	ds_read_b128 v[154:157], v205 offset:4096
	ds_read_b128 v[158:161], v205 offset:8192
	ds_read_b128 v[162:165], v205 offset:12288
	s_waitcnt lgkmcnt(0)
	v_mfma_f32_32x32x16_bf16 v[48:63], v[116:119], v[120:123], v[48:63]
	s_mov_b32 m0, s15
	s_nop 0
	global_load_lds_dwordx4 v[194:195], off
	v_mfma_f32_32x32x16_bf16 v[32:47], v[154:157], v[120:123], v[32:47]
	s_mov_b32 m0, s3
	s_nop 0
	global_load_lds_dwordx4 v[186:187], off
	v_mfma_f32_32x32x16_bf16 v[16:31], v[158:161], v[120:123], v[16:31]
	s_mov_b32 m0, s2
	s_nop 0
	global_load_lds_dwordx4 v[196:197], off
	v_mfma_f32_32x32x16_bf16 v[0:15], v[162:165], v[120:123], v[0:15]
	ds_read_b128 v[116:119], v206
	ds_read_b128 v[120:123], v200 offset:49152
	ds_read_b128 v[154:157], v206 offset:4096
	ds_read_b128 v[158:161], v202 offset:49152
	s_waitcnt lgkmcnt(0)
	v_mfma_f32_32x32x16_bf16 v[48:63], v[116:119], v[120:123], v[48:63]
	v_mfma_f32_32x32x16_bf16 v[32:47], v[154:157], v[120:123], v[32:47]
	ds_read_b128 v[116:119], v206 offset:8192
	ds_read_b128 v[154:157], v206 offset:12288
	s_waitcnt lgkmcnt(0)
	v_mfma_f32_32x32x16_bf16 v[16:31], v[116:119], v[120:123], v[16:31]
	v_mfma_f32_32x32x16_bf16 v[0:15], v[154:157], v[120:123], v[0:15]
	ds_read_b128 v[116:119], v207
	ds_read_b128 v[120:123], v207 offset:4096
	s_waitcnt lgkmcnt(0)
	v_mfma_f32_32x32x16_bf16 v[48:63], v[116:119], v[158:161], v[48:63]
	v_mfma_f32_32x32x16_bf16 v[32:47], v[120:123], v[158:161], v[32:47]
	ds_read_b128 v[116:119], v207 offset:8192
	ds_read_b128 v[120:123], v207 offset:12288
	s_waitcnt vmcnt(6)
	s_barrier
;     ...
;   for (int kt = 0; kt < nk; ++kt) {
;     if (DIST == 2 && kt + 1 < nk) {
;       if (NLD == 6) asm volatile("s_waitcnt vmcnt(6)" ::: "memory");
;       else if (NLD == 5) asm volatile("s_waitcnt vmcnt(5)" ::: "memory");
;       else asm volatile("s_waitcnt vmcnt(8)" ::: "memory");
;     } else {
;       asm volatile("s_waitcnt vmcnt(0)" ::: "memory");
;     }
;     __builtin_amdgcn_s_barrier();
;     const bool pre = (kt + DIST < nk);
;     const char* base = smem + (kt % NSTG) * STAGE;
;     const char* pa = base + (wrow_act + r) * 128;
;     const char* pw = base + ABYTES + (wrow_w + r) * 128;
;     constexpr int NM = NI * MJ;
;     constexpr int PPS = (NLD + 1) / 2;
; #pragma unroll
;     for (int s = 0; s < 4; ++s) {
;       bf16x8 af[MJ], wf[NI];
; #pragma unroll
;       for (int j = 0; j < MJ; ++j) af[j] = *(const bf16x8*)(pa + j * 32 * 128 + xo[s]);
; #pragma unroll
;       for (int i = 0; i < NI; ++i) wf[i] = *(const bf16x8*)(pw + i * 32 * 128 + xo[s]);
; #pragma unroll
;       for (int m = 0; m < NM; ++m) {
;         const int i = m / MJ, j = m % MJ;
;         acc[i][j] = MFMA(wf[i], af[j], acc[i][j]);
;         if (s < 2 && NM >= PPS) {
;           constexpr int EVERY = (NM / PPS) > 0 ? (NM / PPS) : 1;
;           if ((m + 1) % EVERY == 0) {
;             const int pc = s * PPS + (m + 1) / EVERY - 1;
;             if ((m + 1) / EVERY <= PPS && pc < NLD) {
;               __builtin_amdgcn_sched_barrier(0);
;               if (pre) issue_piece(kt + DIST, pc);
;               __builtin_amdgcn_sched_barrier(0);
;             }
;           }
;         }
;         if (s < 2 && NM < PPS) {
;           const int slot = s * NM + m;
;           __builtin_amdgcn_sched_barrier(0);
; #pragma unroll
;           for (int pc = 0; pc < NLD; ++pc)
;             if ((pc * 2 * NM) / NLD == slot && pre) issue_piece(kt + DIST, pc);
;           __builtin_amdgcn_sched_barrier(0);
;         }
;       }
;     }
;   }
; DEV void phase_upproj(const Params& p, int l, int hf, char* smem) {
;     ...
;       const float rckv = rsqrtf((sqv[0] + sqv[1] + sqv[2] + sqv[3]) * (1.f / 256.f) + EPS);
;       float ss = 0;
; #pragma unroll
;       for (int i = 0; i < 4; ++i)
; #pragma unroll
;         for (int e = 0; e < 16; ++e) { acc[i][0][e] *= rckv; if (i < 2) ss += acc[i][0][e] * acc[i][0][e]; }
; #pragma unroll
;       for (int e = 0; e < 16; ++e) ss += kr[e] * kr[e];
	s_waitcnt lgkmcnt(0)
	v_mfma_f32_32x32x16_bf16 v[16:31], v[116:119], v[158:161], v[16:31]
	v_mfma_f32_32x32x16_bf16 v[0:15], v[120:123], v[158:161], v[0:15]
	ds_read_b128 v[116:119], v209
	ds_read_b128 v[120:123], v208
	ds_read_b128 v[154:157], v209 offset:4096
	ds_read_b128 v[158:161], v209 offset:8192
	ds_read_b128 v[162:165], v209 offset:12288
	s_waitcnt lgkmcnt(0)
	v_mfma_f32_32x32x16_bf16 v[48:63], v[116:119], v[120:123], v[48:63]
	v_mfma_f32_32x32x16_bf16 v[32:47], v[154:157], v[120:123], v[32:47]
	v_mfma_f32_32x32x16_bf16 v[16:31], v[158:161], v[120:123], v[16:31]
	v_mfma_f32_32x32x16_bf16 v[0:15], v[162:165], v[120:123], v[0:15]
	ds_read_b128 v[116:119], v211
	ds_read_b128 v[120:123], v210
	ds_read_b128 v[154:157], v211 offset:4096
	ds_read_b128 v[158:161], v211 offset:8192
	ds_read_b128 v[162:165], v211 offset:12288
	s_waitcnt lgkmcnt(0)
	v_mfma_f32_32x32x16_bf16 v[48:63], v[116:119], v[120:123], v[48:63]
	v_mfma_f32_32x32x16_bf16 v[32:47], v[154:157], v[120:123], v[32:47]
	v_mfma_f32_32x32x16_bf16 v[16:31], v[158:161], v[120:123], v[16:31]
	v_mfma_f32_32x32x16_bf16 v[0:15], v[162:165], v[120:123], v[0:15]
	ds_read_b128 v[116:119], v213
	ds_read_b128 v[120:123], v212
	s_waitcnt lgkmcnt(0)
	v_mfma_f32_32x32x16_bf16 v[48:63], v[116:119], v[120:123], v[48:63]
	ds_read_b128 v[116:119], v213 offset:4096
	ds_read_b128 v[154:157], v213 offset:8192
	s_waitcnt lgkmcnt(0)
	v_mfma_f32_32x32x16_bf16 v[32:47], v[116:119], v[120:123], v[32:47]
	v_mfma_f32_32x32x16_bf16 v[16:31], v[154:157], v[120:123], v[16:31]
	ds_read_b128 v[116:119], v213 offset:12288
	ds_read_b128 v[154:157], v214
	s_waitcnt lgkmcnt(0)
	v_mfma_f32_32x32x16_bf16 v[0:15], v[116:119], v[120:123], v[0:15]
	ds_read_b128 v[116:119], v215
	ds_read_b128 v[120:123], v215 offset:4096
	s_waitcnt lgkmcnt(0)
	v_mfma_f32_32x32x16_bf16 v[48:63], v[116:119], v[154:157], v[48:63]
	v_mfma_f32_32x32x16_bf16 v[32:47], v[120:123], v[154:157], v[32:47]
	ds_read_b128 v[116:119], v215 offset:8192
	ds_read_b128 v[120:123], v215 offset:12288
	s_waitcnt vmcnt(0)
	s_barrier
	s_waitcnt lgkmcnt(0)
	v_mfma_f32_32x32x16_bf16 v[16:31], v[116:119], v[154:157], v[16:31]
	v_mfma_f32_32x32x16_bf16 v[0:15], v[120:123], v[154:157], v[0:15]
	ds_read_b128 v[116:119], v144 offset:32768
	ds_read_b128 v[120:123], v115
	ds_read_b128 v[154:157], v144 offset:36864
	ds_read_b128 v[158:161], v144 offset:40960
	ds_read_b128 v[162:165], v144 offset:45056
	s_waitcnt lgkmcnt(0)
	v_mfma_f32_32x32x16_bf16 v[48:63], v[116:119], v[120:123], v[48:63]
	v_mfma_f32_32x32x16_bf16 v[32:47], v[154:157], v[120:123], v[32:47]
	v_mfma_f32_32x32x16_bf16 v[16:31], v[158:161], v[120:123], v[16:31]
	v_mfma_f32_32x32x16_bf16 v[0:15], v[162:165], v[120:123], v[0:15]
	ds_read_b128 v[116:119], v181 offset:32768
	ds_read_b128 v[120:123], v153
	ds_read_b128 v[154:157], v181 offset:36864
	ds_read_b128 v[158:161], v181 offset:40960
	ds_read_b128 v[162:165], v181 offset:45056
	s_waitcnt lgkmcnt(0)
	v_mfma_f32_32x32x16_bf16 v[48:63], v[116:119], v[120:123], v[48:63]
	v_mfma_f32_32x32x16_bf16 v[32:47], v[154:157], v[120:123], v[32:47]
	v_mfma_f32_32x32x16_bf16 v[16:31], v[158:161], v[120:123], v[16:31]
	v_mfma_f32_32x32x16_bf16 v[0:15], v[162:165], v[120:123], v[0:15]
	ds_read_b128 v[116:119], v200
	ds_read_b128 v[120:123], v201 offset:32768
	ds_read_b128 v[154:157], v201 offset:36864
	ds_read_b128 v[158:161], v201 offset:40960
	ds_read_b128 v[162:165], v201 offset:45056
	s_waitcnt lgkmcnt(0)
	v_mfma_f32_32x32x16_bf16 v[48:63], v[120:123], v[116:119], v[48:63]
	v_mfma_f32_32x32x16_bf16 v[32:47], v[154:157], v[116:119], v[32:47]
	v_mfma_f32_32x32x16_bf16 v[16:31], v[158:161], v[116:119], v[16:31]
	v_mfma_f32_32x32x16_bf16 v[0:15], v[162:165], v[116:119], v[0:15]
	ds_read_b128 v[116:119], v202
	ds_read_b128 v[120:123], v203 offset:32768
	ds_read_b128 v[154:157], v203 offset:36864
	ds_read_b128 v[158:161], v203 offset:40960
	ds_read_b128 v[162:165], v203 offset:45056
	s_barrier
	s_waitcnt lgkmcnt(0)
	v_mfma_f32_32x32x16_bf16 v[48:63], v[120:123], v[116:119], v[48:63]
	v_mfma_f32_32x32x16_bf16 v[32:47], v[154:157], v[116:119], v[32:47]
	s_nop 10
	v_mul_f32_e64 v124, v114, v48
	v_mul_f32_e64 v125, v114, v49
	v_mul_f32_e64 v154, v124, v124
	v_mul_f32_e64 v155, v125, v125
	v_mul_f32_e64 v120, v114, v50
	v_mul_f32_e64 v121, v114, v51
	v_pk_mul_f32 v[156:157], v[120:121], v[120:121]
	v_add_f32_e32 v111, v154, v155
	v_pk_mul_f32 v[122:123], v[114:115], v[52:53] op_sel_hi:[0,1]
	v_add_f32_e32 v111, v156, v111
	v_mfma_f32_32x32x16_bf16 v[16:31], v[158:161], v[116:119], v[16:31]
	v_mul_f32_e64 v158, v122, v122
	v_mul_f32_e64 v159, v123, v123
	v_add_f32_e32 v111, v157, v111
	v_add_f32_e32 v111, v158, v111
	v_add_f32_e32 v111, v159, v111
	v_pk_mul_f32 v[48:49], v[114:115], v[58:59] op_sel_hi:[0,1]
	v_pk_mul_f32 v[50:51], v[114:115], v[32:33] op_sel_hi:[0,1]
	v_pk_mul_f32 v[32:33], v[50:51], v[50:51]
	v_mfma_f32_32x32x16_bf16 v[0:15], v[162:165], v[116:119], v[0:15]
	v_mul_f32_e64 v116, v114, v54
	v_mul_f32_e64 v117, v114, v55
	v_mul_f32_e64 v160, v116, v116
	v_mul_f32_e64 v161, v117, v117
	v_mul_f32_e64 v118, v114, v56
	v_mul_f32_e64 v119, v114, v57
	v_add_f32_e32 v111, v160, v111
	v_pk_mul_f32 v[162:163], v[118:119], v[118:119]
	v_add_f32_e32 v111, v161, v111
	v_add_f32_e32 v111, v162, v111
	v_pk_mul_f32 v[164:165], v[48:49], v[48:49]
	v_add_f32_e32 v111, v163, v111
	v_pk_mul_f32 v[54:55], v[114:115], v[60:61] op_sel_hi:[0,1]
	v_add_f32_e32 v111, v164, v111
	v_pk_mul_f32 v[182:183], v[54:55], v[54:55]
	v_add_f32_e32 v111, v165, v111
	v_pk_mul_f32 v[60:61], v[114:115], v[62:63] op_sel_hi:[0,1]
	v_add_f32_e32 v111, v182, v111
	v_pk_mul_f32 v[184:185], v[60:61], v[60:61]
; DEV float fast_exp2(float x) { return __builtin_amdgcn_exp2f(x); }
; DEV float xor32(float v) { return __shfl_xor(v, 32, 64); }
; DEV int crow_of(int reg, int h) { return (reg & 3) + 8 * (reg >> 2) + 4 * h; }
; DEV void phase_upproj(const Params& p, int l, int hf, char* smem) {
;     ...
;       for (int e = 0; e < 16; ++e) ss += kr[e] * kr[e];
;       ss += xor32(ss);
;       const float rs = rsqrtf(ss * (1.f / 96.f) + EPS);
;       const float* gain = p.mla_k_g + l * 96;
;       u16* krow = (u16*)(ws + OFF_MK) + ((size_t)(bl * 8 + hd) * TP + tp) * 96;
;       u16* vrow = (u16*)(ws + OFF_MV) + ((size_t)(bl * 8 + hd) * TP + tp) * 64;
; #pragma unroll
;       for (int e = 0; e < 16; ++e) kr[e] *= rs * gain[64 + crow_of(e, h)];
;       if (latent) {
; #pragma unroll
;         for (int e = 0; e < 8; ++e) {
;           const int a = crow_of(e, h);
;           const float inv = fast_exp2(-(float)(a & 7) * 1.6609640474436813f);
;           const float ang = ((a < 8) ? prow : pcol) * inv;
;           float sn, cs;
;           sincos_fast(ang, sn, cs);
;           const float x1 = kr[e], x2 = kr[e + 8];
;           kr[e] = x1 * cs - x2 * sn;
;           kr[e + 8] = x2 * cs + x1 * sn;
;         }
;       }
	v_add_f32_e32 v111, v183, v111
	v_add_f32_e32 v111, v184, v111
	v_add_f32_e32 v111, v185, v111
	v_pk_mul_f32 v[52:53], v[114:115], v[34:35] op_sel_hi:[0,1]
	v_add_f32_e32 v32, v32, v111
	v_pk_mul_f32 v[34:35], v[52:53], v[52:53]
	v_add_f32_e32 v32, v33, v32
	v_pk_mul_f32 v[56:57], v[114:115], v[36:37] op_sel_hi:[0,1]
	v_add_f32_e32 v32, v34, v32
	v_pk_mul_f32 v[36:37], v[56:57], v[56:57]
	v_add_f32_e32 v32, v35, v32
	v_pk_mul_f32 v[58:59], v[114:115], v[38:39] op_sel_hi:[0,1]
	v_add_f32_e32 v32, v36, v32
	v_pk_mul_f32 v[38:39], v[58:59], v[58:59]
	v_add_f32_e32 v32, v37, v32
	v_pk_mul_f32 v[40:41], v[114:115], v[40:41] op_sel_hi:[0,1]
	v_add_f32_e32 v32, v38, v32
	v_pk_mul_f32 v[186:187], v[40:41], v[40:41]
	v_add_f32_e32 v32, v39, v32
	v_pk_mul_f32 v[62:63], v[114:115], v[42:43] op_sel_hi:[0,1]
	v_add_f32_e32 v32, v186, v32
	v_pk_mul_f32 v[188:189], v[62:63], v[62:63]
	v_add_f32_e32 v32, v187, v32
	v_pk_mul_f32 v[44:45], v[114:115], v[44:45] op_sel_hi:[0,1]
	v_add_f32_e32 v32, v188, v32
	v_pk_mul_f32 v[190:191], v[44:45], v[44:45]
	v_add_f32_e32 v32, v189, v32
	v_pk_mul_f32 v[42:43], v[114:115], v[46:47] op_sel_hi:[0,1]
	v_add_f32_e32 v32, v190, v32
	v_pk_mul_f32 v[46:47], v[42:43], v[42:43]
	v_add_f32_e32 v32, v191, v32
	v_add_f32_e32 v32, v46, v32
	v_add_f32_e32 v32, v47, v32
	v_fmac_f32_e32 v32, v76, v76
	v_fmac_f32_e32 v32, v77, v77
	v_fmac_f32_e32 v32, v78, v78
	v_fmac_f32_e32 v32, v79, v79
	v_fmac_f32_e32 v32, v64, v64
	v_fmac_f32_e32 v32, v65, v65
	v_add_f32_e32 v32, v132, v32
	v_add_f32_e32 v32, v133, v32
	v_add_f32_e32 v32, v130, v32
	v_add_f32_e32 v32, v131, v32
	v_add_f32_e32 v32, v128, v32
	v_add_f32_e32 v32, v129, v32
	global_load_dwordx4 v[36:39], v[100:101], off offset:256
	global_load_dwordx4 v[128:131], v[100:101], off offset:320
	v_add_f32_e32 v32, v126, v32
	v_add_f32_e32 v34, v127, v32
	v_pk_mul_f32 v[32:33], v[70:71], v[70:71]
	s_nop 0
	v_add_f32_e32 v32, v32, v34
	v_and_b32_e32 v34, 64, v175
	v_add_f32_e32 v32, v33, v32
	v_xor_b32_e32 v33, 32, v175
	v_add_u32_e32 v34, 64, v34
	v_cmp_lt_i32_e32 vcc, v33, v34
	s_nop 1
	v_cndmask_b32_e32 v33, v175, v33, vcc
	v_lshlrev_b32_e32 v33, 2, v33
	ds_bpermute_b32 v33, v33, v32
	s_waitcnt lgkmcnt(0)
	v_add_f32_e32 v32, v32, v33
	v_fmamk_f32 v32, v32, 0x3c2aaaab, v169
	v_cmp_gt_f32_e32 vcc, s77, v32
	v_mul_f32_e32 v33, 0x4b800000, v32
	s_nop 0
	v_cndmask_b32_e32 v32, v32, v33, vcc
	v_rsq_f32_e32 v32, v32
	s_nop 0
	v_mul_f32_e32 v33, 0x45800000, v32
	v_cndmask_b32_e32 v46, v32, v33, vcc
	s_waitcnt vmcnt(0)
	v_mul_f32_e32 v32, v36, v46
	v_mul_f32_e32 v36, v128, v46
	v_mov_b32_e32 v128, v37
	v_mul_f32_e32 v126, v72, v36
	v_pk_mul_f32 v[36:37], v[128:129], v[46:47] op_sel_hi:[1,0]
	v_mov_b32_e32 v72, v77
	v_pk_mul_f32 v[128:129], v[72:73], v[36:37]
	v_mul_f32_e32 v36, v130, v46
	v_mov_b32_e32 v130, v39
	v_mul_f32_e32 v76, v76, v32
	v_mul_f32_e32 v32, v38, v46
	v_mul_f32_e32 v72, v74, v36
	v_pk_mul_f32 v[36:37], v[130:131], v[46:47] op_sel_hi:[1,0]
	v_mov_b32_e32 v74, v79
	v_mul_f32_e32 v78, v78, v32
	global_load_dwordx4 v[32:35], v[100:101], off offset:288
	v_pk_mul_f32 v[74:75], v[74:75], v[36:37]
	global_load_dwordx4 v[36:39], v[100:101], off offset:352
	v_mov_b32_e32 v127, v129
	v_mov_b32_e32 v73, v75
	s_waitcnt vmcnt(1)
	v_mul_f32_e32 v32, v32, v46
	v_mul_f32_e32 v32, v64, v32
	s_waitcnt vmcnt(0)
	v_mul_f32_e32 v36, v36, v46
	v_mul_f32_e32 v64, v68, v36
	v_mov_b32_e32 v36, v33
	v_pk_mul_f32 v[36:37], v[36:37], v[46:47] op_sel_hi:[1,0]
	v_mov_b32_e32 v68, v65
	v_mul_f32_e32 v33, v38, v46
	v_mov_b32_e32 v38, v35
	v_pk_mul_f32 v[68:69], v[68:69], v[36:37]
	v_mul_f32_e32 v36, v70, v33
	v_pk_mul_f32 v[38:39], v[38:39], v[46:47] op_sel_hi:[1,0]
	v_mov_b32_e32 v70, v67
	v_mul_f32_e32 v34, v34, v46
	v_pk_mul_f32 v[38:39], v[70:71], v[38:39]
	v_mul_f32_e32 v34, v66, v34
	v_mov_b32_e32 v65, v69
	v_mov_b32_e32 v37, v39
	s_and_saveexec_b64 s[2:3], s[38:39]
	s_cbranch_execz .LBB0_339
	v_mul_f32_e32 v33, v136, v152
	v_mul_f32_e32 v35, 0.15915494, v33
	v_floor_f32_e32 v35, v35
	v_mul_f32_e32 v37, v137, v152
	v_fma_f32 v33, v33, 0.15915494, -v35
	v_mul_f32_e32 v47, 0.15915494, v37
	v_cos_f32_e32 v35, v33
	v_sin_f32_e32 v33, v33
	v_floor_f32_e32 v47, v47
	v_fma_f32 v37, v37, 0.15915494, -v47
	v_sin_f32_e32 v71, v37
	v_cos_f32_e32 v70, v37
	v_mul_f32_e32 v130, v33, v126
	v_mul_f32_e32 v132, v33, v76
	v_mul_f32_e32 v33, v138, v152
	v_mul_f32_e32 v37, v139, v152
	v_mul_f32_e32 v66, v35, v76
	v_mul_f32_e32 v126, v35, v126
	v_mul_f32_e32 v35, 0.15915494, v33
	v_mul_f32_e32 v47, 0.15915494, v37
	v_pk_mul_f32 v[76:77], v[70:71], v[128:129]
	v_floor_f32_e32 v35, v35
	v_floor_f32_e32 v47, v47
	v_mov_b32_e32 v67, v76
	v_mov_b32_e32 v131, v77
	v_fma_f32 v33, v33, 0.15915494, -v35
	v_fma_f32 v37, v37, 0.15915494, -v47
	v_pk_add_f32 v[76:77], v[66:67], v[130:131] neg_lo:[0,1] neg_hi:[0,1]
	v_mov_b32_e32 v66, v71
	v_mov_b32_e32 v67, v70
	v_cos_f32_e32 v35, v33
	v_sin_f32_e32 v33, v33
	v_sin_f32_e32 v71, v37
	v_cos_f32_e32 v70, v37
	v_pk_mul_f32 v[66:67], v[66:67], v[128:129]
	v_mul_f32_e32 v130, v33, v78
	v_mov_b32_e32 v133, v66
	v_mul_f32_e32 v66, v35, v78
	v_pk_mul_f32 v[78:79], v[70:71], v[74:75]
	v_mov_b32_e32 v127, v67
	v_mul_f32_e32 v128, v33, v72
	v_mov_b32_e32 v67, v78
	v_mov_b32_e32 v129, v79
	v_pk_add_f32 v[78:79], v[66:67], v[128:129] neg_lo:[0,1] neg_hi:[0,1]
	v_mov_b32_e32 v66, v71
	v_mov_b32_e32 v67, v70
	v_pk_mul_f32 v[66:67], v[66:67], v[74:75]
	v_mul_f32_e32 v74, v140, v32
	v_mov_b32_e32 v131, v66
	v_mul_f32_e32 v66, v141, v32
	v_pk_mul_f32 v[32:33], v[106:107], v[68:69]
	v_mov_b32_e32 v73, v67
	v_mul_f32_e32 v70, v140, v64
	v_mov_b32_e32 v67, v32
	v_mov_b32_e32 v71, v33
	v_pk_add_f32 v[32:33], v[66:67], v[70:71] neg_lo:[0,1] neg_hi:[0,1]
	v_pk_mul_f32 v[66:67], v[86:87], v[68:69]
	v_mul_f32_e32 v72, v35, v72
	v_mov_b32_e32 v75, v66
	v_mul_f32_e32 v66, v143, v34
	v_mul_f32_e32 v70, v142, v34
	v_pk_mul_f32 v[34:35], v[104:105], v[38:39]
	v_mov_b32_e32 v65, v67
	v_mul_f32_e32 v68, v142, v36
	v_mov_b32_e32 v67, v34
	v_mov_b32_e32 v69, v35
	v_pk_mul_f32 v[38:39], v[88:89], v[38:39]
	v_mul_f32_e32 v64, v141, v64
	v_mul_f32_e32 v36, v143, v36
	v_pk_add_f32 v[34:35], v[66:67], v[68:69] neg_lo:[0,1] neg_hi:[0,1]
	v_mov_b32_e32 v71, v38
	v_mov_b32_e32 v37, v39
	v_pk_add_f32 v[126:127], v[132:133], v[126:127]
	v_pk_add_f32 v[72:73], v[130:131], v[72:73]
	v_pk_add_f32 v[64:65], v[74:75], v[64:65]
	v_pk_add_f32 v[36:37], v[70:71], v[36:37]
	v_mov_b32_e32 v38, v35
	v_mov_b32_e32 v68, v33
	v_mov_b32_e32 v74, v79
	v_mov_b32_e32 v128, v77

;     ...
;   const int nk = K >> 6;
;   const int cch = (tid & 7) ^ ((tid >> 4) & 7);
;   const u16* ga = A + (size_t)(tid >> 3) * lda + cch * 8;
;   const u16* gb = Bt + (size_t)(tid >> 3) * ldb + cch * 8;
;   char* lds_t = smem + tid * 16;
;   auto issue_piece = [&](int kt, int pc) {
;     char* st = lds_t + (kt % NSTG) * STAGE;
;     if (pc < 4)
;       __builtin_amdgcn_global_load_lds((const unsigned*)(ga + (size_t)(64 * pc) * lda + (size_t)kt * ksa), (unsigned __attribute__((address_space(3)))*)(st + pc * 8192), 16, 0, 0);
;     else
;       __builtin_amdgcn_global_load_lds((const unsigned*)(gb + (size_t)(64 * (pc - 4)) * ldb + (size_t)kt * ksb), (unsigned __attribute__((address_space(3)))*)(st + ABYTES + (pc - 4) * 8192), 16, 0, 0);
;   };
;   const int x = (r >> 1) & 7;
;   int xo[4];
; #pragma unroll
;   for (int s = 0; s < 4; ++s) xo[s] = (((2 * s + h) ^ x) << 4);
;   asm volatile("s_waitcnt vmcnt(0)" ::: "memory");
; #pragma unroll
;   for (int d = 0; d < DIST; ++d)
; #pragma unroll
;     for (int pc = 0; pc < NLD; ++pc) issue_piece(d, pc);
;   pre();
;   for (int kt = 0; kt < nk; ++kt) {
;     if (DIST == 2 && kt + 1 < nk) {
;       if (NLD == 6) asm volatile("s_waitcnt vmcnt(6)" ::: "memory");
;       else if (NLD == 5) asm volatile("s_waitcnt vmcnt(5)" ::: "memory");
;       else asm volatile("s_waitcnt vmcnt(8)" ::: "memory");
;     } else {
;       asm volatile("s_waitcnt vmcnt(0)" ::: "memory");
;     }
;     __builtin_amdgcn_s_barrier();
; DEV void phase_upproj(const Params& p, int l, int hf, char* smem) {
;     ...
;     if (nt < 8) {
;       const int hd = nt;
;       float sqv[6];
;       auto load_sq = [&]() {
;         const float* sq = ssq + (size_t)m * 16;
; #pragma unroll
;         for (int i = 0; i < 6; ++i) sqv[i] = sq[i];
;       };
;       gemm_main<4, 1, 128, 3>(acc, (const u16*)(ws + OFF_CQ) + (size_t)mt * 256 * 384, 384,
;                       (const u16*)(ws + OFF_WUQ) + ((size_t)l * 1024 + hd * 128) * 384, 384, 384, smem, w * 32, 0, 64, 64, load_sq);
;       const float rcq = rsqrtf((sqv[0] + sqv[1] + sqv[2] + sqv[3] + sqv[4] + sqv[5]) * (1.f / 384.f) + EPS);
.LBB0_340:
	s_and_b64 vcc, exec, s[2:3]
	s_cbranch_vccz .LBB0_335
	s_mul_i32 s2, s44, 0x30000
	s_mul_hi_i32 s3, s44, 0x30000
	s_add_u32 s2, s8, s2
	s_addc_u32 s3, s9, s3
	s_lshl_b32 s14, s13, 7
	s_ashr_i32 s15, s14, 31
	s_add_u32 s14, s42, s14
	s_addc_u32 s15, s43, s15
	v_mov_b32_e32 v4, v147
	s_mulk_i32 s15, 0x300
	s_mul_hi_u32 s16, s14, 0x300
	s_add_i32 s16, s16, s15
	v_lshrrev_b32_e32 v0, 4, v4
	s_mulk_i32 s14, 0x300
	v_xor_b32_e32 v5, v0, v4
	s_add_u32 s14, s10, s14
	v_ashrrev_i32_e32 v6, 3, v4
	v_mov_b64_e32 v[2:3], s[2:3]
	v_lshlrev_b32_e32 v5, 4, v5
	s_addc_u32 s15, s11, s16
	v_mad_i64_i32 v[2:3], s[2:3], v6, s78, v[2:3]
	v_and_b32_e32 v144, 0x70, v5
	v_lshl_add_u32 v76, v4, 4, 0
	v_mov_b64_e32 v[0:1], s[14:15]
	v_lshl_add_u64 v[56:57], v[2:3], 0, v[144:145]
	v_readfirstlane_b32 s29, v76
	v_add_u32_e32 v3, 0x2000, v76
	v_mad_i64_i32 v[0:1], s[14:15], v6, s78, v[0:1]
	s_mov_b32 m0, s29
	v_readfirstlane_b32 s28, v3
	v_add_u32_e32 v3, 0x4000, v76
	v_lshl_add_u64 v[54:55], v[0:1], 0, v[144:145]
	global_load_lds_dwordx4 v[56:57], off
	v_lshl_add_u64 v[0:1], v[56:57], 0, s[60:61]
	s_mov_b32 m0, s28
	v_readfirstlane_b32 s27, v3
	v_add_u32_e32 v3, 0x6000, v76
	v_add_u32_e32 v2, 0x8000, v76
	global_load_lds_dwordx4 v[0:1], off
	v_lshl_add_u64 v[0:1], v[56:57], 0, s[58:59]
	s_mov_b32 m0, s27
	v_readfirstlane_b32 s26, v3
	global_load_lds_dwordx4 v[0:1], off
	v_lshl_add_u64 v[0:1], v[56:57], 0, s[62:63]
	s_mov_b32 m0, s26
	v_readfirstlane_b32 s25, v2
	v_add_u32_e32 v2, 0xa000, v76
	global_load_lds_dwordx4 v[0:1], off
	s_mov_b32 m0, s25
	v_readfirstlane_b32 s24, v2
	v_add_u32_e32 v5, 0xc000, v76
	global_load_lds_dwordx4 v[54:55], off
	v_lshl_add_u64 v[0:1], v[54:55], 0, s[60:61]
	s_mov_b32 m0, s24
	s_mov_b64 s[2:3], 0x80
	v_readfirstlane_b32 s23, v5
	v_add_u32_e32 v5, 0xe000, v76
	global_load_lds_dwordx4 v[0:1], off
	v_lshl_add_u64 v[2:3], v[56:57], 0, s[2:3]
	s_mov_b32 m0, s23
	s_mov_b64 s[14:15], 0xc080
	v_readfirstlane_b32 s22, v5
	v_add_u32_e32 v5, 0x10000, v76
	global_load_lds_dwordx4 v[2:3], off
	v_lshl_add_u64 v[2:3], v[56:57], 0, s[14:15]
	s_mov_b32 m0, s22
	v_readfirstlane_b32 s21, v5
	v_add_u32_e32 v5, 0x12000, v76
	v_lshl_add_u64 v[0:1], v[54:55], 0, s[2:3]
	global_load_lds_dwordx4 v[2:3], off
	v_lshl_add_u64 v[2:3], v[56:57], 0, s[48:49]
	s_mov_b32 m0, s21
	s_mov_b64 s[2:3], 0x24080
	v_readfirstlane_b32 s20, v5
	v_add_u32_e32 v6, 0x14000, v76
	global_load_lds_dwordx4 v[2:3], off
	v_lshl_add_u64 v[2:3], v[56:57], 0, s[2:3]
	s_mov_b32 m0, s20
	v_readfirstlane_b32 s18, v6
	global_load_lds_dwordx4 v[2:3], off
	v_add_u32_e32 v2, 0x16000, v76
	s_mov_b32 m0, s18
	v_readfirstlane_b32 s16, v2
	global_load_lds_dwordx4 v[0:1], off
	v_lshl_add_u64 v[0:1], v[54:55], 0, s[14:15]
	s_mov_b32 m0, s16
	v_bfe_u32 v9, v4, 1, 3
	global_load_lds_dwordx4 v[0:1], off
	v_lshlrev_b64 v[0:1], 6, v[112:113]
	v_lshl_add_u64 v[0:1], s[40:41], 0, v[0:1]
	flat_load_dwordx4 v[48:51], v[0:1]
	flat_load_dwordx2 v[52:53], v[0:1] offset:16
	v_lshrrev_b32_e32 v0, 5, v4
	v_bfe_u32 v8, v4, 5, 1
	v_bitop3_b32 v0, v0, v9, 1 bitop3:0x6c
	v_lshlrev_b32_e32 v77, 4, v0
	v_bitop3_b32 v0, v8, v9, 2 bitop3:0x36
	v_lshlrev_b32_e32 v78, 4, v0
	v_bitop3_b32 v0, v8, v9, 4 bitop3:0x36
	v_lshlrev_b32_e32 v79, 4, v0
	v_and_b32_e32 v0, 31, v4
	v_or_b32_e32 v1, v0, v134
	v_lshlrev_b32_e32 v111, 7, v1
	v_lshlrev_b32_e32 v112, 7, v0
	v_add_u32_e32 v113, 0, v111
	v_add_u32_e32 v114, 0, v112
	v_add_u32_e32 v115, v113, v77
	s_waitcnt vmcnt(6)
	s_barrier
	v_add_u32_e32 v116, v114, v77
	ds_read_b128 v[0:3], v115
	ds_read_b128 v[4:7], v116 offset:32768
	s_waitcnt lgkmcnt(0)
	v_mfma_f32_32x32x16_bf16 v[32:47], v[4:7], v[0:3], 0
	v_bitop3_b32 v8, v8, v9, 6 bitop3:0x36
	v_lshlrev_b32_e32 v117, 4, v8
	ds_read_b128 v[8:11], v116 offset:36864
	ds_read_b128 v[12:15], v116 offset:40960
	s_mov_b64 s[2:3], 0x100
	v_add_u32_e32 v18, 0x18000, v76
	v_lshl_add_u64 v[74:75], v[54:55], 0, s[2:3]
	v_lshl_add_u64 v[16:17], v[56:57], 0, s[2:3]
	v_add_u32_e32 v118, 0x20000, v76
	v_readfirstlane_b32 s2, v18
	s_mov_b32 m0, s2
	s_nop 0
	global_load_lds_dwordx4 v[16:17], off
	s_waitcnt lgkmcnt(0)
	v_mfma_f32_32x32x16_bf16 v[16:31], v[8:11], v[0:3], 0
	v_add_u32_e32 v6, 0x1a000, v76
	s_mov_b64 s[44:45], 0xc100
	v_readfirstlane_b32 s14, v6
	v_lshl_add_u64 v[4:5], v[56:57], 0, s[44:45]
	s_mov_b32 m0, s14
	s_nop 0
	global_load_lds_dwordx4 v[4:5], off
	v_mfma_f32_32x32x16_bf16 v[0:15], v[12:15], v[0:3], 0
	v_add_u32_e32 v60, 0x1c000, v76
	v_lshl_add_u64 v[58:59], v[56:57], 0, s[52:53]
	v_readfirstlane_b32 s3, v60
	s_mov_b32 m0, s3
	s_nop 0
	global_load_lds_dwordx4 v[58:59], off
	v_add_u32_e32 v119, v114, v78
	ds_read_b128 v[58:61], v119 offset:32768
	v_add_u32_e32 v120, v113, v78
	ds_read_b128 v[62:65], v120
	ds_read_b128 v[66:69], v119 offset:36864
	ds_read_b128 v[70:73], v119 offset:40960
	s_waitcnt lgkmcnt(0)
	v_mfma_f32_32x32x16_bf16 v[32:47], v[58:61], v[62:65], v[32:47]
	v_add_u32_e32 v60, 0x1e000, v76
	s_mov_b64 s[30:31], 0x24100
	v_readfirstlane_b32 s15, v60
	v_lshl_add_u64 v[58:59], v[56:57], 0, s[30:31]
	s_mov_b32 m0, s15
	s_nop 0
	global_load_lds_dwordx4 v[58:59], off
	v_mfma_f32_32x32x16_bf16 v[16:31], v[66:69], v[62:65], v[16:31]
	v_readfirstlane_b32 s17, v118
	s_mov_b32 m0, s17
	s_nop 0
	global_load_lds_dwordx4 v[74:75], off
	v_mfma_f32_32x32x16_bf16 v[0:15], v[70:73], v[62:65], v[0:15]
	v_add_u32_e32 v60, 0x22000, v76
	v_lshl_add_u64 v[58:59], v[54:55], 0, s[44:45]
	v_readfirstlane_b32 s19, v60
	s_mov_b32 m0, s19
	s_nop 0
	global_load_lds_dwordx4 v[58:59], off
	v_add_u32_e32 v76, v114, v79
	ds_read_b128 v[58:61], v76 offset:32768
	v_add_u32_e32 v118, v113, v79
	ds_read_b128 v[62:65], v118
	v_add_u32_e32 v114, v114, v117
	v_add_u32_e32 v113, v113, v117
	s_add_i32 s30, 0, 0x14000
	v_add_u32_e32 v121, s30, v112
	v_add_u32_e32 v122, v121, v77
	s_mov_b64 s[30:31], 0x180
	s_waitcnt lgkmcnt(0)
	v_mfma_f32_32x32x16_bf16 v[32:47], v[58:61], v[62:65], v[32:47]
	ds_read_b128 v[58:61], v76 offset:36864
	ds_read_b128 v[66:69], v76 offset:40960
	v_lshl_add_u64 v[74:75], v[54:55], 0, s[30:31]
	s_waitcnt lgkmcnt(0)
	v_mfma_f32_32x32x16_bf16 v[16:31], v[58:61], v[62:65], v[16:31]
	ds_read_b128 v[58:61], v114 offset:32768
	v_mfma_f32_32x32x16_bf16 v[0:15], v[66:69], v[62:65], v[0:15]
	ds_read_b128 v[62:65], v113
	s_waitcnt lgkmcnt(0)
	v_mfma_f32_32x32x16_bf16 v[32:47], v[58:61], v[62:65], v[32:47]
	ds_read_b128 v[58:61], v114 offset:36864
	ds_read_b128 v[66:69], v114 offset:40960
	s_waitcnt vmcnt(6)
	s_barrier
; #define MFMA(a, b, c) __builtin_amdgcn_mfma_f32_32x32x16_bf16((a), (b), (c), 0, 0, 0)
;     ...
;   for (int kt = 0; kt < nk; ++kt) {
;     if (DIST == 2 && kt + 1 < nk) {
;       if (NLD == 6) asm volatile("s_waitcnt vmcnt(6)" ::: "memory");
;       else if (NLD == 5) asm volatile("s_waitcnt vmcnt(5)" ::: "memory");
;       else asm volatile("s_waitcnt vmcnt(8)" ::: "memory");
;     } else {
;       asm volatile("s_waitcnt vmcnt(0)" ::: "memory");
;     }
;     __builtin_amdgcn_s_barrier();
;     const bool pre = (kt + DIST < nk);
;     const char* base = smem + (kt % NSTG) * STAGE;
;     const char* pa = base + (wrow_act + r) * 128;
;     const char* pw = base + ABYTES + (wrow_w + r) * 128;
;     constexpr int NM = NI * MJ;
;     constexpr int PPS = (NLD + 1) / 2;
; #pragma unroll
;     for (int s = 0; s < 4; ++s) {
;       bf16x8 af[MJ], wf[NI];
; #pragma unroll
;       for (int j = 0; j < MJ; ++j) af[j] = *(const bf16x8*)(pa + j * 32 * 128 + xo[s]);
; #pragma unroll
;       for (int i = 0; i < NI; ++i) wf[i] = *(const bf16x8*)(pw + i * 32 * 128 + xo[s]);
; #pragma unroll
;       for (int m = 0; m < NM; ++m) {
;         const int i = m / MJ, j = m % MJ;
;         acc[i][j] = MFMA(wf[i], af[j], acc[i][j]);
;         if (s < 2 && NM >= PPS) {
;           constexpr int EVERY = (NM / PPS) > 0 ? (NM / PPS) : 1;
;           if ((m + 1) % EVERY == 0) {
;             const int pc = s * PPS + (m + 1) / EVERY - 1;
;             if ((m + 1) / EVERY <= PPS && pc < NLD) {
;               __builtin_amdgcn_sched_barrier(0);
;               if (pre) issue_piece(kt + DIST, pc);
;               __builtin_amdgcn_sched_barrier(0);
;             }
;           }
;         }
;         if (s < 2 && NM < PPS) {
;           const int slot = s * NM + m;
;           __builtin_amdgcn_sched_barrier(0);
; #pragma unroll
;           for (int pc = 0; pc < NLD; ++pc)
;             if ((pc * 2 * NM) / NLD == slot && pre) issue_piece(kt + DIST, pc);
;           __builtin_amdgcn_sched_barrier(0);
;         }
;       }
;     }
;   }
	s_waitcnt lgkmcnt(0)
	v_mfma_f32_32x32x16_bf16 v[16:31], v[58:61], v[62:65], v[16:31]
	v_mfma_f32_32x32x16_bf16 v[0:15], v[66:69], v[62:65], v[0:15]
	ds_read_b128 v[58:61], v122
	ds_read_b128 v[62:65], v115 offset:49152
	ds_read_b128 v[66:69], v122 offset:4096
	ds_read_b128 v[70:73], v122 offset:8192
	s_waitcnt lgkmcnt(0)
	v_mfma_f32_32x32x16_bf16 v[32:47], v[58:61], v[62:65], v[32:47]
	v_lshl_add_u64 v[58:59], v[56:57], 0, s[30:31]
	s_mov_b32 m0, s29
	s_nop 0
	global_load_lds_dwordx4 v[58:59], off
	v_mfma_f32_32x32x16_bf16 v[16:31], v[66:69], v[62:65], v[16:31]
	s_mov_b64 s[30:31], 0xc180
	v_lshl_add_u64 v[58:59], v[56:57], 0, s[30:31]
	s_mov_b32 m0, s28
	s_nop 0
	global_load_lds_dwordx4 v[58:59], off
	v_mfma_f32_32x32x16_bf16 v[0:15], v[70:73], v[62:65], v[0:15]
	v_lshl_add_u64 v[58:59], v[56:57], 0, s[54:55]
	s_mov_b32 m0, s27
	s_nop 0
	global_load_lds_dwordx4 v[58:59], off
	v_add_u32_e32 v123, v121, v78
	ds_read_b128 v[58:61], v123
	ds_read_b128 v[62:65], v120 offset:49152
	ds_read_b128 v[66:69], v123 offset:4096
	ds_read_b128 v[70:73], v123 offset:8192
	s_waitcnt lgkmcnt(0)
	v_mfma_f32_32x32x16_bf16 v[32:47], v[58:61], v[62:65], v[32:47]
	s_mov_b64 s[28:29], 0x24180
	v_lshl_add_u64 v[58:59], v[56:57], 0, s[28:29]
	s_mov_b32 m0, s26
	s_nop 0
	global_load_lds_dwordx4 v[58:59], off
	v_mfma_f32_32x32x16_bf16 v[16:31], v[66:69], v[62:65], v[16:31]
	s_mov_b32 m0, s25
	s_nop 0
	global_load_lds_dwordx4 v[74:75], off
	v_mfma_f32_32x32x16_bf16 v[0:15], v[70:73], v[62:65], v[0:15]
	v_lshl_add_u64 v[58:59], v[54:55], 0, s[30:31]
	s_mov_b32 m0, s24
	s_nop 0
	global_load_lds_dwordx4 v[58:59], off
	v_add_u32_e32 v124, v121, v79
	ds_read_b128 v[58:61], v124
	ds_read_b128 v[62:65], v118 offset:49152
	ds_read_b128 v[66:69], v113 offset:49152
	ds_read_b128 v[70:73], v124 offset:4096
	v_add_u32_e32 v121, v121, v117
	s_add_i32 s24, 0, 0x20000
	s_waitcnt lgkmcnt(0)
	v_mfma_f32_32x32x16_bf16 v[32:47], v[58:61], v[62:65], v[32:47]
	ds_read_b128 v[58:61], v124 offset:8192
	v_add_u32_e32 v112, s24, v112
	v_add_u32_e32 v125, v112, v77
	s_add_i32 s24, 0, 0x18000
	v_add_u32_e32 v111, s24, v111
	v_add_u32_e32 v77, v111, v77
	s_mov_b64 s[24:25], 0x200
	v_mfma_f32_32x32x16_bf16 v[16:31], v[70:73], v[62:65], v[16:31]
	ds_read_b128 v[70:73], v121
	v_lshl_add_u64 v[74:75], v[54:55], 0, s[24:25]
	s_waitcnt lgkmcnt(0)
	v_mfma_f32_32x32x16_bf16 v[0:15], v[58:61], v[62:65], v[0:15]
	ds_read_b128 v[58:61], v121 offset:4096
	ds_read_b128 v[62:65], v121 offset:8192
	s_waitcnt vmcnt(6)
	s_barrier
	s_waitcnt lgkmcnt(0)
	v_mfma_f32_32x32x16_bf16 v[16:31], v[58:61], v[66:69], v[16:31]
	ds_read_b128 v[58:61], v125
	v_mfma_f32_32x32x16_bf16 v[32:47], v[70:73], v[66:69], v[32:47]
	v_mfma_f32_32x32x16_bf16 v[0:15], v[62:65], v[66:69], v[0:15]
	ds_read_b128 v[62:65], v77
	ds_read_b128 v[66:69], v125 offset:4096
	ds_read_b128 v[70:73], v125 offset:8192
	s_waitcnt lgkmcnt(0)
	v_mfma_f32_32x32x16_bf16 v[32:47], v[58:61], v[62:65], v[32:47]
	v_lshl_add_u64 v[58:59], v[56:57], 0, s[24:25]
	s_mov_b32 m0, s23
	s_nop 0
	global_load_lds_dwordx4 v[58:59], off
	v_mfma_f32_32x32x16_bf16 v[16:31], v[66:69], v[62:65], v[16:31]
	s_mov_b64 s[24:25], 0xc200
	v_lshl_add_u64 v[58:59], v[56:57], 0, s[24:25]
	s_mov_b32 m0, s22
	s_nop 0
	global_load_lds_dwordx4 v[58:59], off
	v_mfma_f32_32x32x16_bf16 v[0:15], v[70:73], v[62:65], v[0:15]
	s_mov_b64 s[22:23], 0x18200
	v_lshl_add_u64 v[58:59], v[56:57], 0, s[22:23]
	s_mov_b32 m0, s21
	s_nop 0
	global_load_lds_dwordx4 v[58:59], off
	v_add_u32_e32 v126, v112, v78
	ds_read_b128 v[58:61], v126
	v_add_u32_e32 v78, v111, v78
	ds_read_b128 v[62:65], v78
	ds_read_b128 v[66:69], v126 offset:4096
	ds_read_b128 v[70:73], v126 offset:8192
	s_waitcnt lgkmcnt(0)
	v_mfma_f32_32x32x16_bf16 v[32:47], v[58:61], v[62:65], v[32:47]
	s_mov_b64 s[22:23], 0x24200
	v_lshl_add_u64 v[58:59], v[56:57], 0, s[22:23]
	s_mov_b32 m0, s20
	s_nop 0
	global_load_lds_dwordx4 v[58:59], off
	v_mfma_f32_32x32x16_bf16 v[16:31], v[66:69], v[62:65], v[16:31]
	s_mov_b32 m0, s18
	s_nop 0
	global_load_lds_dwordx4 v[74:75], off
	v_mfma_f32_32x32x16_bf16 v[0:15], v[70:73], v[62:65], v[0:15]
	v_lshl_add_u64 v[58:59], v[54:55], 0, s[24:25]
	s_mov_b32 m0, s16
	s_nop 0
	global_load_lds_dwordx4 v[58:59], off
	v_add_u32_e32 v127, v112, v79
	ds_read_b128 v[58:61], v127
	v_add_u32_e32 v79, v111, v79
	ds_read_b128 v[62:65], v79
	v_add_u32_e32 v112, v112, v117
	v_add_u32_e32 v111, v111, v117
	s_mov_b64 s[20:21], 0x280
	v_lshl_add_u64 v[74:75], v[54:55], 0, s[20:21]
	s_waitcnt lgkmcnt(0)
	v_mfma_f32_32x32x16_bf16 v[32:47], v[58:61], v[62:65], v[32:47]
	ds_read_b128 v[58:61], v127 offset:4096
	ds_read_b128 v[66:69], v127 offset:8192
	s_waitcnt lgkmcnt(0)
	v_mfma_f32_32x32x16_bf16 v[16:31], v[58:61], v[62:65], v[16:31]
	ds_read_b128 v[58:61], v112
	v_mfma_f32_32x32x16_bf16 v[0:15], v[66:69], v[62:65], v[0:15]
	ds_read_b128 v[62:65], v111
	s_waitcnt lgkmcnt(0)
	v_mfma_f32_32x32x16_bf16 v[32:47], v[58:61], v[62:65], v[32:47]
	ds_read_b128 v[58:61], v112 offset:4096
	ds_read_b128 v[66:69], v112 offset:8192
	s_waitcnt vmcnt(6)
	s_barrier
; #define MFMA(a, b, c) __builtin_amdgcn_mfma_f32_32x32x16_bf16((a), (b), (c), 0, 0, 0)
;     ...
;   for (int kt = 0; kt < nk; ++kt) {
;     if (DIST == 2 && kt + 1 < nk) {
;       if (NLD == 6) asm volatile("s_waitcnt vmcnt(6)" ::: "memory");
;       else if (NLD == 5) asm volatile("s_waitcnt vmcnt(5)" ::: "memory");
;       else asm volatile("s_waitcnt vmcnt(8)" ::: "memory");
;     } else {
;       asm volatile("s_waitcnt vmcnt(0)" ::: "memory");
;     }
;     __builtin_amdgcn_s_barrier();
;     const bool pre = (kt + DIST < nk);
;     const char* base = smem + (kt % NSTG) * STAGE;
;     const char* pa = base + (wrow_act + r) * 128;
;     const char* pw = base + ABYTES + (wrow_w + r) * 128;
;     constexpr int NM = NI * MJ;
;     constexpr int PPS = (NLD + 1) / 2;
; #pragma unroll
;     for (int s = 0; s < 4; ++s) {
;       bf16x8 af[MJ], wf[NI];
; #pragma unroll
;       for (int j = 0; j < MJ; ++j) af[j] = *(const bf16x8*)(pa + j * 32 * 128 + xo[s]);
; #pragma unroll
;       for (int i = 0; i < NI; ++i) wf[i] = *(const bf16x8*)(pw + i * 32 * 128 + xo[s]);
; #pragma unroll
;       for (int m = 0; m < NM; ++m) {
;         const int i = m / MJ, j = m % MJ;
;         acc[i][j] = MFMA(wf[i], af[j], acc[i][j]);
;         if (s < 2 && NM >= PPS) {
;           constexpr int EVERY = (NM / PPS) > 0 ? (NM / PPS) : 1;
;           if ((m + 1) % EVERY == 0) {
;             const int pc = s * PPS + (m + 1) / EVERY - 1;
;             if ((m + 1) / EVERY <= PPS && pc < NLD) {
;               __builtin_amdgcn_sched_barrier(0);
;               if (pre) issue_piece(kt + DIST, pc);
;               __builtin_amdgcn_sched_barrier(0);
;             }
;           }
;         }
;         if (s < 2 && NM < PPS) {
;           const int slot = s * NM + m;
;           __builtin_amdgcn_sched_barrier(0);
; #pragma unroll
;           for (int pc = 0; pc < NLD; ++pc)
;             if ((pc * 2 * NM) / NLD == slot && pre) issue_piece(kt + DIST, pc);
;           __builtin_amdgcn_sched_barrier(0);
;         }
;       }
;     }
;   }
; DEV void phase_upproj(const Params& p, int l, int hf, char* smem) {
;     ...
;       const float rcq = rsqrtf((sqv[0] + sqv[1] + sqv[2] + sqv[3] + sqv[4] + sqv[5]) * (1.f / 384.f) + EPS);
	s_waitcnt lgkmcnt(0)
	v_mfma_f32_32x32x16_bf16 v[16:31], v[58:61], v[62:65], v[16:31]
	v_mfma_f32_32x32x16_bf16 v[0:15], v[66:69], v[62:65], v[0:15]
	ds_read_b128 v[58:61], v116 offset:32768
	ds_read_b128 v[62:65], v115
	ds_read_b128 v[66:69], v116 offset:36864
	ds_read_b128 v[70:73], v116 offset:40960
	s_waitcnt lgkmcnt(0)
	v_mfma_f32_32x32x16_bf16 v[32:47], v[58:61], v[62:65], v[32:47]
	v_lshl_add_u64 v[58:59], v[56:57], 0, s[20:21]
	s_mov_b32 m0, s2
	s_nop 0
	global_load_lds_dwordx4 v[58:59], off
	v_mfma_f32_32x32x16_bf16 v[16:31], v[66:69], v[62:65], v[16:31]
	s_mov_b64 s[22:23], 0xc280
	v_lshl_add_u64 v[58:59], v[56:57], 0, s[22:23]
	s_mov_b32 m0, s14
	s_nop 0
	global_load_lds_dwordx4 v[58:59], off
	v_mfma_f32_32x32x16_bf16 v[0:15], v[70:73], v[62:65], v[0:15]
	s_mov_b64 s[20:21], 0x18280
	v_lshl_add_u64 v[58:59], v[56:57], 0, s[20:21]
	s_mov_b32 m0, s3
	s_nop 0
	global_load_lds_dwordx4 v[58:59], off
	ds_read_b128 v[58:61], v119 offset:32768
	ds_read_b128 v[62:65], v120
	ds_read_b128 v[66:69], v119 offset:36864
	ds_read_b128 v[70:73], v119 offset:40960
	s_waitcnt lgkmcnt(0)
	v_mfma_f32_32x32x16_bf16 v[32:47], v[58:61], v[62:65], v[32:47]
	s_mov_b64 s[2:3], 0x24280
	v_lshl_add_u64 v[56:57], v[56:57], 0, s[2:3]
	s_mov_b32 m0, s15
	s_nop 0
	global_load_lds_dwordx4 v[56:57], off
	v_mfma_f32_32x32x16_bf16 v[16:31], v[66:69], v[62:65], v[16:31]
	s_mov_b32 m0, s17
	s_nop 0
	global_load_lds_dwordx4 v[74:75], off
	v_mfma_f32_32x32x16_bf16 v[0:15], v[70:73], v[62:65], v[0:15]
	v_lshl_add_u64 v[54:55], v[54:55], 0, s[22:23]
	s_mov_b32 m0, s19
	s_nop 0
	global_load_lds_dwordx4 v[54:55], off
	ds_read_b128 v[54:57], v76 offset:32768
	ds_read_b128 v[58:61], v118
	s_waitcnt lgkmcnt(0)
	v_mfma_f32_32x32x16_bf16 v[32:47], v[54:57], v[58:61], v[32:47]
	ds_read_b128 v[54:57], v76 offset:36864
	ds_read_b128 v[62:65], v76 offset:40960
	s_waitcnt lgkmcnt(0)
	v_mfma_f32_32x32x16_bf16 v[16:31], v[54:57], v[58:61], v[16:31]
	v_mfma_f32_32x32x16_bf16 v[0:15], v[62:65], v[58:61], v[0:15]
	ds_read_b128 v[54:57], v114 offset:32768
	ds_read_b128 v[58:61], v113
	s_waitcnt lgkmcnt(0)
	v_mfma_f32_32x32x16_bf16 v[32:47], v[54:57], v[58:61], v[32:47]
	ds_read_b128 v[54:57], v114 offset:36864
	ds_read_b128 v[62:65], v114 offset:40960
	s_waitcnt vmcnt(6)
	s_barrier
	s_waitcnt lgkmcnt(0)
	v_mfma_f32_32x32x16_bf16 v[16:31], v[54:57], v[58:61], v[16:31]
	v_mfma_f32_32x32x16_bf16 v[0:15], v[62:65], v[58:61], v[0:15]
	ds_read_b128 v[54:57], v122
	ds_read_b128 v[58:61], v115 offset:49152
	ds_read_b128 v[62:65], v122 offset:4096
	ds_read_b128 v[66:69], v122 offset:8192
	s_waitcnt lgkmcnt(0)
	v_mfma_f32_32x32x16_bf16 v[32:47], v[54:57], v[58:61], v[32:47]
	v_mfma_f32_32x32x16_bf16 v[16:31], v[62:65], v[58:61], v[16:31]
	v_mfma_f32_32x32x16_bf16 v[0:15], v[66:69], v[58:61], v[0:15]
	ds_read_b128 v[54:57], v123
	ds_read_b128 v[58:61], v120 offset:49152
	ds_read_b128 v[62:65], v123 offset:4096
	ds_read_b128 v[66:69], v123 offset:8192
	s_waitcnt lgkmcnt(0)
	v_mfma_f32_32x32x16_bf16 v[32:47], v[54:57], v[58:61], v[32:47]
	v_mfma_f32_32x32x16_bf16 v[16:31], v[62:65], v[58:61], v[16:31]
	v_mfma_f32_32x32x16_bf16 v[0:15], v[66:69], v[58:61], v[0:15]
	ds_read_b128 v[54:57], v124
	ds_read_b128 v[58:61], v118 offset:49152
	s_waitcnt lgkmcnt(0)
	v_mfma_f32_32x32x16_bf16 v[32:47], v[54:57], v[58:61], v[32:47]
	ds_read_b128 v[54:57], v124 offset:4096
	s_waitcnt lgkmcnt(0)
	v_mfma_f32_32x32x16_bf16 v[16:31], v[54:57], v[58:61], v[16:31]
	ds_read_b128 v[54:57], v124 offset:8192
	s_waitcnt lgkmcnt(0)
	v_mfma_f32_32x32x16_bf16 v[0:15], v[54:57], v[58:61], v[0:15]
	ds_read_b128 v[54:57], v121
	ds_read_b128 v[58:61], v113 offset:49152
	s_waitcnt lgkmcnt(0)
	v_mfma_f32_32x32x16_bf16 v[32:47], v[54:57], v[58:61], v[32:47]
	ds_read_b128 v[54:57], v121 offset:4096
	s_waitcnt lgkmcnt(0)
	v_mfma_f32_32x32x16_bf16 v[16:31], v[54:57], v[58:61], v[16:31]
	ds_read_b128 v[54:57], v121 offset:8192
	s_waitcnt vmcnt(0)
	s_barrier
	s_waitcnt lgkmcnt(0)
	v_mfma_f32_32x32x16_bf16 v[0:15], v[54:57], v[58:61], v[0:15]
	ds_read_b128 v[54:57], v125
	ds_read_b128 v[58:61], v77
	ds_read_b128 v[62:65], v125 offset:4096
	ds_read_b128 v[66:69], v125 offset:8192
	s_waitcnt lgkmcnt(0)
	v_mfma_f32_32x32x16_bf16 v[32:47], v[54:57], v[58:61], v[32:47]
	v_mfma_f32_32x32x16_bf16 v[16:31], v[62:65], v[58:61], v[16:31]
	v_mfma_f32_32x32x16_bf16 v[0:15], v[66:69], v[58:61], v[0:15]
	ds_read_b128 v[54:57], v126
	ds_read_b128 v[58:61], v78
	ds_read_b128 v[62:65], v126 offset:4096
	ds_read_b128 v[66:69], v126 offset:8192
	s_waitcnt lgkmcnt(0)
	v_mfma_f32_32x32x16_bf16 v[32:47], v[54:57], v[58:61], v[32:47]
	v_mfma_f32_32x32x16_bf16 v[16:31], v[62:65], v[58:61], v[16:31]
	v_mfma_f32_32x32x16_bf16 v[0:15], v[66:69], v[58:61], v[0:15]
	ds_read_b128 v[54:57], v127
	ds_read_b128 v[58:61], v79
	ds_read_b128 v[62:65], v127 offset:4096
	ds_read_b128 v[66:69], v127 offset:8192
	ds_read_b128 v[70:73], v111
	ds_read_b128 v[74:77], v112 offset:8192
	s_waitcnt vmcnt(0)
	v_add_f32_e32 v48, v48, v49
	v_add_f32_e32 v48, v48, v50
	s_waitcnt lgkmcnt(2)
	v_mfma_f32_32x32x16_bf16 v[0:15], v[66:69], v[58:61], v[0:15]
	v_add_f32_e32 v48, v48, v51
	v_add_f32_e32 v48, v48, v52
	v_add_f32_e32 v48, v48, v53
	v_fmamk_f32 v48, v48, 0x3b2aaaab, v169
	v_mul_f32_e32 v49, 0x4b800000, v48
	v_cmp_gt_f32_e32 vcc, s77, v48
	v_mfma_f32_32x32x16_bf16 v[32:47], v[54:57], v[58:61], v[32:47]
	s_nop 0
	v_cndmask_b32_e32 v48, v48, v49, vcc
	v_rsq_f32_e32 v56, v48
	ds_read_b128 v[48:51], v112 offset:4096
	ds_read_b128 v[52:55], v112
	s_barrier
; DEV float xor32(float v) { return __shfl_xor(v, 32, 64); }
; DEV int crow_of(int reg, int h) { return (reg & 3) + 8 * (reg >> 2) + 4 * h; }
; DEV void phase_upproj(const Params& p, int l, int hf, char* smem) {
;     ...
;       const float rcq = rsqrtf((sqv[0] + sqv[1] + sqv[2] + sqv[3] + sqv[4] + sqv[5]) * (1.f / 384.f) + EPS);
;       float ss = 0;
; #pragma unroll
;       for (int i = 0; i < 3; ++i)
; #pragma unroll
;         for (int e = 0; e < 16; ++e) { acc[i][0][e] *= rcq; ss += acc[i][0][e] * acc[i][0][e]; }
;       ss += xor32(ss);
;       const float rs = rsqrtf(ss * (1.f / 96.f) + EPS);
;       const float* gain = p.mla_q_g + l * 96;
;       const float qs = 0.10206207261596577f * LOG2E;
;       u16* drow = (u16*)(ws + OFF_MQ) + ((size_t)(bl * 8 + hd) * TP + tp) * 96;
; #pragma unroll
;       for (int i = 0; i < 3; ++i)
; #pragma unroll
;         for (int e = 0; e < 16; ++e) acc[i][0][e] *= rs * gain[32 * i + crow_of(e, h)];
	global_load_dwordx4 v[116:119], v[102:103], off offset:288
	global_load_dwordx4 v[120:123], v[102:103], off offset:352
	v_mul_f32_e32 v57, 0x45800000, v56
	v_cndmask_b32_e32 v78, v56, v57, vcc
	v_mfma_f32_32x32x16_bf16 v[16:31], v[62:65], v[58:61], v[16:31]
	s_waitcnt lgkmcnt(2)
	v_mfma_f32_32x32x16_bf16 v[0:15], v[74:77], v[70:73], v[0:15]
	s_waitcnt lgkmcnt(0)
	v_mfma_f32_32x32x16_bf16 v[32:47], v[52:55], v[70:73], v[32:47]
	s_nop 9
	v_mul_f32_e64 v128, v78, v12
	v_mul_f32_e64 v129, v78, v13
	v_and_b32_e32 v12, 64, v175
	v_mul_f32_e32 v115, v78, v6
	v_xor_b32_e32 v6, 32, v175
	v_add_u32_e32 v12, 64, v12
	v_cmp_lt_i32_e32 vcc, v6, v12
	v_mul_f32_e32 v131, v78, v14
	v_mfma_f32_32x32x16_bf16 v[16:31], v[48:51], v[70:73], v[16:31]
	v_cndmask_b32_e32 v6, v175, v6, vcc
	v_lshlrev_b32_e32 v111, 2, v6
	v_mov_b32_e32 v6, v15
	v_mul_f32_e64 v132, v78, v6
	v_mul_f32_e64 v133, v78, v7
	v_pk_mul_f32 v[6:7], v[78:79], v[46:47] op_sel_hi:[0,1]
	v_pk_mul_f32 v[46:47], v[78:79], v[44:45] op_sel_hi:[0,1]
	v_pk_mul_f32 v[48:49], v[78:79], v[42:43] op_sel_hi:[0,1]
	global_load_dwordx4 v[12:15], v[102:103], off offset:96
	global_load_dwordx4 v[42:45], v[102:103], off offset:64
	v_pk_mul_f32 v[52:53], v[78:79], v[40:41] op_sel_hi:[0,1]
	v_pk_mul_f32 v[54:55], v[78:79], v[38:39] op_sel_hi:[0,1]
	v_pk_mul_f32 v[60:61], v[78:79], v[36:37] op_sel_hi:[0,1]
	v_pk_mul_f32 v[62:63], v[78:79], v[34:35] op_sel_hi:[0,1]
	global_load_dwordx4 v[34:37], v[102:103], off offset:32
	global_load_dwordx4 v[38:41], v[102:103], off
	v_pk_mul_f32 v[66:67], v[78:79], v[32:33] op_sel_hi:[0,1]
	v_pk_mul_f32 v[50:51], v[78:79], v[30:31] op_sel_hi:[0,1]
	v_pk_mul_f32 v[56:57], v[78:79], v[28:29] op_sel_hi:[0,1]
	v_pk_mul_f32 v[58:59], v[78:79], v[26:27] op_sel_hi:[0,1]
	global_load_dwordx4 v[26:29], v[102:103], off offset:224
	global_load_dwordx4 v[30:33], v[102:103], off offset:192
	global_load_dwordx4 v[74:77], v[102:103], off offset:256
	v_pk_mul_f32 v[64:65], v[78:79], v[24:25] op_sel_hi:[0,1]
	v_pk_mul_f32 v[68:69], v[78:79], v[22:23] op_sel_hi:[0,1]
	v_pk_mul_f32 v[70:71], v[78:79], v[20:21] op_sel_hi:[0,1]
	v_pk_mul_f32 v[72:73], v[78:79], v[18:19] op_sel_hi:[0,1]
	global_load_dwordx4 v[18:21], v[102:103], off offset:160
	global_load_dwordx4 v[22:25], v[102:103], off offset:128
	global_load_dwordx4 v[124:127], v[102:103], off offset:320
	v_mov_b32_e32 v114, v133
	v_pk_mul_f32 v[188:189], v[66:67], v[66:67]
	v_pk_mul_f32 v[154:155], v[114:115], v[114:115]
	v_pk_mul_f32 v[186:187], v[62:63], v[62:63]
	v_add_f32_e32 v114, v188, v189
	v_add_f32_e32 v114, v186, v114
	v_pk_mul_f32 v[184:185], v[60:61], v[60:61]
	v_add_f32_e32 v114, v187, v114
	v_add_f32_e32 v114, v184, v114
	v_pk_mul_f32 v[182:183], v[54:55], v[54:55]
	v_add_f32_e32 v114, v185, v114
	v_add_f32_e32 v114, v182, v114
	v_pk_mul_f32 v[164:165], v[52:53], v[52:53]
	v_add_f32_e32 v114, v183, v114
	v_add_f32_e32 v114, v164, v114
	v_pk_mul_f32 v[162:163], v[48:49], v[48:49]
	v_add_f32_e32 v114, v165, v114
	v_add_f32_e32 v114, v162, v114
	v_pk_mul_f32 v[160:161], v[46:47], v[46:47]
	v_add_f32_e32 v114, v163, v114
	v_add_f32_e32 v114, v160, v114
	v_pk_mul_f32 v[158:159], v[6:7], v[6:7]
	v_add_f32_e32 v114, v161, v114
	v_pk_mul_f32 v[16:17], v[78:79], v[16:17] op_sel_hi:[0,1]
	v_add_f32_e32 v114, v158, v114
	v_pk_mul_f32 v[204:205], v[16:17], v[16:17]
	v_add_f32_e32 v114, v159, v114
	v_add_f32_e32 v114, v204, v114
	v_pk_mul_f32 v[202:203], v[72:73], v[72:73]
	v_add_f32_e32 v114, v205, v114
	v_add_f32_e32 v114, v202, v114
	v_pk_mul_f32 v[200:201], v[70:71], v[70:71]
	v_add_f32_e32 v114, v203, v114
	v_add_f32_e32 v114, v200, v114
	v_pk_mul_f32 v[198:199], v[68:69], v[68:69]
	v_add_f32_e32 v114, v201, v114
	v_add_f32_e32 v114, v198, v114
	v_pk_mul_f32 v[196:197], v[64:65], v[64:65]
	v_add_f32_e32 v114, v199, v114
	v_add_f32_e32 v114, v196, v114
	v_pk_mul_f32 v[194:195], v[58:59], v[58:59]
	v_add_f32_e32 v114, v197, v114
	v_add_f32_e32 v114, v194, v114
	v_pk_mul_f32 v[192:193], v[56:57], v[56:57]
	v_add_f32_e32 v114, v195, v114
	v_add_f32_e32 v114, v192, v114
	v_pk_mul_f32 v[190:191], v[50:51], v[50:51]
	v_add_f32_e32 v114, v193, v114
	v_pk_mul_f32 v[0:1], v[78:79], v[0:1] op_sel_hi:[0,1]
	v_add_f32_e32 v114, v190, v114
	v_pk_mul_f32 v[206:207], v[0:1], v[0:1]
	v_add_f32_e32 v114, v191, v114
	v_pk_mul_f32 v[2:3], v[78:79], v[2:3] op_sel_hi:[0,1]
	v_add_f32_e32 v114, v206, v114
	v_pk_mul_f32 v[210:211], v[2:3], v[2:3]
	v_add_f32_e32 v114, v207, v114
	v_pk_mul_f32 v[4:5], v[78:79], v[4:5] op_sel_hi:[0,1]
	v_add_f32_e32 v114, v210, v114
	v_pk_mul_f32 v[8:9], v[78:79], v[8:9] op_sel_hi:[0,1]
	v_pk_mul_f32 v[10:11], v[78:79], v[10:11] op_sel_hi:[0,1]
	v_pk_mul_f32 v[78:79], v[4:5], v[4:5]
	v_add_f32_e32 v114, v211, v114
	v_add_f32_e32 v78, v78, v114
	v_add_f32_e32 v78, v79, v78
	v_add_f32_e32 v78, v155, v78
	v_pk_mul_f32 v[208:209], v[8:9], v[8:9]
	v_add_f32_e32 v78, v154, v78
	v_add_f32_e32 v78, v208, v78
	v_pk_mul_f32 v[212:213], v[10:11], v[10:11]
	v_add_f32_e32 v78, v209, v78
	v_add_f32_e32 v78, v212, v78
	v_pk_mul_f32 v[112:113], v[128:129], v[128:129]
	v_add_f32_e32 v78, v213, v78
	v_mov_b32_e32 v130, v132
	v_add_f32_e32 v78, v112, v78
	v_pk_mul_f32 v[156:157], v[130:131], v[130:131]
	v_add_f32_e32 v78, v113, v78
	v_add_f32_e32 v78, v157, v78
	v_add_f32_e32 v78, v156, v78
	ds_bpermute_b32 v79, v111, v78
	s_waitcnt vmcnt(10)
	v_mov_b32_e32 v154, v123
	v_mov_b32_e32 v155, v119
	s_waitcnt lgkmcnt(0)
	v_add_f32_e32 v78, v78, v79
	v_fmamk_f32 v78, v78, 0x3c2aaaab, v169
	v_mul_f32_e32 v79, 0x4b800000, v78
	v_cmp_gt_f32_e32 vcc, s77, v78
	s_nop 1
	v_cndmask_b32_e32 v78, v78, v79, vcc
	v_rsq_f32_e32 v78, v78
	s_nop 0
	v_mul_f32_e32 v79, 0x45800000, v78
	v_cndmask_b32_e32 v114, v78, v79, vcc
	s_waitcnt vmcnt(3)
	v_pk_mul_f32 v[74:75], v[74:75], v[114:115] op_sel_hi:[1,0]
	s_nop 0
	v_pk_mul_f32 v[112:113], v[0:1], v[74:75]
	v_pk_mul_f32 v[0:1], v[76:77], v[114:115] op_sel_hi:[1,0]
	s_nop 0
	v_pk_mul_f32 v[78:79], v[2:3], v[0:1]
	v_pk_mul_f32 v[0:1], v[116:117], v[114:115] op_sel_hi:[1,0]
	s_nop 0
	v_pk_mul_f32 v[76:77], v[4:5], v[0:1]
	v_mul_f32_e32 v0, v118, v114
	v_mul_f32_e32 v4, v115, v0
	v_pk_mul_f32 v[0:1], v[154:155], v[114:115] op_sel_hi:[1,0]
	v_mul_f32_e32 v5, v122, v114
	v_pk_mul_f32 v[74:75], v[132:133], v[0:1]
	s_waitcnt vmcnt(0)
	v_pk_mul_f32 v[0:1], v[124:125], v[114:115] op_sel_hi:[1,0]
	s_nop 0
	v_pk_mul_f32 v[8:9], v[8:9], v[0:1]
	v_pk_mul_f32 v[0:1], v[126:127], v[114:115] op_sel_hi:[1,0]
	s_nop 0
	v_pk_mul_f32 v[2:3], v[10:11], v[0:1]
	v_pk_mul_f32 v[0:1], v[120:121], v[114:115] op_sel_hi:[1,0]
	v_mul_f32_e32 v10, v131, v5
	v_pk_mul_f32 v[0:1], v[128:129], v[0:1]
	s_and_saveexec_b64 s[2:3], s[38:39]
	s_cbranch_execz .LBB0_334
; DEV float fast_exp2(float x) { return __builtin_amdgcn_exp2f(x); }
; DEV int crow_of(int reg, int h) { return (reg & 3) + 8 * (reg >> 2) + 4 * h; }
; DEV void phase_upproj(const Params& p, int l, int hf, char* smem) {
;     ...
;       if (latent) {
; #pragma unroll
;         for (int e = 0; e < 8; ++e) {
;           const int a = crow_of(e, h);
;           const float inv = fast_exp2(-(float)(a & 7) * 1.6609640474436813f);
;           const float ang = ((a < 8) ? prow : pcol) * inv;
;           float sn, cs;
;           sincos_fast(ang, sn, cs);
;           const float x1 = acc[2][0][e], x2 = acc[2][0][e + 8];
;           acc[2][0][e] = x1 * cs - x2 * sn;
;           acc[2][0][e + 8] = x2 * cs + x1 * sn;
;         }
;       }
	v_mul_f32_e32 v5, v146, v152
	v_mul_f32_e32 v11, 0.15915494, v5
	v_floor_f32_e32 v11, v11
	v_fma_f32 v5, v5, 0.15915494, -v11
	v_sin_f32_e32 v116, v5
	v_cos_f32_e32 v118, v5
	v_mul_f32_e32 v5, v148, v152
	v_mul_f32_e32 v11, 0.15915494, v5
	v_floor_f32_e32 v11, v11
	v_fma_f32 v5, v5, 0.15915494, -v11
	v_sin_f32_e32 v117, v5
	v_cos_f32_e32 v119, v5
	v_mul_f32_e32 v5, v149, v152
	v_mul_f32_e32 v11, 0.15915494, v5
	v_pk_mul_f32 v[120:121], v[116:117], v[8:9]
	v_floor_f32_e32 v11, v11
	v_pk_fma_f32 v[120:121], v[118:119], v[112:113], v[120:121] neg_lo:[0,0,1] neg_hi:[0,0,1]
	v_pk_mul_f32 v[112:113], v[116:117], v[112:113]
	v_fma_f32 v5, v5, 0.15915494, -v11
	v_pk_fma_f32 v[8:9], v[118:119], v[8:9], v[112:113]
	v_sin_f32_e32 v112, v5
	v_cos_f32_e32 v116, v5
	v_mul_f32_e32 v5, v150, v152
	v_mul_f32_e32 v11, 0.15915494, v5
	v_floor_f32_e32 v11, v11
	v_fma_f32 v5, v5, 0.15915494, -v11
	v_sin_f32_e32 v113, v5
	v_cos_f32_e32 v117, v5
	v_mov_b32_e32 v11, v74
	v_mov_b32_e32 v5, v75
	v_pk_mul_f32 v[118:119], v[112:113], v[2:3]
	s_nop 0
	v_pk_fma_f32 v[118:119], v[116:117], v[78:79], v[118:119] neg_lo:[0,0,1] neg_hi:[0,0,1]
	v_pk_mul_f32 v[78:79], v[112:113], v[78:79]
	v_mov_b32_e32 v112, v120
	v_pk_fma_f32 v[2:3], v[116:117], v[2:3], v[78:79]
	v_pk_mul_f32 v[78:79], v[90:91], v[0:1]
	v_mov_b32_e32 v113, v121
	v_pk_fma_f32 v[116:117], v[92:93], v[76:77], v[78:79] neg_lo:[0,0,1] neg_hi:[0,0,1]
	v_pk_mul_f32 v[76:77], v[90:91], v[76:77]
	v_mul_f32_e32 v78, v94, v4
	v_pk_fma_f32 v[0:1], v[92:93], v[0:1], v[76:77]
	v_mul_f32_e32 v76, v96, v10
	v_pk_mul_f32 v[10:11], v[94:95], v[10:11]
	s_nop 0
	v_pk_fma_f32 v[4:5], v[96:97], v[4:5], v[10:11] neg_lo:[0,0,1] neg_hi:[0,0,1]
	v_pk_mul_f32 v[10:11], v[98:99], v[74:75]
	v_mov_b32_e32 v75, v5
	v_mov_b32_e32 v77, v10
	v_mov_b32_e32 v79, v11
	v_pk_add_f32 v[10:11], v[76:77], v[78:79]
	v_mov_b32_e32 v78, v118
	v_mov_b32_e32 v79, v119
	v_mov_b32_e32 v76, v116
	v_mov_b32_e32 v77, v117
	v_mov_b32_e32 v74, v11
	s_branch .LBB0_334

; DEV int opaque_tid() { int t = threadIdx.x; asm volatile("" : "+v"(t)); return t; }
;     ...
;   const int nk = K >> 6;
;   const int cch = (tid & 7) ^ ((tid >> 4) & 7);
;   const u16* ga = A + (size_t)(tid >> 3) * lda + cch * 8;
;   const u16* gb = Bt + (size_t)(tid >> 3) * ldb + cch * 8;
;   char* lds_t = smem + tid * 16;
;   auto issue_piece = [&](int kt, int pc) {
;     char* st = lds_t + (kt % NSTG) * STAGE;
;     if (pc < 4)
;       __builtin_amdgcn_global_load_lds((const unsigned*)(ga + (size_t)(64 * pc) * lda + (size_t)kt * ksa), (unsigned __attribute__((address_space(3)))*)(st + pc * 8192), 16, 0, 0);
;     else
;       __builtin_amdgcn_global_load_lds((const unsigned*)(gb + (size_t)(64 * (pc - 4)) * ldb + (size_t)kt * ksb), (unsigned __attribute__((address_space(3)))*)(st + ABYTES + (pc - 4) * 8192), 16, 0, 0);
;   };
;   const int x = (r >> 1) & 7;
;   int xo[4];
; #pragma unroll
;   for (int s = 0; s < 4; ++s) xo[s] = (((2 * s + h) ^ x) << 4);
;   asm volatile("s_waitcnt vmcnt(0)" ::: "memory");
; #pragma unroll
;   for (int d = 0; d < DIST; ++d)
; #pragma unroll
;     for (int pc = 0; pc < NLD; ++pc) issue_piece(d, pc);
;   pre();
;   for (int kt = 0; kt < nk; ++kt) {
;     if (DIST == 2 && kt + 1 < nk) {
;       if (NLD == 6) asm volatile("s_waitcnt vmcnt(6)" ::: "memory");
;       else if (NLD == 5) asm volatile("s_waitcnt vmcnt(5)" ::: "memory");
;       else asm volatile("s_waitcnt vmcnt(8)" ::: "memory");
;     } else {
;       asm volatile("s_waitcnt vmcnt(0)" ::: "memory");
;     }
;     __builtin_amdgcn_s_barrier();
; DEV void phase_inproj(const Params& p, int l, int hf, char* smem) {
;     ...
;   const int w = opaque_tid() >> 6, wm = w >> 1, wn = w & 1;
;   const int nslots = ((66 * 33 + 7) / 8) * 8;
;   for (int t = blockIdx.x; t < nslots; t += gridDim.x) {
;     int mt, nt;
;     if (!tile_decode(t, 66, 33, 3, mt, nt)) continue;
;     f32x16 acc[4][2];
; #pragma unroll
;     for (int i = 0; i < 4; ++i)
; #pragma unroll
;       for (int j = 0; j < 2; ++j)
; #pragma unroll
;         for (int e = 0; e < 16; ++e) acc[i][j][e] = 0.f;
;     gemm_main<4, 2, 256, 2>(acc, H + (size_t)mt * 256 * 1024, 64, W + (size_t)nt * 256 * 1024, 64, 1024, smem, wm * 64, wn * 128, 256 * 64, 256 * 64);
.LBB0_353:
	s_ashr_i32 s53, s52, 31
	s_lshl_b64 s[0:1], s[52:53], 19
	s_add_u32 s0, s22, s0
	v_mov_b32_e32 v4, v147
	s_addc_u32 s1, s23, s1
	s_ashr_i32 s51, s50, 31
	s_lshl_b64 s[2:3], s[50:51], 19
	v_lshrrev_b32_e32 v0, 4, v4
	v_xor_b32_e32 v5, v0, v4
	v_ashrrev_i32_e32 v0, 3, v4
	s_add_u32 s2, s24, s2
	v_ashrrev_i32_e32 v1, 31, v0
	s_addc_u32 s3, s25, s3
	v_lshlrev_b64 v[0:1], 7, v[0:1]
	v_lshlrev_b32_e32 v5, 4, v5
	v_lshl_add_u32 v184, v4, 4, 0
	v_lshl_add_u64 v[2:3], s[2:3], 0, v[0:1]
	v_lshl_add_u64 v[0:1], s[0:1], 0, v[0:1]
	v_and_b32_e32 v144, 0x70, v5
	v_readfirstlane_b32 s15, v184
	v_add_u32_e32 v183, 0x2000, v184
	v_lshl_add_u64 v[130:131], v[0:1], 0, v[144:145]
	s_mov_b32 m0, s15
	s_mov_b64 s[0:1], 0x2000
	v_readfirstlane_b32 s14, v183
	v_add_u32_e32 v182, 0x4000, v184
	global_load_lds_dwordx4 v[130:131], off
	v_lshl_add_u64 v[0:1], v[130:131], 0, s[0:1]
	s_mov_b32 m0, s14
	s_mov_b64 s[2:3], 0x4000
	v_readfirstlane_b32 s13, v182
	v_add_u32_e32 v181, 0x6000, v184
	v_add_u32_e32 v162, 0x8000, v184
	global_load_lds_dwordx4 v[0:1], off
	v_lshl_add_u64 v[0:1], v[130:131], 0, s[2:3]
	s_mov_b32 m0, s13
	s_mov_b64 s[4:5], 0x6000
	v_readfirstlane_b32 s12, v181
	global_load_lds_dwordx4 v[0:1], off
	v_lshl_add_u64 v[0:1], v[130:131], 0, s[4:5]
	s_mov_b32 m0, s12
	v_readfirstlane_b32 s11, v162
	v_add_u32_e32 v165, 0xa000, v184
	v_lshl_add_u64 v[128:129], v[2:3], 0, v[144:145]
	global_load_lds_dwordx4 v[0:1], off
	s_mov_b32 m0, s11
	v_readfirstlane_b32 s10, v165
	v_add_u32_e32 v164, 0xc000, v184
	global_load_lds_dwordx4 v[128:129], off
	v_lshl_add_u64 v[0:1], v[128:129], 0, s[0:1]
	s_mov_b32 m0, s10
	v_readfirstlane_b32 s9, v164
	v_add_u32_e32 v163, 0xe000, v184
	global_load_lds_dwordx4 v[0:1], off
	v_lshl_add_u64 v[0:1], v[128:129], 0, s[2:3]
	s_mov_b32 m0, s9
	v_readfirstlane_b32 s8, v163
	global_load_lds_dwordx4 v[0:1], off
	v_lshl_add_u64 v[0:1], v[128:129], 0, s[4:5]
	s_mov_b32 m0, s8
	v_bfe_u32 v17, v4, 1, 3
	global_load_lds_dwordx4 v[0:1], off
	v_lshrrev_b32_e32 v0, 5, v4
	v_bfe_u32 v16, v4, 5, 1
	v_bitop3_b32 v0, v0, v17, 1 bitop3:0x6c
	v_lshlrev_b32_e32 v142, 4, v0
	v_bitop3_b32 v0, v16, v17, 2 bitop3:0x36
	v_lshlrev_b32_e32 v143, 4, v0
	v_and_b32_e32 v0, 31, v4
	v_lshlrev_b32_e32 v144, 7, v0
	v_add_u32_e32 v151, v149, v144
	v_add_u32_e32 v132, v151, v142
	v_or_b32_e32 v4, v0, v146
	s_waitcnt vmcnt(0)
	s_barrier
	ds_read_b128 v[0:3], v132 offset:32768
	v_lshlrev_b32_e32 v152, 7, v4
	v_add_u32_e32 v153, 0, v152
	v_add_u32_e32 v136, v153, v142
	ds_read_b128 v[4:7], v136
	v_bitop3_b32 v8, v16, v17, 4 bitop3:0x36
	v_lshlrev_b32_e32 v185, 4, v8
	ds_read_b128 v[8:11], v136 offset:4096
	ds_read_b128 v[12:15], v132 offset:36864
	s_waitcnt lgkmcnt(0)
	v_mfma_f32_32x32x16_bf16 v[96:111], v[0:3], v[4:7], 0
	v_bitop3_b32 v16, v16, v17, 6 bitop3:0x36
	v_lshlrev_b32_e32 v210, 4, v16
	ds_read_b128 v[16:19], v132 offset:40960
	ds_read_b128 v[138:141], v132 offset:45056
	v_add_u32_e32 v155, 0x10000, v184
	v_lshl_add_u64 v[134:135], v[128:129], 0, s[34:35]
	v_add_u32_e32 v154, 0x18000, v184
	v_mfma_f32_32x32x16_bf16 v[64:79], v[0:3], v[8:11], 0
	v_readfirstlane_b32 s3, v155
	v_lshl_add_u64 v[0:1], v[130:131], 0, s[34:35]
	s_mov_b32 m0, s3
	s_nop 0
	global_load_lds_dwordx4 v[0:1], off
	v_mfma_f32_32x32x16_bf16 v[112:127], v[12:15], v[4:7], 0
	v_mfma_f32_32x32x16_bf16 v[80:95], v[12:15], v[8:11], 0
	v_add_u32_e32 v158, 0x12000, v184
	s_mov_b64 s[6:7], 0xa000
	v_readfirstlane_b32 s2, v158
	v_lshl_add_u64 v[0:1], v[130:131], 0, s[6:7]
	s_mov_b32 m0, s2
	s_nop 0
	global_load_lds_dwordx4 v[0:1], off
	s_waitcnt lgkmcnt(0)
	v_mfma_f32_32x32x16_bf16 v[48:63], v[16:19], v[4:7], 0
	v_mfma_f32_32x32x16_bf16 v[16:31], v[16:19], v[8:11], 0
	v_add_u32_e32 v157, 0x14000, v184
	v_lshl_add_u64 v[0:1], v[130:131], 0, s[60:61]
	v_readfirstlane_b32 s1, v157
	s_mov_b32 m0, s1
	s_nop 0
	global_load_lds_dwordx4 v[0:1], off
	v_mfma_f32_32x32x16_bf16 v[32:47], v[138:141], v[4:7], 0
	v_mfma_f32_32x32x16_bf16 v[0:15], v[138:141], v[8:11], 0
	v_add_u32_e32 v156, 0x16000, v184
	v_lshl_add_u64 v[138:139], v[130:131], 0, s[36:37]
	v_readfirstlane_b32 s0, v156
	s_mov_b32 m0, s0
	s_nop 0
	global_load_lds_dwordx4 v[138:139], off
	v_add_u32_e32 v133, v151, v143
	ds_read_b128 v[138:141], v133 offset:32768
	v_add_u32_e32 v137, v153, v143
	ds_read_b128 v[186:189], v137
	ds_read_b128 v[190:193], v137 offset:4096
	ds_read_b128 v[194:197], v133 offset:36864
	ds_read_b128 v[198:201], v133 offset:40960
	ds_read_b128 v[202:205], v133 offset:45056
	s_waitcnt lgkmcnt(0)
	v_mfma_f32_32x32x16_bf16 v[96:111], v[138:141], v[186:189], v[96:111]
	v_mfma_f32_32x32x16_bf16 v[64:79], v[138:141], v[190:193], v[64:79]
	v_readfirstlane_b32 s4, v154
	s_mov_b32 m0, s4
	s_nop 0
	global_load_lds_dwordx4 v[134:135], off
	v_mfma_f32_32x32x16_bf16 v[112:127], v[194:197], v[186:189], v[112:127]
	v_mfma_f32_32x32x16_bf16 v[80:95], v[194:197], v[190:193], v[80:95]
	v_add_u32_e32 v159, 0x1a000, v184
	v_lshl_add_u64 v[134:135], v[128:129], 0, s[6:7]
	v_readfirstlane_b32 s5, v159
	s_mov_b32 m0, s5
	s_nop 0
	global_load_lds_dwordx4 v[134:135], off
	v_mfma_f32_32x32x16_bf16 v[48:63], v[198:201], v[186:189], v[48:63]
	v_mfma_f32_32x32x16_bf16 v[16:31], v[198:201], v[190:193], v[16:31]
	v_add_u32_e32 v160, 0x1c000, v184
	v_lshl_add_u64 v[134:135], v[128:129], 0, s[60:61]
	v_readfirstlane_b32 s6, v160
	s_mov_b32 m0, s6
	s_nop 0
	global_load_lds_dwordx4 v[134:135], off
	v_mfma_f32_32x32x16_bf16 v[32:47], v[202:205], v[186:189], v[32:47]
	v_mfma_f32_32x32x16_bf16 v[0:15], v[202:205], v[190:193], v[0:15]
	v_add_u32_e32 v161, 0x1e000, v184
	v_lshl_add_u64 v[134:135], v[128:129], 0, s[36:37]
	v_readfirstlane_b32 s7, v161
	s_mov_b32 m0, s7
	s_nop 0
	global_load_lds_dwordx4 v[134:135], off
	v_add_u32_e32 v135, v151, v185
	ds_read_b128 v[186:189], v135 offset:32768
	v_add_u32_e32 v140, v153, v185
	ds_read_b128 v[190:193], v140
	ds_read_b128 v[194:197], v140 offset:4096
	ds_read_b128 v[198:201], v135 offset:36864
	v_add_u32_e32 v134, v151, v210
	v_add_u32_e32 v139, v153, v210
	s_waitcnt lgkmcnt(0)
; #define MFMA(a, b, c) __builtin_amdgcn_mfma_f32_32x32x16_bf16((a), (b), (c), 0, 0, 0)
;     ...
;   for (int kt = 0; kt < nk; ++kt) {
;     if (DIST == 2 && kt + 1 < nk) {
;       if (NLD == 6) asm volatile("s_waitcnt vmcnt(6)" ::: "memory");
;       else if (NLD == 5) asm volatile("s_waitcnt vmcnt(5)" ::: "memory");
;       else asm volatile("s_waitcnt vmcnt(8)" ::: "memory");
;     } else {
;       asm volatile("s_waitcnt vmcnt(0)" ::: "memory");
;     }
;     __builtin_amdgcn_s_barrier();
;     const bool pre = (kt + DIST < nk);
;     const char* base = smem + (kt % NSTG) * STAGE;
;     const char* pa = base + (wrow_act + r) * 128;
;     const char* pw = base + ABYTES + (wrow_w + r) * 128;
;     constexpr int NM = NI * MJ;
;     constexpr int PPS = (NLD + 1) / 2;
; #pragma unroll
;     for (int s = 0; s < 4; ++s) {
;       bf16x8 af[MJ], wf[NI];
; #pragma unroll
;       for (int j = 0; j < MJ; ++j) af[j] = *(const bf16x8*)(pa + j * 32 * 128 + xo[s]);
; #pragma unroll
;       for (int i = 0; i < NI; ++i) wf[i] = *(const bf16x8*)(pw + i * 32 * 128 + xo[s]);
; #pragma unroll
;       for (int m = 0; m < NM; ++m) {
;         const int i = m / MJ, j = m % MJ;
;         acc[i][j] = MFMA(wf[i], af[j], acc[i][j]);
;         if (s < 2 && NM >= PPS) {
;           constexpr int EVERY = (NM / PPS) > 0 ? (NM / PPS) : 1;
;           if ((m + 1) % EVERY == 0) {
;             const int pc = s * PPS + (m + 1) / EVERY - 1;
;             if ((m + 1) / EVERY <= PPS && pc < NLD) {
;               __builtin_amdgcn_sched_barrier(0);
;               if (pre) issue_piece(kt + DIST, pc);
;               __builtin_amdgcn_sched_barrier(0);
;             }
;           }
;         }
;         if (s < 2 && NM < PPS) {
;           const int slot = s * NM + m;
;           __builtin_amdgcn_sched_barrier(0);
; #pragma unroll
;           for (int pc = 0; pc < NLD; ++pc)
;             if ((pc * 2 * NM) / NLD == slot && pre) issue_piece(kt + DIST, pc);
;           __builtin_amdgcn_sched_barrier(0);
;         }
;       }
;     }
;   }
	v_mfma_f32_32x32x16_bf16 v[112:127], v[198:201], v[190:193], v[112:127]
	v_add_u32_e32 v141, v150, v144
	v_add_u32_e32 v138, v141, v142
	s_add_i32 s16, 0, 0x10000
	v_add_u32_e32 v211, s16, v152
	v_add_u32_e32 v142, v211, v142
	v_lshl_add_u64 v[152:153], v[128:129], 0, s[56:57]
	v_mfma_f32_32x32x16_bf16 v[96:111], v[186:189], v[190:193], v[96:111]
	v_mfma_f32_32x32x16_bf16 v[64:79], v[186:189], v[194:197], v[64:79]
	v_mfma_f32_32x32x16_bf16 v[80:95], v[198:201], v[194:197], v[80:95]
	ds_read_b128 v[186:189], v135 offset:40960
	ds_read_b128 v[198:201], v135 offset:45056
	s_waitcnt lgkmcnt(0)
	v_mfma_f32_32x32x16_bf16 v[48:63], v[186:189], v[190:193], v[48:63]
	v_mfma_f32_32x32x16_bf16 v[16:31], v[186:189], v[194:197], v[16:31]
	ds_read_b128 v[186:189], v134 offset:32768
	v_mfma_f32_32x32x16_bf16 v[32:47], v[198:201], v[190:193], v[32:47]
	v_mfma_f32_32x32x16_bf16 v[0:15], v[198:201], v[194:197], v[0:15]
	ds_read_b128 v[190:193], v139
	ds_read_b128 v[194:197], v139 offset:4096
	ds_read_b128 v[198:201], v134 offset:36864
	s_waitcnt lgkmcnt(0)
	v_mfma_f32_32x32x16_bf16 v[96:111], v[186:189], v[190:193], v[96:111]
	v_mfma_f32_32x32x16_bf16 v[64:79], v[186:189], v[194:197], v[64:79]
	v_mfma_f32_32x32x16_bf16 v[112:127], v[198:201], v[190:193], v[112:127]
	v_mfma_f32_32x32x16_bf16 v[80:95], v[198:201], v[194:197], v[80:95]
	ds_read_b128 v[186:189], v134 offset:40960
	ds_read_b128 v[198:201], v134 offset:45056
	s_waitcnt vmcnt(0)
	s_barrier
	s_waitcnt lgkmcnt(0)
	v_mfma_f32_32x32x16_bf16 v[48:63], v[186:189], v[190:193], v[48:63]
	v_mfma_f32_32x32x16_bf16 v[16:31], v[186:189], v[194:197], v[16:31]
	ds_read_b128 v[186:189], v138
	v_mfma_f32_32x32x16_bf16 v[32:47], v[198:201], v[190:193], v[32:47]
	v_mfma_f32_32x32x16_bf16 v[0:15], v[198:201], v[194:197], v[0:15]
	ds_read_b128 v[190:193], v142
	ds_read_b128 v[194:197], v142 offset:4096
	ds_read_b128 v[198:201], v138 offset:4096
	ds_read_b128 v[202:205], v138 offset:8192
	ds_read_b128 v[206:209], v138 offset:12288
	s_waitcnt lgkmcnt(0)
	v_mfma_f32_32x32x16_bf16 v[96:111], v[186:189], v[190:193], v[96:111]
	v_mfma_f32_32x32x16_bf16 v[64:79], v[186:189], v[194:197], v[64:79]
	v_lshl_add_u64 v[186:187], v[130:131], 0, s[56:57]
	s_mov_b32 m0, s15
	s_nop 0
	global_load_lds_dwordx4 v[186:187], off
	v_mfma_f32_32x32x16_bf16 v[112:127], v[198:201], v[190:193], v[112:127]
	v_mfma_f32_32x32x16_bf16 v[80:95], v[198:201], v[194:197], v[80:95]
	s_mov_b64 s[16:17], 0x12000
	v_lshl_add_u64 v[186:187], v[130:131], 0, s[16:17]
	s_mov_b32 m0, s14
	s_nop 0
	global_load_lds_dwordx4 v[186:187], off
	v_mfma_f32_32x32x16_bf16 v[48:63], v[202:205], v[190:193], v[48:63]
	v_mfma_f32_32x32x16_bf16 v[16:31], v[202:205], v[194:197], v[16:31]
	s_mov_b64 s[18:19], 0x14000
	v_lshl_add_u64 v[186:187], v[130:131], 0, s[18:19]
	s_mov_b32 m0, s13
	s_nop 0
	global_load_lds_dwordx4 v[186:187], off
	v_mfma_f32_32x32x16_bf16 v[32:47], v[206:209], v[190:193], v[32:47]
	v_mfma_f32_32x32x16_bf16 v[0:15], v[206:209], v[194:197], v[0:15]
	s_mov_b64 s[20:21], 0x16000
	v_lshl_add_u64 v[186:187], v[130:131], 0, s[20:21]
	s_mov_b32 m0, s12
	s_nop 0
	global_load_lds_dwordx4 v[186:187], off
	v_add_u32_e32 v144, v141, v143
	ds_read_b128 v[186:189], v144
	v_add_u32_e32 v151, v211, v143
	ds_read_b128 v[190:193], v151
	ds_read_b128 v[194:197], v151 offset:4096
	ds_read_b128 v[198:201], v144 offset:4096
	ds_read_b128 v[202:205], v144 offset:8192
	ds_read_b128 v[206:209], v144 offset:12288
	s_waitcnt lgkmcnt(0)
	v_mfma_f32_32x32x16_bf16 v[96:111], v[186:189], v[190:193], v[96:111]
	v_mfma_f32_32x32x16_bf16 v[64:79], v[186:189], v[194:197], v[64:79]
	s_mov_b32 m0, s11
	s_nop 0
	global_load_lds_dwordx4 v[152:153], off
	v_mfma_f32_32x32x16_bf16 v[112:127], v[198:201], v[190:193], v[112:127]
	v_mfma_f32_32x32x16_bf16 v[80:95], v[198:201], v[194:197], v[80:95]
	v_lshl_add_u64 v[152:153], v[128:129], 0, s[16:17]
	s_mov_b32 m0, s10
	s_nop 0
	global_load_lds_dwordx4 v[152:153], off
	v_mfma_f32_32x32x16_bf16 v[48:63], v[202:205], v[190:193], v[48:63]
	v_mfma_f32_32x32x16_bf16 v[16:31], v[202:205], v[194:197], v[16:31]
	v_lshl_add_u64 v[152:153], v[128:129], 0, s[18:19]
	s_mov_b32 m0, s9
	s_nop 0
	global_load_lds_dwordx4 v[152:153], off
	v_mfma_f32_32x32x16_bf16 v[32:47], v[206:209], v[190:193], v[32:47]
	v_mfma_f32_32x32x16_bf16 v[0:15], v[206:209], v[194:197], v[0:15]
	v_lshl_add_u64 v[152:153], v[128:129], 0, s[20:21]
	s_mov_b32 m0, s8
	s_nop 0
	global_load_lds_dwordx4 v[152:153], off
	v_add_u32_e32 v143, v141, v185
	ds_read_b128 v[186:189], v143
	v_add_u32_e32 v153, v211, v185
	ds_read_b128 v[190:193], v153
	ds_read_b128 v[194:197], v153 offset:4096
	ds_read_b128 v[198:201], v143 offset:4096
	v_add_u32_e32 v141, v141, v210
	v_add_u32_e32 v152, v211, v210
	s_waitcnt lgkmcnt(0)
	v_mfma_f32_32x32x16_bf16 v[112:127], v[198:201], v[190:193], v[112:127]
	v_lshl_add_u64 v[210:211], v[128:129], 0, s[58:59]
	v_mfma_f32_32x32x16_bf16 v[96:111], v[186:189], v[190:193], v[96:111]
	v_mfma_f32_32x32x16_bf16 v[64:79], v[186:189], v[194:197], v[64:79]
	v_mfma_f32_32x32x16_bf16 v[80:95], v[198:201], v[194:197], v[80:95]
	ds_read_b128 v[186:189], v143 offset:8192
	ds_read_b128 v[198:201], v143 offset:12288
	s_waitcnt lgkmcnt(0)
	v_mfma_f32_32x32x16_bf16 v[48:63], v[186:189], v[190:193], v[48:63]
	v_mfma_f32_32x32x16_bf16 v[16:31], v[186:189], v[194:197], v[16:31]
	ds_read_b128 v[186:189], v141
	v_mfma_f32_32x32x16_bf16 v[32:47], v[198:201], v[190:193], v[32:47]
	v_mfma_f32_32x32x16_bf16 v[0:15], v[198:201], v[194:197], v[0:15]
	ds_read_b128 v[190:193], v152
	ds_read_b128 v[194:197], v152 offset:4096
	ds_read_b128 v[198:201], v141 offset:4096
	s_waitcnt lgkmcnt(0)
	v_mfma_f32_32x32x16_bf16 v[96:111], v[186:189], v[190:193], v[96:111]
	v_mfma_f32_32x32x16_bf16 v[64:79], v[186:189], v[194:197], v[64:79]
	v_mfma_f32_32x32x16_bf16 v[112:127], v[198:201], v[190:193], v[112:127]
	v_mfma_f32_32x32x16_bf16 v[80:95], v[198:201], v[194:197], v[80:95]
	ds_read_b128 v[186:189], v141 offset:8192
	ds_read_b128 v[198:201], v141 offset:12288
	s_waitcnt vmcnt(0)
	s_barrier
; #define MFMA(a, b, c) __builtin_amdgcn_mfma_f32_32x32x16_bf16((a), (b), (c), 0, 0, 0)
;     ...
;   for (int kt = 0; kt < nk; ++kt) {
;     if (DIST == 2 && kt + 1 < nk) {
;       if (NLD == 6) asm volatile("s_waitcnt vmcnt(6)" ::: "memory");
;       else if (NLD == 5) asm volatile("s_waitcnt vmcnt(5)" ::: "memory");
;       else asm volatile("s_waitcnt vmcnt(8)" ::: "memory");
;     } else {
;       asm volatile("s_waitcnt vmcnt(0)" ::: "memory");
;     }
;     __builtin_amdgcn_s_barrier();
;     const bool pre = (kt + DIST < nk);
;     const char* base = smem + (kt % NSTG) * STAGE;
;     const char* pa = base + (wrow_act + r) * 128;
;     const char* pw = base + ABYTES + (wrow_w + r) * 128;
;     constexpr int NM = NI * MJ;
;     constexpr int PPS = (NLD + 1) / 2;
; #pragma unroll
;     for (int s = 0; s < 4; ++s) {
;       bf16x8 af[MJ], wf[NI];
; #pragma unroll
;       for (int j = 0; j < MJ; ++j) af[j] = *(const bf16x8*)(pa + j * 32 * 128 + xo[s]);
; #pragma unroll
;       for (int i = 0; i < NI; ++i) wf[i] = *(const bf16x8*)(pw + i * 32 * 128 + xo[s]);
; #pragma unroll
;       for (int m = 0; m < NM; ++m) {
;         const int i = m / MJ, j = m % MJ;
;         acc[i][j] = MFMA(wf[i], af[j], acc[i][j]);
;         if (s < 2 && NM >= PPS) {
;           constexpr int EVERY = (NM / PPS) > 0 ? (NM / PPS) : 1;
;           if ((m + 1) % EVERY == 0) {
;             const int pc = s * PPS + (m + 1) / EVERY - 1;
;             if ((m + 1) / EVERY <= PPS && pc < NLD) {
;               __builtin_amdgcn_sched_barrier(0);
;               if (pre) issue_piece(kt + DIST, pc);
;               __builtin_amdgcn_sched_barrier(0);
;             }
;           }
;         }
;         if (s < 2 && NM < PPS) {
;           const int slot = s * NM + m;
;           __builtin_amdgcn_sched_barrier(0);
; #pragma unroll
;           for (int pc = 0; pc < NLD; ++pc)
;             if ((pc * 2 * NM) / NLD == slot && pre) issue_piece(kt + DIST, pc);
;           __builtin_amdgcn_sched_barrier(0);
;         }
;       }
;     }
;   }
	s_waitcnt lgkmcnt(0)
	v_mfma_f32_32x32x16_bf16 v[48:63], v[186:189], v[190:193], v[48:63]
	v_mfma_f32_32x32x16_bf16 v[16:31], v[186:189], v[194:197], v[16:31]
	v_mfma_f32_32x32x16_bf16 v[32:47], v[198:201], v[190:193], v[32:47]
	v_mfma_f32_32x32x16_bf16 v[0:15], v[198:201], v[194:197], v[0:15]
	ds_read_b128 v[186:189], v132 offset:32768
	ds_read_b128 v[190:193], v136
	ds_read_b128 v[194:197], v136 offset:4096
	ds_read_b128 v[198:201], v132 offset:36864
	ds_read_b128 v[202:205], v132 offset:40960
	ds_read_b128 v[206:209], v132 offset:45056
	s_waitcnt lgkmcnt(0)
	v_mfma_f32_32x32x16_bf16 v[96:111], v[186:189], v[190:193], v[96:111]
	v_mfma_f32_32x32x16_bf16 v[64:79], v[186:189], v[194:197], v[64:79]
	v_lshl_add_u64 v[186:187], v[130:131], 0, s[58:59]
	s_mov_b32 m0, s3
	s_nop 0
	global_load_lds_dwordx4 v[186:187], off
	v_mfma_f32_32x32x16_bf16 v[112:127], v[198:201], v[190:193], v[112:127]
	v_mfma_f32_32x32x16_bf16 v[80:95], v[198:201], v[194:197], v[80:95]
	s_mov_b64 s[16:17], 0x1a000
	v_lshl_add_u64 v[186:187], v[130:131], 0, s[16:17]
	s_mov_b32 m0, s2
	s_nop 0
	global_load_lds_dwordx4 v[186:187], off
	v_mfma_f32_32x32x16_bf16 v[48:63], v[202:205], v[190:193], v[48:63]
	v_mfma_f32_32x32x16_bf16 v[16:31], v[202:205], v[194:197], v[16:31]
	s_mov_b64 s[18:19], 0x1c000
	v_lshl_add_u64 v[186:187], v[130:131], 0, s[18:19]
	s_mov_b32 m0, s1
	s_nop 0
	global_load_lds_dwordx4 v[186:187], off
	v_mfma_f32_32x32x16_bf16 v[32:47], v[206:209], v[190:193], v[32:47]
	v_mfma_f32_32x32x16_bf16 v[0:15], v[206:209], v[194:197], v[0:15]
	s_mov_b64 s[20:21], 0x1e000
	v_lshl_add_u64 v[186:187], v[130:131], 0, s[20:21]
	s_mov_b32 m0, s0
	s_nop 0
	global_load_lds_dwordx4 v[186:187], off
	ds_read_b128 v[186:189], v133 offset:32768
	ds_read_b128 v[190:193], v137
	ds_read_b128 v[194:197], v137 offset:4096
	ds_read_b128 v[198:201], v133 offset:36864
	ds_read_b128 v[202:205], v133 offset:40960
	ds_read_b128 v[206:209], v133 offset:45056
	s_waitcnt lgkmcnt(0)
	v_mfma_f32_32x32x16_bf16 v[96:111], v[186:189], v[190:193], v[96:111]
	v_mfma_f32_32x32x16_bf16 v[64:79], v[186:189], v[194:197], v[64:79]
	s_mov_b32 m0, s4
	s_nop 0
	global_load_lds_dwordx4 v[210:211], off
	v_mfma_f32_32x32x16_bf16 v[112:127], v[198:201], v[190:193], v[112:127]
	v_mfma_f32_32x32x16_bf16 v[80:95], v[198:201], v[194:197], v[80:95]
	v_lshl_add_u64 v[186:187], v[128:129], 0, s[16:17]
	s_mov_b32 m0, s5
	s_nop 0
	global_load_lds_dwordx4 v[186:187], off
	v_mfma_f32_32x32x16_bf16 v[48:63], v[202:205], v[190:193], v[48:63]
	v_mfma_f32_32x32x16_bf16 v[16:31], v[202:205], v[194:197], v[16:31]
	v_lshl_add_u64 v[186:187], v[128:129], 0, s[18:19]
	s_mov_b32 m0, s6
	s_nop 0
	global_load_lds_dwordx4 v[186:187], off
	v_mfma_f32_32x32x16_bf16 v[32:47], v[206:209], v[190:193], v[32:47]
	v_mfma_f32_32x32x16_bf16 v[0:15], v[206:209], v[194:197], v[0:15]
	v_lshl_add_u64 v[186:187], v[128:129], 0, s[20:21]
	s_mov_b32 m0, s7
	s_nop 0
	global_load_lds_dwordx4 v[186:187], off
	ds_read_b128 v[186:189], v135 offset:32768
	ds_read_b128 v[190:193], v140
	ds_read_b128 v[194:197], v140 offset:4096
	ds_read_b128 v[198:201], v135 offset:36864
	s_mov_b64 s[16:17], 0x20000
	v_lshl_add_u64 v[210:211], v[128:129], 0, s[16:17]
	s_waitcnt lgkmcnt(0)
	v_mfma_f32_32x32x16_bf16 v[96:111], v[186:189], v[190:193], v[96:111]
	v_mfma_f32_32x32x16_bf16 v[64:79], v[186:189], v[194:197], v[64:79]
	v_mfma_f32_32x32x16_bf16 v[112:127], v[198:201], v[190:193], v[112:127]
	v_mfma_f32_32x32x16_bf16 v[80:95], v[198:201], v[194:197], v[80:95]
	ds_read_b128 v[186:189], v135 offset:40960
	ds_read_b128 v[198:201], v135 offset:45056
	s_waitcnt lgkmcnt(0)
	v_mfma_f32_32x32x16_bf16 v[48:63], v[186:189], v[190:193], v[48:63]
	v_mfma_f32_32x32x16_bf16 v[16:31], v[186:189], v[194:197], v[16:31]
	v_mfma_f32_32x32x16_bf16 v[32:47], v[198:201], v[190:193], v[32:47]
	v_mfma_f32_32x32x16_bf16 v[0:15], v[198:201], v[194:197], v[0:15]
	ds_read_b128 v[186:189], v134 offset:32768
	ds_read_b128 v[190:193], v139
	ds_read_b128 v[194:197], v139 offset:4096
	ds_read_b128 v[198:201], v134 offset:36864
	s_waitcnt lgkmcnt(0)
	v_mfma_f32_32x32x16_bf16 v[96:111], v[186:189], v[190:193], v[96:111]
	v_mfma_f32_32x32x16_bf16 v[64:79], v[186:189], v[194:197], v[64:79]
	v_mfma_f32_32x32x16_bf16 v[112:127], v[198:201], v[190:193], v[112:127]
	v_mfma_f32_32x32x16_bf16 v[80:95], v[198:201], v[194:197], v[80:95]
	ds_read_b128 v[186:189], v134 offset:40960
	ds_read_b128 v[198:201], v134 offset:45056
	s_waitcnt vmcnt(0)
	s_barrier
; #define MFMA(a, b, c) __builtin_amdgcn_mfma_f32_32x32x16_bf16((a), (b), (c), 0, 0, 0)
;     ...
;   for (int kt = 0; kt < nk; ++kt) {
;     if (DIST == 2 && kt + 1 < nk) {
;       if (NLD == 6) asm volatile("s_waitcnt vmcnt(6)" ::: "memory");
;       else if (NLD == 5) asm volatile("s_waitcnt vmcnt(5)" ::: "memory");
;       else asm volatile("s_waitcnt vmcnt(8)" ::: "memory");
;     } else {
;       asm volatile("s_waitcnt vmcnt(0)" ::: "memory");
;     }
;     __builtin_amdgcn_s_barrier();
;     const bool pre = (kt + DIST < nk);
;     const char* base = smem + (kt % NSTG) * STAGE;
;     const char* pa = base + (wrow_act + r) * 128;
;     const char* pw = base + ABYTES + (wrow_w + r) * 128;
;     constexpr int NM = NI * MJ;
;     constexpr int PPS = (NLD + 1) / 2;
; #pragma unroll
;     for (int s = 0; s < 4; ++s) {
;       bf16x8 af[MJ], wf[NI];
; #pragma unroll
;       for (int j = 0; j < MJ; ++j) af[j] = *(const bf16x8*)(pa + j * 32 * 128 + xo[s]);
; #pragma unroll
;       for (int i = 0; i < NI; ++i) wf[i] = *(const bf16x8*)(pw + i * 32 * 128 + xo[s]);
; #pragma unroll
;       for (int m = 0; m < NM; ++m) {
;         const int i = m / MJ, j = m % MJ;
;         acc[i][j] = MFMA(wf[i], af[j], acc[i][j]);
;         if (s < 2 && NM >= PPS) {
;           constexpr int EVERY = (NM / PPS) > 0 ? (NM / PPS) : 1;
;           if ((m + 1) % EVERY == 0) {
;             const int pc = s * PPS + (m + 1) / EVERY - 1;
;             if ((m + 1) / EVERY <= PPS && pc < NLD) {
;               __builtin_amdgcn_sched_barrier(0);
;               if (pre) issue_piece(kt + DIST, pc);
;               __builtin_amdgcn_sched_barrier(0);
;             }
;           }
;         }
;         if (s < 2 && NM < PPS) {
;           const int slot = s * NM + m;
;           __builtin_amdgcn_sched_barrier(0);
; #pragma unroll
;           for (int pc = 0; pc < NLD; ++pc)
;             if ((pc * 2 * NM) / NLD == slot && pre) issue_piece(kt + DIST, pc);
;           __builtin_amdgcn_sched_barrier(0);
;         }
;       }
;     }
;   }
	s_waitcnt lgkmcnt(0)
	v_mfma_f32_32x32x16_bf16 v[48:63], v[186:189], v[190:193], v[48:63]
	v_mfma_f32_32x32x16_bf16 v[16:31], v[186:189], v[194:197], v[16:31]
	v_mfma_f32_32x32x16_bf16 v[32:47], v[198:201], v[190:193], v[32:47]
	v_mfma_f32_32x32x16_bf16 v[0:15], v[198:201], v[194:197], v[0:15]
	ds_read_b128 v[186:189], v138
	ds_read_b128 v[190:193], v142
	ds_read_b128 v[194:197], v142 offset:4096
	ds_read_b128 v[198:201], v138 offset:4096
	ds_read_b128 v[202:205], v138 offset:8192
	ds_read_b128 v[206:209], v138 offset:12288
	s_waitcnt lgkmcnt(0)
	v_mfma_f32_32x32x16_bf16 v[96:111], v[186:189], v[190:193], v[96:111]
	v_mfma_f32_32x32x16_bf16 v[64:79], v[186:189], v[194:197], v[64:79]
	v_lshl_add_u64 v[186:187], v[130:131], 0, s[16:17]
	s_mov_b32 m0, s15
	s_nop 0
	global_load_lds_dwordx4 v[186:187], off
	v_mfma_f32_32x32x16_bf16 v[112:127], v[198:201], v[190:193], v[112:127]
	v_mfma_f32_32x32x16_bf16 v[80:95], v[198:201], v[194:197], v[80:95]
	s_mov_b64 s[16:17], 0x22000
	v_lshl_add_u64 v[186:187], v[130:131], 0, s[16:17]
	s_mov_b32 m0, s14
	s_nop 0
	global_load_lds_dwordx4 v[186:187], off
	v_mfma_f32_32x32x16_bf16 v[48:63], v[202:205], v[190:193], v[48:63]
	v_mfma_f32_32x32x16_bf16 v[16:31], v[202:205], v[194:197], v[16:31]
	v_lshl_add_u64 v[186:187], v[130:131], 0, s[62:63]
	s_mov_b32 m0, s13
	s_nop 0
	global_load_lds_dwordx4 v[186:187], off
	v_mfma_f32_32x32x16_bf16 v[32:47], v[206:209], v[190:193], v[32:47]
	v_mfma_f32_32x32x16_bf16 v[0:15], v[206:209], v[194:197], v[0:15]
	s_mov_b64 s[14:15], 0x26000
	v_lshl_add_u64 v[186:187], v[130:131], 0, s[14:15]
	s_mov_b32 m0, s12
	s_nop 0
	global_load_lds_dwordx4 v[186:187], off
	ds_read_b128 v[186:189], v144
	ds_read_b128 v[190:193], v151
	ds_read_b128 v[194:197], v151 offset:4096
	ds_read_b128 v[198:201], v144 offset:4096
	ds_read_b128 v[202:205], v144 offset:8192
	ds_read_b128 v[206:209], v144 offset:12288
	s_waitcnt lgkmcnt(0)
	v_mfma_f32_32x32x16_bf16 v[96:111], v[186:189], v[190:193], v[96:111]
	v_mfma_f32_32x32x16_bf16 v[64:79], v[186:189], v[194:197], v[64:79]
	s_mov_b32 m0, s11
	s_nop 0
	global_load_lds_dwordx4 v[210:211], off
	v_mfma_f32_32x32x16_bf16 v[112:127], v[198:201], v[190:193], v[112:127]
	v_mfma_f32_32x32x16_bf16 v[80:95], v[198:201], v[194:197], v[80:95]
	v_lshl_add_u64 v[186:187], v[128:129], 0, s[16:17]
	s_mov_b32 m0, s10
	s_nop 0
	global_load_lds_dwordx4 v[186:187], off
	v_mfma_f32_32x32x16_bf16 v[48:63], v[202:205], v[190:193], v[48:63]
	v_mfma_f32_32x32x16_bf16 v[16:31], v[202:205], v[194:197], v[16:31]
	v_lshl_add_u64 v[186:187], v[128:129], 0, s[62:63]
	s_mov_b32 m0, s9
	s_nop 0
	global_load_lds_dwordx4 v[186:187], off
	v_mfma_f32_32x32x16_bf16 v[32:47], v[206:209], v[190:193], v[32:47]
	v_mfma_f32_32x32x16_bf16 v[0:15], v[206:209], v[194:197], v[0:15]
	v_lshl_add_u64 v[186:187], v[128:129], 0, s[14:15]
	s_mov_b32 m0, s8
	s_nop 0
	global_load_lds_dwordx4 v[186:187], off
	ds_read_b128 v[186:189], v143
	ds_read_b128 v[190:193], v153
	ds_read_b128 v[194:197], v153 offset:4096
	ds_read_b128 v[198:201], v143 offset:4096
	s_mov_b64 s[8:9], 0x28000
	v_lshl_add_u64 v[210:211], v[128:129], 0, s[8:9]
	s_waitcnt lgkmcnt(0)
	v_mfma_f32_32x32x16_bf16 v[96:111], v[186:189], v[190:193], v[96:111]
	v_mfma_f32_32x32x16_bf16 v[64:79], v[186:189], v[194:197], v[64:79]
	v_mfma_f32_32x32x16_bf16 v[112:127], v[198:201], v[190:193], v[112:127]
	v_mfma_f32_32x32x16_bf16 v[80:95], v[198:201], v[194:197], v[80:95]
	ds_read_b128 v[186:189], v143 offset:8192
	ds_read_b128 v[198:201], v143 offset:12288
	s_waitcnt lgkmcnt(0)
	v_mfma_f32_32x32x16_bf16 v[48:63], v[186:189], v[190:193], v[48:63]
	v_mfma_f32_32x32x16_bf16 v[16:31], v[186:189], v[194:197], v[16:31]
	v_mfma_f32_32x32x16_bf16 v[32:47], v[198:201], v[190:193], v[32:47]
	v_mfma_f32_32x32x16_bf16 v[0:15], v[198:201], v[194:197], v[0:15]
	ds_read_b128 v[186:189], v141
	ds_read_b128 v[190:193], v152
	ds_read_b128 v[194:197], v152 offset:4096
	ds_read_b128 v[198:201], v141 offset:4096
	s_waitcnt lgkmcnt(0)
	v_mfma_f32_32x32x16_bf16 v[96:111], v[186:189], v[190:193], v[96:111]
	v_mfma_f32_32x32x16_bf16 v[64:79], v[186:189], v[194:197], v[64:79]
	v_mfma_f32_32x32x16_bf16 v[112:127], v[198:201], v[190:193], v[112:127]
	v_mfma_f32_32x32x16_bf16 v[80:95], v[198:201], v[194:197], v[80:95]
	ds_read_b128 v[186:189], v141 offset:8192
	ds_read_b128 v[198:201], v141 offset:12288
	s_waitcnt vmcnt(0)
	s_barrier
; #define MFMA(a, b, c) __builtin_amdgcn_mfma_f32_32x32x16_bf16((a), (b), (c), 0, 0, 0)
;     ...
;   for (int kt = 0; kt < nk; ++kt) {
;     if (DIST == 2 && kt + 1 < nk) {
;       if (NLD == 6) asm volatile("s_waitcnt vmcnt(6)" ::: "memory");
;       else if (NLD == 5) asm volatile("s_waitcnt vmcnt(5)" ::: "memory");
;       else asm volatile("s_waitcnt vmcnt(8)" ::: "memory");
;     } else {
;       asm volatile("s_waitcnt vmcnt(0)" ::: "memory");
;     }
;     __builtin_amdgcn_s_barrier();
;     const bool pre = (kt + DIST < nk);
;     const char* base = smem + (kt % NSTG) * STAGE;
;     const char* pa = base + (wrow_act + r) * 128;
;     const char* pw = base + ABYTES + (wrow_w + r) * 128;
;     constexpr int NM = NI * MJ;
;     constexpr int PPS = (NLD + 1) / 2;
; #pragma unroll
;     for (int s = 0; s < 4; ++s) {
;       bf16x8 af[MJ], wf[NI];
; #pragma unroll
;       for (int j = 0; j < MJ; ++j) af[j] = *(const bf16x8*)(pa + j * 32 * 128 + xo[s]);
; #pragma unroll
;       for (int i = 0; i < NI; ++i) wf[i] = *(const bf16x8*)(pw + i * 32 * 128 + xo[s]);
; #pragma unroll
;       for (int m = 0; m < NM; ++m) {
;         const int i = m / MJ, j = m % MJ;
;         acc[i][j] = MFMA(wf[i], af[j], acc[i][j]);
;         if (s < 2 && NM >= PPS) {
;           constexpr int EVERY = (NM / PPS) > 0 ? (NM / PPS) : 1;
;           if ((m + 1) % EVERY == 0) {
;             const int pc = s * PPS + (m + 1) / EVERY - 1;
;             if ((m + 1) / EVERY <= PPS && pc < NLD) {
;               __builtin_amdgcn_sched_barrier(0);
;               if (pre) issue_piece(kt + DIST, pc);
;               __builtin_amdgcn_sched_barrier(0);
;             }
;           }
;         }
;         if (s < 2 && NM < PPS) {
;           const int slot = s * NM + m;
;           __builtin_amdgcn_sched_barrier(0);
; #pragma unroll
;           for (int pc = 0; pc < NLD; ++pc)
;             if ((pc * 2 * NM) / NLD == slot && pre) issue_piece(kt + DIST, pc);
;           __builtin_amdgcn_sched_barrier(0);
;         }
;       }
;     }
;   }
	s_waitcnt lgkmcnt(0)
	v_mfma_f32_32x32x16_bf16 v[48:63], v[186:189], v[190:193], v[48:63]
	v_mfma_f32_32x32x16_bf16 v[16:31], v[186:189], v[194:197], v[16:31]
	v_mfma_f32_32x32x16_bf16 v[32:47], v[198:201], v[190:193], v[32:47]
	v_mfma_f32_32x32x16_bf16 v[0:15], v[198:201], v[194:197], v[0:15]
	ds_read_b128 v[186:189], v132 offset:32768
	ds_read_b128 v[190:193], v136
	ds_read_b128 v[194:197], v136 offset:4096
	ds_read_b128 v[198:201], v132 offset:36864
	ds_read_b128 v[202:205], v132 offset:40960
	ds_read_b128 v[206:209], v132 offset:45056
	s_waitcnt lgkmcnt(0)
	v_mfma_f32_32x32x16_bf16 v[96:111], v[186:189], v[190:193], v[96:111]
	v_mfma_f32_32x32x16_bf16 v[64:79], v[186:189], v[194:197], v[64:79]
	v_lshl_add_u64 v[186:187], v[130:131], 0, s[8:9]
	s_mov_b32 m0, s3
	s_nop 0
	global_load_lds_dwordx4 v[186:187], off
	v_mfma_f32_32x32x16_bf16 v[112:127], v[198:201], v[190:193], v[112:127]
	v_mfma_f32_32x32x16_bf16 v[80:95], v[198:201], v[194:197], v[80:95]
	s_mov_b64 s[8:9], 0x2a000
	v_lshl_add_u64 v[186:187], v[130:131], 0, s[8:9]
	s_mov_b32 m0, s2
	s_nop 0
	global_load_lds_dwordx4 v[186:187], off
	v_mfma_f32_32x32x16_bf16 v[48:63], v[202:205], v[190:193], v[48:63]
	v_mfma_f32_32x32x16_bf16 v[16:31], v[202:205], v[194:197], v[16:31]
	s_mov_b64 s[2:3], 0x2c000
	v_lshl_add_u64 v[186:187], v[130:131], 0, s[2:3]
	s_mov_b32 m0, s1
	s_nop 0
	global_load_lds_dwordx4 v[186:187], off
	v_mfma_f32_32x32x16_bf16 v[32:47], v[206:209], v[190:193], v[32:47]
	v_mfma_f32_32x32x16_bf16 v[0:15], v[206:209], v[194:197], v[0:15]
	s_mov_b64 s[10:11], 0x2e000
	v_lshl_add_u64 v[186:187], v[130:131], 0, s[10:11]
	s_mov_b32 m0, s0
	s_nop 0
	global_load_lds_dwordx4 v[186:187], off
	ds_read_b128 v[186:189], v133 offset:32768
	ds_read_b128 v[190:193], v137
	ds_read_b128 v[194:197], v137 offset:4096
	ds_read_b128 v[198:201], v133 offset:36864
	ds_read_b128 v[202:205], v133 offset:40960
	ds_read_b128 v[206:209], v133 offset:45056
	s_waitcnt lgkmcnt(0)
	v_mfma_f32_32x32x16_bf16 v[96:111], v[186:189], v[190:193], v[96:111]
	v_mfma_f32_32x32x16_bf16 v[64:79], v[186:189], v[194:197], v[64:79]
	s_mov_b32 m0, s4
	s_nop 0
	global_load_lds_dwordx4 v[210:211], off
	v_mfma_f32_32x32x16_bf16 v[112:127], v[198:201], v[190:193], v[112:127]
	v_mfma_f32_32x32x16_bf16 v[80:95], v[198:201], v[194:197], v[80:95]
	v_lshl_add_u64 v[186:187], v[128:129], 0, s[8:9]
	s_mov_b32 m0, s5
	s_nop 0
	global_load_lds_dwordx4 v[186:187], off
	v_mfma_f32_32x32x16_bf16 v[48:63], v[202:205], v[190:193], v[48:63]
	v_mfma_f32_32x32x16_bf16 v[16:31], v[202:205], v[194:197], v[16:31]
	v_lshl_add_u64 v[186:187], v[128:129], 0, s[2:3]
	s_mov_b32 m0, s6
	s_nop 0
	global_load_lds_dwordx4 v[186:187], off
	v_mfma_f32_32x32x16_bf16 v[32:47], v[206:209], v[190:193], v[32:47]
	v_mfma_f32_32x32x16_bf16 v[0:15], v[206:209], v[194:197], v[0:15]
	v_lshl_add_u64 v[186:187], v[128:129], 0, s[10:11]
	s_mov_b32 m0, s7
	s_nop 0
	global_load_lds_dwordx4 v[186:187], off
	ds_read_b128 v[186:189], v135 offset:32768
	ds_read_b128 v[190:193], v140
	ds_read_b128 v[194:197], v140 offset:4096
	ds_read_b128 v[198:201], v135 offset:36864
	s_mov_b64 s[0:1], 0x30000
	v_lshl_add_u64 v[210:211], v[128:129], 0, s[0:1]
	s_waitcnt lgkmcnt(0)
	v_mfma_f32_32x32x16_bf16 v[96:111], v[186:189], v[190:193], v[96:111]
	v_mfma_f32_32x32x16_bf16 v[64:79], v[186:189], v[194:197], v[64:79]
	v_mfma_f32_32x32x16_bf16 v[112:127], v[198:201], v[190:193], v[112:127]
	v_mfma_f32_32x32x16_bf16 v[80:95], v[198:201], v[194:197], v[80:95]
	ds_read_b128 v[186:189], v135 offset:40960
	ds_read_b128 v[198:201], v135 offset:45056
	s_waitcnt lgkmcnt(0)
	v_mfma_f32_32x32x16_bf16 v[48:63], v[186:189], v[190:193], v[48:63]
	v_mfma_f32_32x32x16_bf16 v[16:31], v[186:189], v[194:197], v[16:31]
	v_mfma_f32_32x32x16_bf16 v[32:47], v[198:201], v[190:193], v[32:47]
	v_mfma_f32_32x32x16_bf16 v[0:15], v[198:201], v[194:197], v[0:15]
	ds_read_b128 v[186:189], v134 offset:32768
	ds_read_b128 v[190:193], v139
	ds_read_b128 v[194:197], v139 offset:4096
	ds_read_b128 v[198:201], v134 offset:36864
	s_waitcnt lgkmcnt(0)
	v_mfma_f32_32x32x16_bf16 v[96:111], v[186:189], v[190:193], v[96:111]
	v_mfma_f32_32x32x16_bf16 v[64:79], v[186:189], v[194:197], v[64:79]
	v_mfma_f32_32x32x16_bf16 v[112:127], v[198:201], v[190:193], v[112:127]
	v_mfma_f32_32x32x16_bf16 v[80:95], v[198:201], v[194:197], v[80:95]
	ds_read_b128 v[186:189], v134 offset:40960
	ds_read_b128 v[198:201], v134 offset:45056
	s_waitcnt vmcnt(0)
	s_barrier
; #define MFMA(a, b, c) __builtin_amdgcn_mfma_f32_32x32x16_bf16((a), (b), (c), 0, 0, 0)
;     ...
;   for (int kt = 0; kt < nk; ++kt) {
;     if (DIST == 2 && kt + 1 < nk) {
;       if (NLD == 6) asm volatile("s_waitcnt vmcnt(6)" ::: "memory");
;       else if (NLD == 5) asm volatile("s_waitcnt vmcnt(5)" ::: "memory");
;       else asm volatile("s_waitcnt vmcnt(8)" ::: "memory");
;     } else {
;       asm volatile("s_waitcnt vmcnt(0)" ::: "memory");
;     }
;     __builtin_amdgcn_s_barrier();
;     const bool pre = (kt + DIST < nk);
;     const char* base = smem + (kt % NSTG) * STAGE;
;     const char* pa = base + (wrow_act + r) * 128;
;     const char* pw = base + ABYTES + (wrow_w + r) * 128;
;     constexpr int NM = NI * MJ;
;     constexpr int PPS = (NLD + 1) / 2;
; #pragma unroll
;     for (int s = 0; s < 4; ++s) {
;       bf16x8 af[MJ], wf[NI];
; #pragma unroll
;       for (int j = 0; j < MJ; ++j) af[j] = *(const bf16x8*)(pa + j * 32 * 128 + xo[s]);
; #pragma unroll
;       for (int i = 0; i < NI; ++i) wf[i] = *(const bf16x8*)(pw + i * 32 * 128 + xo[s]);
; #pragma unroll
;       for (int m = 0; m < NM; ++m) {
;         const int i = m / MJ, j = m % MJ;
;         acc[i][j] = MFMA(wf[i], af[j], acc[i][j]);
;         if (s < 2 && NM >= PPS) {
;           constexpr int EVERY = (NM / PPS) > 0 ? (NM / PPS) : 1;
;           if ((m + 1) % EVERY == 0) {
;             const int pc = s * PPS + (m + 1) / EVERY - 1;
;             if ((m + 1) / EVERY <= PPS && pc < NLD) {
;               __builtin_amdgcn_sched_barrier(0);
;               if (pre) issue_piece(kt + DIST, pc);
;               __builtin_amdgcn_sched_barrier(0);
;             }
;           }
;         }
;         if (s < 2 && NM < PPS) {
;           const int slot = s * NM + m;
;           __builtin_amdgcn_sched_barrier(0);
; #pragma unroll
;           for (int pc = 0; pc < NLD; ++pc)
;             if ((pc * 2 * NM) / NLD == slot && pre) issue_piece(kt + DIST, pc);
;           __builtin_amdgcn_sched_barrier(0);
;         }
;       }
;     }
;   }
	s_waitcnt lgkmcnt(0)
	v_mfma_f32_32x32x16_bf16 v[48:63], v[186:189], v[190:193], v[48:63]
	v_mfma_f32_32x32x16_bf16 v[16:31], v[186:189], v[194:197], v[16:31]
	v_mfma_f32_32x32x16_bf16 v[32:47], v[198:201], v[190:193], v[32:47]
	v_mfma_f32_32x32x16_bf16 v[0:15], v[198:201], v[194:197], v[0:15]
	ds_read_b128 v[186:189], v138
	ds_read_b128 v[190:193], v142
	ds_read_b128 v[194:197], v142 offset:4096
	ds_read_b128 v[198:201], v138 offset:4096
	ds_read_b128 v[202:205], v138 offset:8192
	ds_read_b128 v[206:209], v138 offset:12288
	s_waitcnt lgkmcnt(0)
	v_mfma_f32_32x32x16_bf16 v[96:111], v[186:189], v[190:193], v[96:111]
	v_mfma_f32_32x32x16_bf16 v[64:79], v[186:189], v[194:197], v[64:79]
	v_lshl_add_u64 v[186:187], v[130:131], 0, s[0:1]
	v_readfirstlane_b32 s0, v184
	s_mov_b32 m0, s0
	s_nop 0
	global_load_lds_dwordx4 v[186:187], off
	v_mfma_f32_32x32x16_bf16 v[112:127], v[198:201], v[190:193], v[112:127]
	v_mfma_f32_32x32x16_bf16 v[80:95], v[198:201], v[194:197], v[80:95]
	s_mov_b64 s[6:7], 0x32000
	v_readfirstlane_b32 s1, v183
	v_lshl_add_u64 v[186:187], v[130:131], 0, s[6:7]
	s_mov_b32 m0, s1
	s_nop 0
	global_load_lds_dwordx4 v[186:187], off
	v_mfma_f32_32x32x16_bf16 v[48:63], v[202:205], v[190:193], v[48:63]
	v_mfma_f32_32x32x16_bf16 v[16:31], v[202:205], v[194:197], v[16:31]
	s_mov_b64 s[8:9], 0x34000
	v_readfirstlane_b32 s2, v182
	v_lshl_add_u64 v[186:187], v[130:131], 0, s[8:9]
	s_mov_b32 m0, s2
	s_nop 0
	global_load_lds_dwordx4 v[186:187], off
	v_mfma_f32_32x32x16_bf16 v[32:47], v[206:209], v[190:193], v[32:47]
	v_mfma_f32_32x32x16_bf16 v[0:15], v[206:209], v[194:197], v[0:15]
	s_mov_b64 s[10:11], 0x36000
	v_readfirstlane_b32 s3, v181
	v_lshl_add_u64 v[186:187], v[130:131], 0, s[10:11]
	s_mov_b32 m0, s3
	s_nop 0
	global_load_lds_dwordx4 v[186:187], off
	ds_read_b128 v[186:189], v144
	ds_read_b128 v[190:193], v151
	ds_read_b128 v[194:197], v151 offset:4096
	ds_read_b128 v[198:201], v144 offset:4096
	ds_read_b128 v[202:205], v144 offset:8192
	ds_read_b128 v[206:209], v144 offset:12288
	s_waitcnt lgkmcnt(0)
	v_mfma_f32_32x32x16_bf16 v[96:111], v[186:189], v[190:193], v[96:111]
	v_mfma_f32_32x32x16_bf16 v[64:79], v[186:189], v[194:197], v[64:79]
	v_readfirstlane_b32 s4, v162
	s_mov_b32 m0, s4
	s_nop 0
	global_load_lds_dwordx4 v[210:211], off
	v_mfma_f32_32x32x16_bf16 v[112:127], v[198:201], v[190:193], v[112:127]
	v_mfma_f32_32x32x16_bf16 v[80:95], v[198:201], v[194:197], v[80:95]
	v_readfirstlane_b32 s5, v165
	v_lshl_add_u64 v[186:187], v[128:129], 0, s[6:7]
	s_mov_b32 m0, s5
	s_nop 0
	global_load_lds_dwordx4 v[186:187], off
	v_mfma_f32_32x32x16_bf16 v[48:63], v[202:205], v[190:193], v[48:63]
	v_mfma_f32_32x32x16_bf16 v[16:31], v[202:205], v[194:197], v[16:31]
	v_readfirstlane_b32 s6, v164
	v_lshl_add_u64 v[186:187], v[128:129], 0, s[8:9]
	s_mov_b32 m0, s6
	s_nop 0
	global_load_lds_dwordx4 v[186:187], off
	v_mfma_f32_32x32x16_bf16 v[32:47], v[206:209], v[190:193], v[32:47]
	v_mfma_f32_32x32x16_bf16 v[0:15], v[206:209], v[194:197], v[0:15]
	v_readfirstlane_b32 s7, v163
	v_lshl_add_u64 v[186:187], v[128:129], 0, s[10:11]
	s_mov_b32 m0, s7
	s_nop 0
	global_load_lds_dwordx4 v[186:187], off
	ds_read_b128 v[186:189], v143
	ds_read_b128 v[190:193], v153
	ds_read_b128 v[194:197], v153 offset:4096
	ds_read_b128 v[198:201], v143 offset:4096
	s_mov_b64 s[8:9], 0x38000
	v_lshl_add_u64 v[210:211], v[128:129], 0, s[8:9]
	s_waitcnt lgkmcnt(0)
	v_mfma_f32_32x32x16_bf16 v[96:111], v[186:189], v[190:193], v[96:111]
	v_mfma_f32_32x32x16_bf16 v[64:79], v[186:189], v[194:197], v[64:79]
	v_mfma_f32_32x32x16_bf16 v[112:127], v[198:201], v[190:193], v[112:127]
	v_mfma_f32_32x32x16_bf16 v[80:95], v[198:201], v[194:197], v[80:95]
	ds_read_b128 v[186:189], v143 offset:8192
	ds_read_b128 v[198:201], v143 offset:12288
	s_waitcnt lgkmcnt(0)
	v_mfma_f32_32x32x16_bf16 v[48:63], v[186:189], v[190:193], v[48:63]
	v_mfma_f32_32x32x16_bf16 v[16:31], v[186:189], v[194:197], v[16:31]
	v_mfma_f32_32x32x16_bf16 v[32:47], v[198:201], v[190:193], v[32:47]
	v_mfma_f32_32x32x16_bf16 v[0:15], v[198:201], v[194:197], v[0:15]
	ds_read_b128 v[186:189], v141
	ds_read_b128 v[190:193], v152
	ds_read_b128 v[194:197], v152 offset:4096
	ds_read_b128 v[198:201], v141 offset:4096
	s_waitcnt lgkmcnt(0)
	v_mfma_f32_32x32x16_bf16 v[96:111], v[186:189], v[190:193], v[96:111]
	v_mfma_f32_32x32x16_bf16 v[64:79], v[186:189], v[194:197], v[64:79]
	v_mfma_f32_32x32x16_bf16 v[112:127], v[198:201], v[190:193], v[112:127]
	v_mfma_f32_32x32x16_bf16 v[80:95], v[198:201], v[194:197], v[80:95]
	ds_read_b128 v[186:189], v141 offset:8192
	ds_read_b128 v[198:201], v141 offset:12288
	s_waitcnt vmcnt(0)
	s_barrier
; #define MFMA(a, b, c) __builtin_amdgcn_mfma_f32_32x32x16_bf16((a), (b), (c), 0, 0, 0)
;     ...
;   for (int kt = 0; kt < nk; ++kt) {
;     if (DIST == 2 && kt + 1 < nk) {
;       if (NLD == 6) asm volatile("s_waitcnt vmcnt(6)" ::: "memory");
;       else if (NLD == 5) asm volatile("s_waitcnt vmcnt(5)" ::: "memory");
;       else asm volatile("s_waitcnt vmcnt(8)" ::: "memory");
;     } else {
;       asm volatile("s_waitcnt vmcnt(0)" ::: "memory");
;     }
;     __builtin_amdgcn_s_barrier();
;     const bool pre = (kt + DIST < nk);
;     const char* base = smem + (kt % NSTG) * STAGE;
;     const char* pa = base + (wrow_act + r) * 128;
;     const char* pw = base + ABYTES + (wrow_w + r) * 128;
;     constexpr int NM = NI * MJ;
;     constexpr int PPS = (NLD + 1) / 2;
; #pragma unroll
;     for (int s = 0; s < 4; ++s) {
;       bf16x8 af[MJ], wf[NI];
; #pragma unroll
;       for (int j = 0; j < MJ; ++j) af[j] = *(const bf16x8*)(pa + j * 32 * 128 + xo[s]);
; #pragma unroll
;       for (int i = 0; i < NI; ++i) wf[i] = *(const bf16x8*)(pw + i * 32 * 128 + xo[s]);
; #pragma unroll
;       for (int m = 0; m < NM; ++m) {
;         const int i = m / MJ, j = m % MJ;
;         acc[i][j] = MFMA(wf[i], af[j], acc[i][j]);
;         if (s < 2 && NM >= PPS) {
;           constexpr int EVERY = (NM / PPS) > 0 ? (NM / PPS) : 1;
;           if ((m + 1) % EVERY == 0) {
;             const int pc = s * PPS + (m + 1) / EVERY - 1;
;             if ((m + 1) / EVERY <= PPS && pc < NLD) {
;               __builtin_amdgcn_sched_barrier(0);
;               if (pre) issue_piece(kt + DIST, pc);
;               __builtin_amdgcn_sched_barrier(0);
;             }
;           }
;         }
;         if (s < 2 && NM < PPS) {
;           const int slot = s * NM + m;
;           __builtin_amdgcn_sched_barrier(0);
; #pragma unroll
;           for (int pc = 0; pc < NLD; ++pc)
;             if ((pc * 2 * NM) / NLD == slot && pre) issue_piece(kt + DIST, pc);
;           __builtin_amdgcn_sched_barrier(0);
;         }
;       }
;     }
;   }
	s_waitcnt lgkmcnt(0)
	v_mfma_f32_32x32x16_bf16 v[48:63], v[186:189], v[190:193], v[48:63]
	v_mfma_f32_32x32x16_bf16 v[16:31], v[186:189], v[194:197], v[16:31]
	v_mfma_f32_32x32x16_bf16 v[32:47], v[198:201], v[190:193], v[32:47]
	v_mfma_f32_32x32x16_bf16 v[0:15], v[198:201], v[194:197], v[0:15]
	ds_read_b128 v[186:189], v132 offset:32768
	ds_read_b128 v[190:193], v136
	ds_read_b128 v[194:197], v136 offset:4096
	ds_read_b128 v[198:201], v132 offset:36864
	ds_read_b128 v[202:205], v132 offset:40960
	ds_read_b128 v[206:209], v132 offset:45056
	s_waitcnt lgkmcnt(0)
	v_mfma_f32_32x32x16_bf16 v[96:111], v[186:189], v[190:193], v[96:111]
	v_mfma_f32_32x32x16_bf16 v[64:79], v[186:189], v[194:197], v[64:79]
	v_lshl_add_u64 v[186:187], v[130:131], 0, s[8:9]
	v_readfirstlane_b32 s8, v155
	s_mov_b32 m0, s8
	s_nop 0
	global_load_lds_dwordx4 v[186:187], off
	v_mfma_f32_32x32x16_bf16 v[112:127], v[198:201], v[190:193], v[112:127]
	v_mfma_f32_32x32x16_bf16 v[80:95], v[198:201], v[194:197], v[80:95]
	s_mov_b64 s[14:15], 0x3a000
	v_readfirstlane_b32 s9, v158
	v_lshl_add_u64 v[186:187], v[130:131], 0, s[14:15]
	s_mov_b32 m0, s9
	s_nop 0
	global_load_lds_dwordx4 v[186:187], off
	v_mfma_f32_32x32x16_bf16 v[48:63], v[202:205], v[190:193], v[48:63]
	v_mfma_f32_32x32x16_bf16 v[16:31], v[202:205], v[194:197], v[16:31]
	s_mov_b64 s[16:17], 0x3c000
	v_readfirstlane_b32 s10, v157
	v_lshl_add_u64 v[186:187], v[130:131], 0, s[16:17]
	s_mov_b32 m0, s10
	s_nop 0
	global_load_lds_dwordx4 v[186:187], off
	v_mfma_f32_32x32x16_bf16 v[32:47], v[206:209], v[190:193], v[32:47]
	v_mfma_f32_32x32x16_bf16 v[0:15], v[206:209], v[194:197], v[0:15]
	s_mov_b64 s[18:19], 0x3e000
	v_readfirstlane_b32 s11, v156
	v_lshl_add_u64 v[186:187], v[130:131], 0, s[18:19]
	s_mov_b32 m0, s11
	s_nop 0
	global_load_lds_dwordx4 v[186:187], off
	ds_read_b128 v[186:189], v133 offset:32768
	ds_read_b128 v[190:193], v137
	ds_read_b128 v[194:197], v137 offset:4096
	ds_read_b128 v[198:201], v133 offset:36864
	ds_read_b128 v[202:205], v133 offset:40960
	ds_read_b128 v[206:209], v133 offset:45056
	s_waitcnt lgkmcnt(0)
	v_mfma_f32_32x32x16_bf16 v[96:111], v[186:189], v[190:193], v[96:111]
	v_mfma_f32_32x32x16_bf16 v[64:79], v[186:189], v[194:197], v[64:79]
	v_readfirstlane_b32 s12, v154
	s_mov_b32 m0, s12
	s_nop 0
	global_load_lds_dwordx4 v[210:211], off
	v_mfma_f32_32x32x16_bf16 v[112:127], v[198:201], v[190:193], v[112:127]
	v_mfma_f32_32x32x16_bf16 v[80:95], v[198:201], v[194:197], v[80:95]
	v_readfirstlane_b32 s13, v159
	v_lshl_add_u64 v[186:187], v[128:129], 0, s[14:15]
	s_mov_b32 m0, s13
	s_nop 0
	global_load_lds_dwordx4 v[186:187], off
	v_mfma_f32_32x32x16_bf16 v[48:63], v[202:205], v[190:193], v[48:63]
	v_mfma_f32_32x32x16_bf16 v[16:31], v[202:205], v[194:197], v[16:31]
	v_readfirstlane_b32 s14, v160
	v_lshl_add_u64 v[186:187], v[128:129], 0, s[16:17]
	s_mov_b32 m0, s14
	s_nop 0
	global_load_lds_dwordx4 v[186:187], off
	v_mfma_f32_32x32x16_bf16 v[32:47], v[206:209], v[190:193], v[32:47]
	v_mfma_f32_32x32x16_bf16 v[0:15], v[206:209], v[194:197], v[0:15]
	v_readfirstlane_b32 s15, v161
	v_lshl_add_u64 v[186:187], v[128:129], 0, s[18:19]
	s_mov_b32 m0, s15
	s_nop 0
	global_load_lds_dwordx4 v[186:187], off
	ds_read_b128 v[186:189], v135 offset:32768
	ds_read_b128 v[190:193], v140
	ds_read_b128 v[194:197], v140 offset:4096
	ds_read_b128 v[198:201], v135 offset:36864
	s_mov_b64 s[16:17], 0x40000
	v_lshl_add_u64 v[210:211], v[128:129], 0, s[16:17]
	s_waitcnt lgkmcnt(0)
	v_mfma_f32_32x32x16_bf16 v[96:111], v[186:189], v[190:193], v[96:111]
	v_mfma_f32_32x32x16_bf16 v[64:79], v[186:189], v[194:197], v[64:79]
	v_mfma_f32_32x32x16_bf16 v[112:127], v[198:201], v[190:193], v[112:127]
	v_mfma_f32_32x32x16_bf16 v[80:95], v[198:201], v[194:197], v[80:95]
	ds_read_b128 v[186:189], v135 offset:40960
	ds_read_b128 v[198:201], v135 offset:45056
	s_waitcnt lgkmcnt(0)
	v_mfma_f32_32x32x16_bf16 v[48:63], v[186:189], v[190:193], v[48:63]
	v_mfma_f32_32x32x16_bf16 v[16:31], v[186:189], v[194:197], v[16:31]
	v_mfma_f32_32x32x16_bf16 v[32:47], v[198:201], v[190:193], v[32:47]
	v_mfma_f32_32x32x16_bf16 v[0:15], v[198:201], v[194:197], v[0:15]
	ds_read_b128 v[186:189], v134 offset:32768
	ds_read_b128 v[190:193], v139
	ds_read_b128 v[194:197], v139 offset:4096
	ds_read_b128 v[198:201], v134 offset:36864
	s_waitcnt lgkmcnt(0)
	v_mfma_f32_32x32x16_bf16 v[96:111], v[186:189], v[190:193], v[96:111]
	v_mfma_f32_32x32x16_bf16 v[64:79], v[186:189], v[194:197], v[64:79]
	v_mfma_f32_32x32x16_bf16 v[112:127], v[198:201], v[190:193], v[112:127]
	v_mfma_f32_32x32x16_bf16 v[80:95], v[198:201], v[194:197], v[80:95]
	ds_read_b128 v[186:189], v134 offset:40960
	ds_read_b128 v[198:201], v134 offset:45056
	s_waitcnt vmcnt(0)
	s_barrier
; #define MFMA(a, b, c) __builtin_amdgcn_mfma_f32_32x32x16_bf16((a), (b), (c), 0, 0, 0)
;     ...
;   for (int kt = 0; kt < nk; ++kt) {
;     if (DIST == 2 && kt + 1 < nk) {
;       if (NLD == 6) asm volatile("s_waitcnt vmcnt(6)" ::: "memory");
;       else if (NLD == 5) asm volatile("s_waitcnt vmcnt(5)" ::: "memory");
;       else asm volatile("s_waitcnt vmcnt(8)" ::: "memory");
;     } else {
;       asm volatile("s_waitcnt vmcnt(0)" ::: "memory");
;     }
;     __builtin_amdgcn_s_barrier();
;     const bool pre = (kt + DIST < nk);
;     const char* base = smem + (kt % NSTG) * STAGE;
;     const char* pa = base + (wrow_act + r) * 128;
;     const char* pw = base + ABYTES + (wrow_w + r) * 128;
;     constexpr int NM = NI * MJ;
;     constexpr int PPS = (NLD + 1) / 2;
; #pragma unroll
;     for (int s = 0; s < 4; ++s) {
;       bf16x8 af[MJ], wf[NI];
; #pragma unroll
;       for (int j = 0; j < MJ; ++j) af[j] = *(const bf16x8*)(pa + j * 32 * 128 + xo[s]);
; #pragma unroll
;       for (int i = 0; i < NI; ++i) wf[i] = *(const bf16x8*)(pw + i * 32 * 128 + xo[s]);
; #pragma unroll
;       for (int m = 0; m < NM; ++m) {
;         const int i = m / MJ, j = m % MJ;
;         acc[i][j] = MFMA(wf[i], af[j], acc[i][j]);
;         if (s < 2 && NM >= PPS) {
;           constexpr int EVERY = (NM / PPS) > 0 ? (NM / PPS) : 1;
;           if ((m + 1) % EVERY == 0) {
;             const int pc = s * PPS + (m + 1) / EVERY - 1;
;             if ((m + 1) / EVERY <= PPS && pc < NLD) {
;               __builtin_amdgcn_sched_barrier(0);
;               if (pre) issue_piece(kt + DIST, pc);
;               __builtin_amdgcn_sched_barrier(0);
;             }
;           }
;         }
;         if (s < 2 && NM < PPS) {
;           const int slot = s * NM + m;
;           __builtin_amdgcn_sched_barrier(0);
; #pragma unroll
;           for (int pc = 0; pc < NLD; ++pc)
;             if ((pc * 2 * NM) / NLD == slot && pre) issue_piece(kt + DIST, pc);
;           __builtin_amdgcn_sched_barrier(0);
;         }
;       }
;     }
;   }
	s_waitcnt lgkmcnt(0)
	v_mfma_f32_32x32x16_bf16 v[48:63], v[186:189], v[190:193], v[48:63]
	v_mfma_f32_32x32x16_bf16 v[16:31], v[186:189], v[194:197], v[16:31]
	v_mfma_f32_32x32x16_bf16 v[32:47], v[198:201], v[190:193], v[32:47]
	v_mfma_f32_32x32x16_bf16 v[0:15], v[198:201], v[194:197], v[0:15]
	ds_read_b128 v[186:189], v138
	ds_read_b128 v[190:193], v142
	ds_read_b128 v[194:197], v142 offset:4096
	ds_read_b128 v[198:201], v138 offset:4096
	ds_read_b128 v[202:205], v138 offset:8192
	ds_read_b128 v[206:209], v138 offset:12288
	s_waitcnt lgkmcnt(0)
	v_mfma_f32_32x32x16_bf16 v[96:111], v[186:189], v[190:193], v[96:111]
	v_mfma_f32_32x32x16_bf16 v[64:79], v[186:189], v[194:197], v[64:79]
	v_lshl_add_u64 v[186:187], v[130:131], 0, s[16:17]
	s_mov_b32 m0, s0
	s_nop 0
	global_load_lds_dwordx4 v[186:187], off
	v_mfma_f32_32x32x16_bf16 v[112:127], v[198:201], v[190:193], v[112:127]
	v_mfma_f32_32x32x16_bf16 v[80:95], v[198:201], v[194:197], v[80:95]
	s_mov_b64 s[16:17], 0x42000
	v_lshl_add_u64 v[186:187], v[130:131], 0, s[16:17]
	s_mov_b32 m0, s1
	s_nop 0
	global_load_lds_dwordx4 v[186:187], off
	v_mfma_f32_32x32x16_bf16 v[48:63], v[202:205], v[190:193], v[48:63]
	v_mfma_f32_32x32x16_bf16 v[16:31], v[202:205], v[194:197], v[16:31]
	s_mov_b64 s[18:19], 0x44000
	v_lshl_add_u64 v[186:187], v[130:131], 0, s[18:19]
	s_mov_b32 m0, s2
	s_nop 0
	global_load_lds_dwordx4 v[186:187], off
	v_mfma_f32_32x32x16_bf16 v[32:47], v[206:209], v[190:193], v[32:47]
	v_mfma_f32_32x32x16_bf16 v[0:15], v[206:209], v[194:197], v[0:15]
	s_mov_b64 s[20:21], 0x46000
	v_lshl_add_u64 v[186:187], v[130:131], 0, s[20:21]
	s_mov_b32 m0, s3
	s_nop 0
	global_load_lds_dwordx4 v[186:187], off
	ds_read_b128 v[186:189], v144
	ds_read_b128 v[190:193], v151
	ds_read_b128 v[194:197], v151 offset:4096
	ds_read_b128 v[198:201], v144 offset:4096
	ds_read_b128 v[202:205], v144 offset:8192
	ds_read_b128 v[206:209], v144 offset:12288
	s_waitcnt lgkmcnt(0)
	v_mfma_f32_32x32x16_bf16 v[96:111], v[186:189], v[190:193], v[96:111]
	v_mfma_f32_32x32x16_bf16 v[64:79], v[186:189], v[194:197], v[64:79]
	s_mov_b32 m0, s4
	s_nop 0
	global_load_lds_dwordx4 v[210:211], off
	v_mfma_f32_32x32x16_bf16 v[112:127], v[198:201], v[190:193], v[112:127]
	v_mfma_f32_32x32x16_bf16 v[80:95], v[198:201], v[194:197], v[80:95]
	v_lshl_add_u64 v[186:187], v[128:129], 0, s[16:17]
	s_mov_b32 m0, s5
	s_nop 0
	global_load_lds_dwordx4 v[186:187], off
	v_mfma_f32_32x32x16_bf16 v[48:63], v[202:205], v[190:193], v[48:63]
	v_mfma_f32_32x32x16_bf16 v[16:31], v[202:205], v[194:197], v[16:31]
	v_lshl_add_u64 v[186:187], v[128:129], 0, s[18:19]
	s_mov_b32 m0, s6
	s_nop 0
	global_load_lds_dwordx4 v[186:187], off
	v_mfma_f32_32x32x16_bf16 v[32:47], v[206:209], v[190:193], v[32:47]
	v_mfma_f32_32x32x16_bf16 v[0:15], v[206:209], v[194:197], v[0:15]
	v_lshl_add_u64 v[186:187], v[128:129], 0, s[20:21]
	s_mov_b32 m0, s7
	s_nop 0
	global_load_lds_dwordx4 v[186:187], off
	ds_read_b128 v[186:189], v143
	ds_read_b128 v[190:193], v153
	ds_read_b128 v[194:197], v153 offset:4096
	ds_read_b128 v[198:201], v143 offset:4096
	s_mov_b64 s[16:17], 0x48000
	v_lshl_add_u64 v[210:211], v[128:129], 0, s[16:17]
	s_waitcnt lgkmcnt(0)
	v_mfma_f32_32x32x16_bf16 v[96:111], v[186:189], v[190:193], v[96:111]
	v_mfma_f32_32x32x16_bf16 v[64:79], v[186:189], v[194:197], v[64:79]
	v_mfma_f32_32x32x16_bf16 v[112:127], v[198:201], v[190:193], v[112:127]
	v_mfma_f32_32x32x16_bf16 v[80:95], v[198:201], v[194:197], v[80:95]
	ds_read_b128 v[186:189], v143 offset:8192
	ds_read_b128 v[198:201], v143 offset:12288
	s_waitcnt lgkmcnt(0)
	v_mfma_f32_32x32x16_bf16 v[48:63], v[186:189], v[190:193], v[48:63]
	v_mfma_f32_32x32x16_bf16 v[16:31], v[186:189], v[194:197], v[16:31]
	v_mfma_f32_32x32x16_bf16 v[32:47], v[198:201], v[190:193], v[32:47]
	v_mfma_f32_32x32x16_bf16 v[0:15], v[198:201], v[194:197], v[0:15]
	ds_read_b128 v[186:189], v141
	ds_read_b128 v[190:193], v152
	ds_read_b128 v[194:197], v152 offset:4096
	ds_read_b128 v[198:201], v141 offset:4096
	s_waitcnt lgkmcnt(0)
	v_mfma_f32_32x32x16_bf16 v[96:111], v[186:189], v[190:193], v[96:111]
	v_mfma_f32_32x32x16_bf16 v[64:79], v[186:189], v[194:197], v[64:79]
	v_mfma_f32_32x32x16_bf16 v[112:127], v[198:201], v[190:193], v[112:127]
	v_mfma_f32_32x32x16_bf16 v[80:95], v[198:201], v[194:197], v[80:95]
	ds_read_b128 v[186:189], v141 offset:8192
	ds_read_b128 v[198:201], v141 offset:12288
	s_waitcnt vmcnt(0)
	s_barrier
; #define MFMA(a, b, c) __builtin_amdgcn_mfma_f32_32x32x16_bf16((a), (b), (c), 0, 0, 0)
;     ...
;   for (int kt = 0; kt < nk; ++kt) {
;     if (DIST == 2 && kt + 1 < nk) {
;       if (NLD == 6) asm volatile("s_waitcnt vmcnt(6)" ::: "memory");
;       else if (NLD == 5) asm volatile("s_waitcnt vmcnt(5)" ::: "memory");
;       else asm volatile("s_waitcnt vmcnt(8)" ::: "memory");
;     } else {
;       asm volatile("s_waitcnt vmcnt(0)" ::: "memory");
;     }
;     __builtin_amdgcn_s_barrier();
;     const bool pre = (kt + DIST < nk);
;     const char* base = smem + (kt % NSTG) * STAGE;
;     const char* pa = base + (wrow_act + r) * 128;
;     const char* pw = base + ABYTES + (wrow_w + r) * 128;
;     constexpr int NM = NI * MJ;
;     constexpr int PPS = (NLD + 1) / 2;
; #pragma unroll
;     for (int s = 0; s < 4; ++s) {
;       bf16x8 af[MJ], wf[NI];
; #pragma unroll
;       for (int j = 0; j < MJ; ++j) af[j] = *(const bf16x8*)(pa + j * 32 * 128 + xo[s]);
; #pragma unroll
;       for (int i = 0; i < NI; ++i) wf[i] = *(const bf16x8*)(pw + i * 32 * 128 + xo[s]);
; #pragma unroll
;       for (int m = 0; m < NM; ++m) {
;         const int i = m / MJ, j = m % MJ;
;         acc[i][j] = MFMA(wf[i], af[j], acc[i][j]);
;         if (s < 2 && NM >= PPS) {
;           constexpr int EVERY = (NM / PPS) > 0 ? (NM / PPS) : 1;
;           if ((m + 1) % EVERY == 0) {
;             const int pc = s * PPS + (m + 1) / EVERY - 1;
;             if ((m + 1) / EVERY <= PPS && pc < NLD) {
;               __builtin_amdgcn_sched_barrier(0);
;               if (pre) issue_piece(kt + DIST, pc);
;               __builtin_amdgcn_sched_barrier(0);
;             }
;           }
;         }
;         if (s < 2 && NM < PPS) {
;           const int slot = s * NM + m;
;           __builtin_amdgcn_sched_barrier(0);
; #pragma unroll
;           for (int pc = 0; pc < NLD; ++pc)
;             if ((pc * 2 * NM) / NLD == slot && pre) issue_piece(kt + DIST, pc);
;           __builtin_amdgcn_sched_barrier(0);
;         }
;       }
;     }
;   }
	s_waitcnt lgkmcnt(0)
	v_mfma_f32_32x32x16_bf16 v[48:63], v[186:189], v[190:193], v[48:63]
	v_mfma_f32_32x32x16_bf16 v[16:31], v[186:189], v[194:197], v[16:31]
	v_mfma_f32_32x32x16_bf16 v[32:47], v[198:201], v[190:193], v[32:47]
	v_mfma_f32_32x32x16_bf16 v[0:15], v[198:201], v[194:197], v[0:15]
	ds_read_b128 v[186:189], v132 offset:32768
	ds_read_b128 v[190:193], v136
	ds_read_b128 v[194:197], v136 offset:4096
	ds_read_b128 v[198:201], v132 offset:36864
	ds_read_b128 v[202:205], v132 offset:40960
	ds_read_b128 v[206:209], v132 offset:45056
	s_waitcnt lgkmcnt(0)
	v_mfma_f32_32x32x16_bf16 v[96:111], v[186:189], v[190:193], v[96:111]
	v_mfma_f32_32x32x16_bf16 v[64:79], v[186:189], v[194:197], v[64:79]
	v_lshl_add_u64 v[186:187], v[130:131], 0, s[16:17]
	s_mov_b32 m0, s8
	s_nop 0
	global_load_lds_dwordx4 v[186:187], off
	v_mfma_f32_32x32x16_bf16 v[112:127], v[198:201], v[190:193], v[112:127]
	v_mfma_f32_32x32x16_bf16 v[80:95], v[198:201], v[194:197], v[80:95]
	s_mov_b64 s[16:17], 0x4a000
	v_lshl_add_u64 v[186:187], v[130:131], 0, s[16:17]
	s_mov_b32 m0, s9
	s_nop 0
	global_load_lds_dwordx4 v[186:187], off
	v_mfma_f32_32x32x16_bf16 v[48:63], v[202:205], v[190:193], v[48:63]
	v_mfma_f32_32x32x16_bf16 v[16:31], v[202:205], v[194:197], v[16:31]
	s_mov_b64 s[18:19], 0x4c000
	v_lshl_add_u64 v[186:187], v[130:131], 0, s[18:19]
	s_mov_b32 m0, s10
	s_nop 0
	global_load_lds_dwordx4 v[186:187], off
	v_mfma_f32_32x32x16_bf16 v[32:47], v[206:209], v[190:193], v[32:47]
	v_mfma_f32_32x32x16_bf16 v[0:15], v[206:209], v[194:197], v[0:15]
	s_mov_b64 s[20:21], 0x4e000
	v_lshl_add_u64 v[186:187], v[130:131], 0, s[20:21]
	s_mov_b32 m0, s11
	s_nop 0
	global_load_lds_dwordx4 v[186:187], off
	ds_read_b128 v[186:189], v133 offset:32768
	ds_read_b128 v[190:193], v137
	ds_read_b128 v[194:197], v137 offset:4096
	ds_read_b128 v[198:201], v133 offset:36864
	ds_read_b128 v[202:205], v133 offset:40960
	ds_read_b128 v[206:209], v133 offset:45056
	s_waitcnt lgkmcnt(0)
	v_mfma_f32_32x32x16_bf16 v[96:111], v[186:189], v[190:193], v[96:111]
	v_mfma_f32_32x32x16_bf16 v[64:79], v[186:189], v[194:197], v[64:79]
	s_mov_b32 m0, s12
	s_nop 0
	global_load_lds_dwordx4 v[210:211], off
	v_mfma_f32_32x32x16_bf16 v[112:127], v[198:201], v[190:193], v[112:127]
	v_mfma_f32_32x32x16_bf16 v[80:95], v[198:201], v[194:197], v[80:95]
	v_lshl_add_u64 v[186:187], v[128:129], 0, s[16:17]
	s_mov_b32 m0, s13
	s_nop 0
	global_load_lds_dwordx4 v[186:187], off
	v_mfma_f32_32x32x16_bf16 v[48:63], v[202:205], v[190:193], v[48:63]
	v_mfma_f32_32x32x16_bf16 v[16:31], v[202:205], v[194:197], v[16:31]
	v_lshl_add_u64 v[186:187], v[128:129], 0, s[18:19]
	s_mov_b32 m0, s14
	s_nop 0
	global_load_lds_dwordx4 v[186:187], off
	v_mfma_f32_32x32x16_bf16 v[32:47], v[206:209], v[190:193], v[32:47]
	v_mfma_f32_32x32x16_bf16 v[0:15], v[206:209], v[194:197], v[0:15]
	v_lshl_add_u64 v[186:187], v[128:129], 0, s[20:21]
	s_mov_b32 m0, s15
	s_nop 0
	global_load_lds_dwordx4 v[186:187], off
	ds_read_b128 v[186:189], v135 offset:32768
	ds_read_b128 v[190:193], v140
	ds_read_b128 v[194:197], v140 offset:4096
	ds_read_b128 v[198:201], v135 offset:36864
	s_mov_b64 s[16:17], 0x50000
	v_lshl_add_u64 v[210:211], v[128:129], 0, s[16:17]
	s_waitcnt lgkmcnt(0)
	v_mfma_f32_32x32x16_bf16 v[96:111], v[186:189], v[190:193], v[96:111]
	v_mfma_f32_32x32x16_bf16 v[64:79], v[186:189], v[194:197], v[64:79]
	v_mfma_f32_32x32x16_bf16 v[112:127], v[198:201], v[190:193], v[112:127]
	v_mfma_f32_32x32x16_bf16 v[80:95], v[198:201], v[194:197], v[80:95]
	ds_read_b128 v[186:189], v135 offset:40960
	ds_read_b128 v[198:201], v135 offset:45056
	s_waitcnt lgkmcnt(0)
	v_mfma_f32_32x32x16_bf16 v[48:63], v[186:189], v[190:193], v[48:63]
	v_mfma_f32_32x32x16_bf16 v[16:31], v[186:189], v[194:197], v[16:31]
	v_mfma_f32_32x32x16_bf16 v[32:47], v[198:201], v[190:193], v[32:47]
	v_mfma_f32_32x32x16_bf16 v[0:15], v[198:201], v[194:197], v[0:15]
	ds_read_b128 v[186:189], v134 offset:32768
	ds_read_b128 v[190:193], v139
	ds_read_b128 v[194:197], v139 offset:4096
	ds_read_b128 v[198:201], v134 offset:36864
	s_waitcnt lgkmcnt(0)
	v_mfma_f32_32x32x16_bf16 v[96:111], v[186:189], v[190:193], v[96:111]
	v_mfma_f32_32x32x16_bf16 v[64:79], v[186:189], v[194:197], v[64:79]
	v_mfma_f32_32x32x16_bf16 v[112:127], v[198:201], v[190:193], v[112:127]
	v_mfma_f32_32x32x16_bf16 v[80:95], v[198:201], v[194:197], v[80:95]
	ds_read_b128 v[186:189], v134 offset:40960
	ds_read_b128 v[198:201], v134 offset:45056
	s_waitcnt vmcnt(0)
	s_barrier
; #define MFMA(a, b, c) __builtin_amdgcn_mfma_f32_32x32x16_bf16((a), (b), (c), 0, 0, 0)
;     ...
;     const bool pre = (kt + DIST < nk);
;     const char* base = smem + (kt % NSTG) * STAGE;
;     const char* pa = base + (wrow_act + r) * 128;
;     const char* pw = base + ABYTES + (wrow_w + r) * 128;
;     constexpr int NM = NI * MJ;
;     constexpr int PPS = (NLD + 1) / 2;
; #pragma unroll
;     for (int s = 0; s < 4; ++s) {
;       bf16x8 af[MJ], wf[NI];
; #pragma unroll
;       for (int j = 0; j < MJ; ++j) af[j] = *(const bf16x8*)(pa + j * 32 * 128 + xo[s]);
; #pragma unroll
;       for (int i = 0; i < NI; ++i) wf[i] = *(const bf16x8*)(pw + i * 32 * 128 + xo[s]);
; #pragma unroll
;       for (int m = 0; m < NM; ++m) {
;         const int i = m / MJ, j = m % MJ;
;         acc[i][j] = MFMA(wf[i], af[j], acc[i][j]);
;         if (s < 2 && NM >= PPS) {
;           constexpr int EVERY = (NM / PPS) > 0 ? (NM / PPS) : 1;
;           if ((m + 1) % EVERY == 0) {
;             const int pc = s * PPS + (m + 1) / EVERY - 1;
;             if ((m + 1) / EVERY <= PPS && pc < NLD) {
;               __builtin_amdgcn_sched_barrier(0);
;               if (pre) issue_piece(kt + DIST, pc);
;               __builtin_amdgcn_sched_barrier(0);
;             }
;           }
;         }
;         if (s < 2 && NM < PPS) {
;           const int slot = s * NM + m;
;           __builtin_amdgcn_sched_barrier(0);
; #pragma unroll
;           for (int pc = 0; pc < NLD; ++pc)
;             if ((pc * 2 * NM) / NLD == slot && pre) issue_piece(kt + DIST, pc);
;           __builtin_amdgcn_sched_barrier(0);
;         }
;       }
;     }
	s_waitcnt lgkmcnt(0)
	v_mfma_f32_32x32x16_bf16 v[48:63], v[186:189], v[190:193], v[48:63]
	v_mfma_f32_32x32x16_bf16 v[16:31], v[186:189], v[194:197], v[16:31]
	v_mfma_f32_32x32x16_bf16 v[32:47], v[198:201], v[190:193], v[32:47]
	v_mfma_f32_32x32x16_bf16 v[0:15], v[198:201], v[194:197], v[0:15]
	ds_read_b128 v[186:189], v138
	ds_read_b128 v[190:193], v142
	ds_read_b128 v[194:197], v142 offset:4096
	ds_read_b128 v[198:201], v138 offset:4096
	ds_read_b128 v[202:205], v138 offset:8192
	ds_read_b128 v[206:209], v138 offset:12288
	s_waitcnt lgkmcnt(0)
	v_mfma_f32_32x32x16_bf16 v[96:111], v[186:189], v[190:193], v[96:111]
	v_mfma_f32_32x32x16_bf16 v[64:79], v[186:189], v[194:197], v[64:79]
	v_lshl_add_u64 v[186:187], v[130:131], 0, s[16:17]
	s_mov_b32 m0, s0
	s_nop 0
	global_load_lds_dwordx4 v[186:187], off
	v_mfma_f32_32x32x16_bf16 v[112:127], v[198:201], v[190:193], v[112:127]
	v_mfma_f32_32x32x16_bf16 v[80:95], v[198:201], v[194:197], v[80:95]
	s_mov_b64 s[16:17], 0x52000
	v_lshl_add_u64 v[186:187], v[130:131], 0, s[16:17]
	s_mov_b32 m0, s1
	s_nop 0
	global_load_lds_dwordx4 v[186:187], off
	v_mfma_f32_32x32x16_bf16 v[48:63], v[202:205], v[190:193], v[48:63]
	v_mfma_f32_32x32x16_bf16 v[16:31], v[202:205], v[194:197], v[16:31]
	s_mov_b64 s[0:1], 0x54000
	v_lshl_add_u64 v[186:187], v[130:131], 0, s[0:1]
	s_mov_b32 m0, s2
	s_nop 0
	global_load_lds_dwordx4 v[186:187], off
	v_mfma_f32_32x32x16_bf16 v[32:47], v[206:209], v[190:193], v[32:47]
	v_mfma_f32_32x32x16_bf16 v[0:15], v[206:209], v[194:197], v[0:15]
	s_mov_b64 s[18:19], 0x56000
	v_lshl_add_u64 v[186:187], v[130:131], 0, s[18:19]
	s_mov_b32 m0, s3
	s_nop 0
	global_load_lds_dwordx4 v[186:187], off
	ds_read_b128 v[186:189], v144
	ds_read_b128 v[190:193], v151
	ds_read_b128 v[194:197], v151 offset:4096
	ds_read_b128 v[198:201], v144 offset:4096
	ds_read_b128 v[202:205], v144 offset:8192
	ds_read_b128 v[206:209], v144 offset:12288
	s_waitcnt lgkmcnt(0)
	v_mfma_f32_32x32x16_bf16 v[96:111], v[186:189], v[190:193], v[96:111]
	v_mfma_f32_32x32x16_bf16 v[64:79], v[186:189], v[194:197], v[64:79]
	s_mov_b32 m0, s4
	s_nop 0
	global_load_lds_dwordx4 v[210:211], off
	v_mfma_f32_32x32x16_bf16 v[112:127], v[198:201], v[190:193], v[112:127]
	v_mfma_f32_32x32x16_bf16 v[80:95], v[198:201], v[194:197], v[80:95]
	v_lshl_add_u64 v[186:187], v[128:129], 0, s[16:17]
	s_mov_b32 m0, s5
	s_nop 0
	global_load_lds_dwordx4 v[186:187], off
	v_mfma_f32_32x32x16_bf16 v[48:63], v[202:205], v[190:193], v[48:63]
	v_mfma_f32_32x32x16_bf16 v[16:31], v[202:205], v[194:197], v[16:31]
	v_lshl_add_u64 v[186:187], v[128:129], 0, s[0:1]
	s_mov_b32 m0, s6
	s_nop 0
	global_load_lds_dwordx4 v[186:187], off
	v_mfma_f32_32x32x16_bf16 v[32:47], v[206:209], v[190:193], v[32:47]
	v_mfma_f32_32x32x16_bf16 v[0:15], v[206:209], v[194:197], v[0:15]
	v_lshl_add_u64 v[186:187], v[128:129], 0, s[18:19]
	s_mov_b32 m0, s7
	s_nop 0
	global_load_lds_dwordx4 v[186:187], off
	ds_read_b128 v[186:189], v143
	ds_read_b128 v[190:193], v153
	ds_read_b128 v[194:197], v153 offset:4096
	ds_read_b128 v[198:201], v143 offset:4096
	s_mov_b64 s[0:1], 0x58000
	v_lshl_add_u64 v[210:211], v[128:129], 0, s[0:1]
	s_waitcnt lgkmcnt(0)
	v_mfma_f32_32x32x16_bf16 v[96:111], v[186:189], v[190:193], v[96:111]
	v_mfma_f32_32x32x16_bf16 v[64:79], v[186:189], v[194:197], v[64:79]
	v_mfma_f32_32x32x16_bf16 v[112:127], v[198:201], v[190:193], v[112:127]
	v_mfma_f32_32x32x16_bf16 v[80:95], v[198:201], v[194:197], v[80:95]
	ds_read_b128 v[186:189], v143 offset:8192
	ds_read_b128 v[198:201], v143 offset:12288
	s_waitcnt lgkmcnt(0)
	v_mfma_f32_32x32x16_bf16 v[48:63], v[186:189], v[190:193], v[48:63]
	v_mfma_f32_32x32x16_bf16 v[16:31], v[186:189], v[194:197], v[16:31]
	v_mfma_f32_32x32x16_bf16 v[32:47], v[198:201], v[190:193], v[32:47]
	v_mfma_f32_32x32x16_bf16 v[0:15], v[198:201], v[194:197], v[0:15]
	ds_read_b128 v[186:189], v141
	ds_read_b128 v[190:193], v152
	ds_read_b128 v[194:197], v152 offset:4096
	ds_read_b128 v[198:201], v141 offset:4096
	s_waitcnt lgkmcnt(0)
	v_mfma_f32_32x32x16_bf16 v[96:111], v[186:189], v[190:193], v[96:111]
	v_mfma_f32_32x32x16_bf16 v[64:79], v[186:189], v[194:197], v[64:79]
	v_mfma_f32_32x32x16_bf16 v[112:127], v[198:201], v[190:193], v[112:127]
	v_mfma_f32_32x32x16_bf16 v[80:95], v[198:201], v[194:197], v[80:95]
	ds_read_b128 v[186:189], v141 offset:8192
	ds_read_b128 v[198:201], v141 offset:12288
	s_waitcnt vmcnt(0)
	s_barrier
; #define MFMA(a, b, c) __builtin_amdgcn_mfma_f32_32x32x16_bf16((a), (b), (c), 0, 0, 0)
;     ...
;     const bool pre = (kt + DIST < nk);
;     const char* base = smem + (kt % NSTG) * STAGE;
;     const char* pa = base + (wrow_act + r) * 128;
;     const char* pw = base + ABYTES + (wrow_w + r) * 128;
;     constexpr int NM = NI * MJ;
;     constexpr int PPS = (NLD + 1) / 2;
; #pragma unroll
;     for (int s = 0; s < 4; ++s) {
;       bf16x8 af[MJ], wf[NI];
; #pragma unroll
;       for (int j = 0; j < MJ; ++j) af[j] = *(const bf16x8*)(pa + j * 32 * 128 + xo[s]);
; #pragma unroll
;       for (int i = 0; i < NI; ++i) wf[i] = *(const bf16x8*)(pw + i * 32 * 128 + xo[s]);
; #pragma unroll
;       for (int m = 0; m < NM; ++m) {
;         const int i = m / MJ, j = m % MJ;
;         acc[i][j] = MFMA(wf[i], af[j], acc[i][j]);
;         if (s < 2 && NM >= PPS) {
;           constexpr int EVERY = (NM / PPS) > 0 ? (NM / PPS) : 1;
;           if ((m + 1) % EVERY == 0) {
;             const int pc = s * PPS + (m + 1) / EVERY - 1;
;             if ((m + 1) / EVERY <= PPS && pc < NLD) {
;               __builtin_amdgcn_sched_barrier(0);
;               if (pre) issue_piece(kt + DIST, pc);
;               __builtin_amdgcn_sched_barrier(0);
;             }
;           }
;         }
;         if (s < 2 && NM < PPS) {
;           const int slot = s * NM + m;
;           __builtin_amdgcn_sched_barrier(0);
; #pragma unroll
;           for (int pc = 0; pc < NLD; ++pc)
;             if ((pc * 2 * NM) / NLD == slot && pre) issue_piece(kt + DIST, pc);
;           __builtin_amdgcn_sched_barrier(0);
;         }
;       }
;     }
	s_waitcnt lgkmcnt(0)
	v_mfma_f32_32x32x16_bf16 v[48:63], v[186:189], v[190:193], v[48:63]
	v_mfma_f32_32x32x16_bf16 v[16:31], v[186:189], v[194:197], v[16:31]
	v_mfma_f32_32x32x16_bf16 v[32:47], v[198:201], v[190:193], v[32:47]
	v_mfma_f32_32x32x16_bf16 v[0:15], v[198:201], v[194:197], v[0:15]
	ds_read_b128 v[186:189], v132 offset:32768
	ds_read_b128 v[190:193], v136
	ds_read_b128 v[194:197], v136 offset:4096
	ds_read_b128 v[198:201], v132 offset:36864
	ds_read_b128 v[202:205], v132 offset:40960
	ds_read_b128 v[206:209], v132 offset:45056
	s_waitcnt lgkmcnt(0)
	v_mfma_f32_32x32x16_bf16 v[96:111], v[186:189], v[190:193], v[96:111]
	v_mfma_f32_32x32x16_bf16 v[64:79], v[186:189], v[194:197], v[64:79]
	v_lshl_add_u64 v[186:187], v[130:131], 0, s[0:1]
	s_mov_b32 m0, s8
	s_nop 0
	global_load_lds_dwordx4 v[186:187], off
	v_mfma_f32_32x32x16_bf16 v[112:127], v[198:201], v[190:193], v[112:127]
	v_mfma_f32_32x32x16_bf16 v[80:95], v[198:201], v[194:197], v[80:95]
	s_mov_b64 s[0:1], 0x5a000
	v_lshl_add_u64 v[186:187], v[130:131], 0, s[0:1]
	s_mov_b32 m0, s9
	s_nop 0
	global_load_lds_dwordx4 v[186:187], off
	v_mfma_f32_32x32x16_bf16 v[48:63], v[202:205], v[190:193], v[48:63]
	v_mfma_f32_32x32x16_bf16 v[16:31], v[202:205], v[194:197], v[16:31]
	s_mov_b64 s[2:3], 0x5c000
	v_lshl_add_u64 v[186:187], v[130:131], 0, s[2:3]
	s_mov_b32 m0, s10
	s_nop 0
	global_load_lds_dwordx4 v[186:187], off
	v_mfma_f32_32x32x16_bf16 v[32:47], v[206:209], v[190:193], v[32:47]
	v_mfma_f32_32x32x16_bf16 v[0:15], v[206:209], v[194:197], v[0:15]
	s_mov_b64 s[4:5], 0x5e000
	v_lshl_add_u64 v[186:187], v[130:131], 0, s[4:5]
	s_mov_b32 m0, s11
	s_nop 0
	global_load_lds_dwordx4 v[186:187], off
	ds_read_b128 v[186:189], v133 offset:32768
	ds_read_b128 v[190:193], v137
	ds_read_b128 v[194:197], v137 offset:4096
	ds_read_b128 v[198:201], v133 offset:36864
	ds_read_b128 v[202:205], v133 offset:40960
	ds_read_b128 v[206:209], v133 offset:45056
	s_waitcnt lgkmcnt(0)
	v_mfma_f32_32x32x16_bf16 v[96:111], v[186:189], v[190:193], v[96:111]
	v_mfma_f32_32x32x16_bf16 v[64:79], v[186:189], v[194:197], v[64:79]
	s_mov_b32 m0, s12
	s_nop 0
	global_load_lds_dwordx4 v[210:211], off
	v_mfma_f32_32x32x16_bf16 v[112:127], v[198:201], v[190:193], v[112:127]
	v_mfma_f32_32x32x16_bf16 v[80:95], v[198:201], v[194:197], v[80:95]
	v_lshl_add_u64 v[186:187], v[128:129], 0, s[0:1]
	s_mov_b32 m0, s13
	s_nop 0
	global_load_lds_dwordx4 v[186:187], off
	v_mfma_f32_32x32x16_bf16 v[48:63], v[202:205], v[190:193], v[48:63]
	v_mfma_f32_32x32x16_bf16 v[16:31], v[202:205], v[194:197], v[16:31]
	v_lshl_add_u64 v[186:187], v[128:129], 0, s[2:3]
	s_mov_b32 m0, s14
	s_nop 0
	global_load_lds_dwordx4 v[186:187], off
	v_mfma_f32_32x32x16_bf16 v[32:47], v[206:209], v[190:193], v[32:47]
	v_mfma_f32_32x32x16_bf16 v[0:15], v[206:209], v[194:197], v[0:15]
	v_lshl_add_u64 v[186:187], v[128:129], 0, s[4:5]
	s_mov_b32 m0, s15
	s_nop 0
	global_load_lds_dwordx4 v[186:187], off
	ds_read_b128 v[186:189], v135 offset:32768
	ds_read_b128 v[190:193], v140
	ds_read_b128 v[194:197], v140 offset:4096
	ds_read_b128 v[198:201], v135 offset:36864
	s_mov_b64 s[0:1], 0x60000
	v_lshl_add_u64 v[210:211], v[128:129], 0, s[0:1]
	s_waitcnt lgkmcnt(0)
	v_mfma_f32_32x32x16_bf16 v[96:111], v[186:189], v[190:193], v[96:111]
	v_mfma_f32_32x32x16_bf16 v[64:79], v[186:189], v[194:197], v[64:79]
	v_mfma_f32_32x32x16_bf16 v[112:127], v[198:201], v[190:193], v[112:127]
	v_mfma_f32_32x32x16_bf16 v[80:95], v[198:201], v[194:197], v[80:95]
	ds_read_b128 v[186:189], v135 offset:40960
	ds_read_b128 v[198:201], v135 offset:45056
	s_waitcnt lgkmcnt(0)
	v_mfma_f32_32x32x16_bf16 v[48:63], v[186:189], v[190:193], v[48:63]
	v_mfma_f32_32x32x16_bf16 v[16:31], v[186:189], v[194:197], v[16:31]
	v_mfma_f32_32x32x16_bf16 v[32:47], v[198:201], v[190:193], v[32:47]
	v_mfma_f32_32x32x16_bf16 v[0:15], v[198:201], v[194:197], v[0:15]
	ds_read_b128 v[186:189], v134 offset:32768
	ds_read_b128 v[190:193], v139
	ds_read_b128 v[194:197], v139 offset:4096
	ds_read_b128 v[198:201], v134 offset:36864
	s_waitcnt lgkmcnt(0)
	v_mfma_f32_32x32x16_bf16 v[96:111], v[186:189], v[190:193], v[96:111]
	v_mfma_f32_32x32x16_bf16 v[64:79], v[186:189], v[194:197], v[64:79]
	v_mfma_f32_32x32x16_bf16 v[112:127], v[198:201], v[190:193], v[112:127]
	v_mfma_f32_32x32x16_bf16 v[80:95], v[198:201], v[194:197], v[80:95]
	ds_read_b128 v[186:189], v134 offset:40960
	ds_read_b128 v[198:201], v134 offset:45056
	s_waitcnt vmcnt(0)
	s_barrier
; #define MFMA(a, b, c) __builtin_amdgcn_mfma_f32_32x32x16_bf16((a), (b), (c), 0, 0, 0)
;     ...
;     const bool pre = (kt + DIST < nk);
;     const char* base = smem + (kt % NSTG) * STAGE;
;     const char* pa = base + (wrow_act + r) * 128;
;     const char* pw = base + ABYTES + (wrow_w + r) * 128;
;     constexpr int NM = NI * MJ;
;     constexpr int PPS = (NLD + 1) / 2;
; #pragma unroll
;     for (int s = 0; s < 4; ++s) {
;       bf16x8 af[MJ], wf[NI];
; #pragma unroll
;       for (int j = 0; j < MJ; ++j) af[j] = *(const bf16x8*)(pa + j * 32 * 128 + xo[s]);
; #pragma unroll
;       for (int i = 0; i < NI; ++i) wf[i] = *(const bf16x8*)(pw + i * 32 * 128 + xo[s]);
; #pragma unroll
;       for (int m = 0; m < NM; ++m) {
;         const int i = m / MJ, j = m % MJ;
;         acc[i][j] = MFMA(wf[i], af[j], acc[i][j]);
;         if (s < 2 && NM >= PPS) {
;           constexpr int EVERY = (NM / PPS) > 0 ? (NM / PPS) : 1;
;           if ((m + 1) % EVERY == 0) {
;             const int pc = s * PPS + (m + 1) / EVERY - 1;
;             if ((m + 1) / EVERY <= PPS && pc < NLD) {
;               __builtin_amdgcn_sched_barrier(0);
;               if (pre) issue_piece(kt + DIST, pc);
;               __builtin_amdgcn_sched_barrier(0);
;             }
;           }
;         }
;         if (s < 2 && NM < PPS) {
;           const int slot = s * NM + m;
;           __builtin_amdgcn_sched_barrier(0);
; #pragma unroll
;           for (int pc = 0; pc < NLD; ++pc)
;             if ((pc * 2 * NM) / NLD == slot && pre) issue_piece(kt + DIST, pc);
;           __builtin_amdgcn_sched_barrier(0);
;         }
;       }
;     }
	s_waitcnt lgkmcnt(0)
	v_mfma_f32_32x32x16_bf16 v[48:63], v[186:189], v[190:193], v[48:63]
	v_mfma_f32_32x32x16_bf16 v[16:31], v[186:189], v[194:197], v[16:31]
	v_mfma_f32_32x32x16_bf16 v[32:47], v[198:201], v[190:193], v[32:47]
	v_mfma_f32_32x32x16_bf16 v[0:15], v[198:201], v[194:197], v[0:15]
	ds_read_b128 v[186:189], v138
	ds_read_b128 v[190:193], v142
	ds_read_b128 v[194:197], v142 offset:4096
	ds_read_b128 v[198:201], v138 offset:4096
	ds_read_b128 v[202:205], v138 offset:8192
	ds_read_b128 v[206:209], v138 offset:12288
	s_waitcnt lgkmcnt(0)
	v_mfma_f32_32x32x16_bf16 v[96:111], v[186:189], v[190:193], v[96:111]
	v_mfma_f32_32x32x16_bf16 v[64:79], v[186:189], v[194:197], v[64:79]
	v_lshl_add_u64 v[186:187], v[130:131], 0, s[0:1]
	v_readfirstlane_b32 s0, v184
	s_mov_b32 m0, s0
	s_nop 0
	global_load_lds_dwordx4 v[186:187], off
	v_mfma_f32_32x32x16_bf16 v[112:127], v[198:201], v[190:193], v[112:127]
	v_mfma_f32_32x32x16_bf16 v[80:95], v[198:201], v[194:197], v[80:95]
	s_mov_b64 s[6:7], 0x62000
	v_readfirstlane_b32 s1, v183
	v_lshl_add_u64 v[184:185], v[130:131], 0, s[6:7]
	s_mov_b32 m0, s1
	s_nop 0
	global_load_lds_dwordx4 v[184:185], off
	v_mfma_f32_32x32x16_bf16 v[48:63], v[202:205], v[190:193], v[48:63]
	v_mfma_f32_32x32x16_bf16 v[16:31], v[202:205], v[194:197], v[16:31]
	s_mov_b64 s[8:9], 0x64000
	v_readfirstlane_b32 s2, v182
	v_lshl_add_u64 v[184:185], v[130:131], 0, s[8:9]
	s_mov_b32 m0, s2
	s_nop 0
	global_load_lds_dwordx4 v[184:185], off
	v_mfma_f32_32x32x16_bf16 v[32:47], v[206:209], v[190:193], v[32:47]
	v_mfma_f32_32x32x16_bf16 v[0:15], v[206:209], v[194:197], v[0:15]
	s_mov_b64 s[10:11], 0x66000
	v_readfirstlane_b32 s3, v181
	v_lshl_add_u64 v[182:183], v[130:131], 0, s[10:11]
	s_mov_b32 m0, s3
	s_nop 0
	global_load_lds_dwordx4 v[182:183], off
	ds_read_b128 v[182:185], v144
	ds_read_b128 v[186:189], v151
	ds_read_b128 v[190:193], v151 offset:4096
	ds_read_b128 v[194:197], v144 offset:4096
	ds_read_b128 v[198:201], v144 offset:8192
	ds_read_b128 v[202:205], v144 offset:12288
	s_waitcnt lgkmcnt(0)
	v_mfma_f32_32x32x16_bf16 v[96:111], v[182:185], v[186:189], v[96:111]
	v_mfma_f32_32x32x16_bf16 v[64:79], v[182:185], v[190:193], v[64:79]
	v_readfirstlane_b32 s4, v162
	s_mov_b32 m0, s4
	s_nop 0
	global_load_lds_dwordx4 v[210:211], off
	v_mfma_f32_32x32x16_bf16 v[112:127], v[194:197], v[186:189], v[112:127]
	v_mfma_f32_32x32x16_bf16 v[80:95], v[194:197], v[190:193], v[80:95]
	v_readfirstlane_b32 s5, v165
	v_lshl_add_u64 v[182:183], v[128:129], 0, s[6:7]
	s_mov_b32 m0, s5
	s_nop 0
	global_load_lds_dwordx4 v[182:183], off
	v_mfma_f32_32x32x16_bf16 v[48:63], v[198:201], v[186:189], v[48:63]
	v_mfma_f32_32x32x16_bf16 v[16:31], v[198:201], v[190:193], v[16:31]
	v_readfirstlane_b32 s6, v164
	v_lshl_add_u64 v[182:183], v[128:129], 0, s[8:9]
	s_mov_b32 m0, s6
	s_nop 0
	global_load_lds_dwordx4 v[182:183], off
	v_mfma_f32_32x32x16_bf16 v[32:47], v[202:205], v[186:189], v[32:47]
	v_mfma_f32_32x32x16_bf16 v[0:15], v[202:205], v[190:193], v[0:15]
	v_readfirstlane_b32 s7, v163
	v_lshl_add_u64 v[164:165], v[128:129], 0, s[10:11]
	s_mov_b32 m0, s7
	s_nop 0
	global_load_lds_dwordx4 v[164:165], off
	ds_read_b128 v[162:165], v143
	ds_read_b128 v[182:185], v153
	ds_read_b128 v[186:189], v153 offset:4096
	ds_read_b128 v[190:193], v143 offset:4096
	s_mov_b64 s[8:9], 0x68000
	v_lshl_add_u64 v[202:203], v[128:129], 0, s[8:9]
	s_waitcnt lgkmcnt(0)
	v_mfma_f32_32x32x16_bf16 v[96:111], v[162:165], v[182:185], v[96:111]
	v_mfma_f32_32x32x16_bf16 v[64:79], v[162:165], v[186:189], v[64:79]
	v_mfma_f32_32x32x16_bf16 v[112:127], v[190:193], v[182:185], v[112:127]
	v_mfma_f32_32x32x16_bf16 v[80:95], v[190:193], v[186:189], v[80:95]
	ds_read_b128 v[162:165], v143 offset:8192
	ds_read_b128 v[190:193], v143 offset:12288
	s_waitcnt lgkmcnt(0)
	v_mfma_f32_32x32x16_bf16 v[48:63], v[162:165], v[182:185], v[48:63]
	v_mfma_f32_32x32x16_bf16 v[16:31], v[162:165], v[186:189], v[16:31]
	v_mfma_f32_32x32x16_bf16 v[32:47], v[190:193], v[182:185], v[32:47]
	v_mfma_f32_32x32x16_bf16 v[0:15], v[190:193], v[186:189], v[0:15]
	ds_read_b128 v[162:165], v141
	ds_read_b128 v[182:185], v152
	ds_read_b128 v[186:189], v152 offset:4096
	ds_read_b128 v[190:193], v141 offset:4096
	s_waitcnt lgkmcnt(0)
	v_mfma_f32_32x32x16_bf16 v[96:111], v[162:165], v[182:185], v[96:111]
	v_mfma_f32_32x32x16_bf16 v[64:79], v[162:165], v[186:189], v[64:79]
	v_mfma_f32_32x32x16_bf16 v[112:127], v[190:193], v[182:185], v[112:127]
	v_mfma_f32_32x32x16_bf16 v[80:95], v[190:193], v[186:189], v[80:95]
	ds_read_b128 v[162:165], v141 offset:8192
	ds_read_b128 v[190:193], v141 offset:12288
	s_waitcnt vmcnt(0)
	s_barrier
; #define MFMA(a, b, c) __builtin_amdgcn_mfma_f32_32x32x16_bf16((a), (b), (c), 0, 0, 0)
;     ...
;     const bool pre = (kt + DIST < nk);
;     const char* base = smem + (kt % NSTG) * STAGE;
;     const char* pa = base + (wrow_act + r) * 128;
;     const char* pw = base + ABYTES + (wrow_w + r) * 128;
;     constexpr int NM = NI * MJ;
;     constexpr int PPS = (NLD + 1) / 2;
; #pragma unroll
;     for (int s = 0; s < 4; ++s) {
;       bf16x8 af[MJ], wf[NI];
; #pragma unroll
;       for (int j = 0; j < MJ; ++j) af[j] = *(const bf16x8*)(pa + j * 32 * 128 + xo[s]);
; #pragma unroll
;       for (int i = 0; i < NI; ++i) wf[i] = *(const bf16x8*)(pw + i * 32 * 128 + xo[s]);
; #pragma unroll
;       for (int m = 0; m < NM; ++m) {
;         const int i = m / MJ, j = m % MJ;
;         acc[i][j] = MFMA(wf[i], af[j], acc[i][j]);
;         if (s < 2 && NM >= PPS) {
;           constexpr int EVERY = (NM / PPS) > 0 ? (NM / PPS) : 1;
;           if ((m + 1) % EVERY == 0) {
;             const int pc = s * PPS + (m + 1) / EVERY - 1;
;             if ((m + 1) / EVERY <= PPS && pc < NLD) {
;               __builtin_amdgcn_sched_barrier(0);
;               if (pre) issue_piece(kt + DIST, pc);
;               __builtin_amdgcn_sched_barrier(0);
;             }
;           }
;         }
;         if (s < 2 && NM < PPS) {
;           const int slot = s * NM + m;
;           __builtin_amdgcn_sched_barrier(0);
; #pragma unroll
;           for (int pc = 0; pc < NLD; ++pc)
;             if ((pc * 2 * NM) / NLD == slot && pre) issue_piece(kt + DIST, pc);
;           __builtin_amdgcn_sched_barrier(0);
;         }
;       }
;     }
	s_waitcnt lgkmcnt(0)
	v_mfma_f32_32x32x16_bf16 v[48:63], v[162:165], v[182:185], v[48:63]
	v_mfma_f32_32x32x16_bf16 v[16:31], v[162:165], v[186:189], v[16:31]
	v_mfma_f32_32x32x16_bf16 v[32:47], v[190:193], v[182:185], v[32:47]
	v_mfma_f32_32x32x16_bf16 v[0:15], v[190:193], v[186:189], v[0:15]
	ds_read_b128 v[162:165], v132 offset:32768
	ds_read_b128 v[182:185], v136
	ds_read_b128 v[186:189], v136 offset:4096
	ds_read_b128 v[190:193], v132 offset:36864
	ds_read_b128 v[194:197], v132 offset:40960
	ds_read_b128 v[198:201], v132 offset:45056
	s_waitcnt lgkmcnt(0)
	v_mfma_f32_32x32x16_bf16 v[96:111], v[162:165], v[182:185], v[96:111]
	v_mfma_f32_32x32x16_bf16 v[64:79], v[162:165], v[186:189], v[64:79]
	v_lshl_add_u64 v[162:163], v[130:131], 0, s[8:9]
	v_readfirstlane_b32 s8, v155
	s_mov_b32 m0, s8
	s_nop 0
	global_load_lds_dwordx4 v[162:163], off
	v_mfma_f32_32x32x16_bf16 v[112:127], v[190:193], v[182:185], v[112:127]
	v_mfma_f32_32x32x16_bf16 v[80:95], v[190:193], v[186:189], v[80:95]
	s_mov_b64 s[14:15], 0x6a000
	v_readfirstlane_b32 s9, v158
	v_lshl_add_u64 v[162:163], v[130:131], 0, s[14:15]
	s_mov_b32 m0, s9
	s_nop 0
	global_load_lds_dwordx4 v[162:163], off
	v_mfma_f32_32x32x16_bf16 v[48:63], v[194:197], v[182:185], v[48:63]
	v_mfma_f32_32x32x16_bf16 v[16:31], v[194:197], v[186:189], v[16:31]
	s_mov_b64 s[16:17], 0x6c000
	v_readfirstlane_b32 s10, v157
	v_lshl_add_u64 v[162:163], v[130:131], 0, s[16:17]
	s_mov_b32 m0, s10
	s_nop 0
	global_load_lds_dwordx4 v[162:163], off
	v_mfma_f32_32x32x16_bf16 v[32:47], v[198:201], v[182:185], v[32:47]
	v_mfma_f32_32x32x16_bf16 v[0:15], v[198:201], v[186:189], v[0:15]
	s_mov_b64 s[18:19], 0x6e000
	v_readfirstlane_b32 s11, v156
	v_lshl_add_u64 v[162:163], v[130:131], 0, s[18:19]
	s_mov_b32 m0, s11
	s_nop 0
	global_load_lds_dwordx4 v[162:163], off
	ds_read_b128 v[162:165], v133 offset:32768
	ds_read_b128 v[182:185], v137
	ds_read_b128 v[186:189], v137 offset:4096
	ds_read_b128 v[190:193], v133 offset:36864
	ds_read_b128 v[194:197], v133 offset:40960
	ds_read_b128 v[198:201], v133 offset:45056
	s_waitcnt lgkmcnt(0)
	v_mfma_f32_32x32x16_bf16 v[96:111], v[162:165], v[182:185], v[96:111]
	v_mfma_f32_32x32x16_bf16 v[64:79], v[162:165], v[186:189], v[64:79]
	v_readfirstlane_b32 s12, v154
	s_mov_b32 m0, s12
	s_nop 0
	global_load_lds_dwordx4 v[202:203], off
	v_mfma_f32_32x32x16_bf16 v[112:127], v[190:193], v[182:185], v[112:127]
	v_mfma_f32_32x32x16_bf16 v[80:95], v[190:193], v[186:189], v[80:95]
	v_readfirstlane_b32 s13, v159
	v_lshl_add_u64 v[154:155], v[128:129], 0, s[14:15]
	s_mov_b32 m0, s13
	s_nop 0
	global_load_lds_dwordx4 v[154:155], off
	v_mfma_f32_32x32x16_bf16 v[48:63], v[194:197], v[182:185], v[48:63]
	v_mfma_f32_32x32x16_bf16 v[16:31], v[194:197], v[186:189], v[16:31]
	v_readfirstlane_b32 s14, v160
	v_lshl_add_u64 v[154:155], v[128:129], 0, s[16:17]
	s_mov_b32 m0, s14
	s_nop 0
	global_load_lds_dwordx4 v[154:155], off
	v_mfma_f32_32x32x16_bf16 v[32:47], v[198:201], v[182:185], v[32:47]
	v_mfma_f32_32x32x16_bf16 v[0:15], v[198:201], v[186:189], v[0:15]
	v_readfirstlane_b32 s15, v161
	v_lshl_add_u64 v[154:155], v[128:129], 0, s[18:19]
	s_mov_b32 m0, s15
	s_nop 0
	global_load_lds_dwordx4 v[154:155], off
	ds_read_b128 v[154:157], v135 offset:32768
	ds_read_b128 v[158:161], v140
	ds_read_b128 v[162:165], v140 offset:4096
	ds_read_b128 v[182:185], v135 offset:36864
	s_mov_b64 s[16:17], 0x70000
	v_lshl_add_u64 v[194:195], v[128:129], 0, s[16:17]
	s_waitcnt lgkmcnt(0)
	v_mfma_f32_32x32x16_bf16 v[96:111], v[154:157], v[158:161], v[96:111]
	v_mfma_f32_32x32x16_bf16 v[64:79], v[154:157], v[162:165], v[64:79]
	v_mfma_f32_32x32x16_bf16 v[112:127], v[182:185], v[158:161], v[112:127]
	v_mfma_f32_32x32x16_bf16 v[80:95], v[182:185], v[162:165], v[80:95]
	ds_read_b128 v[154:157], v135 offset:40960
	ds_read_b128 v[182:185], v135 offset:45056
	s_waitcnt lgkmcnt(0)
	v_mfma_f32_32x32x16_bf16 v[48:63], v[154:157], v[158:161], v[48:63]
	v_mfma_f32_32x32x16_bf16 v[16:31], v[154:157], v[162:165], v[16:31]
	v_mfma_f32_32x32x16_bf16 v[32:47], v[182:185], v[158:161], v[32:47]
	v_mfma_f32_32x32x16_bf16 v[0:15], v[182:185], v[162:165], v[0:15]
	ds_read_b128 v[154:157], v134 offset:32768
	ds_read_b128 v[158:161], v139
	ds_read_b128 v[162:165], v139 offset:4096
	ds_read_b128 v[182:185], v134 offset:36864
	s_waitcnt lgkmcnt(0)
	v_mfma_f32_32x32x16_bf16 v[96:111], v[154:157], v[158:161], v[96:111]
	v_mfma_f32_32x32x16_bf16 v[64:79], v[154:157], v[162:165], v[64:79]
	v_mfma_f32_32x32x16_bf16 v[112:127], v[182:185], v[158:161], v[112:127]
	v_mfma_f32_32x32x16_bf16 v[80:95], v[182:185], v[162:165], v[80:95]
	ds_read_b128 v[154:157], v134 offset:40960
	ds_read_b128 v[182:185], v134 offset:45056
	s_waitcnt vmcnt(0)
	s_barrier
; #define MFMA(a, b, c) __builtin_amdgcn_mfma_f32_32x32x16_bf16((a), (b), (c), 0, 0, 0)
;     ...
;     const bool pre = (kt + DIST < nk);
;     const char* base = smem + (kt % NSTG) * STAGE;
;     const char* pa = base + (wrow_act + r) * 128;
;     const char* pw = base + ABYTES + (wrow_w + r) * 128;
;     constexpr int NM = NI * MJ;
;     constexpr int PPS = (NLD + 1) / 2;
; #pragma unroll
;     for (int s = 0; s < 4; ++s) {
;       bf16x8 af[MJ], wf[NI];
; #pragma unroll
;       for (int j = 0; j < MJ; ++j) af[j] = *(const bf16x8*)(pa + j * 32 * 128 + xo[s]);
; #pragma unroll
;       for (int i = 0; i < NI; ++i) wf[i] = *(const bf16x8*)(pw + i * 32 * 128 + xo[s]);
; #pragma unroll
;       for (int m = 0; m < NM; ++m) {
;         const int i = m / MJ, j = m % MJ;
;         acc[i][j] = MFMA(wf[i], af[j], acc[i][j]);
;         if (s < 2 && NM >= PPS) {
;           constexpr int EVERY = (NM / PPS) > 0 ? (NM / PPS) : 1;
;           if ((m + 1) % EVERY == 0) {
;             const int pc = s * PPS + (m + 1) / EVERY - 1;
;             if ((m + 1) / EVERY <= PPS && pc < NLD) {
;               __builtin_amdgcn_sched_barrier(0);
;               if (pre) issue_piece(kt + DIST, pc);
;               __builtin_amdgcn_sched_barrier(0);
;             }
;           }
;         }
;         if (s < 2 && NM < PPS) {
;           const int slot = s * NM + m;
;           __builtin_amdgcn_sched_barrier(0);
; #pragma unroll
;           for (int pc = 0; pc < NLD; ++pc)
;             if ((pc * 2 * NM) / NLD == slot && pre) issue_piece(kt + DIST, pc);
;           __builtin_amdgcn_sched_barrier(0);
;         }
;       }
;     }
	s_waitcnt lgkmcnt(0)
	v_mfma_f32_32x32x16_bf16 v[48:63], v[154:157], v[158:161], v[48:63]
	v_mfma_f32_32x32x16_bf16 v[16:31], v[154:157], v[162:165], v[16:31]
	v_mfma_f32_32x32x16_bf16 v[32:47], v[182:185], v[158:161], v[32:47]
	v_mfma_f32_32x32x16_bf16 v[0:15], v[182:185], v[162:165], v[0:15]
	ds_read_b128 v[154:157], v138
	ds_read_b128 v[158:161], v142
	ds_read_b128 v[162:165], v142 offset:4096
	ds_read_b128 v[182:185], v138 offset:4096
	ds_read_b128 v[186:189], v138 offset:8192
	ds_read_b128 v[190:193], v138 offset:12288
	s_waitcnt lgkmcnt(0)
	v_mfma_f32_32x32x16_bf16 v[96:111], v[154:157], v[158:161], v[96:111]
	v_mfma_f32_32x32x16_bf16 v[64:79], v[154:157], v[162:165], v[64:79]
	v_lshl_add_u64 v[154:155], v[130:131], 0, s[16:17]
	s_mov_b32 m0, s0
	s_nop 0
	global_load_lds_dwordx4 v[154:155], off
	v_mfma_f32_32x32x16_bf16 v[112:127], v[182:185], v[158:161], v[112:127]
	v_mfma_f32_32x32x16_bf16 v[80:95], v[182:185], v[162:165], v[80:95]
	s_mov_b64 s[16:17], 0x72000
	v_lshl_add_u64 v[154:155], v[130:131], 0, s[16:17]
	s_mov_b32 m0, s1
	s_nop 0
	global_load_lds_dwordx4 v[154:155], off
	v_mfma_f32_32x32x16_bf16 v[48:63], v[186:189], v[158:161], v[48:63]
	v_mfma_f32_32x32x16_bf16 v[16:31], v[186:189], v[162:165], v[16:31]
	s_mov_b64 s[0:1], 0x74000
	v_lshl_add_u64 v[154:155], v[130:131], 0, s[0:1]
	s_mov_b32 m0, s2
	s_nop 0
	global_load_lds_dwordx4 v[154:155], off
	v_mfma_f32_32x32x16_bf16 v[32:47], v[190:193], v[158:161], v[32:47]
	v_mfma_f32_32x32x16_bf16 v[0:15], v[190:193], v[162:165], v[0:15]
	s_mov_b64 s[18:19], 0x76000
	v_lshl_add_u64 v[154:155], v[130:131], 0, s[18:19]
	s_mov_b32 m0, s3
	s_nop 0
	global_load_lds_dwordx4 v[154:155], off
	ds_read_b128 v[154:157], v144
	ds_read_b128 v[158:161], v151
	ds_read_b128 v[162:165], v151 offset:4096
	ds_read_b128 v[182:185], v144 offset:4096
	ds_read_b128 v[186:189], v144 offset:8192
	ds_read_b128 v[190:193], v144 offset:12288
	s_waitcnt lgkmcnt(0)
	v_mfma_f32_32x32x16_bf16 v[96:111], v[154:157], v[158:161], v[96:111]
	v_mfma_f32_32x32x16_bf16 v[64:79], v[154:157], v[162:165], v[64:79]
	s_mov_b32 m0, s4
	s_nop 0
	global_load_lds_dwordx4 v[194:195], off
	v_mfma_f32_32x32x16_bf16 v[112:127], v[182:185], v[158:161], v[112:127]
	v_mfma_f32_32x32x16_bf16 v[80:95], v[182:185], v[162:165], v[80:95]
	v_lshl_add_u64 v[154:155], v[128:129], 0, s[16:17]
	s_mov_b32 m0, s5
	s_nop 0
	global_load_lds_dwordx4 v[154:155], off
	v_mfma_f32_32x32x16_bf16 v[48:63], v[186:189], v[158:161], v[48:63]
	v_mfma_f32_32x32x16_bf16 v[16:31], v[186:189], v[162:165], v[16:31]
	v_lshl_add_u64 v[154:155], v[128:129], 0, s[0:1]
	s_mov_b32 m0, s6
	s_nop 0
	global_load_lds_dwordx4 v[154:155], off
	v_mfma_f32_32x32x16_bf16 v[32:47], v[190:193], v[158:161], v[32:47]
	v_mfma_f32_32x32x16_bf16 v[0:15], v[190:193], v[162:165], v[0:15]
	v_lshl_add_u64 v[154:155], v[128:129], 0, s[18:19]
	s_mov_b32 m0, s7
	s_nop 0
	global_load_lds_dwordx4 v[154:155], off
	ds_read_b128 v[154:157], v143
	ds_read_b128 v[158:161], v153
	ds_read_b128 v[162:165], v153 offset:4096
	ds_read_b128 v[182:185], v143 offset:4096
	s_mov_b64 s[0:1], 0x78000
	v_lshl_add_u64 v[194:195], v[128:129], 0, s[0:1]
	s_waitcnt lgkmcnt(0)
	v_mfma_f32_32x32x16_bf16 v[96:111], v[154:157], v[158:161], v[96:111]
	v_mfma_f32_32x32x16_bf16 v[64:79], v[154:157], v[162:165], v[64:79]
	v_mfma_f32_32x32x16_bf16 v[112:127], v[182:185], v[158:161], v[112:127]
	v_mfma_f32_32x32x16_bf16 v[80:95], v[182:185], v[162:165], v[80:95]
	ds_read_b128 v[154:157], v143 offset:8192
	ds_read_b128 v[182:185], v143 offset:12288
	s_waitcnt lgkmcnt(0)
	v_mfma_f32_32x32x16_bf16 v[48:63], v[154:157], v[158:161], v[48:63]
	v_mfma_f32_32x32x16_bf16 v[16:31], v[154:157], v[162:165], v[16:31]
	v_mfma_f32_32x32x16_bf16 v[32:47], v[182:185], v[158:161], v[32:47]
	v_mfma_f32_32x32x16_bf16 v[0:15], v[182:185], v[162:165], v[0:15]
	ds_read_b128 v[154:157], v141
	ds_read_b128 v[158:161], v152
	ds_read_b128 v[162:165], v152 offset:4096
	ds_read_b128 v[182:185], v141 offset:4096
	s_waitcnt lgkmcnt(0)
	v_mfma_f32_32x32x16_bf16 v[96:111], v[154:157], v[158:161], v[96:111]
	v_mfma_f32_32x32x16_bf16 v[64:79], v[154:157], v[162:165], v[64:79]
	v_mfma_f32_32x32x16_bf16 v[112:127], v[182:185], v[158:161], v[112:127]
	v_mfma_f32_32x32x16_bf16 v[80:95], v[182:185], v[162:165], v[80:95]
	ds_read_b128 v[154:157], v141 offset:8192
	ds_read_b128 v[182:185], v141 offset:12288
	s_waitcnt vmcnt(0)
	s_barrier
; #define MFMA(a, b, c) __builtin_amdgcn_mfma_f32_32x32x16_bf16((a), (b), (c), 0, 0, 0)
;     ...
;     const bool pre = (kt + DIST < nk);
;     const char* base = smem + (kt % NSTG) * STAGE;
;     const char* pa = base + (wrow_act + r) * 128;
;     const char* pw = base + ABYTES + (wrow_w + r) * 128;
;     constexpr int NM = NI * MJ;
;     constexpr int PPS = (NLD + 1) / 2;
; #pragma unroll
;     for (int s = 0; s < 4; ++s) {
;       bf16x8 af[MJ], wf[NI];
; #pragma unroll
;       for (int j = 0; j < MJ; ++j) af[j] = *(const bf16x8*)(pa + j * 32 * 128 + xo[s]);
; #pragma unroll
;       for (int i = 0; i < NI; ++i) wf[i] = *(const bf16x8*)(pw + i * 32 * 128 + xo[s]);
; #pragma unroll
;       for (int m = 0; m < NM; ++m) {
;         const int i = m / MJ, j = m % MJ;
;         acc[i][j] = MFMA(wf[i], af[j], acc[i][j]);
;         if (s < 2 && NM >= PPS) {
;           constexpr int EVERY = (NM / PPS) > 0 ? (NM / PPS) : 1;
;           if ((m + 1) % EVERY == 0) {
;             const int pc = s * PPS + (m + 1) / EVERY - 1;
;             if ((m + 1) / EVERY <= PPS && pc < NLD) {
;               __builtin_amdgcn_sched_barrier(0);
;               if (pre) issue_piece(kt + DIST, pc);
;               __builtin_amdgcn_sched_barrier(0);
;             }
;           }
;         }
;         if (s < 2 && NM < PPS) {
;           const int slot = s * NM + m;
;           __builtin_amdgcn_sched_barrier(0);
; #pragma unroll
;           for (int pc = 0; pc < NLD; ++pc)
;             if ((pc * 2 * NM) / NLD == slot && pre) issue_piece(kt + DIST, pc);
;           __builtin_amdgcn_sched_barrier(0);
;         }
;       }
;     }
	s_waitcnt lgkmcnt(0)
	v_mfma_f32_32x32x16_bf16 v[48:63], v[154:157], v[158:161], v[48:63]
	v_mfma_f32_32x32x16_bf16 v[16:31], v[154:157], v[162:165], v[16:31]
	v_mfma_f32_32x32x16_bf16 v[32:47], v[182:185], v[158:161], v[32:47]
	v_mfma_f32_32x32x16_bf16 v[0:15], v[182:185], v[162:165], v[0:15]
	ds_read_b128 v[154:157], v132 offset:32768
	ds_read_b128 v[158:161], v136
	ds_read_b128 v[162:165], v136 offset:4096
	ds_read_b128 v[182:185], v132 offset:36864
	ds_read_b128 v[186:189], v132 offset:40960
	ds_read_b128 v[190:193], v132 offset:45056
	s_waitcnt lgkmcnt(0)
	v_mfma_f32_32x32x16_bf16 v[96:111], v[154:157], v[158:161], v[96:111]
	v_mfma_f32_32x32x16_bf16 v[64:79], v[154:157], v[162:165], v[64:79]
	v_lshl_add_u64 v[154:155], v[130:131], 0, s[0:1]
	s_mov_b32 m0, s8
	s_nop 0
	global_load_lds_dwordx4 v[154:155], off
	v_mfma_f32_32x32x16_bf16 v[112:127], v[182:185], v[158:161], v[112:127]
	v_mfma_f32_32x32x16_bf16 v[80:95], v[182:185], v[162:165], v[80:95]
	s_mov_b64 s[0:1], 0x7a000
	v_lshl_add_u64 v[154:155], v[130:131], 0, s[0:1]
	s_mov_b32 m0, s9
	s_nop 0
	global_load_lds_dwordx4 v[154:155], off
	v_mfma_f32_32x32x16_bf16 v[48:63], v[186:189], v[158:161], v[48:63]
	v_mfma_f32_32x32x16_bf16 v[16:31], v[186:189], v[162:165], v[16:31]
	s_mov_b64 s[2:3], 0x7c000
	v_lshl_add_u64 v[154:155], v[130:131], 0, s[2:3]
	s_mov_b32 m0, s10
	s_nop 0
	global_load_lds_dwordx4 v[154:155], off
	v_mfma_f32_32x32x16_bf16 v[32:47], v[190:193], v[158:161], v[32:47]
	v_mfma_f32_32x32x16_bf16 v[0:15], v[190:193], v[162:165], v[0:15]
	s_mov_b64 s[4:5], 0x7e000
	v_lshl_add_u64 v[130:131], v[130:131], 0, s[4:5]
	s_mov_b32 m0, s11
	s_nop 0
	global_load_lds_dwordx4 v[130:131], off
	ds_read_b128 v[154:157], v133 offset:32768
	ds_read_b128 v[158:161], v137
	ds_read_b128 v[162:165], v137 offset:4096
	ds_read_b128 v[182:185], v133 offset:36864
	ds_read_b128 v[186:189], v133 offset:40960
	ds_read_b128 v[130:133], v133 offset:45056
	s_waitcnt lgkmcnt(0)
	v_mfma_f32_32x32x16_bf16 v[96:111], v[154:157], v[158:161], v[96:111]
	v_mfma_f32_32x32x16_bf16 v[64:79], v[154:157], v[162:165], v[64:79]
	s_mov_b32 m0, s12
	s_nop 0
	global_load_lds_dwordx4 v[194:195], off
	v_mfma_f32_32x32x16_bf16 v[112:127], v[182:185], v[158:161], v[112:127]
	v_mfma_f32_32x32x16_bf16 v[80:95], v[182:185], v[162:165], v[80:95]
	v_lshl_add_u64 v[136:137], v[128:129], 0, s[0:1]
	s_mov_b32 m0, s13
	s_nop 0
	global_load_lds_dwordx4 v[136:137], off
	v_mfma_f32_32x32x16_bf16 v[48:63], v[186:189], v[158:161], v[48:63]
	v_mfma_f32_32x32x16_bf16 v[16:31], v[186:189], v[162:165], v[16:31]
	v_lshl_add_u64 v[136:137], v[128:129], 0, s[2:3]
	s_mov_b32 m0, s14
	s_nop 0
	global_load_lds_dwordx4 v[136:137], off
	v_mfma_f32_32x32x16_bf16 v[32:47], v[130:133], v[158:161], v[32:47]
	v_mfma_f32_32x32x16_bf16 v[0:15], v[130:133], v[162:165], v[0:15]
	v_lshl_add_u64 v[128:129], v[128:129], 0, s[4:5]
	s_mov_b32 m0, s15
	s_nop 0
	global_load_lds_dwordx4 v[128:129], off
	ds_read_b128 v[128:131], v135 offset:32768
	ds_read_b128 v[154:157], v140
	ds_read_b128 v[158:161], v140 offset:4096
	ds_read_b128 v[162:165], v135 offset:36864
	s_waitcnt lgkmcnt(0)
	v_mfma_f32_32x32x16_bf16 v[96:111], v[128:131], v[154:157], v[96:111]
	v_mfma_f32_32x32x16_bf16 v[64:79], v[128:131], v[158:161], v[64:79]
	v_mfma_f32_32x32x16_bf16 v[112:127], v[162:165], v[154:157], v[112:127]
	v_mfma_f32_32x32x16_bf16 v[80:95], v[162:165], v[158:161], v[80:95]
	ds_read_b128 v[128:131], v135 offset:40960
	ds_read_b128 v[162:165], v135 offset:45056
	s_waitcnt lgkmcnt(0)
	v_mfma_f32_32x32x16_bf16 v[48:63], v[128:131], v[154:157], v[48:63]
	v_mfma_f32_32x32x16_bf16 v[16:31], v[128:131], v[158:161], v[16:31]
	v_mfma_f32_32x32x16_bf16 v[32:47], v[162:165], v[154:157], v[32:47]
	v_mfma_f32_32x32x16_bf16 v[0:15], v[162:165], v[158:161], v[0:15]
	ds_read_b128 v[128:131], v134 offset:32768
	ds_read_b128 v[154:157], v139
	ds_read_b128 v[158:161], v139 offset:4096
	ds_read_b128 v[162:165], v134 offset:36864
	s_waitcnt lgkmcnt(0)
	v_mfma_f32_32x32x16_bf16 v[96:111], v[128:131], v[154:157], v[96:111]
	v_mfma_f32_32x32x16_bf16 v[64:79], v[128:131], v[158:161], v[64:79]
	ds_read_b128 v[128:131], v134 offset:40960
	ds_read_b128 v[132:135], v134 offset:45056
	s_waitcnt vmcnt(0)
	s_barrier
; #define MFMA(a, b, c) __builtin_amdgcn_mfma_f32_32x32x16_bf16((a), (b), (c), 0, 0, 0)
;     ...
;     for (int s = 0; s < 4; ++s) {
;       bf16x8 af[MJ], wf[NI];
; #pragma unroll
;       for (int j = 0; j < MJ; ++j) af[j] = *(const bf16x8*)(pa + j * 32 * 128 + xo[s]);
; #pragma unroll
;       for (int i = 0; i < NI; ++i) wf[i] = *(const bf16x8*)(pw + i * 32 * 128 + xo[s]);
; #pragma unroll
;       for (int m = 0; m < NM; ++m) {
;         const int i = m / MJ, j = m % MJ;
;         acc[i][j] = MFMA(wf[i], af[j], acc[i][j]);
;         if (s < 2 && NM >= PPS) {
;           constexpr int EVERY = (NM / PPS) > 0 ? (NM / PPS) : 1;
;           if ((m + 1) % EVERY == 0) {
;             const int pc = s * PPS + (m + 1) / EVERY - 1;
;             if ((m + 1) / EVERY <= PPS && pc < NLD) {
;               __builtin_amdgcn_sched_barrier(0);
;               if (pre) issue_piece(kt + DIST, pc);
;               __builtin_amdgcn_sched_barrier(0);
;             }
;           }
;         }
;         if (s < 2 && NM < PPS) {
;           const int slot = s * NM + m;
;           __builtin_amdgcn_sched_barrier(0);
; #pragma unroll
;           for (int pc = 0; pc < NLD; ++pc)
;             if ((pc * 2 * NM) / NLD == slot && pre) issue_piece(kt + DIST, pc);
;           __builtin_amdgcn_sched_barrier(0);
;         }
;       }
;     }
;   }
;   __builtin_amdgcn_s_barrier();
; DEV void inproj_epilogue(f32x16 (&acc)[2][2], int fb, int m0w, const Params& p, int l) {
;     ...
;   if (fb == 35) return;
;   const bool is_qk = (fb < 16) || (fb >= 36 && fb < 52);
;   if (is_qk) {
;     const float* gain;
;     u16* dst;
;     float qs = 1.f;
;     bool rope = false;
;     int head;
;     if (fb < 8) { gain = p.na_q_g + l * 64; dst = (u16*)(ws + OFF_NAQ); head = fb; qs = 0.125f * LOG2E; }
;     else if (fb < 16) { gain = p.na_k_g + l * 64; dst = (u16*)(ws + OFF_NAK); head = fb - 8; }
;     else if (fb < 44) { gain = p.diff_q_g + l * 64; dst = (u16*)(ws + OFF_DQ); head = fb - 36; qs = 0.125f * LOG2E; rope = true; }
;     else { gain = p.diff_k_g + l * 64; dst = (u16*)(ws + OFF_DK); head = fb - 44; rope = true; }
	v_mfma_f32_32x32x16_bf16 v[112:127], v[162:165], v[154:157], v[112:127]
	v_mfma_f32_32x32x16_bf16 v[80:95], v[162:165], v[158:161], v[80:95]
	s_waitcnt lgkmcnt(0)
	v_mfma_f32_32x32x16_bf16 v[48:63], v[128:131], v[154:157], v[48:63]
	v_mfma_f32_32x32x16_bf16 v[16:31], v[128:131], v[158:161], v[16:31]
	v_mfma_f32_32x32x16_bf16 v[32:47], v[132:135], v[154:157], v[32:47]
	v_mfma_f32_32x32x16_bf16 v[0:15], v[132:135], v[158:161], v[0:15]
	ds_read_b128 v[128:131], v138
	ds_read_b128 v[132:135], v142
	ds_read_b128 v[154:157], v142 offset:4096
	ds_read_b128 v[158:161], v138 offset:4096
	ds_read_b128 v[162:165], v138 offset:8192
	ds_read_b128 v[136:139], v138 offset:12288
	s_waitcnt lgkmcnt(0)
	v_mfma_f32_32x32x16_bf16 v[96:111], v[128:131], v[132:135], v[96:111]
	v_mfma_f32_32x32x16_bf16 v[64:79], v[128:131], v[154:157], v[64:79]
	v_mfma_f32_32x32x16_bf16 v[112:127], v[158:161], v[132:135], v[112:127]
	v_mfma_f32_32x32x16_bf16 v[80:95], v[158:161], v[154:157], v[80:95]
	v_mfma_f32_32x32x16_bf16 v[48:63], v[162:165], v[132:135], v[48:63]
	v_mfma_f32_32x32x16_bf16 v[16:31], v[162:165], v[154:157], v[16:31]
	v_mfma_f32_32x32x16_bf16 v[32:47], v[136:139], v[132:135], v[32:47]
	v_mfma_f32_32x32x16_bf16 v[0:15], v[136:139], v[154:157], v[0:15]
	ds_read_b128 v[128:131], v144
	ds_read_b128 v[132:135], v151
	ds_read_b128 v[136:139], v151 offset:4096
	ds_read_b128 v[154:157], v144 offset:4096
	ds_read_b128 v[158:161], v144 offset:8192
	ds_read_b128 v[162:165], v144 offset:12288
	s_waitcnt lgkmcnt(0)
	v_mfma_f32_32x32x16_bf16 v[96:111], v[128:131], v[132:135], v[96:111]
	v_mfma_f32_32x32x16_bf16 v[64:79], v[128:131], v[136:139], v[64:79]
	v_mfma_f32_32x32x16_bf16 v[112:127], v[154:157], v[132:135], v[112:127]
	v_mfma_f32_32x32x16_bf16 v[80:95], v[154:157], v[136:139], v[80:95]
	v_mfma_f32_32x32x16_bf16 v[48:63], v[158:161], v[132:135], v[48:63]
	v_mfma_f32_32x32x16_bf16 v[16:31], v[158:161], v[136:139], v[16:31]
	v_mfma_f32_32x32x16_bf16 v[32:47], v[162:165], v[132:135], v[32:47]
	v_mfma_f32_32x32x16_bf16 v[0:15], v[162:165], v[136:139], v[0:15]
	ds_read_b128 v[128:131], v143
	ds_read_b128 v[132:135], v153
	ds_read_b128 v[136:139], v153 offset:4096
	s_lshl_b32 s27, s50, 2
	v_readlane_b32 s0, v242, 1
	v_readlane_b32 s2, v242, 3
	s_waitcnt lgkmcnt(0)
	v_mfma_f32_32x32x16_bf16 v[96:111], v[128:131], v[132:135], v[96:111]
	v_readlane_b32 s3, v242, 4
	v_readlane_b32 s6, v242, 7
	v_readlane_b32 s7, v242, 8
	v_readlane_b32 s1, v242, 2
	s_mov_b64 s[2:3], s[6:7]
	v_lshl_add_u32 v151, s52, 8, v146
	v_readlane_b32 s4, v242, 5
	v_mfma_f32_32x32x16_bf16 v[64:79], v[128:131], v[136:139], v[64:79]
	ds_read_b128 v[128:131], v143 offset:4096
	v_readlane_b32 s5, v242, 6
	s_waitcnt lgkmcnt(0)
	v_mfma_f32_32x32x16_bf16 v[112:127], v[128:131], v[132:135], v[112:127]
	v_mfma_f32_32x32x16_bf16 v[80:95], v[128:131], v[136:139], v[80:95]
	ds_read_b128 v[128:131], v143 offset:8192
	s_waitcnt lgkmcnt(0)
	v_mfma_f32_32x32x16_bf16 v[48:63], v[128:131], v[132:135], v[48:63]
	v_mfma_f32_32x32x16_bf16 v[16:31], v[128:131], v[136:139], v[16:31]
	ds_read_b128 v[128:131], v143 offset:12288
	s_waitcnt lgkmcnt(0)
	v_mfma_f32_32x32x16_bf16 v[32:47], v[128:131], v[132:135], v[32:47]
	v_mfma_f32_32x32x16_bf16 v[0:15], v[128:131], v[136:139], v[0:15]
	ds_read_b128 v[128:131], v141
	ds_read_b128 v[132:135], v152
	ds_read_b128 v[154:157], v152 offset:4096
	v_or_b32_e32 v152, s27, v148
	v_cmp_lt_i32_e64 s[38:39], 15, v152
	s_waitcnt lgkmcnt(0)
	v_mfma_f32_32x32x16_bf16 v[96:111], v[128:131], v[132:135], v[96:111]
	v_mfma_f32_32x32x16_bf16 v[64:79], v[128:131], v[154:157], v[64:79]
	ds_read_b128 v[128:131], v141 offset:4096
	s_waitcnt lgkmcnt(0)
	v_mfma_f32_32x32x16_bf16 v[112:127], v[128:131], v[132:135], v[112:127]
	v_mfma_f32_32x32x16_bf16 v[80:95], v[128:131], v[154:157], v[80:95]
	ds_read_b128 v[128:131], v141 offset:8192
	ds_read_b128 v[138:141], v141 offset:12288
	s_barrier
	s_waitcnt lgkmcnt(0)
	v_mfma_f32_32x32x16_bf16 v[48:63], v[128:131], v[132:135], v[48:63]
	v_mfma_f32_32x32x16_bf16 v[16:31], v[128:131], v[154:157], v[16:31]
	v_subrev_u32_e32 v131, 36, v152
	v_mov_b32_e32 v128, v147
	v_cmp_lt_u32_e32 vcc, 15, v131
	s_and_b64 s[0:1], s[38:39], vcc
	v_bfe_u32 v137, v128, 5, 1
	v_and_b32_e32 v142, 31, v128
	v_mfma_f32_32x32x16_bf16 v[32:47], v[138:141], v[132:135], v[32:47]
	v_mfma_f32_32x32x16_bf16 v[0:15], v[138:141], v[154:157], v[0:15]
	s_and_saveexec_b64 s[4:5], s[0:1]
	s_xor_b64 s[4:5], exec, s[4:5]
	s_cbranch_execz .LBB0_393
	v_cmp_ne_u32_e32 vcc, 34, v152
	s_and_saveexec_b64 s[0:1], vcc
	s_xor_b64 s[6:7], exec, s[0:1]
	s_cbranch_execz .LBB0_390
	s_cmp_gt_u32 s27, 23
	s_mov_b64 s[12:13], -1
	s_cbranch_scc0 .LBB0_373
	v_cmp_lt_u32_e32 vcc, 29, v152
	s_and_saveexec_b64 s[12:13], vcc
	s_xor_b64 s[12:13], exec, s[12:13]
	s_cbranch_execz .LBB0_370
	v_cmp_lt_u32_e32 vcc, 33, v152
	s_and_saveexec_b64 s[16:17], vcc
	s_xor_b64 s[16:17], exec, s[16:17]
	s_cbranch_execz .LBB0_367
	s_cmp_gt_u32 s27, 59
	s_mov_b64 s[0:1], -1
	s_cbranch_scc0 .LBB0_363
	s_cmpk_gt_u32 s27, 0x53
	v_lshlrev_b32_e32 v129, 6, v152
	s_mov_b64 s[8:9], -1
	s_mov_b64 s[10:11], -1
	s_cbranch_scc0 .LBB0_361
	s_add_u32 s14, s2, 0x11fd6100
	s_addc_u32 s15, s3, 0
	v_add_u32_e32 v128, 0xffffeb00, v129
	s_mov_b64 s[10:11], 0
